# all flat_load/flat_store with global addresses (446 sites, compiler epilogues) rewritten as global_load/global_store: no LDS-aperture path, no lgkmcnt coupling
# baseline (speedup 1.0000x reference)
.LBB0_102:
	s_add_u32 s8, s2, 0xfffc0080
	s_addc_u32 s9, s3, -1
	s_add_i32 s79, 0, 0x10000
	s_waitcnt vmcnt(6)
	v_add_u32_e32 v28, s79, v169
	ds_read_b128 v[16:19], v28
	ds_read_b128 v[20:23], v28 offset:1024
	ds_read_b128 v[24:27], v28 offset:2048
	ds_read_b128 v[28:31], v28 offset:3072
	s_cmp_eq_u32 s78, 12
	s_cselect_b32 s15, s13, s9
	s_cselect_b32 s14, s22, s8
	s_cselect_b32 s9, s34, s75
	s_cselect_b32 s8, s35, s71
	v_lshl_add_u64 v[166:167], s[2:3], 0, v[164:165]
	s_add_i32 m0, s55, 0xc000
	ds_read_b128 v[172:175], v171
	ds_read_b128 v[176:179], v171 offset:1024
	ds_read_b128 v[180:183], v171 offset:2048
	ds_read_b128 v[194:197], v171 offset:3072
	ds_read_b128 v[198:201], v171 offset:4096
	ds_read_b128 v[202:205], v171 offset:5120
	ds_read_b128 v[206:209], v171 offset:6144
	ds_read_b128 v[210:213], v171 offset:7168
	global_load_lds_dwordx4 v[166:167], off
	v_lshl_add_u64 v[166:167], s[2:3], 0, v[162:163]
	s_add_i32 m0, s55, 0xe000
	s_nop 0
	global_load_lds_dwordx4 v[166:167], off
	s_waitcnt lgkmcnt(8)
	s_barrier
	s_waitcnt lgkmcnt(0)
	s_setprio 1
	s_waitcnt lgkmcnt(0)
	v_mfma_f32_16x16x32_bf16 v[140:143], v[16:19], v[172:175], v[140:143]
	v_mfma_f32_16x16x32_bf16 v[136:139], v[24:27], v[172:175], v[136:139]
	v_mfma_f32_16x16x32_bf16 v[124:127], v[16:19], v[180:183], v[124:127]
	v_mfma_f32_16x16x32_bf16 v[120:123], v[24:27], v[180:183], v[120:123]
	v_mfma_f32_16x16x32_bf16 v[108:111], v[16:19], v[198:201], v[108:111]
	v_mfma_f32_16x16x32_bf16 v[104:107], v[24:27], v[198:201], v[104:107]
	v_mfma_f32_16x16x32_bf16 v[92:95], v[16:19], v[206:209], v[92:95]
	v_mfma_f32_16x16x32_bf16 v[88:91], v[24:27], v[206:209], v[88:91]
	v_mfma_f32_16x16x32_bf16 v[140:143], v[20:23], v[176:179], v[140:143]
	v_mfma_f32_16x16x32_bf16 v[136:139], v[28:31], v[176:179], v[136:139]
	v_mfma_f32_16x16x32_bf16 v[124:127], v[20:23], v[194:197], v[124:127]
	v_mfma_f32_16x16x32_bf16 v[120:123], v[28:31], v[194:197], v[120:123]
	v_mfma_f32_16x16x32_bf16 v[108:111], v[20:23], v[202:205], v[108:111]
	v_mfma_f32_16x16x32_bf16 v[104:107], v[28:31], v[202:205], v[104:107]
	v_mfma_f32_16x16x32_bf16 v[92:95], v[20:23], v[210:213], v[92:95]
	v_mfma_f32_16x16x32_bf16 v[88:91], v[28:31], v[210:213], v[88:91]
	s_setprio 0
	s_barrier
	s_add_i32 vcc_lo, 0, 0x14000
	v_add_u32_e32 v166, vcc_lo, v169
	s_add_i32 s79, s79, s54
	ds_read_b128 v[214:217], v166
	ds_read_b128 v[218:221], v166 offset:1024
	ds_read_b128 v[222:225], v166 offset:2048
	ds_read_b128 v[232:235], v166 offset:3072
	v_lshl_add_u64 v[166:167], s[8:9], 0, v[146:147]
	s_mov_b32 m0, s79
	v_lshl_add_u64 v[186:187], s[8:9], 0, v[150:151]
	global_load_lds_dwordx4 v[166:167], off
	s_add_i32 m0, s79, 0x2000
	s_nop 0
	global_load_lds_dwordx4 v[186:187], off
	s_barrier
	s_waitcnt lgkmcnt(0)
	s_setprio 1
	s_waitcnt lgkmcnt(0)
	v_mfma_f32_16x16x32_bf16 v[132:135], v[214:217], v[172:175], v[132:135]
	v_mfma_f32_16x16x32_bf16 v[128:131], v[222:225], v[172:175], v[128:131]
	v_mfma_f32_16x16x32_bf16 v[116:119], v[214:217], v[180:183], v[116:119]
	v_mfma_f32_16x16x32_bf16 v[112:115], v[222:225], v[180:183], v[112:115]
	v_mfma_f32_16x16x32_bf16 v[100:103], v[214:217], v[198:201], v[100:103]
	v_mfma_f32_16x16x32_bf16 v[96:99], v[222:225], v[198:201], v[96:99]
	v_mfma_f32_16x16x32_bf16 v[84:87], v[214:217], v[206:209], v[84:87]
	v_mfma_f32_16x16x32_bf16 v[80:83], v[222:225], v[206:209], v[80:83]
	v_mfma_f32_16x16x32_bf16 v[132:135], v[218:221], v[176:179], v[132:135]
	v_mfma_f32_16x16x32_bf16 v[128:131], v[232:235], v[176:179], v[128:131]
	v_mfma_f32_16x16x32_bf16 v[116:119], v[218:221], v[194:197], v[116:119]
	v_mfma_f32_16x16x32_bf16 v[112:115], v[232:235], v[194:197], v[112:115]
	v_mfma_f32_16x16x32_bf16 v[100:103], v[218:221], v[202:205], v[100:103]
	v_mfma_f32_16x16x32_bf16 v[96:99], v[232:235], v[202:205], v[96:99]
	v_mfma_f32_16x16x32_bf16 v[84:87], v[218:221], v[210:213], v[84:87]
	v_mfma_f32_16x16x32_bf16 v[80:83], v[232:235], v[210:213], v[80:83]
	s_setprio 0
	s_mov_b32 m0, s55
	v_lshl_add_u64 v[188:189], s[14:15], 0, v[144:145]
	s_barrier
	ds_read_b128 v[172:175], v171 offset:16384
	ds_read_b128 v[176:179], v171 offset:17408
	ds_read_b128 v[180:183], v171 offset:18432
	ds_read_b128 v[194:197], v171 offset:19456
	ds_read_b128 v[198:201], v171 offset:20480
	ds_read_b128 v[202:205], v171 offset:21504
	ds_read_b128 v[206:209], v171 offset:22528
	ds_read_b128 v[210:213], v171 offset:23552
	global_load_lds_dwordx4 v[188:189], off
	v_lshl_add_u64 v[236:237], s[14:15], 0, v[148:149]
	s_mov_b32 m0, s60
	s_nop 0
	global_load_lds_dwordx4 v[236:237], off
	s_barrier
	s_waitcnt lgkmcnt(0)
	s_setprio 1
	s_waitcnt lgkmcnt(0)
	v_mfma_f32_16x16x32_bf16 v[76:79], v[16:19], v[172:175], v[76:79]
	v_mfma_f32_16x16x32_bf16 v[72:75], v[24:27], v[172:175], v[72:75]
	v_mfma_f32_16x16x32_bf16 v[60:63], v[16:19], v[180:183], v[60:63]
	v_mfma_f32_16x16x32_bf16 v[56:59], v[24:27], v[180:183], v[56:59]
	v_mfma_f32_16x16x32_bf16 v[44:47], v[16:19], v[198:201], v[44:47]
	v_mfma_f32_16x16x32_bf16 v[40:43], v[24:27], v[198:201], v[40:43]
	v_mfma_f32_16x16x32_bf16 v[12:15], v[16:19], v[206:209], v[12:15]
	v_mfma_f32_16x16x32_bf16 v[8:11], v[24:27], v[206:209], v[8:11]
	v_mfma_f32_16x16x32_bf16 v[76:79], v[20:23], v[176:179], v[76:79]
	v_mfma_f32_16x16x32_bf16 v[72:75], v[28:31], v[176:179], v[72:75]
	v_mfma_f32_16x16x32_bf16 v[60:63], v[20:23], v[194:197], v[60:63]
	v_mfma_f32_16x16x32_bf16 v[56:59], v[28:31], v[194:197], v[56:59]
	v_mfma_f32_16x16x32_bf16 v[44:47], v[20:23], v[202:205], v[44:47]
	v_mfma_f32_16x16x32_bf16 v[40:43], v[28:31], v[202:205], v[40:43]
	v_mfma_f32_16x16x32_bf16 v[12:15], v[20:23], v[210:213], v[12:15]
	v_mfma_f32_16x16x32_bf16 v[8:11], v[28:31], v[210:213], v[8:11]
	s_setprio 0
	s_barrier
	s_add_u32 s82, s8, 0x10000
	s_addc_u32 s83, s9, 0
	s_add_i32 s79, vcc_lo, s54
	v_lshl_add_u64 v[16:17], s[82:83], 0, v[146:147]
	s_mov_b32 m0, s79
	s_nop 0
	global_load_lds_dwordx4 v[16:17], off
	v_lshl_add_u64 v[16:17], s[82:83], 0, v[150:151]
	s_add_i32 m0, s79, 0x2000
	s_nop 0
	global_load_lds_dwordx4 v[16:17], off
	s_waitcnt vmcnt(6)
	s_barrier
	s_setprio 1
	v_mfma_f32_16x16x32_bf16 v[36:39], v[214:217], v[198:201], v[36:39]
	v_mfma_f32_16x16x32_bf16 v[32:35], v[222:225], v[198:201], v[32:35]
	v_mfma_f32_16x16x32_bf16 v[4:7], v[214:217], v[206:209], v[4:7]
	v_mfma_f32_16x16x32_bf16 v[0:3], v[222:225], v[206:209], v[0:3]
	v_mfma_f32_16x16x32_bf16 v[16:19], v[214:217], v[172:175], v[68:71]
	v_mfma_f32_16x16x32_bf16 v[20:23], v[222:225], v[172:175], v[64:67]
	v_mfma_f32_16x16x32_bf16 v[24:27], v[214:217], v[180:183], v[52:55]
	v_mfma_f32_16x16x32_bf16 v[28:31], v[222:225], v[180:183], v[48:51]
	v_mfma_f32_16x16x32_bf16 v[36:39], v[218:221], v[202:205], v[36:39]
	v_mfma_f32_16x16x32_bf16 v[32:35], v[232:235], v[202:205], v[32:35]
	v_mfma_f32_16x16x32_bf16 v[4:7], v[218:221], v[210:213], v[4:7]
	v_mfma_f32_16x16x32_bf16 v[0:3], v[232:235], v[210:213], v[0:3]
	v_mfma_f32_16x16x32_bf16 v[16:19], v[218:221], v[176:179], v[16:19]
	v_mfma_f32_16x16x32_bf16 v[20:23], v[232:235], v[176:179], v[20:23]
	v_mfma_f32_16x16x32_bf16 v[24:27], v[218:221], v[194:197], v[24:27]
	v_mfma_f32_16x16x32_bf16 v[28:31], v[232:235], v[194:197], v[28:31]
	s_setprio 0
	s_add_i32 s79, 0, 0x18000
	v_add_u32_e32 v68, s79, v169
	s_barrier
	ds_read_b128 v[48:51], v68
	ds_read_b128 v[52:55], v68 offset:1024
	ds_read_b128 v[64:67], v68 offset:2048
	ds_read_b128 v[68:71], v68 offset:3072
	s_add_u32 s14, s14, 0x40000
	s_addc_u32 s15, s15, 0
	s_mov_b32 m0, s61
	v_lshl_add_u64 v[214:215], s[14:15], 0, v[144:145]
	ds_read_b128 v[172:175], v171 offset:32768
	ds_read_b128 v[176:179], v171 offset:33792
	ds_read_b128 v[180:183], v171 offset:34816
	ds_read_b128 v[194:197], v171 offset:35840
	ds_read_b128 v[198:201], v171 offset:36864
	ds_read_b128 v[202:205], v171 offset:37888
	ds_read_b128 v[206:209], v171 offset:38912
	ds_read_b128 v[210:213], v171 offset:39936
	global_load_lds_dwordx4 v[214:215], off
	v_lshl_add_u64 v[214:215], s[14:15], 0, v[148:149]
	s_mov_b32 m0, s62
	s_nop 0
	global_load_lds_dwordx4 v[214:215], off
	s_waitcnt lgkmcnt(8)
	s_barrier
	s_waitcnt lgkmcnt(0)
	s_setprio 1
	s_waitcnt lgkmcnt(0)
	v_mfma_f32_16x16x32_bf16 v[140:143], v[48:51], v[172:175], v[140:143]
	v_mfma_f32_16x16x32_bf16 v[136:139], v[64:67], v[172:175], v[136:139]
	v_mfma_f32_16x16x32_bf16 v[124:127], v[48:51], v[180:183], v[124:127]
	v_mfma_f32_16x16x32_bf16 v[120:123], v[64:67], v[180:183], v[120:123]
	v_mfma_f32_16x16x32_bf16 v[108:111], v[48:51], v[198:201], v[108:111]
	v_mfma_f32_16x16x32_bf16 v[104:107], v[64:67], v[198:201], v[104:107]
	v_mfma_f32_16x16x32_bf16 v[92:95], v[48:51], v[206:209], v[92:95]
	v_mfma_f32_16x16x32_bf16 v[88:91], v[64:67], v[206:209], v[88:91]
	v_mfma_f32_16x16x32_bf16 v[140:143], v[52:55], v[176:179], v[140:143]
	v_mfma_f32_16x16x32_bf16 v[136:139], v[68:71], v[176:179], v[136:139]
	v_mfma_f32_16x16x32_bf16 v[124:127], v[52:55], v[194:197], v[124:127]
	v_mfma_f32_16x16x32_bf16 v[120:123], v[68:71], v[194:197], v[120:123]
	v_mfma_f32_16x16x32_bf16 v[108:111], v[52:55], v[202:205], v[108:111]
	v_mfma_f32_16x16x32_bf16 v[104:107], v[68:71], v[202:205], v[104:107]
	v_mfma_f32_16x16x32_bf16 v[92:95], v[52:55], v[210:213], v[92:95]
	v_mfma_f32_16x16x32_bf16 v[88:91], v[68:71], v[210:213], v[88:91]
	s_setprio 0
	s_barrier
	s_add_i32 s14, 0, 0x1c000
	s_add_i32 s15, s79, s54
	v_add_u32_e32 v168, s14, v169
	v_lshl_add_u64 v[166:167], v[166:167], 0, s[30:31]
	s_mov_b32 m0, s15
	ds_read_b128 v[214:217], v168
	ds_read_b128 v[218:221], v168 offset:1024
	ds_read_b128 v[222:225], v168 offset:2048
	ds_read_b128 v[232:235], v168 offset:3072
	global_load_lds_dwordx4 v[166:167], off
	v_lshl_add_u64 v[166:167], v[186:187], 0, s[30:31]
	s_add_i32 m0, s15, 0x2000
	s_nop 0
	global_load_lds_dwordx4 v[166:167], off
	s_barrier
	s_waitcnt lgkmcnt(0)
	s_setprio 1
	s_waitcnt lgkmcnt(0)
	v_mfma_f32_16x16x32_bf16 v[132:135], v[214:217], v[172:175], v[132:135]
	v_mfma_f32_16x16x32_bf16 v[128:131], v[222:225], v[172:175], v[128:131]
	v_mfma_f32_16x16x32_bf16 v[116:119], v[214:217], v[180:183], v[116:119]
	v_mfma_f32_16x16x32_bf16 v[112:115], v[222:225], v[180:183], v[112:115]
	v_mfma_f32_16x16x32_bf16 v[100:103], v[214:217], v[198:201], v[100:103]
	v_mfma_f32_16x16x32_bf16 v[96:99], v[222:225], v[198:201], v[96:99]
	v_mfma_f32_16x16x32_bf16 v[84:87], v[214:217], v[206:209], v[84:87]
	v_mfma_f32_16x16x32_bf16 v[80:83], v[222:225], v[206:209], v[80:83]
	v_mfma_f32_16x16x32_bf16 v[132:135], v[218:221], v[176:179], v[132:135]
	v_mfma_f32_16x16x32_bf16 v[128:131], v[232:235], v[176:179], v[128:131]
	v_mfma_f32_16x16x32_bf16 v[116:119], v[218:221], v[194:197], v[116:119]
	v_mfma_f32_16x16x32_bf16 v[112:115], v[232:235], v[194:197], v[112:115]
	v_mfma_f32_16x16x32_bf16 v[100:103], v[218:221], v[202:205], v[100:103]
	v_mfma_f32_16x16x32_bf16 v[96:99], v[232:235], v[202:205], v[96:99]
	v_mfma_f32_16x16x32_bf16 v[84:87], v[218:221], v[210:213], v[84:87]
	v_mfma_f32_16x16x32_bf16 v[80:83], v[232:235], v[210:213], v[80:83]
	s_setprio 0
	s_mov_b32 m0, s63
	v_lshl_add_u64 v[166:167], v[188:189], 0, s[30:31]
	s_barrier
	ds_read_b128 v[172:175], v171 offset:49152
	ds_read_b128 v[176:179], v171 offset:50176
	ds_read_b128 v[180:183], v171 offset:51200
	ds_read_b128 v[194:197], v171 offset:52224
	ds_read_b128 v[198:201], v171 offset:53248
	ds_read_b128 v[202:205], v171 offset:54272
	ds_read_b128 v[206:209], v171 offset:55296
	ds_read_b128 v[210:213], v171 offset:56320
	global_load_lds_dwordx4 v[166:167], off
	v_lshl_add_u64 v[166:167], v[236:237], 0, s[30:31]
	s_mov_b32 m0, s64
	s_nop 0
	global_load_lds_dwordx4 v[166:167], off
	s_barrier
	s_waitcnt lgkmcnt(0)
	s_setprio 1
	s_waitcnt lgkmcnt(0)
	v_mfma_f32_16x16x32_bf16 v[76:79], v[48:51], v[172:175], v[76:79]
	v_mfma_f32_16x16x32_bf16 v[72:75], v[64:67], v[172:175], v[72:75]
	v_mfma_f32_16x16x32_bf16 v[60:63], v[48:51], v[180:183], v[60:63]
	v_mfma_f32_16x16x32_bf16 v[56:59], v[64:67], v[180:183], v[56:59]
	v_mfma_f32_16x16x32_bf16 v[44:47], v[48:51], v[198:201], v[44:47]
	v_mfma_f32_16x16x32_bf16 v[40:43], v[64:67], v[198:201], v[40:43]
	v_mfma_f32_16x16x32_bf16 v[12:15], v[48:51], v[206:209], v[12:15]
	v_mfma_f32_16x16x32_bf16 v[8:11], v[64:67], v[206:209], v[8:11]
	v_mfma_f32_16x16x32_bf16 v[76:79], v[52:55], v[176:179], v[76:79]
	v_mfma_f32_16x16x32_bf16 v[72:75], v[68:71], v[176:179], v[72:75]
	v_mfma_f32_16x16x32_bf16 v[60:63], v[52:55], v[194:197], v[60:63]
	v_mfma_f32_16x16x32_bf16 v[56:59], v[68:71], v[194:197], v[56:59]
	v_mfma_f32_16x16x32_bf16 v[44:47], v[52:55], v[202:205], v[44:47]
	v_mfma_f32_16x16x32_bf16 v[40:43], v[68:71], v[202:205], v[40:43]
	v_mfma_f32_16x16x32_bf16 v[12:15], v[52:55], v[210:213], v[12:15]
	v_mfma_f32_16x16x32_bf16 v[8:11], v[68:71], v[210:213], v[8:11]
	s_setprio 0
	s_barrier
	s_add_u32 s8, s8, 0x10080
	s_addc_u32 s9, s9, 0
	s_add_i32 s14, s14, s54
	v_lshl_add_u64 v[48:49], s[8:9], 0, v[146:147]
	s_mov_b32 m0, s14
	s_nop 0
	global_load_lds_dwordx4 v[48:49], off
	v_lshl_add_u64 v[48:49], s[8:9], 0, v[150:151]
	s_add_i32 m0, s14, 0x2000
	s_nop 0
	global_load_lds_dwordx4 v[48:49], off
	s_waitcnt vmcnt(6)
	s_barrier
	s_setprio 1
	v_mfma_f32_16x16x32_bf16 v[16:19], v[214:217], v[172:175], v[16:19]
	v_mfma_f32_16x16x32_bf16 v[68:71], v[218:221], v[176:179], v[16:19]
	v_mfma_f32_16x16x32_bf16 v[16:19], v[222:225], v[172:175], v[20:23]
	v_mfma_f32_16x16x32_bf16 v[64:67], v[232:235], v[176:179], v[16:19]
	v_mfma_f32_16x16x32_bf16 v[16:19], v[214:217], v[180:183], v[24:27]
	v_mfma_f32_16x16x32_bf16 v[52:55], v[218:221], v[194:197], v[16:19]
	v_mfma_f32_16x16x32_bf16 v[16:19], v[222:225], v[180:183], v[28:31]
	v_mfma_f32_16x16x32_bf16 v[48:51], v[232:235], v[194:197], v[16:19]
	v_mfma_f32_16x16x32_bf16 v[16:19], v[214:217], v[198:201], v[36:39]
	v_mfma_f32_16x16x32_bf16 v[36:39], v[218:221], v[202:205], v[16:19]
	v_mfma_f32_16x16x32_bf16 v[16:19], v[222:225], v[198:201], v[32:35]
	v_mfma_f32_16x16x32_bf16 v[4:7], v[214:217], v[206:209], v[4:7]
	v_mfma_f32_16x16x32_bf16 v[0:3], v[222:225], v[206:209], v[0:3]
	v_mfma_f32_16x16x32_bf16 v[32:35], v[232:235], v[202:205], v[16:19]
	v_mfma_f32_16x16x32_bf16 v[4:7], v[218:221], v[210:213], v[4:7]
	v_mfma_f32_16x16x32_bf16 v[0:3], v[232:235], v[210:213], v[0:3]
	s_setprio 0
	s_add_i32 s78, s78, 2
	s_add_u32 s71, s71, 0x100
	s_addc_u32 s75, s75, 0
	s_add_u32 s2, s2, 0x100
	s_addc_u32 s3, s3, 0
	s_cmp_gt_u32 s78, 13
	s_barrier
	s_cbranch_scc0 .LBB0_102
	s_cmp_lt_i32 s10, 2
	s_cselect_b64 s[8:9], -1, 0
	s_cmp_gt_i32 s10, 3
	s_cselect_b64 s[2:3], -1, 0
	s_and_b64 vcc, exec, s[2:3]
	s_cbranch_vccnz .LBB0_105
	s_and_b64 s[14:15], s[8:9], exec
	s_movk_i32 s13, 0x200
	s_cselect_b32 s22, 0x100, s13
	v_lshl_add_u64 v[16:17], v[154:155], 0, s[22:23]
	s_waitcnt vmcnt(0)
	global_load_dwordx4 v[28:31], v[16:17], off
	global_load_dwordx4 v[24:27], v[16:17], off offset:16
	global_load_dwordx4 v[20:23], v[16:17], off offset:128
	s_nop 0
	global_load_dwordx4 v[16:19], v[16:17], off offset:144
.LBB0_105:
	s_cmp_gt_u32 s11, 7
	v_lshl_add_u32 v166, s12, 8, v153
	s_cselect_b64 s[14:15], -1, 0
	s_cmp_lt_u32 s11, 8
	s_mov_b64 s[12:13], -1
	s_cbranch_scc1 .LBB0_107
	v_ashrrev_i32_e32 v167, 31, v166
	v_lshl_add_u64 v[172:173], v[166:167], 2, s[96:97]
	v_add_co_u32_e32 v174, vcc, 0x10000, v172
	global_load_dword v167, v[172:173], off
	s_nop 0
	v_addc_co_u32_e32 v175, vcc, 0, v173, vcc
	global_load_dword v168, v[174:175], off
	v_add_co_u32_e32 v174, vcc, 0x20000, v172
	s_mov_b64 s[12:13], 0
	s_nop 0
	v_addc_co_u32_e32 v175, vcc, 0, v173, vcc
	s_waitcnt vmcnt(0) lgkmcnt(0)
	v_add_f32_e32 v167, 0, v167
	v_add_f32_e32 v167, v167, v168
	global_load_dword v168, v[174:175], off
	v_add_co_u32_e32 v174, vcc, 0x30000, v172
	s_waitcnt vmcnt(0) lgkmcnt(0)
	v_add_f32_e32 v167, v167, v168
	v_addc_co_u32_e32 v175, vcc, 0, v173, vcc
	global_load_dword v168, v[174:175], off
	v_add_co_u32_e32 v174, vcc, 0x40000, v172
	s_waitcnt vmcnt(0) lgkmcnt(0)
	v_add_f32_e32 v167, v167, v168
	v_addc_co_u32_e32 v175, vcc, 0, v173, vcc
	global_load_dword v168, v[174:175], off
	v_add_co_u32_e32 v174, vcc, 0x50000, v172
	s_waitcnt vmcnt(0) lgkmcnt(0)
	v_add_f32_e32 v167, v167, v168
	v_addc_co_u32_e32 v175, vcc, 0, v173, vcc
	global_load_dword v168, v[174:175], off
	v_add_co_u32_e32 v174, vcc, 0x60000, v172
	s_waitcnt vmcnt(0) lgkmcnt(0)
	v_add_f32_e32 v167, v167, v168
	v_addc_co_u32_e32 v175, vcc, 0, v173, vcc
	global_load_dword v168, v[174:175], off
	v_add_co_u32_e32 v174, vcc, 0x70000, v172
	s_waitcnt vmcnt(0) lgkmcnt(0)
	v_add_f32_e32 v167, v167, v168
	v_addc_co_u32_e32 v175, vcc, 0, v173, vcc
	global_load_dword v168, v[174:175], off
	v_add_co_u32_e32 v174, vcc, 0x80000, v172
	s_waitcnt vmcnt(0) lgkmcnt(0)
	v_add_f32_e32 v167, v167, v168
	v_addc_co_u32_e32 v175, vcc, 0, v173, vcc
	global_load_dword v168, v[174:175], off
	v_add_co_u32_e32 v174, vcc, 0x90000, v172
	s_waitcnt vmcnt(0) lgkmcnt(0)
	v_add_f32_e32 v167, v167, v168
	v_addc_co_u32_e32 v175, vcc, 0, v173, vcc
	global_load_dword v168, v[174:175], off
	v_add_co_u32_e32 v174, vcc, 0xa0000, v172
	s_waitcnt vmcnt(0) lgkmcnt(0)
	v_add_f32_e32 v167, v167, v168
	v_addc_co_u32_e32 v175, vcc, 0, v173, vcc
	global_load_dword v168, v[174:175], off
	v_add_co_u32_e32 v174, vcc, 0xb0000, v172
	s_waitcnt vmcnt(0) lgkmcnt(0)
	v_add_f32_e32 v167, v167, v168
	v_addc_co_u32_e32 v175, vcc, 0, v173, vcc
	global_load_dword v168, v[174:175], off
	v_add_co_u32_e32 v174, vcc, 0xc0000, v172
	s_waitcnt vmcnt(0) lgkmcnt(0)
	v_add_f32_e32 v167, v167, v168
	v_addc_co_u32_e32 v175, vcc, 0, v173, vcc
	global_load_dword v168, v[174:175], off
	v_add_co_u32_e32 v174, vcc, 0xd0000, v172
	s_waitcnt vmcnt(0) lgkmcnt(0)
	v_add_f32_e32 v167, v167, v168
	v_addc_co_u32_e32 v175, vcc, 0, v173, vcc
	global_load_dword v168, v[174:175], off
	v_add_co_u32_e32 v174, vcc, 0xe0000, v172
	s_waitcnt vmcnt(0) lgkmcnt(0)
	v_add_f32_e32 v167, v167, v168
	v_addc_co_u32_e32 v175, vcc, 0, v173, vcc
	global_load_dword v168, v[174:175], off
	v_add_co_u32_e32 v172, vcc, 0xf0000, v172
	s_waitcnt vmcnt(0) lgkmcnt(0)
	v_add_f32_e32 v167, v167, v168
	v_addc_co_u32_e32 v173, vcc, 0, v173, vcc
	global_load_dword v168, v[172:173], off
	s_waitcnt vmcnt(0) lgkmcnt(0)
	v_add_f32_e32 v167, v167, v168
	v_fmamk_f32 v167, v167, 0x3a800000, v227
	v_rsq_f32_e32 v168, v167

.LBB0_109:
	s_waitcnt lgkmcnt(0)
	v_pk_mul_f32 v[140:141], v[140:141], v[168:169] op_sel_hi:[1,0]
	v_pk_mul_f32 v[142:143], v[142:143], v[168:169] op_sel_hi:[1,0]
	v_pk_mul_f32 v[174:175], v[140:141], v[140:141]
	v_pk_mul_f32 v[176:177], v[142:143], v[142:143]
	v_add_f32_e32 v167, v174, v175
	v_pk_mul_f32 v[136:137], v[136:137], v[168:169] op_sel_hi:[1,0]
	v_add_f32_e32 v167, v176, v167
	v_pk_mul_f32 v[178:179], v[136:137], v[136:137]
	v_add_f32_e32 v167, v177, v167
	v_pk_mul_f32 v[138:139], v[138:139], v[168:169] op_sel_hi:[1,0]
	v_add_f32_e32 v167, v178, v167
	v_pk_mul_f32 v[180:181], v[138:139], v[138:139]
	v_add_f32_e32 v167, v179, v167
	v_pk_mul_f32 v[132:133], v[132:133], v[168:169] op_sel_hi:[1,0]
	v_add_f32_e32 v167, v180, v167
	v_pk_mul_f32 v[182:183], v[132:133], v[132:133]
	v_add_f32_e32 v167, v181, v167
	s_cmp_gt_u32 s10, 5
	v_pk_mul_f32 v[134:135], v[134:135], v[168:169] op_sel_hi:[1,0]
	v_add_f32_e32 v167, v182, v167
	s_cselect_b64 s[12:13], -1, 0
	s_add_i32 s11, s10, -10
	v_pk_mul_f32 v[186:187], v[134:135], v[134:135]
	v_add_f32_e32 v167, v183, v167
	s_cmp_gt_u32 s11, -3
	v_pk_mul_f32 v[128:129], v[128:129], v[168:169] op_sel_hi:[1,0]
	v_add_f32_e32 v167, v186, v167
	s_cselect_b64 s[82:83], -1, 0
	s_cmp_lg_u32 s10, 8
	v_pk_mul_f32 v[188:189], v[128:129], v[128:129]
	v_add_f32_e32 v167, v187, v167
	s_cselect_b64 s[78:79], -1, 0
	s_lshl_b32 s11, s10, 8
	v_pk_mul_f32 v[130:131], v[130:131], v[168:169] op_sel_hi:[1,0]
	v_add_f32_e32 v167, v188, v167
	s_cmp_gt_u32 s10, 9
	s_movk_i32 s10, 0xf800
	v_pk_mul_f32 v[194:195], v[130:131], v[130:131]
	v_add_f32_e32 v167, v189, v167
	s_cselect_b32 s10, s10, 0xfffffa00
	v_add_f32_e32 v167, v194, v167
	s_add_i32 s22, s10, s11
	s_and_b32 s71, s11, 0x100
	v_add_f32_e32 v173, v195, v167
	s_mov_b64 s[10:11], -1
	s_and_b64 vcc, exec, s[2:3]
	s_cbranch_vccz .LBB0_133
	s_and_b64 vcc, exec, s[12:13]
	s_cbranch_vccz .LBB0_130
	s_and_b64 vcc, exec, s[82:83]
	s_cbranch_vccz .LBB0_127
	s_and_b64 vcc, exec, s[78:79]
	s_cbranch_vccz .LBB0_122
	s_and_b64 vcc, exec, s[92:93]
	s_cbranch_vccz .LBB0_117
	s_andn2_b64 vcc, exec, s[94:95]
	s_cbranch_vccnz .LBB0_116
	v_ashrrev_i32_e32 v167, 31, v166
	v_lshlrev_b64 v[174:175], 8, v[166:167]
	v_lshl_add_u64 v[174:175], v[156:157], 0, v[174:175]
	s_waitcnt vmcnt(0)
	global_store_dwordx4 v[174:175], v[140:143], off
	global_store_dwordx4 v[174:175], v[136:139], off offset:16
	global_store_dwordx4 v[174:175], v[132:135], off offset:128
	global_store_dwordx4 v[174:175], v[128:131], off offset:144

.LBB0_117:
	s_andn2_b64 vcc, exec, s[10:11]
	s_cbranch_vccnz .LBB0_121
	ds_swizzle_b32 v168, v173 offset:swizzle(SWAP,16)
	v_ashrrev_i32_e32 v167, 31, v166
	v_lshlrev_b64 v[174:175], 8, v[166:167]
	v_lshl_add_u64 v[178:179], v[158:159], 0, v[174:175]
	v_cvt_pk_bf16_f32 v174, v140, v141
	v_cvt_pk_bf16_f32 v175, v142, v143
	v_cvt_pk_bf16_f32 v176, v136, v137
	v_cvt_pk_bf16_f32 v177, v138, v139
	global_store_dwordx4 v[178:179], v[174:177], off
	s_waitcnt lgkmcnt(0)
	v_add_f32_e32 v168, v173, v168
	v_cvt_pk_bf16_f32 v174, v132, v133
	v_cvt_pk_bf16_f32 v175, v134, v135
	v_cvt_pk_bf16_f32 v176, v128, v129
	v_cvt_pk_bf16_f32 v177, v130, v131
	global_store_dwordx4 v[178:179], v[174:177], off offset:64
	s_nop 1
	v_mov_b32_e32 v174, v168
	s_nop 1
	v_permlane32_swap_b32_e32 v168, v174
	s_and_saveexec_b64 s[10:11], s[4:5]
	s_cbranch_execz .LBB0_120
	v_lshl_add_u64 v[176:177], v[166:167], 2, s[98:99]
	v_add_f32_e32 v167, v168, v174
	global_store_dword v[176:177], v167, off

.LBB0_122:
	s_andn2_b64 vcc, exec, s[10:11]
	s_cbranch_vccnz .LBB0_126
	ds_swizzle_b32 v168, v173 offset:swizzle(SWAP,16)
	v_ashrrev_i32_e32 v167, 31, v166
	v_lshlrev_b64 v[174:175], 9, v[166:167]
	v_lshl_add_u64 v[178:179], v[160:161], 0, v[174:175]
	v_cvt_pk_bf16_f32 v174, v140, v141
	v_cvt_pk_bf16_f32 v175, v142, v143
	v_cvt_pk_bf16_f32 v176, v136, v137
	v_cvt_pk_bf16_f32 v177, v138, v139
	global_store_dwordx4 v[178:179], v[174:177], off
	s_waitcnt lgkmcnt(0)
	v_add_f32_e32 v168, v173, v168
	v_cvt_pk_bf16_f32 v174, v132, v133
	v_cvt_pk_bf16_f32 v175, v134, v135
	v_cvt_pk_bf16_f32 v176, v128, v129
	v_cvt_pk_bf16_f32 v177, v130, v131
	global_store_dwordx4 v[178:179], v[174:177], off offset:64
	s_nop 1
	v_mov_b32_e32 v174, v168
	s_nop 1
	v_permlane32_swap_b32_e32 v168, v174
	s_and_saveexec_b64 s[10:11], s[4:5]
	s_cbranch_execz .LBB0_125
	v_lshl_add_u64 v[176:177], v[166:167], 2, s[68:69]
	v_add_f32_e32 v167, v168, v174
	global_store_dword v[176:177], v167, off

.LBB0_127:
	s_andn2_b64 vcc, exec, s[10:11]
	s_cbranch_vccnz .LBB0_129
	v_ashrrev_i32_e32 v167, 31, v166
	v_lshlrev_b64 v[174:175], 11, v[166:167]
	v_lshl_add_u64 v[174:175], s[16:17], 0, v[174:175]
	v_lshl_add_u64 v[174:175], s[22:23], 1, v[174:175]
	s_lshl_b32 s10, s65, 1
	s_mov_b32 s11, s23
	v_lshl_add_u64 v[174:175], v[174:175], 0, s[10:11]
	v_lshlrev_b32_e32 v184, 1, v152
	v_lshl_add_u64 v[178:179], v[174:175], 0, v[184:185]
	v_mul_f32_e32 v174, 0xbfb8aa3b, v142
	v_exp_f32_e32 v174, v174
	v_mul_f32_e32 v175, 0xbfb8aa3b, v143
	v_exp_f32_e32 v175, v175
	v_mul_f32_e32 v177, 0xbfb8aa3b, v137
	v_add_f32_e32 v174, 1.0, v174
	v_rcp_f32_e32 v174, v174
	v_exp_f32_e32 v177, v177
	v_mul_f32_e32 v167, 0xbfb8aa3b, v140
	v_mul_f32_e32 v168, 0xbfb8aa3b, v141
	v_mul_f32_e32 v176, v142, v174
	v_add_f32_e32 v174, 1.0, v175
	v_mul_f32_e32 v175, 0xbfb8aa3b, v136
	v_rcp_f32_e32 v174, v174
	v_exp_f32_e32 v175, v175
	v_exp_f32_e32 v167, v167
	v_exp_f32_e32 v168, v168
	v_mul_f32_e32 v180, v143, v174
	v_add_f32_e32 v174, 1.0, v175
	v_add_f32_e32 v175, 1.0, v177
	v_mul_f32_e32 v177, 0xbfb8aa3b, v138
	v_exp_f32_e32 v177, v177
	v_mul_f32_e32 v181, 0xbfb8aa3b, v139
	v_exp_f32_e32 v181, v181
	v_add_f32_e32 v167, 1.0, v167
	v_add_f32_e32 v168, 1.0, v168
	v_add_f32_e32 v177, 1.0, v177
	v_rcp_f32_e32 v167, v167
	v_rcp_f32_e32 v168, v168
	v_rcp_f32_e32 v174, v174
	v_rcp_f32_e32 v177, v177
	v_add_f32_e32 v181, 1.0, v181
	v_rcp_f32_e32 v175, v175
	v_rcp_f32_e32 v181, v181
	v_mul_f32_e32 v167, v140, v167
	v_mul_f32_e32 v168, v141, v168
	v_mul_f32_e32 v182, v136, v174
	v_mul_f32_e32 v177, v138, v177
	v_cvt_pk_bf16_f32 v174, v167, v168
	v_mul_f32_e32 v183, v137, v175
	v_mul_f32_e32 v181, v139, v181
	v_cvt_pk_bf16_f32 v175, v176, v180
	v_cvt_pk_bf16_f32 v176, v182, v183
	v_cvt_pk_bf16_f32 v177, v177, v181
	global_store_dwordx4 v[178:179], v[174:177], off
	v_mul_f32_e32 v167, 0xbfb8aa3b, v132
	v_mul_f32_e32 v168, 0xbfb8aa3b, v133
	v_mul_f32_e32 v174, 0xbfb8aa3b, v134
	v_exp_f32_e32 v174, v174
	v_mul_f32_e32 v175, 0xbfb8aa3b, v135
	v_exp_f32_e32 v175, v175
	v_mul_f32_e32 v177, 0xbfb8aa3b, v129
	v_add_f32_e32 v174, 1.0, v174
	v_rcp_f32_e32 v174, v174
	v_exp_f32_e32 v177, v177
	v_mul_f32_e32 v181, 0xbfb8aa3b, v131
	v_exp_f32_e32 v167, v167
	v_mul_f32_e32 v176, v134, v174
	v_add_f32_e32 v174, 1.0, v175
	v_mul_f32_e32 v175, 0xbfb8aa3b, v128
	v_rcp_f32_e32 v174, v174
	v_exp_f32_e32 v175, v175
	v_exp_f32_e32 v168, v168
	v_exp_f32_e32 v181, v181
	v_mul_f32_e32 v180, v135, v174
	v_add_f32_e32 v174, 1.0, v175
	v_add_f32_e32 v175, 1.0, v177
	v_mul_f32_e32 v177, 0xbfb8aa3b, v130
	v_exp_f32_e32 v177, v177
	v_add_f32_e32 v167, 1.0, v167
	v_add_f32_e32 v168, 1.0, v168
	v_add_f32_e32 v181, 1.0, v181
	v_add_f32_e32 v177, 1.0, v177
	v_rcp_f32_e32 v177, v177
	v_rcp_f32_e32 v167, v167
	v_rcp_f32_e32 v168, v168
	v_rcp_f32_e32 v174, v174
	v_rcp_f32_e32 v175, v175
	v_rcp_f32_e32 v181, v181
	v_mul_f32_e32 v177, v130, v177
	v_mul_f32_e32 v167, v132, v167
	v_mul_f32_e32 v168, v133, v168
	v_mul_f32_e32 v182, v128, v174
	v_mul_f32_e32 v183, v129, v175
	v_mul_f32_e32 v181, v131, v181
	v_cvt_pk_bf16_f32 v174, v167, v168
	v_cvt_pk_bf16_f32 v175, v176, v180
	v_cvt_pk_bf16_f32 v176, v182, v183
	v_cvt_pk_bf16_f32 v177, v177, v181
	global_store_dwordx4 v[178:179], v[174:177], off offset:64

.LBB0_130:
	s_andn2_b64 vcc, exec, s[10:11]
	s_cbranch_vccnz .LBB0_132
	v_ashrrev_i32_e32 v167, 31, v166
	v_lshlrev_b64 v[174:175], 10, v[166:167]
	v_lshl_add_u64 v[174:175], s[18:19], 0, v[174:175]
	s_lshl_b32 s10, s71, 1
	s_mov_b32 s11, s23
	v_lshl_add_u64 v[174:175], v[174:175], 0, s[10:11]
	s_lshl_b32 s10, s65, 1
	v_lshl_add_u64 v[174:175], v[174:175], 0, s[10:11]
	v_lshlrev_b32_e32 v184, 1, v152
	v_lshl_add_u64 v[178:179], v[174:175], 0, v[184:185]
	v_cvt_pk_bf16_f32 v174, v140, v141
	v_cvt_pk_bf16_f32 v175, v142, v143
	v_cvt_pk_bf16_f32 v176, v136, v137
	v_cvt_pk_bf16_f32 v177, v138, v139
	global_store_dwordx4 v[178:179], v[174:177], off
	s_nop 1
	v_cvt_pk_bf16_f32 v174, v132, v133
	v_cvt_pk_bf16_f32 v175, v134, v135
	v_cvt_pk_bf16_f32 v176, v128, v129
	v_cvt_pk_bf16_f32 v177, v130, v131
	global_store_dwordx4 v[178:179], v[174:177], off offset:64

.LBB0_133:
	v_cndmask_b32_e64 v168, 1.0, v231, s[8:9]
	s_andn2_b64 vcc, exec, s[10:11]
	v_lshlrev_b32_e32 v184, 1, v152
	s_cbranch_vccnz .LBB0_135
	ds_swizzle_b32 v174, v173 offset:swizzle(SWAP,16)
	s_and_b64 s[10:11], s[8:9], exec
	v_ashrrev_i32_e32 v167, 31, v166
	s_cselect_b32 s10, s59, 0x5000000
	s_add_u32 s10, s86, s10
	s_waitcnt lgkmcnt(0)
	v_add_f32_e32 v173, v173, v174
	v_mov_b32_e32 v174, v173
	s_nop 1
	v_permlane32_swap_b32_e32 v173, v174
	v_add_f32_e32 v173, v173, v174
	v_fmamk_f32 v173, v173, 0x3c800000, v227
	v_rsq_f32_e32 v173, v173
	v_lshlrev_b64 v[174:175], 10, v[166:167]
	s_addc_u32 s11, s87, 0
	v_lshl_add_u64 v[174:175], s[10:11], 0, v[174:175]
	v_mul_f32_e32 v167, v168, v173
	v_mul_f32_e32 v140, v140, v167
	v_mul_f32_e32 v136, v136, v167
	s_lshl_b32 s10, s71, 1
	s_mov_b32 s11, s23
	s_waitcnt vmcnt(0)
	v_mul_f32_e32 v173, v28, v140
	v_mul_f32_e32 v140, v141, v167
	v_mul_f32_e32 v177, v24, v136
	v_mul_f32_e32 v136, v137, v167
	v_lshl_add_u64 v[174:175], v[174:175], 0, s[10:11]
	s_lshl_b32 s10, s65, 1
	v_mul_f32_e32 v176, v29, v140
	v_mul_f32_e32 v140, v142, v167
	v_mul_f32_e32 v178, v25, v136
	v_mul_f32_e32 v136, v138, v167
	v_lshl_add_u64 v[174:175], v[174:175], 0, s[10:11]
	v_mul_f32_e32 v142, v30, v140
	v_mul_f32_e32 v140, v143, v167
	v_mul_f32_e32 v179, v26, v136
	v_mul_f32_e32 v136, v139, v167
	v_mul_f32_e32 v143, v31, v140
	v_mul_f32_e32 v139, v27, v136
	v_lshl_add_u64 v[140:141], v[174:175], 0, v[184:185]
	v_cvt_pk_bf16_f32 v136, v173, v176
	v_mul_f32_e32 v128, v128, v167
	v_cvt_pk_bf16_f32 v137, v142, v143
	v_cvt_pk_bf16_f32 v138, v177, v178
	v_cvt_pk_bf16_f32 v139, v179, v139
	global_store_dwordx4 v[140:141], v[136:139], off
	v_mul_f32_e32 v132, v132, v167
	v_mul_f32_e32 v133, v133, v167
	v_mul_f32_e32 v136, v16, v128
	v_mul_f32_e32 v128, v129, v167
	v_mul_f32_e32 v137, v17, v128
	v_mul_f32_e32 v128, v130, v167
	v_mul_f32_e32 v138, v18, v128
	v_mul_f32_e32 v128, v131, v167
	v_mul_f32_e32 v134, v134, v167
	v_mul_f32_e32 v135, v135, v167
	v_mul_f32_e32 v131, v19, v128
	v_mul_f32_e32 v132, v20, v132
	v_mul_f32_e32 v133, v21, v133
	v_mul_f32_e32 v134, v22, v134
	v_mul_f32_e32 v135, v23, v135
	v_cvt_pk_bf16_f32 v128, v132, v133
	v_cvt_pk_bf16_f32 v129, v134, v135
	v_cvt_pk_bf16_f32 v130, v136, v137
	v_cvt_pk_bf16_f32 v131, v138, v131
	global_store_dwordx4 v[140:141], v[128:131], off offset:64
.LBB0_135:
	s_nop 1
	v_cndmask_b32_e64 v128, 0, 1, s[14:15]
	v_cmp_ne_u32_e64 s[10:11], 1, v128
	s_andn2_b64 vcc, exec, s[14:15]
	s_mov_b64 s[14:15], -1
	s_cbranch_vccnz .LBB0_137
	v_ashrrev_i32_e32 v167, 31, v166
	v_lshl_add_u64 v[128:129], v[166:167], 2, s[96:97]
	global_load_dword v130, v[128:129], off offset:64
	s_mov_b64 s[14:15], 0
	s_waitcnt vmcnt(0) lgkmcnt(0)
	v_add_f32_e32 v132, 0, v130
	v_add_co_u32_e32 v130, vcc, 0x10000, v128
	s_nop 1
	v_addc_co_u32_e32 v131, vcc, 0, v129, vcc
	global_load_dword v130, v[130:131], off offset:64
	s_waitcnt vmcnt(0) lgkmcnt(0)
	v_add_f32_e32 v132, v132, v130
	v_add_co_u32_e32 v130, vcc, 0x20000, v128
	s_nop 1
	v_addc_co_u32_e32 v131, vcc, 0, v129, vcc
	global_load_dword v130, v[130:131], off offset:64
	s_waitcnt vmcnt(0) lgkmcnt(0)
	v_add_f32_e32 v132, v132, v130
	v_add_co_u32_e32 v130, vcc, 0x30000, v128
	s_nop 1
	v_addc_co_u32_e32 v131, vcc, 0, v129, vcc
	global_load_dword v130, v[130:131], off offset:64
	s_waitcnt vmcnt(0) lgkmcnt(0)
	v_add_f32_e32 v132, v132, v130
	v_add_co_u32_e32 v130, vcc, 0x40000, v128
	s_nop 1
	v_addc_co_u32_e32 v131, vcc, 0, v129, vcc
	global_load_dword v130, v[130:131], off offset:64
	s_waitcnt vmcnt(0) lgkmcnt(0)
	v_add_f32_e32 v132, v132, v130
	v_add_co_u32_e32 v130, vcc, 0x50000, v128
	s_nop 1
	v_addc_co_u32_e32 v131, vcc, 0, v129, vcc
	global_load_dword v130, v[130:131], off offset:64
	s_waitcnt vmcnt(0) lgkmcnt(0)
	v_add_f32_e32 v132, v132, v130
	v_add_co_u32_e32 v130, vcc, 0x60000, v128
	s_nop 1
	v_addc_co_u32_e32 v131, vcc, 0, v129, vcc
	global_load_dword v130, v[130:131], off offset:64
	s_waitcnt vmcnt(0) lgkmcnt(0)
	v_add_f32_e32 v132, v132, v130
	v_add_co_u32_e32 v130, vcc, 0x70000, v128
	s_nop 1
	v_addc_co_u32_e32 v131, vcc, 0, v129, vcc
	global_load_dword v130, v[130:131], off offset:64
	s_waitcnt vmcnt(0) lgkmcnt(0)
	v_add_f32_e32 v132, v132, v130
	v_add_co_u32_e32 v130, vcc, 0x80000, v128
	s_nop 1
	v_addc_co_u32_e32 v131, vcc, 0, v129, vcc
	global_load_dword v130, v[130:131], off offset:64
	s_waitcnt vmcnt(0) lgkmcnt(0)
	v_add_f32_e32 v132, v132, v130
	v_add_co_u32_e32 v130, vcc, 0x90000, v128
	s_nop 1
	v_addc_co_u32_e32 v131, vcc, 0, v129, vcc
	global_load_dword v130, v[130:131], off offset:64
	s_waitcnt vmcnt(0) lgkmcnt(0)
	v_add_f32_e32 v132, v132, v130
	v_add_co_u32_e32 v130, vcc, 0xa0000, v128
	s_nop 1
	v_addc_co_u32_e32 v131, vcc, 0, v129, vcc
	global_load_dword v130, v[130:131], off offset:64
	s_waitcnt vmcnt(0) lgkmcnt(0)
	v_add_f32_e32 v132, v132, v130
	v_add_co_u32_e32 v130, vcc, 0xb0000, v128
	s_nop 1
	v_addc_co_u32_e32 v131, vcc, 0, v129, vcc
	global_load_dword v130, v[130:131], off offset:64
	s_waitcnt vmcnt(0) lgkmcnt(0)
	v_add_f32_e32 v132, v132, v130
	v_add_co_u32_e32 v130, vcc, 0xc0000, v128
	s_nop 1
	v_addc_co_u32_e32 v131, vcc, 0, v129, vcc
	global_load_dword v130, v[130:131], off offset:64
	s_waitcnt vmcnt(0) lgkmcnt(0)
	v_add_f32_e32 v132, v132, v130
	v_add_co_u32_e32 v130, vcc, 0xd0000, v128
	s_nop 1
	v_addc_co_u32_e32 v131, vcc, 0, v129, vcc
	global_load_dword v130, v[130:131], off offset:64
	s_waitcnt vmcnt(0) lgkmcnt(0)
	v_add_f32_e32 v132, v132, v130
	v_add_co_u32_e32 v130, vcc, 0xe0000, v128
	s_nop 1
	v_addc_co_u32_e32 v131, vcc, 0, v129, vcc
	v_add_co_u32_e32 v128, vcc, 0xf0000, v128
	global_load_dword v130, v[130:131], off offset:64
	s_nop 0
	v_addc_co_u32_e32 v129, vcc, 0, v129, vcc
	global_load_dword v128, v[128:129], off offset:64
	s_waitcnt vmcnt(0) lgkmcnt(0)
	v_add_f32_e32 v130, v132, v130
	v_add_f32_e32 v128, v130, v128
	v_fmamk_f32 v128, v128, 0x3a800000, v227
	v_rsq_f32_e32 v130, v128

.LBB0_149:
	s_waitcnt lgkmcnt(0)
	v_pk_mul_f32 v[92:93], v[92:93], v[98:99] op_sel_hi:[1,0]
	v_pk_mul_f32 v[94:95], v[94:95], v[98:99] op_sel_hi:[1,0]
	v_pk_mul_f32 v[100:101], v[92:93], v[92:93]
	v_pk_mul_f32 v[102:103], v[94:95], v[94:95]
	v_add_f32_e32 v97, v100, v101
	v_pk_mul_f32 v[88:89], v[88:89], v[98:99] op_sel_hi:[1,0]
	v_add_f32_e32 v97, v102, v97
	v_pk_mul_f32 v[104:105], v[88:89], v[88:89]
	v_add_f32_e32 v97, v103, v97
	v_pk_mul_f32 v[90:91], v[90:91], v[98:99] op_sel_hi:[1,0]
	v_add_f32_e32 v97, v104, v97
	v_pk_mul_f32 v[106:107], v[90:91], v[90:91]
	v_add_f32_e32 v97, v105, v97
	v_pk_mul_f32 v[84:85], v[84:85], v[98:99] op_sel_hi:[1,0]
	v_add_f32_e32 v97, v106, v97
	v_pk_mul_f32 v[108:109], v[84:85], v[84:85]
	v_add_f32_e32 v97, v107, v97
	v_pk_mul_f32 v[86:87], v[86:87], v[98:99] op_sel_hi:[1,0]
	v_add_f32_e32 v97, v108, v97
	v_pk_mul_f32 v[110:111], v[86:87], v[86:87]
	v_add_f32_e32 v97, v109, v97
	v_pk_mul_f32 v[80:81], v[80:81], v[98:99] op_sel_hi:[1,0]
	v_add_f32_e32 v97, v110, v97
	v_pk_mul_f32 v[112:113], v[80:81], v[80:81]
	v_add_f32_e32 v97, v111, v97
	v_pk_mul_f32 v[82:83], v[82:83], v[98:99] op_sel_hi:[1,0]
	v_add_f32_e32 v97, v112, v97
	v_pk_mul_f32 v[98:99], v[82:83], v[82:83]
	v_add_f32_e32 v97, v113, v97
	v_add_f32_e32 v97, v98, v97
	v_or_b32_e32 v96, 48, v166
	v_add_f32_e32 v98, v99, v97
	s_and_b64 vcc, exec, s[14:15]
	s_mov_b64 s[2:3], -1
	s_cbranch_vccnz .LBB0_173
	s_and_b64 vcc, exec, s[12:13]
	s_cbranch_vccnz .LBB0_170
	s_andn2_b64 vcc, exec, s[82:83]
	s_cbranch_vccnz .LBB0_167
	s_andn2_b64 vcc, exec, s[78:79]
	s_cbranch_vccnz .LBB0_162
	s_andn2_b64 vcc, exec, s[92:93]
	s_cbranch_vccnz .LBB0_157
	s_andn2_b64 vcc, exec, s[94:95]
	s_cbranch_vccnz .LBB0_156
	v_ashrrev_i32_e32 v97, 31, v96
	v_lshlrev_b64 v[100:101], 8, v[96:97]
	v_lshl_add_u64 v[100:101], v[156:157], 0, v[100:101]
	s_waitcnt vmcnt(0)
	global_store_dwordx4 v[100:101], v[92:95], off
	global_store_dwordx4 v[100:101], v[88:91], off offset:16
	global_store_dwordx4 v[100:101], v[84:87], off offset:128
	global_store_dwordx4 v[100:101], v[80:83], off offset:144

.LBB0_157:
	s_andn2_b64 vcc, exec, s[2:3]
	s_cbranch_vccnz .LBB0_161
	v_ashrrev_i32_e32 v97, 31, v96
	v_lshlrev_b64 v[100:101], 8, v[96:97]
	ds_swizzle_b32 v97, v98 offset:swizzle(SWAP,16)
	v_lshl_add_u64 v[104:105], v[158:159], 0, v[100:101]
	v_cvt_pk_bf16_f32 v100, v92, v93
	v_cvt_pk_bf16_f32 v101, v94, v95
	v_cvt_pk_bf16_f32 v102, v88, v89
	s_waitcnt lgkmcnt(0)
	v_add_f32_e32 v97, v98, v97
	v_mov_b32_e32 v99, v97
	v_cvt_pk_bf16_f32 v103, v90, v91
	s_nop 1
	v_permlane32_swap_b32_e32 v97, v99
	global_store_dwordx4 v[104:105], v[100:103], off
	s_nop 1
	v_cvt_pk_bf16_f32 v100, v84, v85
	v_cvt_pk_bf16_f32 v101, v86, v87
	v_cvt_pk_bf16_f32 v102, v80, v81
	v_cvt_pk_bf16_f32 v103, v82, v83
	global_store_dwordx4 v[104:105], v[100:103], off offset:64
	s_and_saveexec_b64 s[2:3], s[4:5]
	s_cbranch_execz .LBB0_160
	v_ashrrev_i32_e32 v167, 31, v166
	v_lshl_add_u64 v[100:101], v[166:167], 2, s[98:99]
	v_add_f32_e32 v97, v97, v99
	global_store_dword v[100:101], v97, off offset:192

.LBB0_162:
	s_andn2_b64 vcc, exec, s[2:3]
	s_cbranch_vccnz .LBB0_166
	v_ashrrev_i32_e32 v97, 31, v96
	v_lshlrev_b64 v[100:101], 9, v[96:97]
	ds_swizzle_b32 v97, v98 offset:swizzle(SWAP,16)
	v_lshl_add_u64 v[104:105], v[160:161], 0, v[100:101]
	v_cvt_pk_bf16_f32 v100, v92, v93
	v_cvt_pk_bf16_f32 v101, v94, v95
	v_cvt_pk_bf16_f32 v102, v88, v89
	s_waitcnt lgkmcnt(0)
	v_add_f32_e32 v97, v98, v97
	v_mov_b32_e32 v99, v97
	v_cvt_pk_bf16_f32 v103, v90, v91
	s_nop 1
	v_permlane32_swap_b32_e32 v97, v99
	global_store_dwordx4 v[104:105], v[100:103], off
	s_nop 1
	v_cvt_pk_bf16_f32 v100, v84, v85
	v_cvt_pk_bf16_f32 v101, v86, v87
	v_cvt_pk_bf16_f32 v102, v80, v81
	v_cvt_pk_bf16_f32 v103, v82, v83
	global_store_dwordx4 v[104:105], v[100:103], off offset:64
	s_and_saveexec_b64 s[2:3], s[4:5]
	s_cbranch_execz .LBB0_165
	v_ashrrev_i32_e32 v167, 31, v166
	v_lshl_add_u64 v[100:101], v[166:167], 2, s[68:69]
	v_add_f32_e32 v97, v97, v99
	global_store_dword v[100:101], v97, off offset:192

.LBB0_167:
	s_andn2_b64 vcc, exec, s[2:3]
	s_cbranch_vccnz .LBB0_169
	v_ashrrev_i32_e32 v97, 31, v96
	v_lshlrev_b64 v[100:101], 11, v[96:97]
	v_lshl_add_u64 v[100:101], s[16:17], 0, v[100:101]
	v_lshl_add_u64 v[100:101], s[22:23], 1, v[100:101]
	s_lshl_b32 s2, s65, 1
	s_mov_b32 s3, s23
	v_lshl_add_u64 v[100:101], v[100:101], 0, s[2:3]
	v_lshl_add_u64 v[104:105], v[100:101], 0, v[184:185]
	v_mul_f32_e32 v100, 0xbfb8aa3b, v94
	v_exp_f32_e32 v100, v100
	v_mul_f32_e32 v101, 0xbfb8aa3b, v95
	v_exp_f32_e32 v101, v101
	v_mul_f32_e32 v103, 0xbfb8aa3b, v89
	v_add_f32_e32 v100, 1.0, v100
	v_rcp_f32_e32 v100, v100
	v_exp_f32_e32 v103, v103
	v_mul_f32_e32 v97, 0xbfb8aa3b, v92
	v_mul_f32_e32 v99, 0xbfb8aa3b, v93
	v_mul_f32_e32 v102, v94, v100
	v_add_f32_e32 v100, 1.0, v101
	v_mul_f32_e32 v101, 0xbfb8aa3b, v88
	v_rcp_f32_e32 v100, v100
	v_exp_f32_e32 v101, v101
	v_exp_f32_e32 v97, v97
	v_exp_f32_e32 v99, v99
	v_mul_f32_e32 v106, v95, v100
	v_add_f32_e32 v100, 1.0, v101
	v_add_f32_e32 v101, 1.0, v103
	v_mul_f32_e32 v103, 0xbfb8aa3b, v90
	v_exp_f32_e32 v103, v103
	v_mul_f32_e32 v107, 0xbfb8aa3b, v91
	v_exp_f32_e32 v107, v107
	v_add_f32_e32 v97, 1.0, v97
	v_add_f32_e32 v99, 1.0, v99
	v_add_f32_e32 v103, 1.0, v103
	v_rcp_f32_e32 v97, v97
	v_rcp_f32_e32 v99, v99
	v_rcp_f32_e32 v100, v100
	v_rcp_f32_e32 v103, v103
	v_add_f32_e32 v107, 1.0, v107
	v_rcp_f32_e32 v101, v101
	v_rcp_f32_e32 v107, v107
	v_mul_f32_e32 v97, v92, v97
	v_mul_f32_e32 v99, v93, v99
	v_mul_f32_e32 v108, v88, v100
	v_mul_f32_e32 v103, v90, v103
	v_cvt_pk_bf16_f32 v100, v97, v99
	v_mul_f32_e32 v109, v89, v101
	v_mul_f32_e32 v107, v91, v107
	v_cvt_pk_bf16_f32 v101, v102, v106
	v_cvt_pk_bf16_f32 v102, v108, v109
	v_cvt_pk_bf16_f32 v103, v103, v107
	global_store_dwordx4 v[104:105], v[100:103], off
	v_mul_f32_e32 v97, 0xbfb8aa3b, v84
	v_mul_f32_e32 v99, 0xbfb8aa3b, v85
	v_mul_f32_e32 v100, 0xbfb8aa3b, v86
	v_exp_f32_e32 v100, v100
	v_mul_f32_e32 v101, 0xbfb8aa3b, v87
	v_exp_f32_e32 v101, v101
	v_mul_f32_e32 v103, 0xbfb8aa3b, v81
	v_add_f32_e32 v100, 1.0, v100
	v_rcp_f32_e32 v100, v100
	v_exp_f32_e32 v103, v103
	v_mul_f32_e32 v107, 0xbfb8aa3b, v83
	v_exp_f32_e32 v97, v97
	v_mul_f32_e32 v102, v86, v100
	v_add_f32_e32 v100, 1.0, v101
	v_mul_f32_e32 v101, 0xbfb8aa3b, v80
	v_rcp_f32_e32 v100, v100
	v_exp_f32_e32 v101, v101
	v_exp_f32_e32 v99, v99
	v_exp_f32_e32 v107, v107
	v_mul_f32_e32 v106, v87, v100
	v_add_f32_e32 v100, 1.0, v101
	v_add_f32_e32 v101, 1.0, v103
	v_mul_f32_e32 v103, 0xbfb8aa3b, v82
	v_exp_f32_e32 v103, v103
	v_add_f32_e32 v97, 1.0, v97
	v_add_f32_e32 v99, 1.0, v99
	v_add_f32_e32 v107, 1.0, v107
	v_add_f32_e32 v103, 1.0, v103
	v_rcp_f32_e32 v103, v103
	v_rcp_f32_e32 v97, v97
	v_rcp_f32_e32 v99, v99
	v_rcp_f32_e32 v100, v100
	v_rcp_f32_e32 v101, v101
	v_rcp_f32_e32 v107, v107
	v_mul_f32_e32 v103, v82, v103
	v_mul_f32_e32 v97, v84, v97
	v_mul_f32_e32 v99, v85, v99
	v_mul_f32_e32 v108, v80, v100
	v_mul_f32_e32 v109, v81, v101
	v_mul_f32_e32 v107, v83, v107
	v_cvt_pk_bf16_f32 v100, v97, v99
	v_cvt_pk_bf16_f32 v101, v102, v106
	v_cvt_pk_bf16_f32 v102, v108, v109
	v_cvt_pk_bf16_f32 v103, v103, v107
	global_store_dwordx4 v[104:105], v[100:103], off offset:64

.LBB0_170:
	s_andn2_b64 vcc, exec, s[2:3]
	s_cbranch_vccnz .LBB0_172
	v_ashrrev_i32_e32 v97, 31, v96
	v_lshlrev_b64 v[100:101], 10, v[96:97]
	v_lshl_add_u64 v[100:101], s[18:19], 0, v[100:101]
	s_lshl_b32 s2, s71, 1
	s_mov_b32 s3, s23
	v_lshl_add_u64 v[100:101], v[100:101], 0, s[2:3]
	s_lshl_b32 s2, s65, 1
	v_lshl_add_u64 v[100:101], v[100:101], 0, s[2:3]
	v_lshl_add_u64 v[104:105], v[100:101], 0, v[184:185]
	v_cvt_pk_bf16_f32 v100, v92, v93
	v_cvt_pk_bf16_f32 v101, v94, v95
	v_cvt_pk_bf16_f32 v102, v88, v89
	v_cvt_pk_bf16_f32 v103, v90, v91
	global_store_dwordx4 v[104:105], v[100:103], off
	s_nop 1
	v_cvt_pk_bf16_f32 v100, v84, v85
	v_cvt_pk_bf16_f32 v101, v86, v87
	v_cvt_pk_bf16_f32 v102, v80, v81
	v_cvt_pk_bf16_f32 v103, v82, v83
	global_store_dwordx4 v[104:105], v[100:103], off offset:64

.LBB0_173:
	s_andn2_b64 vcc, exec, s[2:3]
	s_cbranch_vccnz .LBB0_175
	ds_swizzle_b32 v99, v98 offset:swizzle(SWAP,16)
	s_and_b64 s[2:3], s[8:9], exec
	s_cselect_b32 s2, s59, 0x5000000
	v_ashrrev_i32_e32 v97, 31, v96
	s_add_u32 s2, s86, s2
	s_waitcnt lgkmcnt(0)
	v_add_f32_e32 v98, v98, v99
	v_mov_b32_e32 v99, v98
	s_nop 1
	v_permlane32_swap_b32_e32 v98, v99
	v_add_f32_e32 v98, v98, v99
	v_fmamk_f32 v98, v98, 0x3c800000, v227
	v_rsq_f32_e32 v98, v98
	v_lshlrev_b64 v[96:97], 10, v[96:97]
	s_addc_u32 s3, s87, 0
	v_lshl_add_u64 v[96:97], s[2:3], 0, v[96:97]
	v_mul_f32_e32 v98, v168, v98
	v_mul_f32_e32 v92, v92, v98
	v_mul_f32_e32 v88, v88, v98
	s_lshl_b32 s2, s71, 1
	s_mov_b32 s3, s23
	v_mul_f32_e32 v99, v28, v92
	v_mul_f32_e32 v92, v93, v98
	v_mul_f32_e32 v101, v24, v88
	v_mul_f32_e32 v88, v89, v98
	v_lshl_add_u64 v[96:97], v[96:97], 0, s[2:3]
	s_lshl_b32 s2, s65, 1
	v_mul_f32_e32 v100, v29, v92
	v_mul_f32_e32 v92, v94, v98
	v_mul_f32_e32 v102, v25, v88
	v_mul_f32_e32 v88, v90, v98
	v_lshl_add_u64 v[96:97], v[96:97], 0, s[2:3]
	v_mul_f32_e32 v94, v30, v92
	v_mul_f32_e32 v92, v95, v98
	v_mul_f32_e32 v103, v26, v88
	v_mul_f32_e32 v88, v91, v98
	v_mul_f32_e32 v95, v31, v92
	v_mul_f32_e32 v91, v27, v88
	v_lshl_add_u64 v[92:93], v[96:97], 0, v[184:185]
	v_cvt_pk_bf16_f32 v88, v99, v100
	v_mul_f32_e32 v80, v80, v98
	v_cvt_pk_bf16_f32 v89, v94, v95
	v_cvt_pk_bf16_f32 v90, v101, v102
	v_cvt_pk_bf16_f32 v91, v103, v91
	global_store_dwordx4 v[92:93], v[88:91], off
	v_mul_f32_e32 v84, v84, v98
	v_mul_f32_e32 v85, v85, v98
	v_mul_f32_e32 v88, v16, v80
	v_mul_f32_e32 v80, v81, v98
	v_mul_f32_e32 v89, v17, v80
	v_mul_f32_e32 v80, v82, v98
	v_mul_f32_e32 v90, v18, v80
	v_mul_f32_e32 v80, v83, v98
	v_mul_f32_e32 v86, v86, v98
	v_mul_f32_e32 v87, v87, v98
	v_mul_f32_e32 v83, v19, v80
	v_mul_f32_e32 v84, v20, v84
	v_mul_f32_e32 v85, v21, v85
	v_mul_f32_e32 v86, v22, v86
	v_mul_f32_e32 v87, v23, v87
	v_cvt_pk_bf16_f32 v80, v84, v85
	v_cvt_pk_bf16_f32 v81, v86, v87
	v_cvt_pk_bf16_f32 v82, v88, v89
	v_cvt_pk_bf16_f32 v83, v90, v83
	global_store_dwordx4 v[92:93], v[80:83], off offset:64
.LBB0_175:
	s_nop 1
	v_add_u32_e32 v80, 0x80, v166
	s_mov_b64 s[2:3], -1
	s_and_b64 vcc, exec, s[10:11]
	v_ashrrev_i32_e32 v81, 31, v80
	s_cbranch_vccnz .LBB0_177
	v_lshl_add_u64 v[82:83], v[80:81], 2, s[96:97]
	global_load_dword v84, v[82:83], off
	s_mov_b64 s[2:3], 0
	s_waitcnt vmcnt(0) lgkmcnt(0)
	v_add_f32_e32 v86, 0, v84
	v_add_co_u32_e32 v84, vcc, 0x10000, v82
	s_nop 1
	v_addc_co_u32_e32 v85, vcc, 0, v83, vcc
	global_load_dword v84, v[84:85], off
	s_waitcnt vmcnt(0) lgkmcnt(0)
	v_add_f32_e32 v86, v86, v84
	v_add_co_u32_e32 v84, vcc, 0x20000, v82
	s_nop 1
	v_addc_co_u32_e32 v85, vcc, 0, v83, vcc
	global_load_dword v84, v[84:85], off
	s_waitcnt vmcnt(0) lgkmcnt(0)
	v_add_f32_e32 v86, v86, v84
	v_add_co_u32_e32 v84, vcc, 0x30000, v82
	s_nop 1
	v_addc_co_u32_e32 v85, vcc, 0, v83, vcc
	global_load_dword v84, v[84:85], off
	s_waitcnt vmcnt(0) lgkmcnt(0)
	v_add_f32_e32 v86, v86, v84
	v_add_co_u32_e32 v84, vcc, 0x40000, v82
	s_nop 1
	v_addc_co_u32_e32 v85, vcc, 0, v83, vcc
	global_load_dword v84, v[84:85], off
	s_waitcnt vmcnt(0) lgkmcnt(0)
	v_add_f32_e32 v86, v86, v84
	v_add_co_u32_e32 v84, vcc, 0x50000, v82
	s_nop 1
	v_addc_co_u32_e32 v85, vcc, 0, v83, vcc
	global_load_dword v84, v[84:85], off
	s_waitcnt vmcnt(0) lgkmcnt(0)
	v_add_f32_e32 v86, v86, v84
	v_add_co_u32_e32 v84, vcc, 0x60000, v82
	s_nop 1
	v_addc_co_u32_e32 v85, vcc, 0, v83, vcc
	global_load_dword v84, v[84:85], off
	s_waitcnt vmcnt(0) lgkmcnt(0)
	v_add_f32_e32 v86, v86, v84
	v_add_co_u32_e32 v84, vcc, 0x70000, v82
	s_nop 1
	v_addc_co_u32_e32 v85, vcc, 0, v83, vcc
	global_load_dword v84, v[84:85], off
	s_waitcnt vmcnt(0) lgkmcnt(0)
	v_add_f32_e32 v86, v86, v84
	v_add_co_u32_e32 v84, vcc, 0x80000, v82
	s_nop 1
	v_addc_co_u32_e32 v85, vcc, 0, v83, vcc
	global_load_dword v84, v[84:85], off
	s_waitcnt vmcnt(0) lgkmcnt(0)
	v_add_f32_e32 v86, v86, v84
	v_add_co_u32_e32 v84, vcc, 0x90000, v82
	s_nop 1
	v_addc_co_u32_e32 v85, vcc, 0, v83, vcc
	global_load_dword v84, v[84:85], off
	s_waitcnt vmcnt(0) lgkmcnt(0)
	v_add_f32_e32 v86, v86, v84
	v_add_co_u32_e32 v84, vcc, 0xa0000, v82
	s_nop 1
	v_addc_co_u32_e32 v85, vcc, 0, v83, vcc
	global_load_dword v84, v[84:85], off
	s_waitcnt vmcnt(0) lgkmcnt(0)
	v_add_f32_e32 v86, v86, v84
	v_add_co_u32_e32 v84, vcc, 0xb0000, v82
	s_nop 1
	v_addc_co_u32_e32 v85, vcc, 0, v83, vcc
	global_load_dword v84, v[84:85], off
	s_waitcnt vmcnt(0) lgkmcnt(0)
	v_add_f32_e32 v86, v86, v84
	v_add_co_u32_e32 v84, vcc, 0xc0000, v82
	s_nop 1
	v_addc_co_u32_e32 v85, vcc, 0, v83, vcc
	global_load_dword v84, v[84:85], off
	s_waitcnt vmcnt(0) lgkmcnt(0)
	v_add_f32_e32 v86, v86, v84
	v_add_co_u32_e32 v84, vcc, 0xd0000, v82
	s_nop 1
	v_addc_co_u32_e32 v85, vcc, 0, v83, vcc
	global_load_dword v84, v[84:85], off
	s_waitcnt vmcnt(0) lgkmcnt(0)
	v_add_f32_e32 v86, v86, v84
	v_add_co_u32_e32 v84, vcc, 0xe0000, v82
	s_nop 1
	v_addc_co_u32_e32 v85, vcc, 0, v83, vcc
	v_add_co_u32_e32 v82, vcc, 0xf0000, v82
	global_load_dword v84, v[84:85], off
	s_nop 0
	v_addc_co_u32_e32 v83, vcc, 0, v83, vcc
	global_load_dword v82, v[82:83], off
	s_waitcnt vmcnt(0) lgkmcnt(0)
	v_add_f32_e32 v84, v86, v84
	v_add_f32_e32 v82, v84, v82
	v_fmamk_f32 v82, v82, 0x3a800000, v227
	v_rsq_f32_e32 v82, v82

.LBB0_179:
	s_waitcnt lgkmcnt(0)
	v_pk_mul_f32 v[76:77], v[76:77], v[82:83] op_sel_hi:[1,0]
	v_pk_mul_f32 v[78:79], v[78:79], v[82:83] op_sel_hi:[1,0]
	v_pk_mul_f32 v[84:85], v[76:77], v[76:77]
	v_pk_mul_f32 v[86:87], v[78:79], v[78:79]
	v_add_f32_e32 v84, v84, v85
	v_pk_mul_f32 v[72:73], v[72:73], v[82:83] op_sel_hi:[1,0]
	v_add_f32_e32 v84, v86, v84
	v_pk_mul_f32 v[88:89], v[72:73], v[72:73]
	v_add_f32_e32 v84, v87, v84
	v_pk_mul_f32 v[74:75], v[74:75], v[82:83] op_sel_hi:[1,0]
	v_add_f32_e32 v84, v88, v84
	v_pk_mul_f32 v[90:91], v[74:75], v[74:75]
	v_add_f32_e32 v84, v89, v84
	v_pk_mul_f32 v[68:69], v[68:69], v[82:83] op_sel_hi:[1,0]
	v_add_f32_e32 v84, v90, v84
	v_pk_mul_f32 v[92:93], v[68:69], v[68:69]
	v_add_f32_e32 v84, v91, v84
	v_pk_mul_f32 v[70:71], v[70:71], v[82:83] op_sel_hi:[1,0]
	v_add_f32_e32 v84, v92, v84
	v_pk_mul_f32 v[94:95], v[70:71], v[70:71]
	v_add_f32_e32 v84, v93, v84
	v_pk_mul_f32 v[64:65], v[64:65], v[82:83] op_sel_hi:[1,0]
	v_add_f32_e32 v84, v94, v84
	v_pk_mul_f32 v[96:97], v[64:65], v[64:65]
	v_add_f32_e32 v84, v95, v84
	v_pk_mul_f32 v[66:67], v[66:67], v[82:83] op_sel_hi:[1,0]
	v_add_f32_e32 v84, v96, v84
	v_pk_mul_f32 v[82:83], v[66:67], v[66:67]
	v_add_f32_e32 v84, v97, v84
	v_add_f32_e32 v82, v82, v84
	v_add_f32_e32 v82, v83, v82
	s_and_b64 vcc, exec, s[14:15]
	s_mov_b64 s[2:3], -1
	s_cbranch_vccnz .LBB0_203
	s_and_b64 vcc, exec, s[12:13]
	s_cbranch_vccnz .LBB0_200
	s_andn2_b64 vcc, exec, s[82:83]
	s_cbranch_vccnz .LBB0_197
	s_andn2_b64 vcc, exec, s[78:79]
	s_cbranch_vccnz .LBB0_192
	s_andn2_b64 vcc, exec, s[92:93]
	s_cbranch_vccnz .LBB0_187
	s_andn2_b64 vcc, exec, s[94:95]
	s_cbranch_vccnz .LBB0_186
	v_lshlrev_b64 v[84:85], 8, v[80:81]
	v_lshl_add_u64 v[84:85], v[156:157], 0, v[84:85]
	s_waitcnt vmcnt(0)
	global_store_dwordx4 v[84:85], v[76:79], off
	global_store_dwordx4 v[84:85], v[72:75], off offset:16
	global_store_dwordx4 v[84:85], v[68:71], off offset:128
	global_store_dwordx4 v[84:85], v[64:67], off offset:144

.LBB0_187:
	s_andn2_b64 vcc, exec, s[2:3]
	s_cbranch_vccnz .LBB0_191
	ds_swizzle_b32 v83, v82 offset:swizzle(SWAP,16)
	v_lshlrev_b64 v[84:85], 8, v[80:81]
	v_lshl_add_u64 v[88:89], v[158:159], 0, v[84:85]
	v_cvt_pk_bf16_f32 v84, v76, v77
	v_cvt_pk_bf16_f32 v85, v78, v79
	v_cvt_pk_bf16_f32 v86, v72, v73
	v_cvt_pk_bf16_f32 v87, v74, v75
	global_store_dwordx4 v[88:89], v[84:87], off
	s_waitcnt lgkmcnt(0)
	v_add_f32_e32 v83, v82, v83
	v_cvt_pk_bf16_f32 v84, v68, v69
	v_cvt_pk_bf16_f32 v85, v70, v71
	v_cvt_pk_bf16_f32 v86, v64, v65
	v_cvt_pk_bf16_f32 v87, v66, v67
	global_store_dwordx4 v[88:89], v[84:87], off offset:64
	s_nop 1
	v_mov_b32_e32 v84, v83
	s_nop 1
	v_permlane32_swap_b32_e32 v83, v84
	s_and_saveexec_b64 s[2:3], s[4:5]
	s_cbranch_execz .LBB0_190
	v_lshl_add_u64 v[86:87], v[80:81], 2, s[98:99]
	v_add_f32_e32 v83, v83, v84
	global_store_dword v[86:87], v83, off

.LBB0_192:
	s_andn2_b64 vcc, exec, s[2:3]
	s_cbranch_vccnz .LBB0_196
	ds_swizzle_b32 v83, v82 offset:swizzle(SWAP,16)
	v_lshlrev_b64 v[84:85], 9, v[80:81]
	v_lshl_add_u64 v[88:89], v[160:161], 0, v[84:85]
	v_cvt_pk_bf16_f32 v84, v76, v77
	v_cvt_pk_bf16_f32 v85, v78, v79
	v_cvt_pk_bf16_f32 v86, v72, v73
	v_cvt_pk_bf16_f32 v87, v74, v75
	global_store_dwordx4 v[88:89], v[84:87], off
	s_waitcnt lgkmcnt(0)
	v_add_f32_e32 v83, v82, v83
	v_cvt_pk_bf16_f32 v84, v68, v69
	v_cvt_pk_bf16_f32 v85, v70, v71
	v_cvt_pk_bf16_f32 v86, v64, v65
	v_cvt_pk_bf16_f32 v87, v66, v67
	global_store_dwordx4 v[88:89], v[84:87], off offset:64
	s_nop 1
	v_mov_b32_e32 v84, v83
	s_nop 1
	v_permlane32_swap_b32_e32 v83, v84
	s_and_saveexec_b64 s[2:3], s[4:5]
	s_cbranch_execz .LBB0_195
	v_lshl_add_u64 v[86:87], v[80:81], 2, s[68:69]
	v_add_f32_e32 v83, v83, v84
	global_store_dword v[86:87], v83, off

.LBB0_197:
	s_andn2_b64 vcc, exec, s[2:3]
	s_cbranch_vccnz .LBB0_199
	v_lshlrev_b64 v[84:85], 11, v[80:81]
	v_lshl_add_u64 v[84:85], s[16:17], 0, v[84:85]
	v_lshl_add_u64 v[84:85], s[22:23], 1, v[84:85]
	s_lshl_b32 s2, s65, 1
	s_mov_b32 s3, s23
	v_lshl_add_u64 v[84:85], v[84:85], 0, s[2:3]
	v_lshl_add_u64 v[88:89], v[84:85], 0, v[184:185]
	v_mul_f32_e32 v84, 0xbfb8aa3b, v77
	v_mul_f32_e32 v85, 0xbfb8aa3b, v78
	v_mul_f32_e32 v86, 0xbfb8aa3b, v79
	v_mul_f32_e32 v87, 0xbfb8aa3b, v72
	v_mul_f32_e32 v83, 0xbfb8aa3b, v76
	v_exp_f32_e32 v84, v84
	v_exp_f32_e32 v85, v85
	v_exp_f32_e32 v86, v86
	v_exp_f32_e32 v87, v87
	v_mul_f32_e32 v90, 0xbfb8aa3b, v73
	v_mul_f32_e32 v91, 0xbfb8aa3b, v74
	v_mul_f32_e32 v92, 0xbfb8aa3b, v75
	v_exp_f32_e32 v83, v83
	v_exp_f32_e32 v90, v90
	v_exp_f32_e32 v91, v91
	v_exp_f32_e32 v92, v92
	v_add_f32_e32 v84, 1.0, v84
	v_add_f32_e32 v85, 1.0, v85
	v_add_f32_e32 v86, 1.0, v86
	v_add_f32_e32 v87, 1.0, v87
	v_add_f32_e32 v83, 1.0, v83
	v_rcp_f32_e32 v84, v84
	v_rcp_f32_e32 v85, v85
	v_rcp_f32_e32 v86, v86
	v_rcp_f32_e32 v87, v87
	v_add_f32_e32 v90, 1.0, v90
	v_add_f32_e32 v91, 1.0, v91
	v_add_f32_e32 v92, 1.0, v92
	v_rcp_f32_e32 v83, v83
	v_rcp_f32_e32 v90, v90
	v_rcp_f32_e32 v91, v91
	v_rcp_f32_e32 v92, v92
	v_mul_f32_e32 v84, v77, v84
	v_mul_f32_e32 v85, v78, v85
	v_mul_f32_e32 v86, v79, v86
	v_mul_f32_e32 v87, v72, v87
	v_mul_f32_e32 v83, v76, v83
	v_mul_f32_e32 v90, v73, v90
	v_mul_f32_e32 v91, v74, v91
	v_mul_f32_e32 v92, v75, v92
	v_cvt_pk_bf16_f32 v84, v83, v84
	v_cvt_pk_bf16_f32 v85, v85, v86
	v_cvt_pk_bf16_f32 v86, v87, v90
	v_cvt_pk_bf16_f32 v87, v91, v92
	global_store_dwordx4 v[88:89], v[84:87], off
	v_mul_f32_e32 v83, 0xbfb8aa3b, v68
	v_mul_f32_e32 v90, 0xbfb8aa3b, v65
	v_mul_f32_e32 v84, 0xbfb8aa3b, v69
	v_mul_f32_e32 v85, 0xbfb8aa3b, v70
	v_mul_f32_e32 v86, 0xbfb8aa3b, v71
	v_mul_f32_e32 v87, 0xbfb8aa3b, v64
	v_exp_f32_e32 v84, v84
	v_exp_f32_e32 v85, v85
	v_exp_f32_e32 v86, v86
	v_exp_f32_e32 v87, v87
	v_mul_f32_e32 v91, 0xbfb8aa3b, v66
	v_mul_f32_e32 v92, 0xbfb8aa3b, v67
	v_exp_f32_e32 v83, v83
	v_exp_f32_e32 v90, v90
	v_exp_f32_e32 v91, v91
	v_exp_f32_e32 v92, v92
	v_add_f32_e32 v84, 1.0, v84
	v_add_f32_e32 v85, 1.0, v85
	v_add_f32_e32 v86, 1.0, v86
	v_add_f32_e32 v87, 1.0, v87
	v_add_f32_e32 v83, 1.0, v83
	v_rcp_f32_e32 v84, v84
	v_rcp_f32_e32 v85, v85
	v_rcp_f32_e32 v86, v86
	v_rcp_f32_e32 v87, v87
	v_add_f32_e32 v90, 1.0, v90
	v_add_f32_e32 v91, 1.0, v91
	v_add_f32_e32 v92, 1.0, v92
	v_rcp_f32_e32 v83, v83
	v_rcp_f32_e32 v90, v90
	v_rcp_f32_e32 v91, v91
	v_rcp_f32_e32 v92, v92
	v_mul_f32_e32 v84, v69, v84
	v_mul_f32_e32 v85, v70, v85
	v_mul_f32_e32 v86, v71, v86
	v_mul_f32_e32 v87, v64, v87
	v_mul_f32_e32 v83, v68, v83
	v_mul_f32_e32 v90, v65, v90
	v_mul_f32_e32 v91, v66, v91
	v_mul_f32_e32 v92, v67, v92
	v_cvt_pk_bf16_f32 v84, v83, v84
	v_cvt_pk_bf16_f32 v85, v85, v86
	v_cvt_pk_bf16_f32 v86, v87, v90
	v_cvt_pk_bf16_f32 v87, v91, v92
	global_store_dwordx4 v[88:89], v[84:87], off offset:64

.LBB0_200:
	s_andn2_b64 vcc, exec, s[2:3]
	s_cbranch_vccnz .LBB0_202
	v_lshlrev_b64 v[84:85], 10, v[80:81]
	v_lshl_add_u64 v[84:85], s[18:19], 0, v[84:85]
	s_lshl_b32 s2, s71, 1
	s_mov_b32 s3, s23
	v_lshl_add_u64 v[84:85], v[84:85], 0, s[2:3]
	s_lshl_b32 s2, s65, 1
	v_lshl_add_u64 v[84:85], v[84:85], 0, s[2:3]
	v_lshl_add_u64 v[88:89], v[84:85], 0, v[184:185]
	v_cvt_pk_bf16_f32 v84, v76, v77
	v_cvt_pk_bf16_f32 v85, v78, v79
	v_cvt_pk_bf16_f32 v86, v72, v73
	v_cvt_pk_bf16_f32 v87, v74, v75
	global_store_dwordx4 v[88:89], v[84:87], off
	s_nop 1
	v_cvt_pk_bf16_f32 v84, v68, v69
	v_cvt_pk_bf16_f32 v85, v70, v71
	v_cvt_pk_bf16_f32 v86, v64, v65
	v_cvt_pk_bf16_f32 v87, v66, v67
	global_store_dwordx4 v[88:89], v[84:87], off offset:64

.LBB0_203:
	s_andn2_b64 vcc, exec, s[2:3]
	s_cbranch_vccnz .LBB0_205
	ds_swizzle_b32 v83, v82 offset:swizzle(SWAP,16)
	s_and_b64 s[2:3], s[8:9], exec
	s_cselect_b32 s2, s59, 0x5000000
	s_add_u32 s2, s86, s2
	s_addc_u32 s3, s87, 0
	s_waitcnt lgkmcnt(0)
	v_add_f32_e32 v82, v82, v83
	v_mov_b32_e32 v83, v82
	s_nop 1
	v_permlane32_swap_b32_e32 v82, v83
	v_add_f32_e32 v82, v82, v83
	v_fmamk_f32 v82, v82, 0x3c800000, v227
	v_rsq_f32_e32 v82, v82
	v_lshlrev_b64 v[80:81], 10, v[80:81]
	v_lshl_add_u64 v[80:81], s[2:3], 0, v[80:81]
	s_lshl_b32 s2, s71, 1
	v_mul_f32_e32 v82, v168, v82
	v_mul_f32_e32 v76, v76, v82
	v_mul_f32_e32 v72, v72, v82
	s_mov_b32 s3, s23
	v_mul_f32_e32 v83, v28, v76
	v_mul_f32_e32 v76, v77, v82
	v_mul_f32_e32 v85, v24, v72
	v_mul_f32_e32 v72, v73, v82
	v_lshl_add_u64 v[80:81], v[80:81], 0, s[2:3]
	s_lshl_b32 s2, s65, 1
	v_mul_f32_e32 v84, v29, v76
	v_mul_f32_e32 v76, v78, v82
	v_mul_f32_e32 v86, v25, v72
	v_mul_f32_e32 v72, v74, v82
	v_lshl_add_u64 v[80:81], v[80:81], 0, s[2:3]
	v_mul_f32_e32 v78, v30, v76
	v_mul_f32_e32 v76, v79, v82
	v_mul_f32_e32 v87, v26, v72
	v_mul_f32_e32 v72, v75, v82
	v_mul_f32_e32 v79, v31, v76
	v_mul_f32_e32 v75, v27, v72
	v_lshl_add_u64 v[76:77], v[80:81], 0, v[184:185]
	v_cvt_pk_bf16_f32 v72, v83, v84
	v_mul_f32_e32 v64, v64, v82
	v_cvt_pk_bf16_f32 v73, v78, v79
	v_cvt_pk_bf16_f32 v74, v85, v86
	v_cvt_pk_bf16_f32 v75, v87, v75
	global_store_dwordx4 v[76:77], v[72:75], off
	v_mul_f32_e32 v68, v68, v82
	v_mul_f32_e32 v69, v69, v82
	v_mul_f32_e32 v72, v16, v64
	v_mul_f32_e32 v64, v65, v82
	v_mul_f32_e32 v73, v17, v64
	v_mul_f32_e32 v64, v66, v82
	v_mul_f32_e32 v74, v18, v64
	v_mul_f32_e32 v64, v67, v82
	v_mul_f32_e32 v70, v70, v82
	v_mul_f32_e32 v71, v71, v82
	v_mul_f32_e32 v67, v19, v64
	v_mul_f32_e32 v68, v20, v68
	v_mul_f32_e32 v69, v21, v69
	v_mul_f32_e32 v70, v22, v70
	v_mul_f32_e32 v71, v23, v71
	v_cvt_pk_bf16_f32 v64, v68, v69
	v_cvt_pk_bf16_f32 v65, v70, v71
	v_cvt_pk_bf16_f32 v66, v72, v73
	v_cvt_pk_bf16_f32 v67, v74, v67
	global_store_dwordx4 v[76:77], v[64:67], off offset:64
.LBB0_205:
	s_nop 1
	v_add_u32_e32 v64, 0x90, v166
	s_mov_b64 s[2:3], -1
	s_and_b64 vcc, exec, s[10:11]
	v_ashrrev_i32_e32 v65, 31, v64
	s_cbranch_vccnz .LBB0_207
	v_lshl_add_u64 v[66:67], v[64:65], 2, s[96:97]
	global_load_dword v68, v[66:67], off
	s_mov_b64 s[2:3], 0
	s_waitcnt vmcnt(0) lgkmcnt(0)
	v_add_f32_e32 v70, 0, v68
	v_add_co_u32_e32 v68, vcc, 0x10000, v66
	s_nop 1
	v_addc_co_u32_e32 v69, vcc, 0, v67, vcc
	global_load_dword v68, v[68:69], off
	s_waitcnt vmcnt(0) lgkmcnt(0)
	v_add_f32_e32 v70, v70, v68
	v_add_co_u32_e32 v68, vcc, 0x20000, v66
	s_nop 1
	v_addc_co_u32_e32 v69, vcc, 0, v67, vcc
	global_load_dword v68, v[68:69], off
	s_waitcnt vmcnt(0) lgkmcnt(0)
	v_add_f32_e32 v70, v70, v68
	v_add_co_u32_e32 v68, vcc, 0x30000, v66
	s_nop 1
	v_addc_co_u32_e32 v69, vcc, 0, v67, vcc
	global_load_dword v68, v[68:69], off
	s_waitcnt vmcnt(0) lgkmcnt(0)
	v_add_f32_e32 v70, v70, v68
	v_add_co_u32_e32 v68, vcc, 0x40000, v66
	s_nop 1
	v_addc_co_u32_e32 v69, vcc, 0, v67, vcc
	global_load_dword v68, v[68:69], off
	s_waitcnt vmcnt(0) lgkmcnt(0)
	v_add_f32_e32 v70, v70, v68
	v_add_co_u32_e32 v68, vcc, 0x50000, v66
	s_nop 1
	v_addc_co_u32_e32 v69, vcc, 0, v67, vcc
	global_load_dword v68, v[68:69], off
	s_waitcnt vmcnt(0) lgkmcnt(0)
	v_add_f32_e32 v70, v70, v68
	v_add_co_u32_e32 v68, vcc, 0x60000, v66
	s_nop 1
	v_addc_co_u32_e32 v69, vcc, 0, v67, vcc
	global_load_dword v68, v[68:69], off
	s_waitcnt vmcnt(0) lgkmcnt(0)
	v_add_f32_e32 v70, v70, v68
	v_add_co_u32_e32 v68, vcc, 0x70000, v66
	s_nop 1
	v_addc_co_u32_e32 v69, vcc, 0, v67, vcc
	global_load_dword v68, v[68:69], off
	s_waitcnt vmcnt(0) lgkmcnt(0)
	v_add_f32_e32 v70, v70, v68
	v_add_co_u32_e32 v68, vcc, 0x80000, v66
	s_nop 1
	v_addc_co_u32_e32 v69, vcc, 0, v67, vcc
	global_load_dword v68, v[68:69], off
	s_waitcnt vmcnt(0) lgkmcnt(0)
	v_add_f32_e32 v70, v70, v68
	v_add_co_u32_e32 v68, vcc, 0x90000, v66
	s_nop 1
	v_addc_co_u32_e32 v69, vcc, 0, v67, vcc
	global_load_dword v68, v[68:69], off
	s_waitcnt vmcnt(0) lgkmcnt(0)
	v_add_f32_e32 v70, v70, v68
	v_add_co_u32_e32 v68, vcc, 0xa0000, v66
	s_nop 1
	v_addc_co_u32_e32 v69, vcc, 0, v67, vcc
	global_load_dword v68, v[68:69], off
	s_waitcnt vmcnt(0) lgkmcnt(0)
	v_add_f32_e32 v70, v70, v68
	v_add_co_u32_e32 v68, vcc, 0xb0000, v66
	s_nop 1
	v_addc_co_u32_e32 v69, vcc, 0, v67, vcc
	global_load_dword v68, v[68:69], off
	s_waitcnt vmcnt(0) lgkmcnt(0)
	v_add_f32_e32 v70, v70, v68
	v_add_co_u32_e32 v68, vcc, 0xc0000, v66
	s_nop 1
	v_addc_co_u32_e32 v69, vcc, 0, v67, vcc
	global_load_dword v68, v[68:69], off
	s_waitcnt vmcnt(0) lgkmcnt(0)
	v_add_f32_e32 v70, v70, v68
	v_add_co_u32_e32 v68, vcc, 0xd0000, v66
	s_nop 1
	v_addc_co_u32_e32 v69, vcc, 0, v67, vcc
	global_load_dword v68, v[68:69], off
	s_waitcnt vmcnt(0) lgkmcnt(0)
	v_add_f32_e32 v70, v70, v68
	v_add_co_u32_e32 v68, vcc, 0xe0000, v66
	s_nop 1
	v_addc_co_u32_e32 v69, vcc, 0, v67, vcc
	v_add_co_u32_e32 v66, vcc, 0xf0000, v66
	global_load_dword v68, v[68:69], off
	s_nop 0
	v_addc_co_u32_e32 v67, vcc, 0, v67, vcc
	global_load_dword v66, v[66:67], off
	s_waitcnt vmcnt(0) lgkmcnt(0)
	v_add_f32_e32 v68, v70, v68
	v_add_f32_e32 v66, v68, v66
	v_fmamk_f32 v66, v66, 0x3a800000, v227
	v_rsq_f32_e32 v66, v66

.LBB0_209:
	s_waitcnt lgkmcnt(0)
	v_pk_mul_f32 v[60:61], v[60:61], v[66:67] op_sel_hi:[1,0]
	v_pk_mul_f32 v[62:63], v[62:63], v[66:67] op_sel_hi:[1,0]
	v_pk_mul_f32 v[68:69], v[60:61], v[60:61]
	v_pk_mul_f32 v[70:71], v[62:63], v[62:63]
	v_add_f32_e32 v68, v68, v69
	v_pk_mul_f32 v[56:57], v[56:57], v[66:67] op_sel_hi:[1,0]
	v_add_f32_e32 v68, v70, v68
	v_pk_mul_f32 v[72:73], v[56:57], v[56:57]
	v_add_f32_e32 v68, v71, v68
	v_pk_mul_f32 v[58:59], v[58:59], v[66:67] op_sel_hi:[1,0]
	v_add_f32_e32 v68, v72, v68
	v_pk_mul_f32 v[74:75], v[58:59], v[58:59]
	v_add_f32_e32 v68, v73, v68
	v_pk_mul_f32 v[52:53], v[52:53], v[66:67] op_sel_hi:[1,0]
	v_add_f32_e32 v68, v74, v68
	v_pk_mul_f32 v[76:77], v[52:53], v[52:53]
	v_add_f32_e32 v68, v75, v68
	v_pk_mul_f32 v[54:55], v[54:55], v[66:67] op_sel_hi:[1,0]
	v_add_f32_e32 v68, v76, v68
	v_pk_mul_f32 v[78:79], v[54:55], v[54:55]
	v_add_f32_e32 v68, v77, v68
	v_pk_mul_f32 v[48:49], v[48:49], v[66:67] op_sel_hi:[1,0]
	v_add_f32_e32 v68, v78, v68
	v_pk_mul_f32 v[80:81], v[48:49], v[48:49]
	v_add_f32_e32 v68, v79, v68
	v_pk_mul_f32 v[50:51], v[50:51], v[66:67] op_sel_hi:[1,0]
	v_add_f32_e32 v68, v80, v68
	v_pk_mul_f32 v[66:67], v[50:51], v[50:51]
	v_add_f32_e32 v68, v81, v68
	v_add_f32_e32 v66, v66, v68
	v_add_f32_e32 v66, v67, v66
	s_and_b64 vcc, exec, s[14:15]
	s_mov_b64 s[2:3], -1
	s_cbranch_vccnz .LBB0_233
	s_and_b64 vcc, exec, s[12:13]
	s_cbranch_vccnz .LBB0_230
	s_andn2_b64 vcc, exec, s[82:83]
	s_cbranch_vccnz .LBB0_227
	s_andn2_b64 vcc, exec, s[78:79]
	s_cbranch_vccnz .LBB0_222
	s_andn2_b64 vcc, exec, s[92:93]
	s_cbranch_vccnz .LBB0_217
	s_andn2_b64 vcc, exec, s[94:95]
	s_cbranch_vccnz .LBB0_216
	v_lshlrev_b64 v[68:69], 8, v[64:65]
	v_lshl_add_u64 v[68:69], v[156:157], 0, v[68:69]
	s_waitcnt vmcnt(0)
	global_store_dwordx4 v[68:69], v[60:63], off
	global_store_dwordx4 v[68:69], v[56:59], off offset:16
	global_store_dwordx4 v[68:69], v[52:55], off offset:128
	global_store_dwordx4 v[68:69], v[48:51], off offset:144

.LBB0_217:
	s_andn2_b64 vcc, exec, s[2:3]
	s_cbranch_vccnz .LBB0_221
	ds_swizzle_b32 v67, v66 offset:swizzle(SWAP,16)
	v_lshlrev_b64 v[68:69], 8, v[64:65]
	v_lshl_add_u64 v[72:73], v[158:159], 0, v[68:69]
	v_cvt_pk_bf16_f32 v68, v60, v61
	v_cvt_pk_bf16_f32 v69, v62, v63
	v_cvt_pk_bf16_f32 v70, v56, v57
	v_cvt_pk_bf16_f32 v71, v58, v59
	global_store_dwordx4 v[72:73], v[68:71], off
	s_waitcnt lgkmcnt(0)
	v_add_f32_e32 v67, v66, v67
	v_cvt_pk_bf16_f32 v68, v52, v53
	v_cvt_pk_bf16_f32 v69, v54, v55
	v_cvt_pk_bf16_f32 v70, v48, v49
	v_cvt_pk_bf16_f32 v71, v50, v51
	global_store_dwordx4 v[72:73], v[68:71], off offset:64
	s_nop 1
	v_mov_b32_e32 v68, v67
	s_nop 1
	v_permlane32_swap_b32_e32 v67, v68
	s_and_saveexec_b64 s[2:3], s[4:5]
	s_cbranch_execz .LBB0_220
	v_lshl_add_u64 v[70:71], v[64:65], 2, s[98:99]
	v_add_f32_e32 v67, v67, v68
	global_store_dword v[70:71], v67, off

.LBB0_222:
	s_andn2_b64 vcc, exec, s[2:3]
	s_cbranch_vccnz .LBB0_226
	ds_swizzle_b32 v67, v66 offset:swizzle(SWAP,16)
	v_lshlrev_b64 v[68:69], 9, v[64:65]
	v_lshl_add_u64 v[72:73], v[160:161], 0, v[68:69]
	v_cvt_pk_bf16_f32 v68, v60, v61
	v_cvt_pk_bf16_f32 v69, v62, v63
	v_cvt_pk_bf16_f32 v70, v56, v57
	v_cvt_pk_bf16_f32 v71, v58, v59
	global_store_dwordx4 v[72:73], v[68:71], off
	s_waitcnt lgkmcnt(0)
	v_add_f32_e32 v67, v66, v67
	v_cvt_pk_bf16_f32 v68, v52, v53
	v_cvt_pk_bf16_f32 v69, v54, v55
	v_cvt_pk_bf16_f32 v70, v48, v49
	v_cvt_pk_bf16_f32 v71, v50, v51
	global_store_dwordx4 v[72:73], v[68:71], off offset:64
	s_nop 1
	v_mov_b32_e32 v68, v67
	s_nop 1
	v_permlane32_swap_b32_e32 v67, v68
	s_and_saveexec_b64 s[2:3], s[4:5]
	s_cbranch_execz .LBB0_225
	v_lshl_add_u64 v[70:71], v[64:65], 2, s[68:69]
	v_add_f32_e32 v67, v67, v68
	global_store_dword v[70:71], v67, off

.LBB0_227:
	s_andn2_b64 vcc, exec, s[2:3]
	s_cbranch_vccnz .LBB0_229
	v_lshlrev_b64 v[68:69], 11, v[64:65]
	v_lshl_add_u64 v[68:69], s[16:17], 0, v[68:69]
	v_lshl_add_u64 v[68:69], s[22:23], 1, v[68:69]
	s_lshl_b32 s2, s65, 1
	s_mov_b32 s3, s23
	v_lshl_add_u64 v[68:69], v[68:69], 0, s[2:3]
	v_lshl_add_u64 v[72:73], v[68:69], 0, v[184:185]
	v_mul_f32_e32 v68, 0xbfb8aa3b, v61
	v_mul_f32_e32 v69, 0xbfb8aa3b, v62
	v_mul_f32_e32 v70, 0xbfb8aa3b, v63
	v_mul_f32_e32 v71, 0xbfb8aa3b, v56
	v_mul_f32_e32 v67, 0xbfb8aa3b, v60
	v_exp_f32_e32 v68, v68
	v_exp_f32_e32 v69, v69
	v_exp_f32_e32 v70, v70
	v_exp_f32_e32 v71, v71
	v_mul_f32_e32 v74, 0xbfb8aa3b, v57
	v_mul_f32_e32 v75, 0xbfb8aa3b, v58
	v_mul_f32_e32 v76, 0xbfb8aa3b, v59
	v_exp_f32_e32 v67, v67
	v_exp_f32_e32 v74, v74
	v_exp_f32_e32 v75, v75
	v_exp_f32_e32 v76, v76
	v_add_f32_e32 v68, 1.0, v68
	v_add_f32_e32 v69, 1.0, v69
	v_add_f32_e32 v70, 1.0, v70
	v_add_f32_e32 v71, 1.0, v71
	v_add_f32_e32 v67, 1.0, v67
	v_rcp_f32_e32 v68, v68
	v_rcp_f32_e32 v69, v69
	v_rcp_f32_e32 v70, v70
	v_rcp_f32_e32 v71, v71
	v_add_f32_e32 v74, 1.0, v74
	v_add_f32_e32 v75, 1.0, v75
	v_add_f32_e32 v76, 1.0, v76
	v_rcp_f32_e32 v67, v67
	v_rcp_f32_e32 v74, v74
	v_rcp_f32_e32 v75, v75
	v_rcp_f32_e32 v76, v76
	v_mul_f32_e32 v68, v61, v68
	v_mul_f32_e32 v69, v62, v69
	v_mul_f32_e32 v70, v63, v70
	v_mul_f32_e32 v71, v56, v71
	v_mul_f32_e32 v67, v60, v67
	v_mul_f32_e32 v74, v57, v74
	v_mul_f32_e32 v75, v58, v75
	v_mul_f32_e32 v76, v59, v76
	v_cvt_pk_bf16_f32 v68, v67, v68
	v_cvt_pk_bf16_f32 v69, v69, v70
	v_cvt_pk_bf16_f32 v70, v71, v74
	v_cvt_pk_bf16_f32 v71, v75, v76
	global_store_dwordx4 v[72:73], v[68:71], off
	v_mul_f32_e32 v67, 0xbfb8aa3b, v52
	v_mul_f32_e32 v74, 0xbfb8aa3b, v49
	v_mul_f32_e32 v68, 0xbfb8aa3b, v53
	v_mul_f32_e32 v69, 0xbfb8aa3b, v54
	v_mul_f32_e32 v70, 0xbfb8aa3b, v55
	v_mul_f32_e32 v71, 0xbfb8aa3b, v48
	v_exp_f32_e32 v68, v68
	v_exp_f32_e32 v69, v69
	v_exp_f32_e32 v70, v70
	v_exp_f32_e32 v71, v71
	v_mul_f32_e32 v75, 0xbfb8aa3b, v50
	v_mul_f32_e32 v76, 0xbfb8aa3b, v51
	v_exp_f32_e32 v67, v67
	v_exp_f32_e32 v74, v74
	v_exp_f32_e32 v75, v75
	v_exp_f32_e32 v76, v76
	v_add_f32_e32 v68, 1.0, v68
	v_add_f32_e32 v69, 1.0, v69
	v_add_f32_e32 v70, 1.0, v70
	v_add_f32_e32 v71, 1.0, v71
	v_add_f32_e32 v67, 1.0, v67
	v_rcp_f32_e32 v68, v68
	v_rcp_f32_e32 v69, v69
	v_rcp_f32_e32 v70, v70
	v_rcp_f32_e32 v71, v71
	v_add_f32_e32 v74, 1.0, v74
	v_add_f32_e32 v75, 1.0, v75
	v_add_f32_e32 v76, 1.0, v76
	v_rcp_f32_e32 v67, v67
	v_rcp_f32_e32 v74, v74
	v_rcp_f32_e32 v75, v75
	v_rcp_f32_e32 v76, v76
	v_mul_f32_e32 v68, v53, v68
	v_mul_f32_e32 v69, v54, v69
	v_mul_f32_e32 v70, v55, v70
	v_mul_f32_e32 v71, v48, v71
	v_mul_f32_e32 v67, v52, v67
	v_mul_f32_e32 v74, v49, v74
	v_mul_f32_e32 v75, v50, v75
	v_mul_f32_e32 v76, v51, v76
	v_cvt_pk_bf16_f32 v68, v67, v68
	v_cvt_pk_bf16_f32 v69, v69, v70
	v_cvt_pk_bf16_f32 v70, v71, v74
	v_cvt_pk_bf16_f32 v71, v75, v76
	global_store_dwordx4 v[72:73], v[68:71], off offset:64

.LBB0_230:
	s_andn2_b64 vcc, exec, s[2:3]
	s_cbranch_vccnz .LBB0_232
	v_lshlrev_b64 v[68:69], 10, v[64:65]
	v_lshl_add_u64 v[68:69], s[18:19], 0, v[68:69]
	s_lshl_b32 s2, s71, 1
	s_mov_b32 s3, s23
	v_lshl_add_u64 v[68:69], v[68:69], 0, s[2:3]
	s_lshl_b32 s2, s65, 1
	v_lshl_add_u64 v[68:69], v[68:69], 0, s[2:3]
	v_lshl_add_u64 v[72:73], v[68:69], 0, v[184:185]
	v_cvt_pk_bf16_f32 v68, v60, v61
	v_cvt_pk_bf16_f32 v69, v62, v63
	v_cvt_pk_bf16_f32 v70, v56, v57
	v_cvt_pk_bf16_f32 v71, v58, v59
	global_store_dwordx4 v[72:73], v[68:71], off
	s_nop 1
	v_cvt_pk_bf16_f32 v68, v52, v53
	v_cvt_pk_bf16_f32 v69, v54, v55
	v_cvt_pk_bf16_f32 v70, v48, v49
	v_cvt_pk_bf16_f32 v71, v50, v51
	global_store_dwordx4 v[72:73], v[68:71], off offset:64

.LBB0_233:
	s_andn2_b64 vcc, exec, s[2:3]
	s_cbranch_vccnz .LBB0_235
	ds_swizzle_b32 v67, v66 offset:swizzle(SWAP,16)
	s_and_b64 s[2:3], s[8:9], exec
	s_cselect_b32 s2, s59, 0x5000000
	s_add_u32 s2, s86, s2
	s_addc_u32 s3, s87, 0
	s_waitcnt lgkmcnt(0)
	v_add_f32_e32 v66, v66, v67
	v_mov_b32_e32 v67, v66
	s_nop 1
	v_permlane32_swap_b32_e32 v66, v67
	v_add_f32_e32 v66, v66, v67
	v_fmamk_f32 v66, v66, 0x3c800000, v227
	v_rsq_f32_e32 v66, v66
	v_lshlrev_b64 v[64:65], 10, v[64:65]
	v_lshl_add_u64 v[64:65], s[2:3], 0, v[64:65]
	s_lshl_b32 s2, s71, 1
	v_mul_f32_e32 v66, v168, v66
	v_mul_f32_e32 v60, v60, v66
	v_mul_f32_e32 v56, v56, v66
	s_mov_b32 s3, s23
	v_mul_f32_e32 v67, v28, v60
	v_mul_f32_e32 v60, v61, v66
	v_mul_f32_e32 v69, v24, v56
	v_mul_f32_e32 v56, v57, v66
	v_lshl_add_u64 v[64:65], v[64:65], 0, s[2:3]
	s_lshl_b32 s2, s65, 1
	v_mul_f32_e32 v68, v29, v60
	v_mul_f32_e32 v60, v62, v66
	v_mul_f32_e32 v70, v25, v56
	v_mul_f32_e32 v56, v58, v66
	v_lshl_add_u64 v[64:65], v[64:65], 0, s[2:3]
	v_mul_f32_e32 v62, v30, v60
	v_mul_f32_e32 v60, v63, v66
	v_mul_f32_e32 v71, v26, v56
	v_mul_f32_e32 v56, v59, v66
	v_mul_f32_e32 v63, v31, v60
	v_mul_f32_e32 v59, v27, v56
	v_lshl_add_u64 v[60:61], v[64:65], 0, v[184:185]
	v_cvt_pk_bf16_f32 v56, v67, v68
	v_mul_f32_e32 v48, v48, v66
	v_cvt_pk_bf16_f32 v57, v62, v63
	v_cvt_pk_bf16_f32 v58, v69, v70
	v_cvt_pk_bf16_f32 v59, v71, v59
	global_store_dwordx4 v[60:61], v[56:59], off
	v_mul_f32_e32 v52, v52, v66
	v_mul_f32_e32 v53, v53, v66
	v_mul_f32_e32 v56, v16, v48
	v_mul_f32_e32 v48, v49, v66
	v_mul_f32_e32 v57, v17, v48
	v_mul_f32_e32 v48, v50, v66
	v_mul_f32_e32 v58, v18, v48
	v_mul_f32_e32 v48, v51, v66
	v_mul_f32_e32 v54, v54, v66
	v_mul_f32_e32 v55, v55, v66
	v_mul_f32_e32 v51, v19, v48
	v_mul_f32_e32 v52, v20, v52
	v_mul_f32_e32 v53, v21, v53
	v_mul_f32_e32 v54, v22, v54
	v_mul_f32_e32 v55, v23, v55
	v_cvt_pk_bf16_f32 v48, v52, v53
	v_cvt_pk_bf16_f32 v49, v54, v55
	v_cvt_pk_bf16_f32 v50, v56, v57
	v_cvt_pk_bf16_f32 v51, v58, v51
	global_store_dwordx4 v[60:61], v[48:51], off offset:64
.LBB0_235:
	s_nop 1
	v_add_u32_e32 v48, 0xa0, v166
	s_mov_b64 s[2:3], -1
	s_and_b64 vcc, exec, s[10:11]
	v_ashrrev_i32_e32 v49, 31, v48
	s_cbranch_vccnz .LBB0_237
	v_lshl_add_u64 v[50:51], v[48:49], 2, s[96:97]
	global_load_dword v52, v[50:51], off
	s_mov_b64 s[2:3], 0
	s_waitcnt vmcnt(0) lgkmcnt(0)
	v_add_f32_e32 v54, 0, v52
	v_add_co_u32_e32 v52, vcc, 0x10000, v50
	s_nop 1
	v_addc_co_u32_e32 v53, vcc, 0, v51, vcc
	global_load_dword v52, v[52:53], off
	s_waitcnt vmcnt(0) lgkmcnt(0)
	v_add_f32_e32 v54, v54, v52
	v_add_co_u32_e32 v52, vcc, 0x20000, v50
	s_nop 1
	v_addc_co_u32_e32 v53, vcc, 0, v51, vcc
	global_load_dword v52, v[52:53], off
	s_waitcnt vmcnt(0) lgkmcnt(0)
	v_add_f32_e32 v54, v54, v52
	v_add_co_u32_e32 v52, vcc, 0x30000, v50
	s_nop 1
	v_addc_co_u32_e32 v53, vcc, 0, v51, vcc
	global_load_dword v52, v[52:53], off
	s_waitcnt vmcnt(0) lgkmcnt(0)
	v_add_f32_e32 v54, v54, v52
	v_add_co_u32_e32 v52, vcc, 0x40000, v50
	s_nop 1
	v_addc_co_u32_e32 v53, vcc, 0, v51, vcc
	global_load_dword v52, v[52:53], off
	s_waitcnt vmcnt(0) lgkmcnt(0)
	v_add_f32_e32 v54, v54, v52
	v_add_co_u32_e32 v52, vcc, 0x50000, v50
	s_nop 1
	v_addc_co_u32_e32 v53, vcc, 0, v51, vcc
	global_load_dword v52, v[52:53], off
	s_waitcnt vmcnt(0) lgkmcnt(0)
	v_add_f32_e32 v54, v54, v52
	v_add_co_u32_e32 v52, vcc, 0x60000, v50
	s_nop 1
	v_addc_co_u32_e32 v53, vcc, 0, v51, vcc
	global_load_dword v52, v[52:53], off
	s_waitcnt vmcnt(0) lgkmcnt(0)
	v_add_f32_e32 v54, v54, v52
	v_add_co_u32_e32 v52, vcc, 0x70000, v50
	s_nop 1
	v_addc_co_u32_e32 v53, vcc, 0, v51, vcc
	global_load_dword v52, v[52:53], off
	s_waitcnt vmcnt(0) lgkmcnt(0)
	v_add_f32_e32 v54, v54, v52
	v_add_co_u32_e32 v52, vcc, 0x80000, v50
	s_nop 1
	v_addc_co_u32_e32 v53, vcc, 0, v51, vcc
	global_load_dword v52, v[52:53], off
	s_waitcnt vmcnt(0) lgkmcnt(0)
	v_add_f32_e32 v54, v54, v52
	v_add_co_u32_e32 v52, vcc, 0x90000, v50
	s_nop 1
	v_addc_co_u32_e32 v53, vcc, 0, v51, vcc
	global_load_dword v52, v[52:53], off
	s_waitcnt vmcnt(0) lgkmcnt(0)
	v_add_f32_e32 v54, v54, v52
	v_add_co_u32_e32 v52, vcc, 0xa0000, v50
	s_nop 1
	v_addc_co_u32_e32 v53, vcc, 0, v51, vcc
	global_load_dword v52, v[52:53], off
	s_waitcnt vmcnt(0) lgkmcnt(0)
	v_add_f32_e32 v54, v54, v52
	v_add_co_u32_e32 v52, vcc, 0xb0000, v50
	s_nop 1
	v_addc_co_u32_e32 v53, vcc, 0, v51, vcc
	global_load_dword v52, v[52:53], off
	s_waitcnt vmcnt(0) lgkmcnt(0)
	v_add_f32_e32 v54, v54, v52
	v_add_co_u32_e32 v52, vcc, 0xc0000, v50
	s_nop 1
	v_addc_co_u32_e32 v53, vcc, 0, v51, vcc
	global_load_dword v52, v[52:53], off
	s_waitcnt vmcnt(0) lgkmcnt(0)
	v_add_f32_e32 v54, v54, v52
	v_add_co_u32_e32 v52, vcc, 0xd0000, v50
	s_nop 1
	v_addc_co_u32_e32 v53, vcc, 0, v51, vcc
	global_load_dword v52, v[52:53], off
	s_waitcnt vmcnt(0) lgkmcnt(0)
	v_add_f32_e32 v54, v54, v52
	v_add_co_u32_e32 v52, vcc, 0xe0000, v50
	s_nop 1
	v_addc_co_u32_e32 v53, vcc, 0, v51, vcc
	v_add_co_u32_e32 v50, vcc, 0xf0000, v50
	global_load_dword v52, v[52:53], off
	s_nop 0
	v_addc_co_u32_e32 v51, vcc, 0, v51, vcc
	global_load_dword v50, v[50:51], off
	s_waitcnt vmcnt(0) lgkmcnt(0)
	v_add_f32_e32 v52, v54, v52
	v_add_f32_e32 v50, v52, v50
	v_fmamk_f32 v50, v50, 0x3a800000, v227
	v_rsq_f32_e32 v50, v50

.LBB0_239:
	s_waitcnt lgkmcnt(0)
	v_pk_mul_f32 v[44:45], v[44:45], v[50:51] op_sel_hi:[1,0]
	v_pk_mul_f32 v[46:47], v[46:47], v[50:51] op_sel_hi:[1,0]
	v_pk_mul_f32 v[52:53], v[44:45], v[44:45]
	v_pk_mul_f32 v[54:55], v[46:47], v[46:47]
	v_add_f32_e32 v52, v52, v53
	v_pk_mul_f32 v[40:41], v[40:41], v[50:51] op_sel_hi:[1,0]
	v_add_f32_e32 v52, v54, v52
	v_pk_mul_f32 v[56:57], v[40:41], v[40:41]
	v_add_f32_e32 v52, v55, v52
	v_pk_mul_f32 v[42:43], v[42:43], v[50:51] op_sel_hi:[1,0]
	v_add_f32_e32 v52, v56, v52
	v_pk_mul_f32 v[58:59], v[42:43], v[42:43]
	v_add_f32_e32 v52, v57, v52
	v_pk_mul_f32 v[36:37], v[36:37], v[50:51] op_sel_hi:[1,0]
	v_add_f32_e32 v52, v58, v52
	v_pk_mul_f32 v[60:61], v[36:37], v[36:37]
	v_add_f32_e32 v52, v59, v52
	v_pk_mul_f32 v[38:39], v[38:39], v[50:51] op_sel_hi:[1,0]
	v_add_f32_e32 v52, v60, v52
	v_pk_mul_f32 v[62:63], v[38:39], v[38:39]
	v_add_f32_e32 v52, v61, v52
	v_pk_mul_f32 v[32:33], v[32:33], v[50:51] op_sel_hi:[1,0]
	v_add_f32_e32 v52, v62, v52
	v_pk_mul_f32 v[64:65], v[32:33], v[32:33]
	v_add_f32_e32 v52, v63, v52
	v_pk_mul_f32 v[34:35], v[34:35], v[50:51] op_sel_hi:[1,0]
	v_add_f32_e32 v52, v64, v52
	v_pk_mul_f32 v[50:51], v[34:35], v[34:35]
	v_add_f32_e32 v52, v65, v52
	v_add_f32_e32 v50, v50, v52
	v_add_f32_e32 v50, v51, v50
	s_and_b64 vcc, exec, s[14:15]
	s_mov_b64 s[2:3], -1
	s_cbranch_vccnz .LBB0_263
	s_and_b64 vcc, exec, s[12:13]
	s_cbranch_vccnz .LBB0_260
	s_andn2_b64 vcc, exec, s[82:83]
	s_cbranch_vccnz .LBB0_257
	s_andn2_b64 vcc, exec, s[78:79]
	s_cbranch_vccnz .LBB0_252
	s_andn2_b64 vcc, exec, s[92:93]
	s_cbranch_vccnz .LBB0_247
	s_andn2_b64 vcc, exec, s[94:95]
	s_cbranch_vccnz .LBB0_246
	v_lshlrev_b64 v[52:53], 8, v[48:49]
	v_lshl_add_u64 v[52:53], v[156:157], 0, v[52:53]
	s_waitcnt vmcnt(0)
	global_store_dwordx4 v[52:53], v[44:47], off
	global_store_dwordx4 v[52:53], v[40:43], off offset:16
	global_store_dwordx4 v[52:53], v[36:39], off offset:128
	global_store_dwordx4 v[52:53], v[32:35], off offset:144

.LBB0_247:
	s_andn2_b64 vcc, exec, s[2:3]
	s_cbranch_vccnz .LBB0_251
	ds_swizzle_b32 v51, v50 offset:swizzle(SWAP,16)
	v_lshlrev_b64 v[52:53], 8, v[48:49]
	v_lshl_add_u64 v[56:57], v[158:159], 0, v[52:53]
	v_cvt_pk_bf16_f32 v52, v44, v45
	v_cvt_pk_bf16_f32 v53, v46, v47
	v_cvt_pk_bf16_f32 v54, v40, v41
	v_cvt_pk_bf16_f32 v55, v42, v43
	global_store_dwordx4 v[56:57], v[52:55], off
	s_waitcnt lgkmcnt(0)
	v_add_f32_e32 v51, v50, v51
	v_cvt_pk_bf16_f32 v52, v36, v37
	v_cvt_pk_bf16_f32 v53, v38, v39
	v_cvt_pk_bf16_f32 v54, v32, v33
	v_cvt_pk_bf16_f32 v55, v34, v35
	global_store_dwordx4 v[56:57], v[52:55], off offset:64
	s_nop 1
	v_mov_b32_e32 v52, v51
	s_nop 1
	v_permlane32_swap_b32_e32 v51, v52
	s_and_saveexec_b64 s[2:3], s[4:5]
	s_cbranch_execz .LBB0_250
	v_lshl_add_u64 v[54:55], v[48:49], 2, s[98:99]
	v_add_f32_e32 v51, v51, v52
	global_store_dword v[54:55], v51, off

.LBB0_252:
	s_andn2_b64 vcc, exec, s[2:3]
	s_cbranch_vccnz .LBB0_256
	ds_swizzle_b32 v51, v50 offset:swizzle(SWAP,16)
	v_lshlrev_b64 v[52:53], 9, v[48:49]
	v_lshl_add_u64 v[56:57], v[160:161], 0, v[52:53]
	v_cvt_pk_bf16_f32 v52, v44, v45
	v_cvt_pk_bf16_f32 v53, v46, v47
	v_cvt_pk_bf16_f32 v54, v40, v41
	v_cvt_pk_bf16_f32 v55, v42, v43
	global_store_dwordx4 v[56:57], v[52:55], off
	s_waitcnt lgkmcnt(0)
	v_add_f32_e32 v51, v50, v51
	v_cvt_pk_bf16_f32 v52, v36, v37
	v_cvt_pk_bf16_f32 v53, v38, v39
	v_cvt_pk_bf16_f32 v54, v32, v33
	v_cvt_pk_bf16_f32 v55, v34, v35
	global_store_dwordx4 v[56:57], v[52:55], off offset:64
	s_nop 1
	v_mov_b32_e32 v52, v51
	s_nop 1
	v_permlane32_swap_b32_e32 v51, v52
	s_and_saveexec_b64 s[2:3], s[4:5]
	s_cbranch_execz .LBB0_255
	v_lshl_add_u64 v[54:55], v[48:49], 2, s[68:69]
	v_add_f32_e32 v51, v51, v52
	global_store_dword v[54:55], v51, off

.LBB0_257:
	s_andn2_b64 vcc, exec, s[2:3]
	s_cbranch_vccnz .LBB0_259
	v_lshlrev_b64 v[52:53], 11, v[48:49]
	v_lshl_add_u64 v[52:53], s[16:17], 0, v[52:53]
	v_lshl_add_u64 v[52:53], s[22:23], 1, v[52:53]
	s_lshl_b32 s2, s65, 1
	s_mov_b32 s3, s23
	v_lshl_add_u64 v[52:53], v[52:53], 0, s[2:3]
	v_lshl_add_u64 v[56:57], v[52:53], 0, v[184:185]
	v_mul_f32_e32 v52, 0xbfb8aa3b, v45
	v_mul_f32_e32 v53, 0xbfb8aa3b, v46
	v_mul_f32_e32 v54, 0xbfb8aa3b, v47
	v_mul_f32_e32 v55, 0xbfb8aa3b, v40
	v_mul_f32_e32 v51, 0xbfb8aa3b, v44
	v_exp_f32_e32 v52, v52
	v_exp_f32_e32 v53, v53
	v_exp_f32_e32 v54, v54
	v_exp_f32_e32 v55, v55
	v_mul_f32_e32 v58, 0xbfb8aa3b, v41
	v_mul_f32_e32 v59, 0xbfb8aa3b, v42
	v_mul_f32_e32 v60, 0xbfb8aa3b, v43
	v_exp_f32_e32 v51, v51
	v_exp_f32_e32 v58, v58
	v_exp_f32_e32 v59, v59
	v_exp_f32_e32 v60, v60
	v_add_f32_e32 v52, 1.0, v52
	v_add_f32_e32 v53, 1.0, v53
	v_add_f32_e32 v54, 1.0, v54
	v_add_f32_e32 v55, 1.0, v55
	v_add_f32_e32 v51, 1.0, v51
	v_rcp_f32_e32 v52, v52
	v_rcp_f32_e32 v53, v53
	v_rcp_f32_e32 v54, v54
	v_rcp_f32_e32 v55, v55
	v_add_f32_e32 v58, 1.0, v58
	v_add_f32_e32 v59, 1.0, v59
	v_add_f32_e32 v60, 1.0, v60
	v_rcp_f32_e32 v51, v51
	v_rcp_f32_e32 v58, v58
	v_rcp_f32_e32 v59, v59
	v_rcp_f32_e32 v60, v60
	v_mul_f32_e32 v52, v45, v52
	v_mul_f32_e32 v53, v46, v53
	v_mul_f32_e32 v54, v47, v54
	v_mul_f32_e32 v55, v40, v55
	v_mul_f32_e32 v51, v44, v51
	v_mul_f32_e32 v58, v41, v58
	v_mul_f32_e32 v59, v42, v59
	v_mul_f32_e32 v60, v43, v60
	v_cvt_pk_bf16_f32 v52, v51, v52
	v_cvt_pk_bf16_f32 v53, v53, v54
	v_cvt_pk_bf16_f32 v54, v55, v58
	v_cvt_pk_bf16_f32 v55, v59, v60
	global_store_dwordx4 v[56:57], v[52:55], off
	v_mul_f32_e32 v51, 0xbfb8aa3b, v36
	v_mul_f32_e32 v58, 0xbfb8aa3b, v33
	v_mul_f32_e32 v52, 0xbfb8aa3b, v37
	v_mul_f32_e32 v53, 0xbfb8aa3b, v38
	v_mul_f32_e32 v54, 0xbfb8aa3b, v39
	v_mul_f32_e32 v55, 0xbfb8aa3b, v32
	v_exp_f32_e32 v52, v52
	v_exp_f32_e32 v53, v53
	v_exp_f32_e32 v54, v54
	v_exp_f32_e32 v55, v55
	v_mul_f32_e32 v59, 0xbfb8aa3b, v34
	v_mul_f32_e32 v60, 0xbfb8aa3b, v35
	v_exp_f32_e32 v51, v51
	v_exp_f32_e32 v58, v58
	v_exp_f32_e32 v59, v59
	v_exp_f32_e32 v60, v60
	v_add_f32_e32 v52, 1.0, v52
	v_add_f32_e32 v53, 1.0, v53
	v_add_f32_e32 v54, 1.0, v54
	v_add_f32_e32 v55, 1.0, v55
	v_add_f32_e32 v51, 1.0, v51
	v_rcp_f32_e32 v52, v52
	v_rcp_f32_e32 v53, v53
	v_rcp_f32_e32 v54, v54
	v_rcp_f32_e32 v55, v55
	v_add_f32_e32 v58, 1.0, v58
	v_add_f32_e32 v59, 1.0, v59
	v_add_f32_e32 v60, 1.0, v60
	v_rcp_f32_e32 v51, v51
	v_rcp_f32_e32 v58, v58
	v_rcp_f32_e32 v59, v59
	v_rcp_f32_e32 v60, v60
	v_mul_f32_e32 v52, v37, v52
	v_mul_f32_e32 v53, v38, v53
	v_mul_f32_e32 v54, v39, v54
	v_mul_f32_e32 v55, v32, v55
	v_mul_f32_e32 v51, v36, v51
	v_mul_f32_e32 v58, v33, v58
	v_mul_f32_e32 v59, v34, v59
	v_mul_f32_e32 v60, v35, v60
	v_cvt_pk_bf16_f32 v52, v51, v52
	v_cvt_pk_bf16_f32 v53, v53, v54
	v_cvt_pk_bf16_f32 v54, v55, v58
	v_cvt_pk_bf16_f32 v55, v59, v60
	global_store_dwordx4 v[56:57], v[52:55], off offset:64

.LBB0_260:
	s_andn2_b64 vcc, exec, s[2:3]
	s_cbranch_vccnz .LBB0_262
	v_lshlrev_b64 v[52:53], 10, v[48:49]
	v_lshl_add_u64 v[52:53], s[18:19], 0, v[52:53]
	s_lshl_b32 s2, s71, 1
	s_mov_b32 s3, s23
	v_lshl_add_u64 v[52:53], v[52:53], 0, s[2:3]
	s_lshl_b32 s2, s65, 1
	v_lshl_add_u64 v[52:53], v[52:53], 0, s[2:3]
	v_lshl_add_u64 v[56:57], v[52:53], 0, v[184:185]
	v_cvt_pk_bf16_f32 v52, v44, v45
	v_cvt_pk_bf16_f32 v53, v46, v47
	v_cvt_pk_bf16_f32 v54, v40, v41
	v_cvt_pk_bf16_f32 v55, v42, v43
	global_store_dwordx4 v[56:57], v[52:55], off
	s_nop 1
	v_cvt_pk_bf16_f32 v52, v36, v37
	v_cvt_pk_bf16_f32 v53, v38, v39
	v_cvt_pk_bf16_f32 v54, v32, v33
	v_cvt_pk_bf16_f32 v55, v34, v35
	global_store_dwordx4 v[56:57], v[52:55], off offset:64

; DEV float red4(float s) { s += SWZ_XOR(s, 16); return swapsum(s); }
;   DEV void operator()(f32x4 (&acc)[2][2][4][2], const PgUnit& u, int ui, int wr, int wc, int fr, int fq) const {
;     ...
;         const int t = u.pm * 256 + ai * 128 + wr * 64 + m * 16 + fr;
;         float rstd;
;         if (ui < 8) rstd = rl[ui * 256 + ai * 128 + wr * 64 + m * 16 + fr];
;         else { float ss = 0.f;
; #pragma unroll
;           for (int j = 0; j < 16; ++j) ss += WS{P.ws}.ssq_x()[((long)batch * 16 + j) * TB + t];
;           rstd = __builtin_amdgcn_rsqf(ss * (1.f / 1024.f) + EPS); }
;         float v[2][8];
;         float s = 0.f;
; #pragma unroll
;         for (int bj = 0; bj < 2; ++bj)
; #pragma unroll
;           for (int n = 0; n < 2; ++n)
; #pragma unroll
;             for (int r = 0; r < 4; ++r) { const float x = acc[ai][bj][m][n][r] * rstd; v[bj][n * 4 + r] = x; s += x * x; }
;         if (nt < 4) {
;           s = red4(s);
;           const float inv = __builtin_amdgcn_rsqf(s * (1.f / 64.f) + EPS) * (nt < 2 ? 0.125f * LOG2E : 1.f);
;           u16* dst = (nt < 2 ? WS{P.ws}.QA() : WS{P.ws}.KA()) + (long)t * 512 + (nt & 1) * 256 + wc * 64;
; #pragma unroll
;           for (int bj = 0; bj < 2; ++bj) {
;             const int c8 = bj * 32 + 8 * fq;
;             const float4 g0 = gg[bj][0], g1 = gg[bj][1];
;             float y[8] = {v[bj][0] * inv * g0.x, v[bj][1] * inv * g0.y, v[bj][2] * inv * g0.z, v[bj][3] * inv * g0.w, v[bj][4] * inv * g1.x, v[bj][5] * inv * g1.y, v[bj][6] * inv * g1.z, v[bj][7] * inv * g1.w};
;             store8bf(dst + c8, y);
;           }
.LBB0_263:
	s_andn2_b64 vcc, exec, s[2:3]
	s_cbranch_vccnz .LBB0_265
	ds_swizzle_b32 v51, v50 offset:swizzle(SWAP,16)
	s_and_b64 s[2:3], s[8:9], exec
	s_cselect_b32 s2, s59, 0x5000000
	s_add_u32 s2, s86, s2
	s_addc_u32 s3, s87, 0
	s_waitcnt lgkmcnt(0)
	v_add_f32_e32 v50, v50, v51
	v_mov_b32_e32 v51, v50
	s_nop 1
	v_permlane32_swap_b32_e32 v50, v51
	v_add_f32_e32 v50, v50, v51
	v_fmamk_f32 v50, v50, 0x3c800000, v227
	v_rsq_f32_e32 v50, v50
	v_lshlrev_b64 v[48:49], 10, v[48:49]
	v_lshl_add_u64 v[48:49], s[2:3], 0, v[48:49]
	s_lshl_b32 s2, s71, 1
	v_mul_f32_e32 v50, v168, v50
	v_mul_f32_e32 v44, v44, v50
	v_mul_f32_e32 v40, v40, v50
	s_mov_b32 s3, s23
	v_mul_f32_e32 v51, v28, v44
	v_mul_f32_e32 v44, v45, v50
	v_mul_f32_e32 v53, v24, v40
	v_mul_f32_e32 v40, v41, v50
	v_lshl_add_u64 v[48:49], v[48:49], 0, s[2:3]
	s_lshl_b32 s2, s65, 1
	v_mul_f32_e32 v52, v29, v44
	v_mul_f32_e32 v44, v46, v50
	v_mul_f32_e32 v54, v25, v40
	v_mul_f32_e32 v40, v42, v50
	v_lshl_add_u64 v[48:49], v[48:49], 0, s[2:3]
	v_mul_f32_e32 v46, v30, v44
	v_mul_f32_e32 v44, v47, v50
	v_mul_f32_e32 v55, v26, v40
	v_mul_f32_e32 v40, v43, v50
	v_mul_f32_e32 v47, v31, v44
	v_mul_f32_e32 v43, v27, v40
	v_lshl_add_u64 v[44:45], v[48:49], 0, v[184:185]
	v_cvt_pk_bf16_f32 v40, v51, v52
	v_mul_f32_e32 v32, v32, v50
	v_cvt_pk_bf16_f32 v41, v46, v47
	v_cvt_pk_bf16_f32 v42, v53, v54
	v_cvt_pk_bf16_f32 v43, v55, v43
	global_store_dwordx4 v[44:45], v[40:43], off
	v_mul_f32_e32 v36, v36, v50
	v_mul_f32_e32 v37, v37, v50
	v_mul_f32_e32 v40, v16, v32
	v_mul_f32_e32 v32, v33, v50
	v_mul_f32_e32 v41, v17, v32
	v_mul_f32_e32 v32, v34, v50
	v_mul_f32_e32 v42, v18, v32
	v_mul_f32_e32 v32, v35, v50
	v_mul_f32_e32 v38, v38, v50
	v_mul_f32_e32 v39, v39, v50
	v_mul_f32_e32 v35, v19, v32
	v_mul_f32_e32 v36, v20, v36
	v_mul_f32_e32 v37, v21, v37
	v_mul_f32_e32 v38, v22, v38
	v_mul_f32_e32 v39, v23, v39
	v_cvt_pk_bf16_f32 v32, v36, v37
	v_cvt_pk_bf16_f32 v33, v38, v39
	v_cvt_pk_bf16_f32 v34, v40, v41
	v_cvt_pk_bf16_f32 v35, v42, v35
	global_store_dwordx4 v[44:45], v[32:35], off offset:64
.LBB0_265:
	s_nop 1
	v_add_u32_e32 v32, 0xb0, v166
	s_mov_b64 s[2:3], -1
	s_and_b64 vcc, exec, s[10:11]
	v_ashrrev_i32_e32 v33, 31, v32
	s_cbranch_vccnz .LBB0_267
	v_lshl_add_u64 v[34:35], v[32:33], 2, s[96:97]
	global_load_dword v36, v[34:35], off
	s_mov_b64 s[2:3], 0
	s_waitcnt vmcnt(0) lgkmcnt(0)
	v_add_f32_e32 v38, 0, v36
	v_add_co_u32_e32 v36, vcc, 0x10000, v34
	s_nop 1
	v_addc_co_u32_e32 v37, vcc, 0, v35, vcc
	global_load_dword v36, v[36:37], off
	s_waitcnt vmcnt(0) lgkmcnt(0)
	v_add_f32_e32 v38, v38, v36
	v_add_co_u32_e32 v36, vcc, 0x20000, v34
	s_nop 1
	v_addc_co_u32_e32 v37, vcc, 0, v35, vcc
	global_load_dword v36, v[36:37], off
	s_waitcnt vmcnt(0) lgkmcnt(0)
	v_add_f32_e32 v38, v38, v36
	v_add_co_u32_e32 v36, vcc, 0x30000, v34
	s_nop 1
	v_addc_co_u32_e32 v37, vcc, 0, v35, vcc
	global_load_dword v36, v[36:37], off
	s_waitcnt vmcnt(0) lgkmcnt(0)
	v_add_f32_e32 v38, v38, v36
	v_add_co_u32_e32 v36, vcc, 0x40000, v34
	s_nop 1
	v_addc_co_u32_e32 v37, vcc, 0, v35, vcc
	global_load_dword v36, v[36:37], off
	s_waitcnt vmcnt(0) lgkmcnt(0)
	v_add_f32_e32 v38, v38, v36
	v_add_co_u32_e32 v36, vcc, 0x50000, v34
	s_nop 1
	v_addc_co_u32_e32 v37, vcc, 0, v35, vcc
	global_load_dword v36, v[36:37], off
	s_waitcnt vmcnt(0) lgkmcnt(0)
	v_add_f32_e32 v38, v38, v36
	v_add_co_u32_e32 v36, vcc, 0x60000, v34
	s_nop 1
	v_addc_co_u32_e32 v37, vcc, 0, v35, vcc
	global_load_dword v36, v[36:37], off
	s_waitcnt vmcnt(0) lgkmcnt(0)
	v_add_f32_e32 v38, v38, v36
	v_add_co_u32_e32 v36, vcc, 0x70000, v34
	s_nop 1
	v_addc_co_u32_e32 v37, vcc, 0, v35, vcc
	global_load_dword v36, v[36:37], off
	s_waitcnt vmcnt(0) lgkmcnt(0)
	v_add_f32_e32 v38, v38, v36
	v_add_co_u32_e32 v36, vcc, 0x80000, v34
	s_nop 1
	v_addc_co_u32_e32 v37, vcc, 0, v35, vcc
	global_load_dword v36, v[36:37], off
	s_waitcnt vmcnt(0) lgkmcnt(0)
	v_add_f32_e32 v38, v38, v36
	v_add_co_u32_e32 v36, vcc, 0x90000, v34
	s_nop 1
	v_addc_co_u32_e32 v37, vcc, 0, v35, vcc
	global_load_dword v36, v[36:37], off
	s_waitcnt vmcnt(0) lgkmcnt(0)
	v_add_f32_e32 v38, v38, v36
	v_add_co_u32_e32 v36, vcc, 0xa0000, v34
	s_nop 1
	v_addc_co_u32_e32 v37, vcc, 0, v35, vcc
	global_load_dword v36, v[36:37], off
	s_waitcnt vmcnt(0) lgkmcnt(0)
	v_add_f32_e32 v38, v38, v36
	v_add_co_u32_e32 v36, vcc, 0xb0000, v34
	s_nop 1
	v_addc_co_u32_e32 v37, vcc, 0, v35, vcc
	global_load_dword v36, v[36:37], off
	s_waitcnt vmcnt(0) lgkmcnt(0)
	v_add_f32_e32 v38, v38, v36
	v_add_co_u32_e32 v36, vcc, 0xc0000, v34
	s_nop 1
	v_addc_co_u32_e32 v37, vcc, 0, v35, vcc
	global_load_dword v36, v[36:37], off
	s_waitcnt vmcnt(0) lgkmcnt(0)
	v_add_f32_e32 v38, v38, v36
	v_add_co_u32_e32 v36, vcc, 0xd0000, v34
	s_nop 1
	v_addc_co_u32_e32 v37, vcc, 0, v35, vcc
	global_load_dword v36, v[36:37], off
	s_waitcnt vmcnt(0) lgkmcnt(0)
	v_add_f32_e32 v38, v38, v36
	v_add_co_u32_e32 v36, vcc, 0xe0000, v34
	s_nop 1
	v_addc_co_u32_e32 v37, vcc, 0, v35, vcc
	v_add_co_u32_e32 v34, vcc, 0xf0000, v34
	global_load_dword v36, v[36:37], off
	s_nop 0
	v_addc_co_u32_e32 v35, vcc, 0, v35, vcc
	global_load_dword v34, v[34:35], off
	s_waitcnt vmcnt(0) lgkmcnt(0)
	v_add_f32_e32 v36, v38, v36
	v_add_f32_e32 v34, v36, v34
	v_fmamk_f32 v34, v34, 0x3a800000, v227
	v_rsq_f32_e32 v34, v34

;   DEV void operator()(f32x4 (&acc)[2][2][4][2], const PgUnit& u, int ui, int wr, int wc, int fr, int fq) const {
;     ...
;         for (int bj = 0; bj < 2; ++bj)
; #pragma unroll
;           for (int n = 0; n < 2; ++n)
; #pragma unroll
;             for (int r = 0; r < 4; ++r) { const float x = acc[ai][bj][m][n][r] * rstd; v[bj][n * 4 + r] = x; s += x * x; }
;     ...
;         } else if (wc == 2) {
;           float* dst = WS{P.ws}.KR() + (long)t * 64;
; #pragma unroll
;           for (int bj = 0; bj < 2; ++bj) {
;             *reinterpret_cast<float4*>(dst + bj * 32 + 8 * fq) = make_float4(v[bj][0], v[bj][1], v[bj][2], v[bj][3]);
;             *reinterpret_cast<float4*>(dst + bj * 32 + 8 * fq + 4) = make_float4(v[bj][4], v[bj][5], v[bj][6], v[bj][7]);
;           }
.LBB0_269:
	s_waitcnt lgkmcnt(0)
	v_pk_mul_f32 v[12:13], v[12:13], v[34:35] op_sel_hi:[1,0]
	v_pk_mul_f32 v[14:15], v[14:15], v[34:35] op_sel_hi:[1,0]
	v_pk_mul_f32 v[36:37], v[12:13], v[12:13]
	v_pk_mul_f32 v[38:39], v[14:15], v[14:15]
	v_add_f32_e32 v36, v36, v37
	v_pk_mul_f32 v[8:9], v[8:9], v[34:35] op_sel_hi:[1,0]
	v_add_f32_e32 v36, v38, v36
	v_pk_mul_f32 v[40:41], v[8:9], v[8:9]
	v_add_f32_e32 v36, v39, v36
	v_pk_mul_f32 v[10:11], v[10:11], v[34:35] op_sel_hi:[1,0]
	v_add_f32_e32 v36, v40, v36
	v_pk_mul_f32 v[42:43], v[10:11], v[10:11]
	v_add_f32_e32 v36, v41, v36
	v_pk_mul_f32 v[4:5], v[4:5], v[34:35] op_sel_hi:[1,0]
	v_add_f32_e32 v36, v42, v36
	v_pk_mul_f32 v[44:45], v[4:5], v[4:5]
	v_add_f32_e32 v36, v43, v36
	v_pk_mul_f32 v[6:7], v[6:7], v[34:35] op_sel_hi:[1,0]
	v_add_f32_e32 v36, v44, v36
	v_pk_mul_f32 v[46:47], v[6:7], v[6:7]
	v_add_f32_e32 v36, v45, v36
	v_pk_mul_f32 v[0:1], v[0:1], v[34:35] op_sel_hi:[1,0]
	v_add_f32_e32 v36, v46, v36
	v_pk_mul_f32 v[48:49], v[0:1], v[0:1]
	v_add_f32_e32 v36, v47, v36
	v_pk_mul_f32 v[2:3], v[2:3], v[34:35] op_sel_hi:[1,0]
	v_add_f32_e32 v36, v48, v36
	v_pk_mul_f32 v[34:35], v[2:3], v[2:3]
	v_add_f32_e32 v36, v49, v36
	v_add_f32_e32 v34, v34, v36
	v_add_f32_e32 v34, v35, v34
	s_and_b64 vcc, exec, s[14:15]
	s_mov_b64 s[2:3], -1
	s_cbranch_vccnz .LBB0_293
	s_and_b64 vcc, exec, s[12:13]
	s_cbranch_vccnz .LBB0_290
	s_andn2_b64 vcc, exec, s[82:83]
	s_cbranch_vccnz .LBB0_287
	s_andn2_b64 vcc, exec, s[78:79]
	s_cbranch_vccnz .LBB0_282
	s_andn2_b64 vcc, exec, s[92:93]
	s_cbranch_vccnz .LBB0_277
	s_andn2_b64 vcc, exec, s[94:95]
	s_cbranch_vccnz .LBB0_276
	v_lshlrev_b64 v[36:37], 8, v[32:33]
	v_lshl_add_u64 v[36:37], v[156:157], 0, v[36:37]
	s_waitcnt vmcnt(0)
	global_store_dwordx4 v[36:37], v[12:15], off
	global_store_dwordx4 v[36:37], v[8:11], off offset:16
	global_store_dwordx4 v[36:37], v[4:7], off offset:128
	global_store_dwordx4 v[36:37], v[0:3], off offset:144

;   DEV float* ssq_ckv() const { return (float*)(b + O_SSQCKV); }
; DEV float red4(float s) { s += SWZ_XOR(s, 16); return swapsum(s); }
;   DEV void operator()(f32x4 (&acc)[2][2][4][2], const PgUnit& u, int ui, int wr, int wc, int fr, int fq) const {
;     ...
;         } else if (wc < 2) {
;           u16* dst = WS{P.ws}.CKV() + (long)t * 128 + wc * 64;
; #pragma unroll
;           for (int bj = 0; bj < 2; ++bj) store8bf(dst + bj * 32 + 8 * fq, v[bj]);
;           s = red4(s);
;           if (fq == 0) WS{P.ws}.ssq_ckv()[(long)wc * TB + t] = s;
.LBB0_277:
	s_andn2_b64 vcc, exec, s[2:3]
	s_cbranch_vccnz .LBB0_281
	ds_swizzle_b32 v35, v34 offset:swizzle(SWAP,16)
	v_lshlrev_b64 v[36:37], 8, v[32:33]
	v_lshl_add_u64 v[40:41], v[158:159], 0, v[36:37]
	v_cvt_pk_bf16_f32 v36, v12, v13
	v_cvt_pk_bf16_f32 v37, v14, v15
	v_cvt_pk_bf16_f32 v38, v8, v9
	v_cvt_pk_bf16_f32 v39, v10, v11
	global_store_dwordx4 v[40:41], v[36:39], off
	s_waitcnt lgkmcnt(0)
	v_add_f32_e32 v35, v34, v35
	v_cvt_pk_bf16_f32 v36, v4, v5
	v_cvt_pk_bf16_f32 v37, v6, v7
	v_cvt_pk_bf16_f32 v38, v0, v1
	v_cvt_pk_bf16_f32 v39, v2, v3
	global_store_dwordx4 v[40:41], v[36:39], off offset:64
	s_nop 1
	v_mov_b32_e32 v36, v35
	s_nop 1
	v_permlane32_swap_b32_e32 v35, v36
	s_and_saveexec_b64 s[2:3], s[4:5]
	s_cbranch_execz .LBB0_280
	v_lshl_add_u64 v[38:39], v[32:33], 2, s[98:99]
	v_add_f32_e32 v35, v35, v36
	global_store_dword v[38:39], v35, off

; DEV float red4(float s) { s += SWZ_XOR(s, 16); return swapsum(s); }
;   DEV void operator()(f32x4 (&acc)[2][2][4][2], const PgUnit& u, int ui, int wr, int wc, int fr, int fq) const {
;     ...
;         } else if (nt == 8) {
;           u16* dst = WS{P.ws}.CQ() + (long)t * 256 + wc * 64;
; #pragma unroll
;           for (int bj = 0; bj < 2; ++bj) store8bf(dst + bj * 32 + 8 * fq, v[bj]);
;           s = red4(s);
;           if (fq == 0) WS{P.ws}.ssq_cq()[(long)wc * TB + t] = s;
.LBB0_282:
	s_andn2_b64 vcc, exec, s[2:3]
	s_cbranch_vccnz .LBB0_286
	ds_swizzle_b32 v35, v34 offset:swizzle(SWAP,16)
	v_lshlrev_b64 v[36:37], 9, v[32:33]
	v_lshl_add_u64 v[40:41], v[160:161], 0, v[36:37]
	v_cvt_pk_bf16_f32 v36, v12, v13
	v_cvt_pk_bf16_f32 v37, v14, v15
	v_cvt_pk_bf16_f32 v38, v8, v9
	v_cvt_pk_bf16_f32 v39, v10, v11
	global_store_dwordx4 v[40:41], v[36:39], off
	s_waitcnt lgkmcnt(0)
	v_add_f32_e32 v35, v34, v35
	v_cvt_pk_bf16_f32 v36, v4, v5
	v_cvt_pk_bf16_f32 v37, v6, v7
	v_cvt_pk_bf16_f32 v38, v0, v1
	v_cvt_pk_bf16_f32 v39, v2, v3
	global_store_dwordx4 v[40:41], v[36:39], off offset:64
	s_nop 1
	v_mov_b32_e32 v36, v35
	s_nop 1
	v_permlane32_swap_b32_e32 v35, v36
	s_and_saveexec_b64 s[2:3], s[4:5]
	s_cbranch_execz .LBB0_285
	v_lshl_add_u64 v[38:39], v[32:33], 2, s[68:69]
	v_add_f32_e32 v35, v35, v36
	global_store_dword v[38:39], v35, off

; DEV float siluf(float x) { return x * __builtin_amdgcn_rcpf(1.f + __builtin_amdgcn_exp2f(-LOG2E * x)); }
;   DEV void operator()(f32x4 (&acc)[2][2][4][2], const PgUnit& u, int ui, int wr, int wc, int fr, int fq) const {
;     ...
;         } else if (nt < 8 || nt >= 10) {
;           u16* dst = WS{P.ws}.G() + (long)t * 1024 + (nt >= 10 ? 512 + (nt - 10) * 256 : (nt - 6) * 256) + wc * 64;
; #pragma unroll
;           for (int bj = 0; bj < 2; ++bj) {
;             float y[8];
; #pragma unroll
;             for (int e = 0; e < 8; ++e) y[e] = siluf(v[bj][e]);
;             store8bf(dst + bj * 32 + 8 * fq, y);
;           }
.LBB0_287:
	s_andn2_b64 vcc, exec, s[2:3]
	s_cbranch_vccnz .LBB0_289
	v_lshlrev_b64 v[36:37], 11, v[32:33]
	v_lshl_add_u64 v[36:37], s[16:17], 0, v[36:37]
	v_lshl_add_u64 v[36:37], s[22:23], 1, v[36:37]
	s_lshl_b32 s22, s65, 1
	v_lshl_add_u64 v[36:37], v[36:37], 0, s[22:23]
	v_lshl_add_u64 v[40:41], v[36:37], 0, v[184:185]
	v_mul_f32_e32 v36, 0xbfb8aa3b, v13
	v_mul_f32_e32 v37, 0xbfb8aa3b, v14
	v_mul_f32_e32 v38, 0xbfb8aa3b, v15
	v_mul_f32_e32 v39, 0xbfb8aa3b, v8
	v_mul_f32_e32 v35, 0xbfb8aa3b, v12
	v_exp_f32_e32 v36, v36
	v_exp_f32_e32 v37, v37
	v_exp_f32_e32 v38, v38
	v_exp_f32_e32 v39, v39
	v_mul_f32_e32 v42, 0xbfb8aa3b, v9
	v_mul_f32_e32 v43, 0xbfb8aa3b, v10
	v_mul_f32_e32 v44, 0xbfb8aa3b, v11
	v_exp_f32_e32 v35, v35
	v_exp_f32_e32 v42, v42
	v_exp_f32_e32 v43, v43
	v_exp_f32_e32 v44, v44
	v_add_f32_e32 v36, 1.0, v36
	v_add_f32_e32 v37, 1.0, v37
	v_add_f32_e32 v38, 1.0, v38
	v_add_f32_e32 v39, 1.0, v39
	v_add_f32_e32 v35, 1.0, v35
	v_rcp_f32_e32 v36, v36
	v_rcp_f32_e32 v37, v37
	v_rcp_f32_e32 v38, v38
	v_rcp_f32_e32 v39, v39
	v_add_f32_e32 v42, 1.0, v42
	v_add_f32_e32 v43, 1.0, v43
	v_add_f32_e32 v44, 1.0, v44
	v_rcp_f32_e32 v35, v35
	v_rcp_f32_e32 v42, v42
	v_rcp_f32_e32 v43, v43
	v_rcp_f32_e32 v44, v44
	v_mul_f32_e32 v36, v13, v36
	v_mul_f32_e32 v37, v14, v37
	v_mul_f32_e32 v38, v15, v38
	v_mul_f32_e32 v39, v8, v39
	v_mul_f32_e32 v35, v12, v35
	v_mul_f32_e32 v42, v9, v42
	v_mul_f32_e32 v43, v10, v43
	v_mul_f32_e32 v44, v11, v44
	v_cvt_pk_bf16_f32 v36, v35, v36
	v_cvt_pk_bf16_f32 v37, v37, v38
	v_cvt_pk_bf16_f32 v38, v39, v42
	v_cvt_pk_bf16_f32 v39, v43, v44
	global_store_dwordx4 v[40:41], v[36:39], off
	v_mul_f32_e32 v35, 0xbfb8aa3b, v4
	v_mul_f32_e32 v42, 0xbfb8aa3b, v1
	v_mul_f32_e32 v36, 0xbfb8aa3b, v5
	v_mul_f32_e32 v37, 0xbfb8aa3b, v6
	v_mul_f32_e32 v38, 0xbfb8aa3b, v7
	v_mul_f32_e32 v39, 0xbfb8aa3b, v0
	v_exp_f32_e32 v36, v36
	v_exp_f32_e32 v37, v37
	v_exp_f32_e32 v38, v38
	v_exp_f32_e32 v39, v39
	v_mul_f32_e32 v43, 0xbfb8aa3b, v2
	v_mul_f32_e32 v44, 0xbfb8aa3b, v3
	v_exp_f32_e32 v35, v35
	v_exp_f32_e32 v42, v42
	v_exp_f32_e32 v43, v43
	v_exp_f32_e32 v44, v44
	v_add_f32_e32 v36, 1.0, v36
	v_add_f32_e32 v37, 1.0, v37
	v_add_f32_e32 v38, 1.0, v38
	v_add_f32_e32 v39, 1.0, v39
	v_add_f32_e32 v35, 1.0, v35
	v_rcp_f32_e32 v36, v36
	v_rcp_f32_e32 v37, v37
	v_rcp_f32_e32 v38, v38
	v_rcp_f32_e32 v39, v39
	v_add_f32_e32 v42, 1.0, v42
	v_add_f32_e32 v43, 1.0, v43
	v_add_f32_e32 v44, 1.0, v44
	v_rcp_f32_e32 v35, v35
	v_rcp_f32_e32 v42, v42
	v_rcp_f32_e32 v43, v43
	v_rcp_f32_e32 v44, v44
	v_mul_f32_e32 v36, v5, v36
	v_mul_f32_e32 v37, v6, v37
	v_mul_f32_e32 v38, v7, v38
	v_mul_f32_e32 v39, v0, v39
	v_mul_f32_e32 v35, v4, v35
	v_mul_f32_e32 v42, v1, v42
	v_mul_f32_e32 v43, v2, v43
	v_mul_f32_e32 v44, v3, v44
	v_cvt_pk_bf16_f32 v36, v35, v36
	v_cvt_pk_bf16_f32 v37, v37, v38
	v_cvt_pk_bf16_f32 v38, v39, v42
	v_cvt_pk_bf16_f32 v39, v43, v44
	global_store_dwordx4 v[40:41], v[36:39], off offset:64

;   DEV void operator()(f32x4 (&acc)[2][2][4][2], const PgUnit& u, int ui, int wr, int wc, int fr, int fq) const {
;     ...
;         } else if (nt < 6) {
;           u16* dst = WS{P.ws}.VA() + (long)t * 512 + (nt & 1) * 256 + wc * 64;
; #pragma unroll
;           for (int bj = 0; bj < 2; ++bj) store8bf(dst + bj * 32 + 8 * fq, v[bj]);
.LBB0_290:
	s_andn2_b64 vcc, exec, s[2:3]
	s_cbranch_vccnz .LBB0_292
	v_lshlrev_b64 v[36:37], 10, v[32:33]
	v_lshl_add_u64 v[36:37], s[18:19], 0, v[36:37]
	s_lshl_b32 s22, s71, 1
	v_lshl_add_u64 v[36:37], v[36:37], 0, s[22:23]
	s_lshl_b32 s22, s65, 1
	v_lshl_add_u64 v[36:37], v[36:37], 0, s[22:23]
	v_lshl_add_u64 v[40:41], v[36:37], 0, v[184:185]
	v_cvt_pk_bf16_f32 v36, v12, v13
	v_cvt_pk_bf16_f32 v37, v14, v15
	v_cvt_pk_bf16_f32 v38, v8, v9
	v_cvt_pk_bf16_f32 v39, v10, v11
	global_store_dwordx4 v[40:41], v[36:39], off
	s_nop 1
	v_cvt_pk_bf16_f32 v36, v4, v5
	v_cvt_pk_bf16_f32 v37, v6, v7
	v_cvt_pk_bf16_f32 v38, v0, v1
	v_cvt_pk_bf16_f32 v39, v2, v3
	global_store_dwordx4 v[40:41], v[36:39], off offset:64

; DEV float red4(float s) { s += SWZ_XOR(s, 16); return swapsum(s); }
;   DEV void operator()(f32x4 (&acc)[2][2][4][2], const PgUnit& u, int ui, int wr, int wc, int fr, int fq) const {
;     ...
;         if (nt < 4) {
;           s = red4(s);
;           const float inv = __builtin_amdgcn_rsqf(s * (1.f / 64.f) + EPS) * (nt < 2 ? 0.125f * LOG2E : 1.f);
;           u16* dst = (nt < 2 ? WS{P.ws}.QA() : WS{P.ws}.KA()) + (long)t * 512 + (nt & 1) * 256 + wc * 64;
; #pragma unroll
;           for (int bj = 0; bj < 2; ++bj) {
;             const int c8 = bj * 32 + 8 * fq;
;             const float4 g0 = gg[bj][0], g1 = gg[bj][1];
;             float y[8] = {v[bj][0] * inv * g0.x, v[bj][1] * inv * g0.y, v[bj][2] * inv * g0.z, v[bj][3] * inv * g0.w, v[bj][4] * inv * g1.x, v[bj][5] * inv * g1.y, v[bj][6] * inv * g1.z, v[bj][7] * inv * g1.w};
;             store8bf(dst + c8, y);
;           }
;     ...
;         } else if (wc == 2) {
;           float* dst = WS{P.ws}.KR() + (long)t * 64;
; #pragma unroll
;           for (int bj = 0; bj < 2; ++bj) {
;             *reinterpret_cast<float4*>(dst + bj * 32 + 8 * fq) = make_float4(v[bj][0], v[bj][1], v[bj][2], v[bj][3]);
;             *reinterpret_cast<float4*>(dst + bj * 32 + 8 * fq + 4) = make_float4(v[bj][4], v[bj][5], v[bj][6], v[bj][7]);
;           }
.LBB0_293:
	s_andn2_b64 vcc, exec, s[2:3]
	s_cbranch_vccnz .LBB0_98
	ds_swizzle_b32 v35, v34 offset:swizzle(SWAP,16)
	s_and_b64 s[2:3], s[8:9], exec
	s_cselect_b32 s2, s59, 0x5000000
	s_add_u32 s2, s86, s2
	s_addc_u32 s3, s87, 0
	s_waitcnt lgkmcnt(0)
	v_add_f32_e32 v34, v34, v35
	v_mov_b32_e32 v35, v34
	s_nop 1
	v_permlane32_swap_b32_e32 v34, v35
	v_add_f32_e32 v34, v34, v35
	v_fmamk_f32 v34, v34, 0x3c800000, v227
	v_rsq_f32_e32 v34, v34
	v_lshlrev_b64 v[32:33], 10, v[32:33]
	v_lshl_add_u64 v[32:33], s[2:3], 0, v[32:33]
	s_lshl_b32 s22, s71, 1
	v_mul_f32_e32 v34, v168, v34
	v_mul_f32_e32 v12, v12, v34
	v_mul_f32_e32 v8, v8, v34
	v_mul_f32_e32 v28, v28, v12
	v_mul_f32_e32 v12, v13, v34
	v_mul_f32_e32 v24, v24, v8
	v_mul_f32_e32 v8, v9, v34
	v_lshl_add_u64 v[32:33], v[32:33], 0, s[22:23]
	s_lshl_b32 s22, s65, 1
	v_mul_f32_e32 v29, v29, v12
	v_mul_f32_e32 v12, v14, v34
	v_mul_f32_e32 v25, v25, v8
	v_mul_f32_e32 v8, v10, v34
	v_lshl_add_u64 v[32:33], v[32:33], 0, s[22:23]
	v_mul_f32_e32 v14, v30, v12
	v_mul_f32_e32 v12, v15, v34
	v_mul_f32_e32 v26, v26, v8
	v_mul_f32_e32 v8, v11, v34
	v_mul_f32_e32 v15, v31, v12
	v_mul_f32_e32 v11, v27, v8
	v_lshl_add_u64 v[12:13], v[32:33], 0, v[184:185]
	v_cvt_pk_bf16_f32 v8, v28, v29
	v_mul_f32_e32 v0, v0, v34
	v_cvt_pk_bf16_f32 v9, v14, v15
	v_cvt_pk_bf16_f32 v10, v24, v25
	v_cvt_pk_bf16_f32 v11, v26, v11
	global_store_dwordx4 v[12:13], v[8:11], off
	v_mul_f32_e32 v4, v4, v34
	v_mul_f32_e32 v5, v5, v34
	v_mul_f32_e32 v8, v16, v0
	v_mul_f32_e32 v0, v1, v34
	v_mul_f32_e32 v9, v17, v0
	v_mul_f32_e32 v0, v2, v34
	v_mul_f32_e32 v10, v18, v0
	v_mul_f32_e32 v0, v3, v34
	v_mul_f32_e32 v6, v6, v34
	v_mul_f32_e32 v7, v7, v34
	v_mul_f32_e32 v3, v19, v0
	v_mul_f32_e32 v4, v20, v4
	v_mul_f32_e32 v5, v21, v5
	v_mul_f32_e32 v6, v22, v6
	v_mul_f32_e32 v7, v23, v7
	v_cvt_pk_bf16_f32 v0, v4, v5
	v_cvt_pk_bf16_f32 v1, v6, v7
	v_cvt_pk_bf16_f32 v2, v8, v9
	v_cvt_pk_bf16_f32 v3, v10, v3
	global_store_dwordx4 v[12:13], v[0:3], off offset:64
	s_branch .LBB0_98
.LBB0_295:
	s_and_b64 vcc, exec, s[12:13]
	s_mov_b64 s[2:3], -1
	s_cbranch_vccnz .LBB0_315
	s_andn2_b64 vcc, exec, s[82:83]
	s_cbranch_vccnz .LBB0_312
	s_andn2_b64 vcc, exec, s[78:79]
	s_cbranch_vccnz .LBB0_307
	s_andn2_b64 vcc, exec, s[92:93]
	s_cbranch_vccnz .LBB0_302
	s_andn2_b64 vcc, exec, s[94:95]
	s_cbranch_vccnz .LBB0_301
	v_ashrrev_i32_e32 v129, 31, v128
	v_lshlrev_b64 v[132:133], 8, v[128:129]
	v_lshl_add_u64 v[132:133], v[156:157], 0, v[132:133]
	s_waitcnt vmcnt(0)
	global_store_dwordx4 v[132:133], v[124:127], off
	global_store_dwordx4 v[132:133], v[120:123], off offset:16
	global_store_dwordx4 v[132:133], v[116:119], off offset:128
	global_store_dwordx4 v[132:133], v[112:115], off offset:144

;   DEV float* ssq_ckv() const { return (float*)(b + O_SSQCKV); }
; DEV float red4(float s) { s += SWZ_XOR(s, 16); return swapsum(s); }
;   DEV void operator()(f32x4 (&acc)[2][2][4][2], const PgUnit& u, int ui, int wr, int wc, int fr, int fq) const {
;     ...
;         } else if (wc < 2) {
;           u16* dst = WS{P.ws}.CKV() + (long)t * 128 + wc * 64;
; #pragma unroll
;           for (int bj = 0; bj < 2; ++bj) store8bf(dst + bj * 32 + 8 * fq, v[bj]);
;           s = red4(s);
;           if (fq == 0) WS{P.ws}.ssq_ckv()[(long)wc * TB + t] = s;
.LBB0_302:
	s_andn2_b64 vcc, exec, s[2:3]
	s_cbranch_vccnz .LBB0_306
	v_ashrrev_i32_e32 v129, 31, v128
	v_lshlrev_b64 v[132:133], 8, v[128:129]
	ds_swizzle_b32 v129, v130 offset:swizzle(SWAP,16)
	v_lshl_add_u64 v[136:137], v[158:159], 0, v[132:133]
	v_cvt_pk_bf16_f32 v132, v124, v125
	v_cvt_pk_bf16_f32 v133, v126, v127
	v_cvt_pk_bf16_f32 v134, v120, v121
	s_waitcnt lgkmcnt(0)
	v_add_f32_e32 v129, v130, v129
	v_mov_b32_e32 v131, v129
	v_cvt_pk_bf16_f32 v135, v122, v123
	s_nop 1
	v_permlane32_swap_b32_e32 v129, v131
	global_store_dwordx4 v[136:137], v[132:135], off
	s_nop 1
	v_cvt_pk_bf16_f32 v132, v116, v117
	v_cvt_pk_bf16_f32 v133, v118, v119
	v_cvt_pk_bf16_f32 v134, v112, v113
	v_cvt_pk_bf16_f32 v135, v114, v115
	global_store_dwordx4 v[136:137], v[132:135], off offset:64
	s_and_saveexec_b64 s[2:3], s[4:5]
	s_cbranch_execz .LBB0_305
	v_ashrrev_i32_e32 v167, 31, v166
	v_lshl_add_u64 v[132:133], v[166:167], 2, s[98:99]
	v_add_f32_e32 v129, v129, v131
	global_store_dword v[132:133], v129, off offset:64

; DEV float red4(float s) { s += SWZ_XOR(s, 16); return swapsum(s); }
;   DEV void operator()(f32x4 (&acc)[2][2][4][2], const PgUnit& u, int ui, int wr, int wc, int fr, int fq) const {
;     ...
;         } else if (nt == 8) {
;           u16* dst = WS{P.ws}.CQ() + (long)t * 256 + wc * 64;
; #pragma unroll
;           for (int bj = 0; bj < 2; ++bj) store8bf(dst + bj * 32 + 8 * fq, v[bj]);
;           s = red4(s);
;           if (fq == 0) WS{P.ws}.ssq_cq()[(long)wc * TB + t] = s;
.LBB0_307:
	s_andn2_b64 vcc, exec, s[2:3]
	s_cbranch_vccnz .LBB0_311
	v_ashrrev_i32_e32 v129, 31, v128
	v_lshlrev_b64 v[132:133], 9, v[128:129]
	ds_swizzle_b32 v129, v130 offset:swizzle(SWAP,16)
	v_lshl_add_u64 v[136:137], v[160:161], 0, v[132:133]
	v_cvt_pk_bf16_f32 v132, v124, v125
	v_cvt_pk_bf16_f32 v133, v126, v127
	v_cvt_pk_bf16_f32 v134, v120, v121
	s_waitcnt lgkmcnt(0)
	v_add_f32_e32 v129, v130, v129
	v_mov_b32_e32 v131, v129
	v_cvt_pk_bf16_f32 v135, v122, v123
	s_nop 1
	v_permlane32_swap_b32_e32 v129, v131
	global_store_dwordx4 v[136:137], v[132:135], off
	s_nop 1
	v_cvt_pk_bf16_f32 v132, v116, v117
	v_cvt_pk_bf16_f32 v133, v118, v119
	v_cvt_pk_bf16_f32 v134, v112, v113
	v_cvt_pk_bf16_f32 v135, v114, v115
	global_store_dwordx4 v[136:137], v[132:135], off offset:64
	s_and_saveexec_b64 s[2:3], s[4:5]
	s_cbranch_execz .LBB0_310
	v_ashrrev_i32_e32 v167, 31, v166
	v_lshl_add_u64 v[132:133], v[166:167], 2, s[68:69]
	v_add_f32_e32 v129, v129, v131
	global_store_dword v[132:133], v129, off offset:64

; DEV float siluf(float x) { return x * __builtin_amdgcn_rcpf(1.f + __builtin_amdgcn_exp2f(-LOG2E * x)); }
;   DEV void operator()(f32x4 (&acc)[2][2][4][2], const PgUnit& u, int ui, int wr, int wc, int fr, int fq) const {
;     ...
;         } else if (nt < 8 || nt >= 10) {
;           u16* dst = WS{P.ws}.G() + (long)t * 1024 + (nt >= 10 ? 512 + (nt - 10) * 256 : (nt - 6) * 256) + wc * 64;
; #pragma unroll
;           for (int bj = 0; bj < 2; ++bj) {
;             float y[8];
; #pragma unroll
;             for (int e = 0; e < 8; ++e) y[e] = siluf(v[bj][e]);
;             store8bf(dst + bj * 32 + 8 * fq, y);
;           }
.LBB0_312:
	s_andn2_b64 vcc, exec, s[2:3]
	s_cbranch_vccnz .LBB0_314
	v_ashrrev_i32_e32 v129, 31, v128
	v_lshlrev_b64 v[132:133], 11, v[128:129]
	v_lshl_add_u64 v[132:133], s[16:17], 0, v[132:133]
	v_lshl_add_u64 v[132:133], s[22:23], 1, v[132:133]
	s_lshl_b32 s2, s65, 1
	s_mov_b32 s3, s23
	v_lshl_add_u64 v[132:133], v[132:133], 0, s[2:3]
	v_lshl_add_u64 v[136:137], v[132:133], 0, v[184:185]
	v_mul_f32_e32 v132, 0xbfb8aa3b, v126
	v_exp_f32_e32 v132, v132
	v_mul_f32_e32 v133, 0xbfb8aa3b, v127
	v_exp_f32_e32 v133, v133
	v_mul_f32_e32 v135, 0xbfb8aa3b, v121
	v_add_f32_e32 v132, 1.0, v132
	v_rcp_f32_e32 v132, v132
	v_exp_f32_e32 v135, v135
	v_mul_f32_e32 v129, 0xbfb8aa3b, v124
	v_mul_f32_e32 v131, 0xbfb8aa3b, v125
	v_mul_f32_e32 v134, v126, v132
	v_add_f32_e32 v132, 1.0, v133
	v_mul_f32_e32 v133, 0xbfb8aa3b, v120
	v_rcp_f32_e32 v132, v132
	v_exp_f32_e32 v133, v133
	v_exp_f32_e32 v129, v129
	v_exp_f32_e32 v131, v131
	v_mul_f32_e32 v138, v127, v132
	v_add_f32_e32 v132, 1.0, v133
	v_add_f32_e32 v133, 1.0, v135
	v_mul_f32_e32 v135, 0xbfb8aa3b, v122
	v_exp_f32_e32 v135, v135
	v_mul_f32_e32 v139, 0xbfb8aa3b, v123
	v_exp_f32_e32 v139, v139
	v_add_f32_e32 v129, 1.0, v129
	v_add_f32_e32 v131, 1.0, v131
	v_add_f32_e32 v135, 1.0, v135
	v_rcp_f32_e32 v129, v129
	v_rcp_f32_e32 v131, v131
	v_rcp_f32_e32 v132, v132
	v_rcp_f32_e32 v135, v135
	v_add_f32_e32 v139, 1.0, v139
	v_rcp_f32_e32 v133, v133
	v_rcp_f32_e32 v139, v139
	v_mul_f32_e32 v129, v124, v129
	v_mul_f32_e32 v131, v125, v131
	v_mul_f32_e32 v140, v120, v132
	v_mul_f32_e32 v135, v122, v135
	v_cvt_pk_bf16_f32 v132, v129, v131
	v_mul_f32_e32 v141, v121, v133
	v_mul_f32_e32 v139, v123, v139
	v_cvt_pk_bf16_f32 v133, v134, v138
	v_cvt_pk_bf16_f32 v134, v140, v141
	v_cvt_pk_bf16_f32 v135, v135, v139
	global_store_dwordx4 v[136:137], v[132:135], off
	v_mul_f32_e32 v129, 0xbfb8aa3b, v116
	v_mul_f32_e32 v131, 0xbfb8aa3b, v117
	v_mul_f32_e32 v132, 0xbfb8aa3b, v118
	v_exp_f32_e32 v132, v132
	v_mul_f32_e32 v133, 0xbfb8aa3b, v119
	v_exp_f32_e32 v133, v133
	v_mul_f32_e32 v135, 0xbfb8aa3b, v113
	v_add_f32_e32 v132, 1.0, v132
	v_rcp_f32_e32 v132, v132
	v_exp_f32_e32 v135, v135
	v_mul_f32_e32 v139, 0xbfb8aa3b, v115
	v_exp_f32_e32 v129, v129
	v_mul_f32_e32 v134, v118, v132
	v_add_f32_e32 v132, 1.0, v133
	v_mul_f32_e32 v133, 0xbfb8aa3b, v112
	v_rcp_f32_e32 v132, v132
	v_exp_f32_e32 v133, v133
	v_exp_f32_e32 v131, v131
	v_exp_f32_e32 v139, v139
	v_mul_f32_e32 v138, v119, v132
	v_add_f32_e32 v132, 1.0, v133
	v_add_f32_e32 v133, 1.0, v135
	v_mul_f32_e32 v135, 0xbfb8aa3b, v114
	v_exp_f32_e32 v135, v135
	v_add_f32_e32 v129, 1.0, v129
	v_add_f32_e32 v131, 1.0, v131
	v_add_f32_e32 v139, 1.0, v139
	v_add_f32_e32 v135, 1.0, v135
	v_rcp_f32_e32 v135, v135
	v_rcp_f32_e32 v129, v129
	v_rcp_f32_e32 v131, v131
	v_rcp_f32_e32 v132, v132
	v_rcp_f32_e32 v133, v133
	v_rcp_f32_e32 v139, v139
	v_mul_f32_e32 v135, v114, v135
	v_mul_f32_e32 v129, v116, v129
	v_mul_f32_e32 v131, v117, v131
	v_mul_f32_e32 v140, v112, v132
	v_mul_f32_e32 v141, v113, v133
	v_mul_f32_e32 v139, v115, v139
	v_cvt_pk_bf16_f32 v132, v129, v131
	v_cvt_pk_bf16_f32 v133, v134, v138
	v_cvt_pk_bf16_f32 v134, v140, v141
	v_cvt_pk_bf16_f32 v135, v135, v139
	global_store_dwordx4 v[136:137], v[132:135], off offset:64

;   DEV void operator()(f32x4 (&acc)[2][2][4][2], const PgUnit& u, int ui, int wr, int wc, int fr, int fq) const {
;     ...
;         } else if (nt < 6) {
;           u16* dst = WS{P.ws}.VA() + (long)t * 512 + (nt & 1) * 256 + wc * 64;
; #pragma unroll
;           for (int bj = 0; bj < 2; ++bj) store8bf(dst + bj * 32 + 8 * fq, v[bj]);
.LBB0_315:
	s_andn2_b64 vcc, exec, s[2:3]
	s_cbranch_vccnz .LBB0_317
	v_ashrrev_i32_e32 v129, 31, v128
	v_lshlrev_b64 v[132:133], 10, v[128:129]
	v_lshl_add_u64 v[132:133], s[18:19], 0, v[132:133]
	s_lshl_b32 s2, s71, 1
	s_mov_b32 s3, s23
	v_lshl_add_u64 v[132:133], v[132:133], 0, s[2:3]
	s_lshl_b32 s2, s65, 1
	v_lshl_add_u64 v[132:133], v[132:133], 0, s[2:3]
	v_lshl_add_u64 v[136:137], v[132:133], 0, v[184:185]
	v_cvt_pk_bf16_f32 v132, v124, v125
	v_cvt_pk_bf16_f32 v133, v126, v127
	v_cvt_pk_bf16_f32 v134, v120, v121
	v_cvt_pk_bf16_f32 v135, v122, v123
	global_store_dwordx4 v[136:137], v[132:135], off
	s_nop 1
	v_cvt_pk_bf16_f32 v132, v116, v117
	v_cvt_pk_bf16_f32 v133, v118, v119
	v_cvt_pk_bf16_f32 v134, v112, v113
	v_cvt_pk_bf16_f32 v135, v114, v115
	global_store_dwordx4 v[136:137], v[132:135], off offset:64

; DEV float red4(float s) { s += SWZ_XOR(s, 16); return swapsum(s); }
;   DEV void operator()(f32x4 (&acc)[2][2][4][2], const PgUnit& u, int ui, int wr, int wc, int fr, int fq) const {
;     ...
;         if (ui < 8) rstd = rl[ui * 256 + ai * 128 + wr * 64 + m * 16 + fr];
;         else { float ss = 0.f;
; #pragma unroll
;           for (int j = 0; j < 16; ++j) ss += WS{P.ws}.ssq_x()[((long)batch * 16 + j) * TB + t];
;           rstd = __builtin_amdgcn_rsqf(ss * (1.f / 1024.f) + EPS); }
;         float v[2][8];
;         float s = 0.f;
; #pragma unroll
;         for (int bj = 0; bj < 2; ++bj)
; #pragma unroll
;           for (int n = 0; n < 2; ++n)
; #pragma unroll
;             for (int r = 0; r < 4; ++r) { const float x = acc[ai][bj][m][n][r] * rstd; v[bj][n * 4 + r] = x; s += x * x; }
;         if (nt < 4) {
;           s = red4(s);
;           const float inv = __builtin_amdgcn_rsqf(s * (1.f / 64.f) + EPS) * (nt < 2 ? 0.125f * LOG2E : 1.f);
;           u16* dst = (nt < 2 ? WS{P.ws}.QA() : WS{P.ws}.KA()) + (long)t * 512 + (nt & 1) * 256 + wc * 64;
; #pragma unroll
;           for (int bj = 0; bj < 2; ++bj) {
;             const int c8 = bj * 32 + 8 * fq;
;             const float4 g0 = gg[bj][0], g1 = gg[bj][1];
;             float y[8] = {v[bj][0] * inv * g0.x, v[bj][1] * inv * g0.y, v[bj][2] * inv * g0.z, v[bj][3] * inv * g0.w, v[bj][4] * inv * g1.x, v[bj][5] * inv * g1.y, v[bj][6] * inv * g1.z, v[bj][7] * inv * g1.w};
;             store8bf(dst + c8, y);
;           }
.LBB0_318:
	ds_swizzle_b32 v131, v130 offset:swizzle(SWAP,16)
	s_and_b64 s[2:3], s[8:9], exec
	s_cselect_b32 s2, s59, 0x5000000
	v_ashrrev_i32_e32 v129, 31, v128
	s_add_u32 s2, s86, s2
	s_waitcnt lgkmcnt(0)
	v_add_f32_e32 v130, v130, v131
	v_mov_b32_e32 v131, v130
	s_nop 1
	v_permlane32_swap_b32_e32 v130, v131
	v_add_f32_e32 v130, v130, v131
	v_fmamk_f32 v130, v130, 0x3c800000, v227
	v_rsq_f32_e32 v130, v130
	v_lshlrev_b64 v[128:129], 10, v[128:129]
	s_addc_u32 s3, s87, 0
	v_lshl_add_u64 v[128:129], s[2:3], 0, v[128:129]
	v_mul_f32_e32 v130, v168, v130
	v_mul_f32_e32 v124, v124, v130
	v_mul_f32_e32 v120, v120, v130
	s_lshl_b32 s2, s71, 1
	s_mov_b32 s3, s23
	v_mul_f32_e32 v131, v28, v124
	v_mul_f32_e32 v124, v125, v130
	v_mul_f32_e32 v133, v24, v120
	v_mul_f32_e32 v120, v121, v130
	v_lshl_add_u64 v[128:129], v[128:129], 0, s[2:3]
	s_lshl_b32 s2, s65, 1
	v_mul_f32_e32 v132, v29, v124
	v_mul_f32_e32 v124, v126, v130
	v_mul_f32_e32 v134, v25, v120
	v_mul_f32_e32 v120, v122, v130
	v_lshl_add_u64 v[128:129], v[128:129], 0, s[2:3]
	v_mul_f32_e32 v126, v30, v124
	v_mul_f32_e32 v124, v127, v130
	v_mul_f32_e32 v135, v26, v120
	v_mul_f32_e32 v120, v123, v130
	v_mul_f32_e32 v127, v31, v124
	v_mul_f32_e32 v123, v27, v120
	v_lshl_add_u64 v[124:125], v[128:129], 0, v[184:185]
	v_cvt_pk_bf16_f32 v120, v131, v132
	v_mul_f32_e32 v112, v112, v130
	v_cvt_pk_bf16_f32 v121, v126, v127
	v_cvt_pk_bf16_f32 v122, v133, v134
	v_cvt_pk_bf16_f32 v123, v135, v123
	global_store_dwordx4 v[124:125], v[120:123], off
	v_mul_f32_e32 v116, v116, v130
	v_mul_f32_e32 v117, v117, v130
	v_mul_f32_e32 v120, v16, v112
	v_mul_f32_e32 v112, v113, v130
	v_mul_f32_e32 v121, v17, v112
	v_mul_f32_e32 v112, v114, v130
	v_mul_f32_e32 v122, v18, v112
	v_mul_f32_e32 v112, v115, v130
	v_mul_f32_e32 v118, v118, v130
	v_mul_f32_e32 v119, v119, v130
	v_mul_f32_e32 v115, v19, v112
	v_mul_f32_e32 v116, v20, v116
	v_mul_f32_e32 v117, v21, v117
	v_mul_f32_e32 v118, v22, v118
	v_mul_f32_e32 v119, v23, v119
	v_cvt_pk_bf16_f32 v112, v116, v117
	v_cvt_pk_bf16_f32 v113, v118, v119
	v_cvt_pk_bf16_f32 v114, v120, v121
	v_cvt_pk_bf16_f32 v115, v122, v115
	global_store_dwordx4 v[124:125], v[112:115], off offset:64
	s_and_b64 vcc, exec, s[10:11]
	s_mov_b64 s[2:3], -1
	s_cbranch_vccnz .LBB0_142
.LBB0_319:
	v_ashrrev_i32_e32 v167, 31, v166
	v_lshl_add_u64 v[112:113], v[166:167], 2, s[96:97]
	global_load_dword v114, v[112:113], off offset:128
	s_waitcnt vmcnt(0) lgkmcnt(0)
	v_add_f32_e32 v116, 0, v114
	v_add_co_u32_e32 v114, vcc, 0x10000, v112
	s_nop 1
	v_addc_co_u32_e32 v115, vcc, 0, v113, vcc
	global_load_dword v114, v[114:115], off offset:128
	s_waitcnt vmcnt(0) lgkmcnt(0)
	v_add_f32_e32 v116, v116, v114
	v_add_co_u32_e32 v114, vcc, 0x20000, v112
	s_nop 1
	v_addc_co_u32_e32 v115, vcc, 0, v113, vcc
	global_load_dword v114, v[114:115], off offset:128
	s_waitcnt vmcnt(0) lgkmcnt(0)
	v_add_f32_e32 v116, v116, v114
	v_add_co_u32_e32 v114, vcc, 0x30000, v112
	s_nop 1
	v_addc_co_u32_e32 v115, vcc, 0, v113, vcc
	global_load_dword v114, v[114:115], off offset:128
	s_waitcnt vmcnt(0) lgkmcnt(0)
	v_add_f32_e32 v116, v116, v114
	v_add_co_u32_e32 v114, vcc, 0x40000, v112
	s_nop 1
	v_addc_co_u32_e32 v115, vcc, 0, v113, vcc
	global_load_dword v114, v[114:115], off offset:128
	s_waitcnt vmcnt(0) lgkmcnt(0)
	v_add_f32_e32 v116, v116, v114
	v_add_co_u32_e32 v114, vcc, 0x50000, v112
	s_nop 1
	v_addc_co_u32_e32 v115, vcc, 0, v113, vcc
	global_load_dword v114, v[114:115], off offset:128
	s_waitcnt vmcnt(0) lgkmcnt(0)
	v_add_f32_e32 v116, v116, v114
	v_add_co_u32_e32 v114, vcc, 0x60000, v112
	s_nop 1
	v_addc_co_u32_e32 v115, vcc, 0, v113, vcc
	global_load_dword v114, v[114:115], off offset:128
	s_waitcnt vmcnt(0) lgkmcnt(0)
	v_add_f32_e32 v116, v116, v114
	v_add_co_u32_e32 v114, vcc, 0x70000, v112
	s_nop 1
	v_addc_co_u32_e32 v115, vcc, 0, v113, vcc
	global_load_dword v114, v[114:115], off offset:128
	s_waitcnt vmcnt(0) lgkmcnt(0)
	v_add_f32_e32 v116, v116, v114
	v_add_co_u32_e32 v114, vcc, 0x80000, v112
	s_nop 1
	v_addc_co_u32_e32 v115, vcc, 0, v113, vcc
	global_load_dword v114, v[114:115], off offset:128
	s_waitcnt vmcnt(0) lgkmcnt(0)
	v_add_f32_e32 v116, v116, v114
	v_add_co_u32_e32 v114, vcc, 0x90000, v112
	s_nop 1
	v_addc_co_u32_e32 v115, vcc, 0, v113, vcc
	global_load_dword v114, v[114:115], off offset:128
	s_waitcnt vmcnt(0) lgkmcnt(0)
	v_add_f32_e32 v116, v116, v114
	v_add_co_u32_e32 v114, vcc, 0xa0000, v112
	s_nop 1
	v_addc_co_u32_e32 v115, vcc, 0, v113, vcc
	global_load_dword v114, v[114:115], off offset:128
	s_waitcnt vmcnt(0) lgkmcnt(0)
	v_add_f32_e32 v116, v116, v114
	v_add_co_u32_e32 v114, vcc, 0xb0000, v112
	s_nop 1
	v_addc_co_u32_e32 v115, vcc, 0, v113, vcc
	global_load_dword v114, v[114:115], off offset:128
	s_waitcnt vmcnt(0) lgkmcnt(0)
	v_add_f32_e32 v116, v116, v114
	v_add_co_u32_e32 v114, vcc, 0xc0000, v112
	s_nop 1
	v_addc_co_u32_e32 v115, vcc, 0, v113, vcc
	global_load_dword v114, v[114:115], off offset:128
	s_waitcnt vmcnt(0) lgkmcnt(0)
	v_add_f32_e32 v116, v116, v114
	v_add_co_u32_e32 v114, vcc, 0xd0000, v112
	s_nop 1
	v_addc_co_u32_e32 v115, vcc, 0, v113, vcc
	global_load_dword v114, v[114:115], off offset:128
	s_waitcnt vmcnt(0) lgkmcnt(0)
	v_add_f32_e32 v116, v116, v114
	v_add_co_u32_e32 v114, vcc, 0xe0000, v112
	s_nop 1
	v_addc_co_u32_e32 v115, vcc, 0, v113, vcc
	v_add_co_u32_e32 v112, vcc, 0xf0000, v112
	global_load_dword v114, v[114:115], off offset:128
	s_nop 0
	v_addc_co_u32_e32 v113, vcc, 0, v113, vcc
	global_load_dword v112, v[112:113], off offset:128
	s_waitcnt vmcnt(0) lgkmcnt(0)
	v_add_f32_e32 v114, v116, v114
	v_add_f32_e32 v112, v114, v112
	v_fmamk_f32 v112, v112, 0x3a800000, v227
	v_rsq_f32_e32 v114, v112
	s_cbranch_execz .LBB0_143
	s_branch .LBB0_144
.LBB0_320:
	s_and_b64 vcc, exec, s[12:13]
	s_cbranch_vccnz .LBB0_340
	s_andn2_b64 vcc, exec, s[82:83]
	s_cbranch_vccnz .LBB0_337
	s_andn2_b64 vcc, exec, s[78:79]
	s_cbranch_vccnz .LBB0_332
	s_andn2_b64 vcc, exec, s[92:93]
	s_cbranch_vccnz .LBB0_327
	s_andn2_b64 vcc, exec, s[94:95]
	s_cbranch_vccnz .LBB0_326
	v_ashrrev_i32_e32 v113, 31, v112
	v_lshlrev_b64 v[116:117], 8, v[112:113]
	v_lshl_add_u64 v[116:117], v[156:157], 0, v[116:117]
	s_waitcnt vmcnt(0)
	global_store_dwordx4 v[116:117], v[108:111], off
	global_store_dwordx4 v[116:117], v[104:107], off offset:16
	global_store_dwordx4 v[116:117], v[100:103], off offset:128
	global_store_dwordx4 v[116:117], v[96:99], off offset:144

;   DEV float* ssq_ckv() const { return (float*)(b + O_SSQCKV); }
; DEV float red4(float s) { s += SWZ_XOR(s, 16); return swapsum(s); }
;   DEV void operator()(f32x4 (&acc)[2][2][4][2], const PgUnit& u, int ui, int wr, int wc, int fr, int fq) const {
;     ...
;         } else if (wc < 2) {
;           u16* dst = WS{P.ws}.CKV() + (long)t * 128 + wc * 64;
; #pragma unroll
;           for (int bj = 0; bj < 2; ++bj) store8bf(dst + bj * 32 + 8 * fq, v[bj]);
;           s = red4(s);
;           if (fq == 0) WS{P.ws}.ssq_ckv()[(long)wc * TB + t] = s;
.LBB0_327:
	s_andn2_b64 vcc, exec, s[2:3]
	s_cbranch_vccnz .LBB0_331
	v_ashrrev_i32_e32 v113, 31, v112
	v_lshlrev_b64 v[116:117], 8, v[112:113]
	ds_swizzle_b32 v113, v114 offset:swizzle(SWAP,16)
	v_lshl_add_u64 v[120:121], v[158:159], 0, v[116:117]
	v_cvt_pk_bf16_f32 v116, v108, v109
	v_cvt_pk_bf16_f32 v117, v110, v111
	v_cvt_pk_bf16_f32 v118, v104, v105
	s_waitcnt lgkmcnt(0)
	v_add_f32_e32 v113, v114, v113
	v_mov_b32_e32 v115, v113
	v_cvt_pk_bf16_f32 v119, v106, v107
	s_nop 1
	v_permlane32_swap_b32_e32 v113, v115
	global_store_dwordx4 v[120:121], v[116:119], off
	s_nop 1
	v_cvt_pk_bf16_f32 v116, v100, v101
	v_cvt_pk_bf16_f32 v117, v102, v103
	v_cvt_pk_bf16_f32 v118, v96, v97
	v_cvt_pk_bf16_f32 v119, v98, v99
	global_store_dwordx4 v[120:121], v[116:119], off offset:64
	s_and_saveexec_b64 s[2:3], s[4:5]
	s_cbranch_execz .LBB0_330
	v_ashrrev_i32_e32 v167, 31, v166
	v_lshl_add_u64 v[116:117], v[166:167], 2, s[98:99]
	v_add_f32_e32 v113, v113, v115
	global_store_dword v[116:117], v113, off offset:128

; DEV float red4(float s) { s += SWZ_XOR(s, 16); return swapsum(s); }
;   DEV void operator()(f32x4 (&acc)[2][2][4][2], const PgUnit& u, int ui, int wr, int wc, int fr, int fq) const {
;     ...
;         } else if (nt == 8) {
;           u16* dst = WS{P.ws}.CQ() + (long)t * 256 + wc * 64;
; #pragma unroll
;           for (int bj = 0; bj < 2; ++bj) store8bf(dst + bj * 32 + 8 * fq, v[bj]);
;           s = red4(s);
;           if (fq == 0) WS{P.ws}.ssq_cq()[(long)wc * TB + t] = s;
.LBB0_332:
	s_andn2_b64 vcc, exec, s[2:3]
	s_cbranch_vccnz .LBB0_336
	v_ashrrev_i32_e32 v113, 31, v112
	v_lshlrev_b64 v[116:117], 9, v[112:113]
	ds_swizzle_b32 v113, v114 offset:swizzle(SWAP,16)
	v_lshl_add_u64 v[120:121], v[160:161], 0, v[116:117]
	v_cvt_pk_bf16_f32 v116, v108, v109
	v_cvt_pk_bf16_f32 v117, v110, v111
	v_cvt_pk_bf16_f32 v118, v104, v105
	s_waitcnt lgkmcnt(0)
	v_add_f32_e32 v113, v114, v113
	v_mov_b32_e32 v115, v113
	v_cvt_pk_bf16_f32 v119, v106, v107
	s_nop 1
	v_permlane32_swap_b32_e32 v113, v115
	global_store_dwordx4 v[120:121], v[116:119], off
	s_nop 1
	v_cvt_pk_bf16_f32 v116, v100, v101
	v_cvt_pk_bf16_f32 v117, v102, v103
	v_cvt_pk_bf16_f32 v118, v96, v97
	v_cvt_pk_bf16_f32 v119, v98, v99
	global_store_dwordx4 v[120:121], v[116:119], off offset:64
	s_and_saveexec_b64 s[2:3], s[4:5]
	s_cbranch_execz .LBB0_335
	v_ashrrev_i32_e32 v167, 31, v166
	v_lshl_add_u64 v[116:117], v[166:167], 2, s[68:69]
	v_add_f32_e32 v113, v113, v115
	global_store_dword v[116:117], v113, off offset:128

; DEV float siluf(float x) { return x * __builtin_amdgcn_rcpf(1.f + __builtin_amdgcn_exp2f(-LOG2E * x)); }
;   DEV void operator()(f32x4 (&acc)[2][2][4][2], const PgUnit& u, int ui, int wr, int wc, int fr, int fq) const {
;     ...
;         } else if (nt < 8 || nt >= 10) {
;           u16* dst = WS{P.ws}.G() + (long)t * 1024 + (nt >= 10 ? 512 + (nt - 10) * 256 : (nt - 6) * 256) + wc * 64;
; #pragma unroll
;           for (int bj = 0; bj < 2; ++bj) {
;             float y[8];
; #pragma unroll
;             for (int e = 0; e < 8; ++e) y[e] = siluf(v[bj][e]);
;             store8bf(dst + bj * 32 + 8 * fq, y);
;           }
.LBB0_337:
	s_andn2_b64 vcc, exec, s[2:3]
	s_cbranch_vccnz .LBB0_339
	v_ashrrev_i32_e32 v113, 31, v112
	v_lshlrev_b64 v[116:117], 11, v[112:113]
	v_lshl_add_u64 v[116:117], s[16:17], 0, v[116:117]
	v_lshl_add_u64 v[116:117], s[22:23], 1, v[116:117]
	s_lshl_b32 s2, s65, 1
	s_mov_b32 s3, s23
	v_lshl_add_u64 v[116:117], v[116:117], 0, s[2:3]
	v_lshl_add_u64 v[120:121], v[116:117], 0, v[184:185]
	v_mul_f32_e32 v116, 0xbfb8aa3b, v110
	v_exp_f32_e32 v116, v116
	v_mul_f32_e32 v117, 0xbfb8aa3b, v111
	v_exp_f32_e32 v117, v117
	v_mul_f32_e32 v119, 0xbfb8aa3b, v105
	v_add_f32_e32 v116, 1.0, v116
	v_rcp_f32_e32 v116, v116
	v_exp_f32_e32 v119, v119
	v_mul_f32_e32 v113, 0xbfb8aa3b, v108
	v_mul_f32_e32 v115, 0xbfb8aa3b, v109
	v_mul_f32_e32 v118, v110, v116
	v_add_f32_e32 v116, 1.0, v117
	v_mul_f32_e32 v117, 0xbfb8aa3b, v104
	v_rcp_f32_e32 v116, v116
	v_exp_f32_e32 v117, v117
	v_exp_f32_e32 v113, v113
	v_exp_f32_e32 v115, v115
	v_mul_f32_e32 v122, v111, v116
	v_add_f32_e32 v116, 1.0, v117
	v_add_f32_e32 v117, 1.0, v119
	v_mul_f32_e32 v119, 0xbfb8aa3b, v106
	v_exp_f32_e32 v119, v119
	v_mul_f32_e32 v123, 0xbfb8aa3b, v107
	v_exp_f32_e32 v123, v123
	v_add_f32_e32 v113, 1.0, v113
	v_add_f32_e32 v115, 1.0, v115
	v_add_f32_e32 v119, 1.0, v119
	v_rcp_f32_e32 v113, v113
	v_rcp_f32_e32 v115, v115
	v_rcp_f32_e32 v116, v116
	v_rcp_f32_e32 v119, v119
	v_add_f32_e32 v123, 1.0, v123
	v_rcp_f32_e32 v117, v117
	v_rcp_f32_e32 v123, v123
	v_mul_f32_e32 v113, v108, v113
	v_mul_f32_e32 v115, v109, v115
	v_mul_f32_e32 v124, v104, v116
	v_mul_f32_e32 v119, v106, v119
	v_cvt_pk_bf16_f32 v116, v113, v115
	v_mul_f32_e32 v125, v105, v117
	v_mul_f32_e32 v123, v107, v123
	v_cvt_pk_bf16_f32 v117, v118, v122
	v_cvt_pk_bf16_f32 v118, v124, v125
	v_cvt_pk_bf16_f32 v119, v119, v123
	global_store_dwordx4 v[120:121], v[116:119], off
	v_mul_f32_e32 v113, 0xbfb8aa3b, v100
	v_mul_f32_e32 v115, 0xbfb8aa3b, v101
	v_mul_f32_e32 v116, 0xbfb8aa3b, v102
	v_exp_f32_e32 v116, v116
	v_mul_f32_e32 v117, 0xbfb8aa3b, v103
	v_exp_f32_e32 v117, v117
	v_mul_f32_e32 v119, 0xbfb8aa3b, v97
	v_add_f32_e32 v116, 1.0, v116
	v_rcp_f32_e32 v116, v116
	v_exp_f32_e32 v119, v119
	v_mul_f32_e32 v123, 0xbfb8aa3b, v99
	v_exp_f32_e32 v113, v113
	v_mul_f32_e32 v118, v102, v116
	v_add_f32_e32 v116, 1.0, v117
	v_mul_f32_e32 v117, 0xbfb8aa3b, v96
	v_rcp_f32_e32 v116, v116
	v_exp_f32_e32 v117, v117
	v_exp_f32_e32 v115, v115
	v_exp_f32_e32 v123, v123
	v_mul_f32_e32 v122, v103, v116
	v_add_f32_e32 v116, 1.0, v117
	v_add_f32_e32 v117, 1.0, v119
	v_mul_f32_e32 v119, 0xbfb8aa3b, v98
	v_exp_f32_e32 v119, v119
	v_add_f32_e32 v113, 1.0, v113
	v_add_f32_e32 v115, 1.0, v115
	v_add_f32_e32 v123, 1.0, v123
	v_add_f32_e32 v119, 1.0, v119
	v_rcp_f32_e32 v119, v119
	v_rcp_f32_e32 v113, v113
	v_rcp_f32_e32 v115, v115
	v_rcp_f32_e32 v116, v116
	v_rcp_f32_e32 v117, v117
	v_rcp_f32_e32 v123, v123
	v_mul_f32_e32 v119, v98, v119
	v_mul_f32_e32 v113, v100, v113
	v_mul_f32_e32 v115, v101, v115
	v_mul_f32_e32 v124, v96, v116
	v_mul_f32_e32 v125, v97, v117
	v_mul_f32_e32 v123, v99, v123
	v_cvt_pk_bf16_f32 v116, v113, v115
	v_cvt_pk_bf16_f32 v117, v118, v122
	v_cvt_pk_bf16_f32 v118, v124, v125
	v_cvt_pk_bf16_f32 v119, v119, v123
	global_store_dwordx4 v[120:121], v[116:119], off offset:64

;   DEV void operator()(f32x4 (&acc)[2][2][4][2], const PgUnit& u, int ui, int wr, int wc, int fr, int fq) const {
;     ...
;         } else if (nt < 6) {
;           u16* dst = WS{P.ws}.VA() + (long)t * 512 + (nt & 1) * 256 + wc * 64;
; #pragma unroll
;           for (int bj = 0; bj < 2; ++bj) store8bf(dst + bj * 32 + 8 * fq, v[bj]);
.LBB0_340:
	s_andn2_b64 vcc, exec, s[2:3]
	s_cbranch_vccnz .LBB0_342
	v_ashrrev_i32_e32 v113, 31, v112
	v_lshlrev_b64 v[116:117], 10, v[112:113]
	v_lshl_add_u64 v[116:117], s[18:19], 0, v[116:117]
	s_lshl_b32 s2, s71, 1
	s_mov_b32 s3, s23
	v_lshl_add_u64 v[116:117], v[116:117], 0, s[2:3]
	s_lshl_b32 s2, s65, 1
	v_lshl_add_u64 v[116:117], v[116:117], 0, s[2:3]
	v_lshl_add_u64 v[120:121], v[116:117], 0, v[184:185]
	v_cvt_pk_bf16_f32 v116, v108, v109
	v_cvt_pk_bf16_f32 v117, v110, v111
	v_cvt_pk_bf16_f32 v118, v104, v105
	v_cvt_pk_bf16_f32 v119, v106, v107
	global_store_dwordx4 v[120:121], v[116:119], off
	s_nop 1
	v_cvt_pk_bf16_f32 v116, v100, v101
	v_cvt_pk_bf16_f32 v117, v102, v103
	v_cvt_pk_bf16_f32 v118, v96, v97
	v_cvt_pk_bf16_f32 v119, v98, v99
	global_store_dwordx4 v[120:121], v[116:119], off offset:64

; DEV float red4(float s) { s += SWZ_XOR(s, 16); return swapsum(s); }
;   DEV void operator()(f32x4 (&acc)[2][2][4][2], const PgUnit& u, int ui, int wr, int wc, int fr, int fq) const {
;     ...
;         else { float ss = 0.f;
; #pragma unroll
;           for (int j = 0; j < 16; ++j) ss += WS{P.ws}.ssq_x()[((long)batch * 16 + j) * TB + t];
;           rstd = __builtin_amdgcn_rsqf(ss * (1.f / 1024.f) + EPS); }
;         float v[2][8];
;         float s = 0.f;
; #pragma unroll
;         for (int bj = 0; bj < 2; ++bj)
; #pragma unroll
;           for (int n = 0; n < 2; ++n)
; #pragma unroll
;             for (int r = 0; r < 4; ++r) { const float x = acc[ai][bj][m][n][r] * rstd; v[bj][n * 4 + r] = x; s += x * x; }
;         if (nt < 4) {
;           s = red4(s);
;           const float inv = __builtin_amdgcn_rsqf(s * (1.f / 64.f) + EPS) * (nt < 2 ? 0.125f * LOG2E : 1.f);
;           u16* dst = (nt < 2 ? WS{P.ws}.QA() : WS{P.ws}.KA()) + (long)t * 512 + (nt & 1) * 256 + wc * 64;
; #pragma unroll
;           for (int bj = 0; bj < 2; ++bj) {
;             const int c8 = bj * 32 + 8 * fq;
;             const float4 g0 = gg[bj][0], g1 = gg[bj][1];
;             float y[8] = {v[bj][0] * inv * g0.x, v[bj][1] * inv * g0.y, v[bj][2] * inv * g0.z, v[bj][3] * inv * g0.w, v[bj][4] * inv * g1.x, v[bj][5] * inv * g1.y, v[bj][6] * inv * g1.z, v[bj][7] * inv * g1.w};
;             store8bf(dst + c8, y);
;           }
.LBB0_343:
	ds_swizzle_b32 v115, v114 offset:swizzle(SWAP,16)
	s_and_b64 s[2:3], s[8:9], exec
	s_cselect_b32 s2, s59, 0x5000000
	v_ashrrev_i32_e32 v113, 31, v112
	s_add_u32 s2, s86, s2
	s_waitcnt lgkmcnt(0)
	v_add_f32_e32 v114, v114, v115
	v_mov_b32_e32 v115, v114
	s_nop 1
	v_permlane32_swap_b32_e32 v114, v115
	v_add_f32_e32 v114, v114, v115
	v_fmamk_f32 v114, v114, 0x3c800000, v227
	v_rsq_f32_e32 v114, v114
	v_lshlrev_b64 v[112:113], 10, v[112:113]
	s_addc_u32 s3, s87, 0
	v_lshl_add_u64 v[112:113], s[2:3], 0, v[112:113]
	v_mul_f32_e32 v114, v168, v114
	v_mul_f32_e32 v108, v108, v114
	v_mul_f32_e32 v104, v104, v114
	s_lshl_b32 s2, s71, 1
	s_mov_b32 s3, s23
	v_mul_f32_e32 v115, v28, v108
	v_mul_f32_e32 v108, v109, v114
	v_mul_f32_e32 v117, v24, v104
	v_mul_f32_e32 v104, v105, v114
	v_lshl_add_u64 v[112:113], v[112:113], 0, s[2:3]
	s_lshl_b32 s2, s65, 1
	v_mul_f32_e32 v116, v29, v108
	v_mul_f32_e32 v108, v110, v114
	v_mul_f32_e32 v118, v25, v104
	v_mul_f32_e32 v104, v106, v114
	v_lshl_add_u64 v[112:113], v[112:113], 0, s[2:3]
	v_mul_f32_e32 v110, v30, v108
	v_mul_f32_e32 v108, v111, v114
	v_mul_f32_e32 v119, v26, v104
	v_mul_f32_e32 v104, v107, v114
	v_mul_f32_e32 v111, v31, v108
	v_mul_f32_e32 v107, v27, v104
	v_lshl_add_u64 v[108:109], v[112:113], 0, v[184:185]
	v_cvt_pk_bf16_f32 v104, v115, v116
	v_mul_f32_e32 v96, v96, v114
	v_cvt_pk_bf16_f32 v105, v110, v111
	v_cvt_pk_bf16_f32 v106, v117, v118
	v_cvt_pk_bf16_f32 v107, v119, v107
	global_store_dwordx4 v[108:109], v[104:107], off
	v_mul_f32_e32 v100, v100, v114
	v_mul_f32_e32 v101, v101, v114
	v_mul_f32_e32 v104, v16, v96
	v_mul_f32_e32 v96, v97, v114
	v_mul_f32_e32 v105, v17, v96
	v_mul_f32_e32 v96, v98, v114
	v_mul_f32_e32 v106, v18, v96
	v_mul_f32_e32 v96, v99, v114
	v_mul_f32_e32 v102, v102, v114
	v_mul_f32_e32 v103, v103, v114
	v_mul_f32_e32 v99, v19, v96
	v_mul_f32_e32 v100, v20, v100
	v_mul_f32_e32 v101, v21, v101
	v_mul_f32_e32 v102, v22, v102
	v_mul_f32_e32 v103, v23, v103
	v_cvt_pk_bf16_f32 v96, v100, v101
	v_cvt_pk_bf16_f32 v97, v102, v103
	v_cvt_pk_bf16_f32 v98, v104, v105
	v_cvt_pk_bf16_f32 v99, v106, v99
	global_store_dwordx4 v[108:109], v[96:99], off offset:64
	s_and_b64 vcc, exec, s[10:11]
	s_mov_b64 s[2:3], -1
	s_cbranch_vccnz .LBB0_147
.LBB0_344:
	v_ashrrev_i32_e32 v167, 31, v166
	v_lshl_add_u64 v[96:97], v[166:167], 2, s[96:97]
	global_load_dword v98, v[96:97], off offset:192
	s_waitcnt vmcnt(0) lgkmcnt(0)
	v_add_f32_e32 v100, 0, v98
	v_add_co_u32_e32 v98, vcc, 0x10000, v96
	s_nop 1
	v_addc_co_u32_e32 v99, vcc, 0, v97, vcc
	global_load_dword v98, v[98:99], off offset:192
	s_waitcnt vmcnt(0) lgkmcnt(0)
	v_add_f32_e32 v100, v100, v98
	v_add_co_u32_e32 v98, vcc, 0x20000, v96
	s_nop 1
	v_addc_co_u32_e32 v99, vcc, 0, v97, vcc
	global_load_dword v98, v[98:99], off offset:192
	s_waitcnt vmcnt(0) lgkmcnt(0)
	v_add_f32_e32 v100, v100, v98
	v_add_co_u32_e32 v98, vcc, 0x30000, v96
	s_nop 1
	v_addc_co_u32_e32 v99, vcc, 0, v97, vcc
	global_load_dword v98, v[98:99], off offset:192
	s_waitcnt vmcnt(0) lgkmcnt(0)
	v_add_f32_e32 v100, v100, v98
	v_add_co_u32_e32 v98, vcc, 0x40000, v96
	s_nop 1
	v_addc_co_u32_e32 v99, vcc, 0, v97, vcc
	global_load_dword v98, v[98:99], off offset:192
	s_waitcnt vmcnt(0) lgkmcnt(0)
	v_add_f32_e32 v100, v100, v98
	v_add_co_u32_e32 v98, vcc, 0x50000, v96
	s_nop 1
	v_addc_co_u32_e32 v99, vcc, 0, v97, vcc
	global_load_dword v98, v[98:99], off offset:192
	s_waitcnt vmcnt(0) lgkmcnt(0)
	v_add_f32_e32 v100, v100, v98
	v_add_co_u32_e32 v98, vcc, 0x60000, v96
	s_nop 1
	v_addc_co_u32_e32 v99, vcc, 0, v97, vcc
	global_load_dword v98, v[98:99], off offset:192
	s_waitcnt vmcnt(0) lgkmcnt(0)
	v_add_f32_e32 v100, v100, v98
	v_add_co_u32_e32 v98, vcc, 0x70000, v96
	s_nop 1
	v_addc_co_u32_e32 v99, vcc, 0, v97, vcc
	global_load_dword v98, v[98:99], off offset:192
	s_waitcnt vmcnt(0) lgkmcnt(0)
	v_add_f32_e32 v100, v100, v98
	v_add_co_u32_e32 v98, vcc, 0x80000, v96
	s_nop 1
	v_addc_co_u32_e32 v99, vcc, 0, v97, vcc
	global_load_dword v98, v[98:99], off offset:192
	s_waitcnt vmcnt(0) lgkmcnt(0)
	v_add_f32_e32 v100, v100, v98
	v_add_co_u32_e32 v98, vcc, 0x90000, v96
	s_nop 1
	v_addc_co_u32_e32 v99, vcc, 0, v97, vcc
	global_load_dword v98, v[98:99], off offset:192
	s_waitcnt vmcnt(0) lgkmcnt(0)
	v_add_f32_e32 v100, v100, v98
	v_add_co_u32_e32 v98, vcc, 0xa0000, v96
	s_nop 1
	v_addc_co_u32_e32 v99, vcc, 0, v97, vcc
	global_load_dword v98, v[98:99], off offset:192
	s_waitcnt vmcnt(0) lgkmcnt(0)
	v_add_f32_e32 v100, v100, v98
	v_add_co_u32_e32 v98, vcc, 0xb0000, v96
	s_nop 1
	v_addc_co_u32_e32 v99, vcc, 0, v97, vcc
	global_load_dword v98, v[98:99], off offset:192
	s_waitcnt vmcnt(0) lgkmcnt(0)
	v_add_f32_e32 v100, v100, v98
	v_add_co_u32_e32 v98, vcc, 0xc0000, v96
	s_nop 1
	v_addc_co_u32_e32 v99, vcc, 0, v97, vcc
	global_load_dword v98, v[98:99], off offset:192
	s_waitcnt vmcnt(0) lgkmcnt(0)
	v_add_f32_e32 v100, v100, v98
	v_add_co_u32_e32 v98, vcc, 0xd0000, v96
	s_nop 1
	v_addc_co_u32_e32 v99, vcc, 0, v97, vcc
	global_load_dword v98, v[98:99], off offset:192
	s_waitcnt vmcnt(0) lgkmcnt(0)
	v_add_f32_e32 v100, v100, v98
	v_add_co_u32_e32 v98, vcc, 0xe0000, v96
	s_nop 1
	v_addc_co_u32_e32 v99, vcc, 0, v97, vcc
	v_add_co_u32_e32 v96, vcc, 0xf0000, v96
	global_load_dword v98, v[98:99], off offset:192
	s_nop 0
	v_addc_co_u32_e32 v97, vcc, 0, v97, vcc
	global_load_dword v96, v[96:97], off offset:192
	s_waitcnt vmcnt(0) lgkmcnt(0)
	v_add_f32_e32 v98, v100, v98
	v_add_f32_e32 v96, v98, v96
	v_fmamk_f32 v96, v96, 0x3a800000, v227
	v_rsq_f32_e32 v98, v96
	s_cbranch_execz .LBB0_148
	s_branch .LBB0_149

; #define SBAR() __builtin_amdgcn_sched_barrier(0)
; DEV int opaque_tid() { int t = threadIdx.x; asm volatile("" : "+v"(t)); return t; }
; DEV void glds16(const u16* g, char* l) { __builtin_amdgcn_global_load_lds((const unsigned*)g, (unsigned*)l, 16, 0, 0); }
; template <int WM, int WN, int BN, int EPI>
; DEV void gemm_tile(const u16* __restrict__ A, int lda, const u16* __restrict__ Bt, int ldb, int K, int m0, char* lds,
;                    const Params& P, int layer, int batch, int nt) {
;     ...
;   const int tid = opaque_tid(), wid = tid >> 6, lane = tid & 63, r32 = lane & 31, hi = lane >> 5;
;   const int wm = wid / WN, wn = wid % WN;
;   char* As = lds; char* Bs = lds + 65536;
;   f32x16 acc[MI][NI];
; #pragma unroll
;   for (int mi = 0; mi < MI; ++mi)
; #pragma unroll
;     for (int ni = 0; ni < NI; ++ni) acc[mi][ni] = f32x16{};
;   const int srow = tid >> 3, sch = (tid & 7) ^ ((srow >> 1) & 7);
;   const u16* Ap = A + (long)(m0 + srow) * lda + sch * 8;
;   const u16* Bp = Bt + (long)srow * ldb + sch * 8;
;   const int soff = tid * 16;
;     ...
;   GLOAD(0, 0); asm volatile("s_waitcnt vmcnt(0)" ::: "memory"); __syncthreads();
;   const int nk = K >> 6;
;   for (int kt = 0; kt < nk; ++kt) {
;     const bool more = kt + 1 < nk;
;     const int nb = (kt + 1) & 1;
;     const char* as = As + (kt & 1) * 32768; const char* bs = Bs + (kt & 1) * 32768;
; #pragma unroll
;     for (int ks = 0; ks < 4; ++ks) {
;       if (more) { glds16(Ap + (long)ks * 64 * lda + (kt + 1) * 64, As + nb * 32768 + soff + ks * 8192);
;                   if (ks < NB) glds16(Bp + (long)ks * 64 * ldb + (kt + 1) * 64, Bs + nb * 32768 + soff + ks * 8192); }
;       SBAR();
;       bf16x8 xf[MI], wf[NI];
; #pragma unroll
;       for (int mi = 0; mi < MI; ++mi) xf[mi] = *reinterpret_cast<const bf16x8*>(as + swz128(wm * (MI * 32) + mi * 32 + r32, ks * 2 + hi));
; #pragma unroll
;       for (int ni = 0; ni < NI; ++ni) wf[ni] = *reinterpret_cast<const bf16x8*>(bs + swz128(wn * (NI * 32) + ni * 32 + r32, ks * 2 + hi));
; #pragma unroll
;       for (int mi = 0; mi < MI; ++mi)
; #pragma unroll
;         for (int ni = 0; ni < NI; ++ni) acc[mi][ni] = __builtin_amdgcn_mfma_f32_32x32x16_bf16(wf[ni], xf[mi], acc[mi][ni], 0, 0, 0);
;     }
.LBB0_358:
	s_mul_i32 s2, s54, 0xc0
	s_mul_i32 s3, s51, 0x300
	s_add_i32 s3, s2, s3
	s_lshl_b32 s3, s3, 9
	s_add_u32 s60, s36, s3
	s_addc_u32 s61, s38, 0
	s_lshl_b32 s3, s55, 8
	v_mov_b32_e32 v100, v226
	s_and_b32 s3, s3, 0x3f00
	s_add_i32 s22, 0, 0x10000
	v_ashrrev_i32_e32 v0, 3, v100
	v_lshrrev_b32_e32 v1, 4, v100
	v_add_u32_e32 v2, s3, v0
	v_xor_b32_e32 v1, v1, v100
	v_ashrrev_i32_e32 v3, 31, v2
	v_lshlrev_b32_e32 v5, 4, v100
	v_lshlrev_b64 v[2:3], 9, v[2:3]
	v_lshlrev_b32_e32 v1, 4, v1
	v_add_u32_e32 v120, 0, v5
	v_lshl_add_u64 v[2:3], s[6:7], 0, v[2:3]
	v_and_b32_e32 v184, 0x70, v1
	v_readfirstlane_b32 s82, v120
	v_add_u32_e32 v6, 0x2000, v120
	v_lshl_add_u64 v[96:97], v[2:3], 0, v[184:185]
	v_ashrrev_i32_e32 v1, 31, v0
	s_mov_b32 m0, s82
	v_readfirstlane_b32 s79, v6
	v_add_u32_e32 v6, 0x4000, v120
	v_lshlrev_b64 v[0:1], 9, v[0:1]
	global_load_lds_dwordx4 v[96:97], off
	v_lshl_add_u64 v[2:3], v[96:97], 0, s[40:41]
	s_mov_b32 m0, s79
	v_readfirstlane_b32 s65, v6
	v_lshl_add_u64 v[0:1], s[60:61], 0, v[0:1]
	global_load_lds_dwordx4 v[2:3], off
	v_lshl_add_u64 v[2:3], v[96:97], 0, s[28:29]
	s_mov_b32 m0, s65
	s_mov_b64 s[60:61], 0x18000
	v_add_u32_e32 v6, 0x6000, v120
	global_load_lds_dwordx4 v[2:3], off
	v_lshl_add_u64 v[2:3], v[96:97], 0, s[60:61]
	v_readfirstlane_b32 s60, v6
	s_mov_b32 m0, s60
	v_add_u32_e32 v121, s22, v5
	global_load_lds_dwordx4 v[2:3], off
	v_readfirstlane_b32 s81, v121
	v_add_u32_e32 v2, 0x2000, v121
	v_lshl_add_u64 v[98:99], v[0:1], 0, v[184:185]
	s_mov_b32 m0, s81
	v_readfirstlane_b32 s75, v2
	v_add_u32_e32 v2, 0x4000, v121
	global_load_lds_dwordx4 v[98:99], off
	v_lshl_add_u64 v[0:1], v[98:99], 0, s[40:41]
	s_mov_b32 m0, s75
	v_readfirstlane_b32 s61, v2
	v_and_b32_e32 v101, 31, v100
	global_load_lds_dwordx4 v[0:1], off
	v_lshl_add_u64 v[0:1], v[98:99], 0, s[28:29]
	s_mov_b32 m0, s61
	v_add_u32_e32 v5, 0x8000, v120
	v_ashrrev_i32_e32 v103, 6, v100
	global_load_lds_dwordx4 v[0:1], off
	v_lshlrev_b32_e32 v1, 7, v101
	v_add_u32_e32 v6, 0x8000, v121
	v_readfirstlane_b32 s62, v5
	v_lshlrev_b32_e32 v0, 12, v103
	v_add_u32_e32 v124, s22, v1
	v_lshl_add_u64 v[2:3], v[96:97], 0, s[30:31]
	s_mov_b32 m0, s62
	v_readfirstlane_b32 s22, v6
	s_waitcnt vmcnt(0)
	s_waitcnt vmcnt(0) lgkmcnt(0)
	s_barrier
	v_add3_u32 v123, 0, v0, v1
	v_lshl_add_u64 v[0:1], v[98:99], 0, s[30:31]
	global_load_lds_dwordx4 v[2:3], off
	s_mov_b32 m0, s22
	v_lshrrev_b32_e32 v4, 5, v100
	global_load_lds_dwordx4 v[0:1], off
	v_bfe_u32 v102, v100, 5, 1
	v_bfe_u32 v122, v100, 1, 3
	v_bitop3_b32 v0, v4, v122, 1 bitop3:0x6c
	v_lshlrev_b32_e32 v4, 4, v0
	v_add_u32_e32 v104, v124, v4
	ds_read_b128 v[0:3], v104
	v_add_u32_e32 v125, v123, v4
	ds_read_b128 v[16:19], v125
	v_add_u32_e32 v26, 0xa000, v121
	v_lshl_add_u64 v[24:25], v[96:97], 0, s[42:43]
	v_readfirstlane_b32 s63, v26
	s_waitcnt lgkmcnt(0)
	v_mfma_f32_32x32x16_bf16 v[80:95], v[0:3], v[16:19], 0
	ds_read_b128 v[0:3], v104 offset:4096
	ds_read_b128 v[4:7], v104 offset:8192
	s_waitcnt lgkmcnt(0)
	v_mfma_f32_32x32x16_bf16 v[64:79], v[0:3], v[16:19], 0
	v_mfma_f32_32x32x16_bf16 v[48:63], v[4:7], v[16:19], 0
	ds_read_b128 v[0:3], v104 offset:12288
	ds_read_b128 v[4:7], v104 offset:16384
	ds_read_b128 v[20:23], v104 offset:20480
	s_waitcnt lgkmcnt(0)
	v_mfma_f32_32x32x16_bf16 v[32:47], v[0:3], v[16:19], 0
	v_add_u32_e32 v0, 0xa000, v120
	s_nop 0
	v_readfirstlane_b32 s74, v0
	s_mov_b32 m0, s74
	s_nop 0
	global_load_lds_dwordx4 v[24:25], off
	v_lshl_add_u64 v[24:25], v[98:99], 0, s[42:43]
	s_mov_b32 m0, s63
	v_mfma_f32_32x32x16_bf16 v[0:15], v[4:7], v[16:19], 0
	global_load_lds_dwordx4 v[24:25], off
	v_mfma_f32_32x32x16_bf16 v[16:31], v[20:23], v[16:19], 0
	v_bitop3_b32 v105, v102, v122, 2 bitop3:0x36
	v_lshlrev_b32_e32 v110, 4, v105
	v_add_u32_e32 v105, v124, v110
	ds_read_b128 v[106:109], v105
	v_add_u32_e32 v126, v123, v110
	ds_read_b128 v[110:113], v126
	v_add_u32_e32 v127, 0xc000, v120
	s_mov_b64 s[86:87], 0x10080
	v_readfirstlane_b32 s78, v127
	v_lshl_add_u64 v[118:119], v[96:97], 0, s[86:87]
	s_mov_b32 m0, s78
	s_waitcnt lgkmcnt(0)
	v_mfma_f32_32x32x16_bf16 v[80:95], v[106:109], v[110:113], v[80:95]
	ds_read_b128 v[106:109], v105 offset:4096
	ds_read_b128 v[114:117], v105 offset:8192
	s_waitcnt lgkmcnt(0)
	v_mfma_f32_32x32x16_bf16 v[64:79], v[106:109], v[110:113], v[64:79]
	v_mfma_f32_32x32x16_bf16 v[48:63], v[114:117], v[110:113], v[48:63]
	ds_read_b128 v[106:109], v105 offset:12288
	ds_read_b128 v[114:117], v105 offset:16384
	s_waitcnt lgkmcnt(0)
	v_mfma_f32_32x32x16_bf16 v[0:15], v[114:117], v[110:113], v[0:15]
	v_add_u32_e32 v116, 0xc000, v121
	v_lshl_add_u64 v[114:115], v[98:99], 0, s[86:87]
	v_readfirstlane_b32 s64, v116
	v_mfma_f32_32x32x16_bf16 v[32:47], v[106:109], v[110:113], v[32:47]
	ds_read_b128 v[106:109], v105 offset:20480
	global_load_lds_dwordx4 v[118:119], off
	s_mov_b32 m0, s64
	s_nop 0
	global_load_lds_dwordx4 v[114:115], off
	s_waitcnt lgkmcnt(0)
	v_mfma_f32_32x32x16_bf16 v[16:31], v[106:109], v[110:113], v[16:31]
	v_bitop3_b32 v106, v102, v122, 4 bitop3:0x36
	v_lshlrev_b32_e32 v110, 4, v106
	v_add_u32_e32 v118, v124, v110
	ds_read_b128 v[106:109], v118
	v_add_u32_e32 v119, v123, v110
	ds_read_b128 v[110:113], v119
	s_mov_b64 s[86:87], 0x18080
	s_waitcnt lgkmcnt(0)
	v_mfma_f32_32x32x16_bf16 v[80:95], v[106:109], v[110:113], v[80:95]
	ds_read_b128 v[106:109], v118 offset:4096
	ds_read_b128 v[114:117], v118 offset:8192
	s_waitcnt lgkmcnt(0)
	v_mfma_f32_32x32x16_bf16 v[64:79], v[106:109], v[110:113], v[64:79]
	v_mfma_f32_32x32x16_bf16 v[48:63], v[114:117], v[110:113], v[48:63]
	ds_read_b128 v[106:109], v118 offset:12288
	ds_read_b128 v[114:117], v118 offset:16384
	s_waitcnt lgkmcnt(0)
; #define SBAR() __builtin_amdgcn_sched_barrier(0)
; DEV void glds16(const u16* g, char* l) { __builtin_amdgcn_global_load_lds((const unsigned*)g, (unsigned*)l, 16, 0, 0); }
; template <int WM, int WN, int BN, int EPI>
; DEV void gemm_tile(const u16* __restrict__ A, int lda, const u16* __restrict__ Bt, int ldb, int K, int m0, char* lds,
;                    const Params& P, int layer, int batch, int nt) {
;     ...
;   for (int kt = 0; kt < nk; ++kt) {
;     const bool more = kt + 1 < nk;
;     const int nb = (kt + 1) & 1;
;     const char* as = As + (kt & 1) * 32768; const char* bs = Bs + (kt & 1) * 32768;
; #pragma unroll
;     for (int ks = 0; ks < 4; ++ks) {
;       if (more) { glds16(Ap + (long)ks * 64 * lda + (kt + 1) * 64, As + nb * 32768 + soff + ks * 8192);
;                   if (ks < NB) glds16(Bp + (long)ks * 64 * ldb + (kt + 1) * 64, Bs + nb * 32768 + soff + ks * 8192); }
;       SBAR();
;       bf16x8 xf[MI], wf[NI];
; #pragma unroll
;       for (int mi = 0; mi < MI; ++mi) xf[mi] = *reinterpret_cast<const bf16x8*>(as + swz128(wm * (MI * 32) + mi * 32 + r32, ks * 2 + hi));
; #pragma unroll
;       for (int ni = 0; ni < NI; ++ni) wf[ni] = *reinterpret_cast<const bf16x8*>(bs + swz128(wn * (NI * 32) + ni * 32 + r32, ks * 2 + hi));
; #pragma unroll
;       for (int mi = 0; mi < MI; ++mi)
; #pragma unroll
;         for (int ni = 0; ni < NI; ++ni) acc[mi][ni] = __builtin_amdgcn_mfma_f32_32x32x16_bf16(wf[ni], xf[mi], acc[mi][ni], 0, 0, 0);
;     }
	v_mfma_f32_32x32x16_bf16 v[0:15], v[114:117], v[110:113], v[0:15]
	v_add_u32_e32 v116, 0xe000, v120
	v_lshl_add_u64 v[114:115], v[96:97], 0, s[86:87]
	v_readfirstlane_b32 s80, v116
	s_mov_b32 m0, s80
	v_mfma_f32_32x32x16_bf16 v[32:47], v[106:109], v[110:113], v[32:47]
	ds_read_b128 v[106:109], v118 offset:20480
	global_load_lds_dwordx4 v[114:115], off
	s_waitcnt lgkmcnt(0)
	v_mfma_f32_32x32x16_bf16 v[16:31], v[106:109], v[110:113], v[16:31]
	v_bitop3_b32 v106, v102, v122, 6 bitop3:0x36
	v_lshlrev_b32_e32 v110, 4, v106
	v_add_u32_e32 v124, v124, v110
	ds_read_b128 v[106:109], v124
	v_add_u32_e32 v120, v123, v110
	ds_read_b128 v[110:113], v120
	s_mov_b32 m0, s82
	s_mov_b64 s[82:83], 0x100
	s_waitcnt lgkmcnt(0)
	v_mfma_f32_32x32x16_bf16 v[80:95], v[106:109], v[110:113], v[80:95]
	ds_read_b128 v[106:109], v124 offset:4096
	ds_read_b128 v[114:117], v124 offset:8192
	s_waitcnt lgkmcnt(0)
	v_mfma_f32_32x32x16_bf16 v[64:79], v[106:109], v[110:113], v[64:79]
	v_mfma_f32_32x32x16_bf16 v[48:63], v[114:117], v[110:113], v[48:63]
	ds_read_b128 v[106:109], v124 offset:12288
	ds_read_b128 v[114:117], v124 offset:16384
	s_waitcnt lgkmcnt(0)
	v_mfma_f32_32x32x16_bf16 v[0:15], v[114:117], v[110:113], v[0:15]
	v_lshl_add_u64 v[116:117], v[96:97], 0, s[82:83]
	v_lshl_add_u64 v[114:115], v[98:99], 0, s[82:83]
	v_mfma_f32_32x32x16_bf16 v[32:47], v[106:109], v[110:113], v[32:47]
	ds_read_b128 v[106:109], v124 offset:20480
	s_waitcnt vmcnt(0)
	s_waitcnt vmcnt(0) lgkmcnt(0)
	s_barrier
	global_load_lds_dwordx4 v[116:117], off
	s_mov_b32 m0, s81
	v_mfma_f32_32x32x16_bf16 v[16:31], v[106:109], v[110:113], v[16:31]
	global_load_lds_dwordx4 v[114:115], off
	ds_read_b128 v[106:109], v104 offset:32768
	ds_read_b128 v[110:113], v125 offset:32768
	s_mov_b64 s[82:83], 0x8100
	s_mov_b32 m0, s79
	s_waitcnt lgkmcnt(0)
	v_mfma_f32_32x32x16_bf16 v[80:95], v[106:109], v[110:113], v[80:95]
	ds_read_b128 v[106:109], v104 offset:36864
	ds_read_b128 v[114:117], v104 offset:40960
	s_waitcnt lgkmcnt(0)
	v_mfma_f32_32x32x16_bf16 v[64:79], v[106:109], v[110:113], v[64:79]
	v_mfma_f32_32x32x16_bf16 v[48:63], v[114:117], v[110:113], v[48:63]
	ds_read_b128 v[106:109], v104 offset:45056
	ds_read_b128 v[114:117], v104 offset:49152
	s_waitcnt lgkmcnt(0)
	v_mfma_f32_32x32x16_bf16 v[0:15], v[114:117], v[110:113], v[0:15]
	v_lshl_add_u64 v[114:115], v[96:97], 0, s[82:83]
	v_mfma_f32_32x32x16_bf16 v[32:47], v[106:109], v[110:113], v[32:47]
	ds_read_b128 v[106:109], v104 offset:53248
	global_load_lds_dwordx4 v[114:115], off
	v_lshl_add_u64 v[114:115], v[98:99], 0, s[82:83]
	s_mov_b32 m0, s75
	s_nop 0
	global_load_lds_dwordx4 v[114:115], off
	s_waitcnt lgkmcnt(0)
	v_mfma_f32_32x32x16_bf16 v[16:31], v[106:109], v[110:113], v[16:31]
	ds_read_b128 v[106:109], v105 offset:32768
	ds_read_b128 v[110:113], v126 offset:32768
	s_mov_b64 s[82:83], 0x10100
	s_mov_b32 m0, s65
	s_waitcnt lgkmcnt(0)
	v_mfma_f32_32x32x16_bf16 v[80:95], v[106:109], v[110:113], v[80:95]
	ds_read_b128 v[106:109], v105 offset:36864
	ds_read_b128 v[114:117], v105 offset:40960
	s_waitcnt lgkmcnt(0)
	v_mfma_f32_32x32x16_bf16 v[64:79], v[106:109], v[110:113], v[64:79]
	v_mfma_f32_32x32x16_bf16 v[48:63], v[114:117], v[110:113], v[48:63]
	ds_read_b128 v[106:109], v105 offset:45056
	ds_read_b128 v[114:117], v105 offset:49152
	s_waitcnt lgkmcnt(0)
	v_mfma_f32_32x32x16_bf16 v[0:15], v[114:117], v[110:113], v[0:15]
	v_lshl_add_u64 v[114:115], v[96:97], 0, s[82:83]
	v_mfma_f32_32x32x16_bf16 v[32:47], v[106:109], v[110:113], v[32:47]
	ds_read_b128 v[106:109], v105 offset:53248
	global_load_lds_dwordx4 v[114:115], off
	v_lshl_add_u64 v[114:115], v[98:99], 0, s[82:83]
	s_mov_b32 m0, s61
	s_nop 0
	global_load_lds_dwordx4 v[114:115], off
	s_waitcnt lgkmcnt(0)
	v_mfma_f32_32x32x16_bf16 v[16:31], v[106:109], v[110:113], v[16:31]
	ds_read_b128 v[106:109], v118 offset:32768
	ds_read_b128 v[110:113], v119 offset:32768
	s_mov_b32 m0, s60
	s_mov_b64 s[60:61], 0x18100
	s_waitcnt lgkmcnt(0)
	v_mfma_f32_32x32x16_bf16 v[80:95], v[106:109], v[110:113], v[80:95]
	ds_read_b128 v[106:109], v118 offset:36864
	ds_read_b128 v[114:117], v118 offset:40960
	s_waitcnt lgkmcnt(0)
	v_mfma_f32_32x32x16_bf16 v[64:79], v[106:109], v[110:113], v[64:79]
	v_mfma_f32_32x32x16_bf16 v[48:63], v[114:117], v[110:113], v[48:63]
	ds_read_b128 v[106:109], v118 offset:45056
	ds_read_b128 v[114:117], v118 offset:49152
	s_waitcnt lgkmcnt(0)
	v_mfma_f32_32x32x16_bf16 v[0:15], v[114:117], v[110:113], v[0:15]
	v_lshl_add_u64 v[114:115], v[96:97], 0, s[60:61]
	v_mfma_f32_32x32x16_bf16 v[32:47], v[106:109], v[110:113], v[32:47]
	ds_read_b128 v[106:109], v118 offset:53248
	global_load_lds_dwordx4 v[114:115], off
	s_waitcnt lgkmcnt(0)
	v_mfma_f32_32x32x16_bf16 v[16:31], v[106:109], v[110:113], v[16:31]
	ds_read_b128 v[106:109], v124 offset:32768
	ds_read_b128 v[110:113], v120 offset:32768
	s_mov_b64 s[60:61], 0x180
	s_mov_b32 m0, s62
	s_waitcnt lgkmcnt(0)
	v_mfma_f32_32x32x16_bf16 v[80:95], v[106:109], v[110:113], v[80:95]
	ds_read_b128 v[106:109], v124 offset:36864
	ds_read_b128 v[114:117], v124 offset:40960
	s_waitcnt lgkmcnt(0)
	v_mfma_f32_32x32x16_bf16 v[64:79], v[106:109], v[110:113], v[64:79]
	v_mfma_f32_32x32x16_bf16 v[48:63], v[114:117], v[110:113], v[48:63]
	ds_read_b128 v[106:109], v124 offset:45056
	ds_read_b128 v[114:117], v124 offset:49152
	s_waitcnt lgkmcnt(0)
	v_mfma_f32_32x32x16_bf16 v[0:15], v[114:117], v[110:113], v[0:15]
	v_lshl_add_u64 v[116:117], v[96:97], 0, s[60:61]
	v_lshl_add_u64 v[114:115], v[98:99], 0, s[60:61]
	v_mfma_f32_32x32x16_bf16 v[32:47], v[106:109], v[110:113], v[32:47]
	ds_read_b128 v[106:109], v124 offset:53248
	s_waitcnt vmcnt(0)
	s_waitcnt vmcnt(0) lgkmcnt(0)
	s_barrier
; #define SBAR() __builtin_amdgcn_sched_barrier(0)
; DEV void glds16(const u16* g, char* l) { __builtin_amdgcn_global_load_lds((const unsigned*)g, (unsigned*)l, 16, 0, 0); }
; template <int WM, int WN, int BN, int EPI>
; DEV void gemm_tile(const u16* __restrict__ A, int lda, const u16* __restrict__ Bt, int ldb, int K, int m0, char* lds,
;                    const Params& P, int layer, int batch, int nt) {
;     ...
;   for (int kt = 0; kt < nk; ++kt) {
;     const bool more = kt + 1 < nk;
;     const int nb = (kt + 1) & 1;
;     const char* as = As + (kt & 1) * 32768; const char* bs = Bs + (kt & 1) * 32768;
; #pragma unroll
;     for (int ks = 0; ks < 4; ++ks) {
;       if (more) { glds16(Ap + (long)ks * 64 * lda + (kt + 1) * 64, As + nb * 32768 + soff + ks * 8192);
;                   if (ks < NB) glds16(Bp + (long)ks * 64 * ldb + (kt + 1) * 64, Bs + nb * 32768 + soff + ks * 8192); }
;       SBAR();
;       bf16x8 xf[MI], wf[NI];
; #pragma unroll
;       for (int mi = 0; mi < MI; ++mi) xf[mi] = *reinterpret_cast<const bf16x8*>(as + swz128(wm * (MI * 32) + mi * 32 + r32, ks * 2 + hi));
; #pragma unroll
;       for (int ni = 0; ni < NI; ++ni) wf[ni] = *reinterpret_cast<const bf16x8*>(bs + swz128(wn * (NI * 32) + ni * 32 + r32, ks * 2 + hi));
; #pragma unroll
;       for (int mi = 0; mi < MI; ++mi)
; #pragma unroll
;         for (int ni = 0; ni < NI; ++ni) acc[mi][ni] = __builtin_amdgcn_mfma_f32_32x32x16_bf16(wf[ni], xf[mi], acc[mi][ni], 0, 0, 0);
;     }
;     asm volatile("s_waitcnt vmcnt(0)" ::: "memory");
;     __syncthreads();
;   }
	global_load_lds_dwordx4 v[116:117], off
	s_mov_b32 m0, s22
	v_mfma_f32_32x32x16_bf16 v[16:31], v[106:109], v[110:113], v[16:31]
	global_load_lds_dwordx4 v[114:115], off
	ds_read_b128 v[106:109], v104
	ds_read_b128 v[110:113], v125
	s_mov_b64 s[60:61], 0x8180
	s_mov_b32 m0, s74
	s_waitcnt lgkmcnt(0)
	v_mfma_f32_32x32x16_bf16 v[80:95], v[106:109], v[110:113], v[80:95]
	ds_read_b128 v[106:109], v104 offset:4096
	ds_read_b128 v[114:117], v104 offset:8192
	s_waitcnt lgkmcnt(0)
	v_mfma_f32_32x32x16_bf16 v[64:79], v[106:109], v[110:113], v[64:79]
	v_mfma_f32_32x32x16_bf16 v[48:63], v[114:117], v[110:113], v[48:63]
	ds_read_b128 v[106:109], v104 offset:12288
	ds_read_b128 v[114:117], v104 offset:16384
	s_waitcnt lgkmcnt(0)
	v_mfma_f32_32x32x16_bf16 v[0:15], v[114:117], v[110:113], v[0:15]
	v_lshl_add_u64 v[114:115], v[96:97], 0, s[60:61]
	v_mfma_f32_32x32x16_bf16 v[32:47], v[106:109], v[110:113], v[32:47]
	ds_read_b128 v[106:109], v104 offset:20480
	global_load_lds_dwordx4 v[114:115], off
	v_lshl_add_u64 v[114:115], v[98:99], 0, s[60:61]
	s_mov_b32 m0, s63
	s_nop 0
	global_load_lds_dwordx4 v[114:115], off
	s_waitcnt lgkmcnt(0)
	v_mfma_f32_32x32x16_bf16 v[16:31], v[106:109], v[110:113], v[16:31]
	ds_read_b128 v[106:109], v105
	ds_read_b128 v[110:113], v126
	s_mov_b64 s[60:61], 0x10180
	s_mov_b32 m0, s78
	v_lshl_add_u64 v[98:99], v[98:99], 0, s[60:61]
	s_waitcnt lgkmcnt(0)
	v_mfma_f32_32x32x16_bf16 v[80:95], v[106:109], v[110:113], v[80:95]
	ds_read_b128 v[106:109], v105 offset:4096
	ds_read_b128 v[114:117], v105 offset:8192
	s_waitcnt lgkmcnt(0)
	v_mfma_f32_32x32x16_bf16 v[64:79], v[106:109], v[110:113], v[64:79]
	v_mfma_f32_32x32x16_bf16 v[48:63], v[114:117], v[110:113], v[48:63]
	ds_read_b128 v[106:109], v105 offset:12288
	ds_read_b128 v[114:117], v105 offset:16384
	s_waitcnt lgkmcnt(0)
	v_mfma_f32_32x32x16_bf16 v[0:15], v[114:117], v[110:113], v[0:15]
	v_lshl_add_u64 v[114:115], v[96:97], 0, s[60:61]
	v_mfma_f32_32x32x16_bf16 v[32:47], v[106:109], v[110:113], v[32:47]
	ds_read_b128 v[106:109], v105 offset:20480
	global_load_lds_dwordx4 v[114:115], off
	s_mov_b32 m0, s64
	s_nop 0
	global_load_lds_dwordx4 v[98:99], off
	s_waitcnt lgkmcnt(0)
	v_mfma_f32_32x32x16_bf16 v[16:31], v[106:109], v[110:113], v[16:31]
	ds_read_b128 v[106:109], v118
	ds_read_b128 v[110:113], v119
	s_mov_b64 s[60:61], 0x18180
	s_mov_b32 m0, s80
	v_lshl_add_u64 v[96:97], v[96:97], 0, s[60:61]
	s_waitcnt lgkmcnt(0)
	v_mfma_f32_32x32x16_bf16 v[80:95], v[106:109], v[110:113], v[80:95]
	ds_read_b128 v[106:109], v118 offset:4096
	ds_read_b128 v[114:117], v118 offset:8192
	s_waitcnt lgkmcnt(0)
	v_mfma_f32_32x32x16_bf16 v[64:79], v[106:109], v[110:113], v[64:79]
	v_mfma_f32_32x32x16_bf16 v[48:63], v[114:117], v[110:113], v[48:63]
	ds_read_b128 v[106:109], v118 offset:12288
	ds_read_b128 v[114:117], v118 offset:16384
	s_waitcnt lgkmcnt(0)
	v_mfma_f32_32x32x16_bf16 v[32:47], v[106:109], v[110:113], v[32:47]
	ds_read_b128 v[106:109], v118 offset:20480
	global_load_lds_dwordx4 v[96:97], off
	v_mfma_f32_32x32x16_bf16 v[0:15], v[114:117], v[110:113], v[0:15]
	s_waitcnt lgkmcnt(0)
	v_mfma_f32_32x32x16_bf16 v[16:31], v[106:109], v[110:113], v[16:31]
	ds_read_b128 v[96:99], v124
	ds_read_b128 v[106:109], v120
	s_waitcnt lgkmcnt(0)
	v_mfma_f32_32x32x16_bf16 v[80:95], v[96:99], v[106:109], v[80:95]
	ds_read_b128 v[96:99], v124 offset:4096
	s_waitcnt lgkmcnt(0)
	v_mfma_f32_32x32x16_bf16 v[64:79], v[96:99], v[106:109], v[64:79]
	ds_read_b128 v[96:99], v124 offset:8192
	s_waitcnt lgkmcnt(0)
	v_mfma_f32_32x32x16_bf16 v[48:63], v[96:99], v[106:109], v[48:63]
	ds_read_b128 v[96:99], v124 offset:12288
	s_waitcnt lgkmcnt(0)
	v_mfma_f32_32x32x16_bf16 v[32:47], v[96:99], v[106:109], v[32:47]
	ds_read_b128 v[96:99], v124 offset:16384
	s_waitcnt lgkmcnt(0)
	v_mfma_f32_32x32x16_bf16 v[0:15], v[96:99], v[106:109], v[0:15]
	ds_read_b128 v[96:99], v124 offset:20480
	s_waitcnt vmcnt(0)
	s_waitcnt vmcnt(0) lgkmcnt(0)
	s_barrier
	v_mfma_f32_32x32x16_bf16 v[16:31], v[96:99], v[106:109], v[16:31]
	ds_read_b128 v[96:99], v104 offset:32768
	ds_read_b128 v[106:109], v125 offset:32768
	s_waitcnt lgkmcnt(0)
	v_mfma_f32_32x32x16_bf16 v[80:95], v[96:99], v[106:109], v[80:95]
	ds_read_b128 v[96:99], v104 offset:36864
	s_waitcnt lgkmcnt(0)
	v_mfma_f32_32x32x16_bf16 v[64:79], v[96:99], v[106:109], v[64:79]
	ds_read_b128 v[96:99], v104 offset:40960
	s_waitcnt lgkmcnt(0)
	v_mfma_f32_32x32x16_bf16 v[48:63], v[96:99], v[106:109], v[48:63]
	ds_read_b128 v[96:99], v104 offset:45056
	s_waitcnt lgkmcnt(0)
	v_mfma_f32_32x32x16_bf16 v[32:47], v[96:99], v[106:109], v[32:47]
	ds_read_b128 v[96:99], v104 offset:49152
	s_waitcnt lgkmcnt(0)
	v_mfma_f32_32x32x16_bf16 v[0:15], v[96:99], v[106:109], v[0:15]
	ds_read_b128 v[96:99], v104 offset:53248
	s_waitcnt lgkmcnt(0)
	v_mfma_f32_32x32x16_bf16 v[16:31], v[96:99], v[106:109], v[16:31]
	ds_read_b128 v[96:99], v105 offset:32768
	ds_read_b128 v[106:109], v126 offset:32768
	s_waitcnt lgkmcnt(0)
	v_mfma_f32_32x32x16_bf16 v[80:95], v[96:99], v[106:109], v[80:95]
	ds_read_b128 v[96:99], v105 offset:36864
	s_waitcnt lgkmcnt(0)
	v_mfma_f32_32x32x16_bf16 v[64:79], v[96:99], v[106:109], v[64:79]
	ds_read_b128 v[96:99], v105 offset:40960
	s_waitcnt lgkmcnt(0)
	v_mfma_f32_32x32x16_bf16 v[48:63], v[96:99], v[106:109], v[48:63]
	ds_read_b128 v[96:99], v105 offset:45056
	s_waitcnt lgkmcnt(0)
	v_mfma_f32_32x32x16_bf16 v[32:47], v[96:99], v[106:109], v[32:47]
	ds_read_b128 v[96:99], v105 offset:49152
	s_waitcnt lgkmcnt(0)
	v_mfma_f32_32x32x16_bf16 v[0:15], v[96:99], v[106:109], v[0:15]
	ds_read_b128 v[96:99], v105 offset:53248
	s_waitcnt lgkmcnt(0)
	v_mfma_f32_32x32x16_bf16 v[16:31], v[96:99], v[106:109], v[16:31]
	ds_read_b128 v[96:99], v118 offset:32768
	ds_read_b128 v[104:107], v119 offset:32768
	s_waitcnt lgkmcnt(0)
	v_mfma_f32_32x32x16_bf16 v[80:95], v[96:99], v[104:107], v[80:95]
	ds_read_b128 v[96:99], v118 offset:36864
	s_waitcnt lgkmcnt(0)
	v_mfma_f32_32x32x16_bf16 v[64:79], v[96:99], v[104:107], v[64:79]
	ds_read_b128 v[96:99], v118 offset:40960
	s_waitcnt lgkmcnt(0)
	v_mfma_f32_32x32x16_bf16 v[48:63], v[96:99], v[104:107], v[48:63]
	ds_read_b128 v[96:99], v118 offset:45056
	s_waitcnt lgkmcnt(0)
	v_mfma_f32_32x32x16_bf16 v[32:47], v[96:99], v[104:107], v[32:47]
	ds_read_b128 v[96:99], v118 offset:49152
	s_waitcnt lgkmcnt(0)
	v_mfma_f32_32x32x16_bf16 v[0:15], v[96:99], v[104:107], v[0:15]
	ds_read_b128 v[96:99], v118 offset:53248
	s_waitcnt lgkmcnt(0)
	v_mfma_f32_32x32x16_bf16 v[16:31], v[96:99], v[104:107], v[16:31]
	ds_read_b128 v[96:99], v124 offset:32768
	ds_read_b128 v[104:107], v120 offset:32768
	ds_read_b128 v[108:111], v124 offset:36864
	ds_read_b128 v[112:115], v124 offset:40960
	ds_read_b128 v[116:119], v124 offset:45056
	ds_read_b128 v[120:123], v124 offset:49152
	ds_read_b128 v[124:127], v124 offset:53248
	s_waitcnt vmcnt(0)
	s_waitcnt lgkmcnt(5)
	v_mfma_f32_32x32x16_bf16 v[80:95], v[96:99], v[104:107], v[80:95]
	v_lshl_add_u32 v99, v103, 5, s3
	v_or_b32_e32 v96, v99, v101
	v_ashrrev_i32_e32 v97, 31, v96
	s_mov_b32 s3, 0x20000
	s_waitcnt lgkmcnt(0)
	s_barrier
; DEV void epi_uq(f32x16 (&acc)[1][6], const Params& P, int layer, int batch, int m0, int head, int wid, int r32, int hi, char* lds) {
;   const int t = m0 + wid * 32 + r32;
;   const float rc = __builtin_amdgcn_rsqf((WS{P.ws}.ssq_cq()[t] + WS{P.ws}.ssq_cq()[TB + t] + WS{P.ws}.ssq_cq()[2 * TB + t] + WS{P.ws}.ssq_cq()[3 * TB + t]) * (1.f / 256.f) + EPS);
;   float s = 0.f;
; #pragma unroll
;   for (int ni = 0; ni < 6; ++ni)
; #pragma unroll
;     for (int r = 0; r < 16; ++r) { acc[0][ni][r] *= rc; s += acc[0][ni][r] * acc[0][ni][r]; }
;   s = swapsum(s);
;   constexpr float SCQ = 0.07216878364870323f * LOG2E;
;   const float inv = __builtin_amdgcn_rsqf(s * (1.f / 192.f) + EPS) * SCQ;
	v_mfma_f32_32x32x16_bf16 v[64:79], v[108:111], v[104:107], v[64:79]
	v_lshl_add_u64 v[108:109], v[96:97], 2, s[8:9]
	v_add_co_u32_e32 v110, vcc, s93, v108
	v_lshlrev_b32_e32 v184, 4, v102
	s_nop 0
	v_addc_co_u32_e32 v111, vcc, 0, v109, vcc
	s_lshl_b32 s22, s2, 1
	v_mfma_f32_32x32x16_bf16 v[48:63], v[112:115], v[104:107], v[48:63]
	v_add_co_u32_e32 v112, vcc, s3, v108
	s_mov_b32 s3, 0x30000
	s_nop 0
	v_addc_co_u32_e32 v113, vcc, 0, v109, vcc
	v_add_co_u32_e32 v114, vcc, s3, v108
	v_mfma_f32_32x32x16_bf16 v[32:47], v[116:119], v[104:107], v[32:47]
	s_nop 0
	v_addc_co_u32_e32 v115, vcc, 0, v109, vcc
	global_load_dword v97, v[108:109], off
	global_load_dword v98, v[110:111], off
	s_nop 0
	global_load_dword v108, v[112:113], off
	global_load_dword v109, v[114:115], off
	s_movk_i32 s3, 0xfff
	s_waitcnt vmcnt(0) lgkmcnt(0)
	v_add_f32_e32 v97, v97, v98
	v_add_f32_e32 v97, v97, v108
	v_add_f32_e32 v97, v97, v109
	v_fmamk_f32 v97, v97, 0x3b800000, v227
	v_rsq_f32_e32 v98, v97
	v_mfma_f32_32x32x16_bf16 v[0:15], v[120:123], v[104:107], v[0:15]
	v_mul_f32_e32 v108, v81, v98
	v_mul_f32_e32 v97, v80, v98
	v_mul_f32_e32 v113, v86, v98
	v_mul_f32_e32 v86, v108, v108
	v_mul_f32_e32 v109, v82, v98
	v_fmac_f32_e32 v86, v97, v97
	v_mul_f32_e32 v110, v83, v98
	v_fmac_f32_e32 v86, v109, v109
	v_mul_f32_e32 v111, v84, v98
	v_fmac_f32_e32 v86, v110, v110
	v_mul_f32_e32 v112, v85, v98
	v_fmac_f32_e32 v86, v111, v111
	v_fmac_f32_e32 v86, v112, v112
	v_mul_f32_e32 v114, v87, v98
	v_fmac_f32_e32 v86, v113, v113
	v_mul_f32_e32 v115, v88, v98
	v_fmac_f32_e32 v86, v114, v114
	v_mul_f32_e32 v116, v89, v98
	v_fmac_f32_e32 v86, v115, v115
	v_mul_f32_e32 v117, v90, v98
	v_fmac_f32_e32 v86, v116, v116
	v_mul_f32_e32 v118, v91, v98
	v_fmac_f32_e32 v86, v117, v117
	v_mul_f32_e32 v119, v92, v98
	v_fmac_f32_e32 v86, v118, v118
	v_mul_f32_e32 v120, v93, v98
	v_fmac_f32_e32 v86, v119, v119
	v_mul_f32_e32 v121, v94, v98
	v_fmac_f32_e32 v86, v120, v120
	v_mul_f32_e32 v122, v95, v98
	v_fmac_f32_e32 v86, v121, v121
	v_mul_f32_e32 v123, v64, v98
	v_fmac_f32_e32 v86, v122, v122
	v_mfma_f32_32x32x16_bf16 v[16:31], v[124:127], v[104:107], v[16:31]
	v_mul_f32_e32 v124, v65, v98
	v_fmac_f32_e32 v86, v123, v123
	v_mul_f32_e32 v125, v66, v98
	v_fmac_f32_e32 v86, v124, v124
	v_mul_f32_e32 v126, v67, v98
	v_fmac_f32_e32 v86, v125, v125
	v_mul_f32_e32 v127, v68, v98
	v_fmac_f32_e32 v86, v126, v126
	v_mul_f32_e32 v128, v69, v98
	v_fmac_f32_e32 v86, v127, v127
	v_mul_f32_e32 v129, v70, v98
	v_fmac_f32_e32 v86, v128, v128
	v_mul_f32_e32 v130, v71, v98
	v_fmac_f32_e32 v86, v129, v129
	v_mul_f32_e32 v80, v72, v98
	v_fmac_f32_e32 v86, v130, v130
	v_mul_f32_e32 v81, v73, v98
	v_fmac_f32_e32 v86, v80, v80
	v_mul_f32_e32 v82, v74, v98
	v_fmac_f32_e32 v86, v81, v81
	v_mul_f32_e32 v83, v75, v98
	v_fmac_f32_e32 v86, v82, v82
	v_mul_f32_e32 v72, v76, v98
	v_fmac_f32_e32 v86, v83, v83
	v_mul_f32_e32 v73, v77, v98
	v_fmac_f32_e32 v86, v72, v72
	v_mul_f32_e32 v74, v78, v98
	v_fmac_f32_e32 v86, v73, v73
	v_mul_f32_e32 v75, v79, v98
	v_fmac_f32_e32 v86, v74, v74
	v_mul_f32_e32 v131, v36, v98
	v_mul_f32_e32 v132, v37, v98
	v_lshl_add_u64 v[36:37], s[10:11], 0, v[184:185]
	v_mul_f32_e32 v68, v48, v98
	v_mul_f32_e32 v70, v50, v98
	v_mul_f32_e32 v71, v51, v98
	v_mul_f32_e32 v66, v54, v98
	v_mul_f32_e32 v67, v55, v98
	v_mul_f32_e32 v54, v56, v98
	v_mul_f32_e32 v55, v57, v98
	v_mul_f32_e32 v56, v58, v98
	v_mul_f32_e32 v57, v59, v98
	v_mul_f32_e32 v50, v60, v98
	v_mul_f32_e32 v51, v61, v98
	v_fmac_f32_e32 v86, v75, v75
	global_load_dwordx4 v[58:61], v[36:37], off offset:1280
	global_load_dwordx4 v[194:197], v[36:37], off offset:1312
	global_load_dwordx4 v[198:201], v[36:37], off offset:1344
	global_load_dwordx4 v[202:205], v[36:37], off offset:1376
	global_load_dwordx4 v[206:209], v[36:37], off offset:1408
	global_load_dwordx4 v[210:213], v[36:37], off offset:1440
	global_load_dwordx4 v[214:217], v[36:37], off offset:1472
	global_load_dwordx4 v[218:221], v[36:37], off offset:1504
	global_load_dwordx4 v[222:225], v[36:37], off offset:1536
	global_load_dwordx4 v[232:235], v[36:37], off offset:1568
	global_load_dwordx4 v[236:239], v[36:37], off offset:1600
	global_load_dwordx4 v[240:243], v[36:37], off offset:1632
	global_load_dwordx4 v[244:247], v[36:37], off offset:1664
	global_load_dwordx4 v[248:251], v[36:37], off offset:1696
	global_load_dwordx4 v[170:173], v[36:37], off offset:1728
	global_load_dwordx4 v[174:177], v[36:37], off offset:1760
	v_mul_f32_e32 v69, v49, v98
	v_fmac_f32_e32 v86, v68, v68
	v_fmac_f32_e32 v86, v69, v69
	v_fmac_f32_e32 v86, v70, v70
	v_mul_f32_e32 v64, v52, v98
	v_fmac_f32_e32 v86, v71, v71
	v_mul_f32_e32 v65, v53, v98
	v_fmac_f32_e32 v86, v64, v64
	v_fmac_f32_e32 v86, v65, v65
	v_fmac_f32_e32 v86, v66, v66
	v_fmac_f32_e32 v86, v67, v67
	v_fmac_f32_e32 v86, v54, v54
	v_fmac_f32_e32 v86, v55, v55
	v_fmac_f32_e32 v86, v56, v56
	v_fmac_f32_e32 v86, v57, v57
	v_fmac_f32_e32 v86, v50, v50
	v_mul_f32_e32 v52, v62, v98
	v_fmac_f32_e32 v86, v51, v51
	v_mul_f32_e32 v53, v63, v98
	v_fmac_f32_e32 v86, v52, v52
	v_mul_f32_e32 v48, v32, v98
	v_fmac_f32_e32 v86, v53, v53
	v_mul_f32_e32 v33, v33, v98
	v_fmac_f32_e32 v86, v48, v48
	v_mul_f32_e32 v49, v34, v98
	v_fmac_f32_e32 v86, v33, v33
	v_mul_f32_e32 v35, v35, v98
	v_fmac_f32_e32 v86, v49, v49
	v_fmac_f32_e32 v86, v35, v35
	v_fmac_f32_e32 v86, v131, v131
	v_fmac_f32_e32 v86, v132, v132
	v_mul_f32_e32 v133, v38, v98
	v_fmac_f32_e32 v86, v133, v133
	v_mul_f32_e32 v134, v39, v98
	v_fmac_f32_e32 v86, v134, v134
	v_mul_f32_e32 v135, v40, v98
	v_fmac_f32_e32 v86, v135, v135
	v_mul_f32_e32 v136, v41, v98
	v_fmac_f32_e32 v86, v136, v136
	v_mul_f32_e32 v137, v42, v98
; DEV void epi_uq(f32x16 (&acc)[1][6], const Params& P, int layer, int batch, int m0, int head, int wid, int r32, int hi, char* lds) {
;     ...
;   float s = 0.f;
; #pragma unroll
;   for (int ni = 0; ni < 6; ++ni)
; #pragma unroll
;     for (int r = 0; r < 16; ++r) { acc[0][ni][r] *= rc; s += acc[0][ni][r] * acc[0][ni][r]; }
;   s = swapsum(s);
;   constexpr float SCQ = 0.07216878364870323f * LOG2E;
;   const float inv = __builtin_amdgcn_rsqf(s * (1.f / 192.f) + EPS) * SCQ;
;   const float* g = WS{P.ws}.consts() + layer * 1024 + 320;
;   char* slab = lds + wid * 12800; char* dst = slab + r32 * 400;
; #pragma unroll
;   for (int ni = 0; ni < 4; ++ni)
; #pragma unroll
;     for (int r4 = 0; r4 < 4; ++r4) {
;       const int c = ni * 32 + r4 * 8 + hi * 4;
;       const float4 gg = *reinterpret_cast<const float4*>(g + c);
;       const f32x16& a = acc[0][ni];
;       st4lds(dst, c, a[r4 * 4] * inv * gg.x, a[r4 * 4 + 1] * inv * gg.y, a[r4 * 4 + 2] * inv * gg.z, a[r4 * 4 + 3] * inv * gg.w);
;     }
	v_fmac_f32_e32 v86, v137, v137
	v_mul_f32_e32 v138, v43, v98
	v_fmac_f32_e32 v86, v138, v138
	v_mul_f32_e32 v139, v44, v98
	v_fmac_f32_e32 v86, v139, v139
	v_mul_f32_e32 v140, v45, v98
	v_mul_f32_e32 v34, v14, v98
	v_mul_lo_u32 v14, v103, s99
	v_fmac_f32_e32 v86, v140, v140
	v_mul_f32_e32 v141, v46, v98
	v_mul_f32_e32 v32, v15, v98
	v_add_u32_e32 v46, 0, v14
	v_mov_b32_e32 v14, v2
	v_mov_b32_e32 v15, v18
	v_mov_b32_e32 v18, v3
	v_mov_b32_e32 v2, v0
	v_mov_b32_e32 v3, v16
	v_fmac_f32_e32 v86, v141, v141
	v_mul_f32_e32 v47, v47, v98
	v_pk_mul_f32 v[42:43], v[2:3], v[98:99] op_sel_hi:[1,0]
	v_mov_b32_e32 v16, v1
	v_fmac_f32_e32 v86, v47, v47
	v_pk_mul_f32 v[84:85], v[42:43], v[42:43]
	v_pk_mul_f32 v[44:45], v[16:17], v[98:99] op_sel_hi:[1,0]
	v_pk_mul_f32 v[14:15], v[14:15], v[98:99] op_sel_hi:[1,0]
	v_add_f32_e32 v0, v84, v86
	v_pk_mul_f32 v[86:87], v[44:45], v[44:45]
	v_pk_mul_f32 v[76:77], v[14:15], v[14:15]
	v_pk_mul_f32 v[40:41], v[18:19], v[98:99] op_sel_hi:[1,0]
	v_add_f32_e32 v0, v86, v0
	v_pk_mul_f32 v[78:79], v[40:41], v[40:41]
	v_add_f32_e32 v0, v76, v0
	v_add_f32_e32 v16, v78, v0
	v_mov_b32_e32 v0, v6
	v_mov_b32_e32 v1, v22
	v_mov_b32_e32 v22, v7
	v_mov_b32_e32 v6, v4
	v_mov_b32_e32 v7, v20
	v_pk_mul_f32 v[6:7], v[6:7], v[98:99] op_sel_hi:[1,0]
	v_mov_b32_e32 v20, v5
	v_pk_mul_f32 v[92:93], v[6:7], v[6:7]
	v_pk_mul_f32 v[4:5], v[20:21], v[98:99] op_sel_hi:[1,0]
	v_pk_mul_f32 v[0:1], v[0:1], v[98:99] op_sel_hi:[1,0]
	v_add_f32_e32 v16, v92, v16
	v_pk_mul_f32 v[20:21], v[4:5], v[4:5]
	v_pk_mul_f32 v[88:89], v[0:1], v[0:1]
	v_pk_mul_f32 v[2:3], v[22:23], v[98:99] op_sel_hi:[1,0]
	v_add_f32_e32 v16, v20, v16
	v_pk_mul_f32 v[90:91], v[2:3], v[2:3]
	v_add_f32_e32 v16, v88, v16
	v_add_f32_e32 v18, v90, v16
	v_mov_b32_e32 v16, v10
	v_mov_b32_e32 v17, v26
	v_pk_mul_f32 v[22:23], v[16:17], v[98:99] op_sel_hi:[1,0]
	v_mov_b32_e32 v16, v8
	v_mov_b32_e32 v17, v24
	v_pk_mul_f32 v[38:39], v[16:17], v[98:99] op_sel_hi:[1,0]
	v_mov_b32_e32 v24, v9
	v_pk_mul_f32 v[104:105], v[38:39], v[38:39]
	v_pk_mul_f32 v[24:25], v[24:25], v[98:99] op_sel_hi:[1,0]
	v_mov_b32_e32 v26, v11
	v_add_f32_e32 v16, v104, v18
	v_pk_mul_f32 v[8:9], v[24:25], v[24:25]
	v_pk_mul_f32 v[94:95], v[22:23], v[22:23]
	v_pk_mul_f32 v[26:27], v[26:27], v[98:99] op_sel_hi:[1,0]
	v_add_f32_e32 v8, v8, v16
	v_mov_b32_e32 v16, v12
	v_mov_b32_e32 v17, v28
	v_pk_mul_f32 v[10:11], v[26:27], v[26:27]
	v_add_f32_e32 v8, v94, v8
	v_pk_mul_f32 v[16:17], v[16:17], v[98:99] op_sel_hi:[1,0]
	v_mov_b32_e32 v28, v13
	v_add_f32_e32 v8, v10, v8
	v_pk_mul_f32 v[106:107], v[16:17], v[16:17]
	v_pk_mul_f32 v[18:19], v[28:29], v[98:99] op_sel_hi:[1,0]
	v_add_f32_e32 v8, v106, v8
	v_pk_mul_f32 v[12:13], v[18:19], v[18:19]
	v_pk_mul_f32 v[30:31], v[30:31], v[98:99] op_sel_hi:[1,0]
	v_add_f32_e32 v8, v12, v8
	v_fmac_f32_e32 v8, v34, v34
	v_fmac_f32_e32 v8, v32, v32
	v_add_f32_e32 v8, v85, v8
	v_add_f32_e32 v8, v87, v8
	v_add_f32_e32 v8, v77, v8
	v_add_f32_e32 v8, v79, v8
	v_add_f32_e32 v8, v93, v8
	v_add_f32_e32 v8, v21, v8
	v_add_f32_e32 v8, v89, v8
	v_add_f32_e32 v8, v91, v8
	v_add_f32_e32 v8, v105, v8
	v_add_f32_e32 v8, v9, v8
	v_add_f32_e32 v8, v95, v8
	v_add_f32_e32 v8, v11, v8
	v_add_f32_e32 v8, v107, v8
	v_pk_mul_f32 v[62:63], v[30:31], v[30:31]
	v_add_f32_e32 v8, v13, v8
	v_add_f32_e32 v8, v62, v8
	v_add_f32_e32 v8, v63, v8
	v_mov_b32_e32 v9, v8
	s_nop 1
	v_permlane32_swap_b32_e32 v8, v9
	v_add_f32_e32 v8, v8, v9
	v_fmamk_f32 v8, v8, 0x3baaaaab, v227
	v_rsq_f32_e32 v8, v8
	v_mul_u32_u24_e32 v9, 0x190, v101
	v_lshlrev_b32_e32 v10, 3, v102
	v_add3_u32 v21, v46, v9, v10
	v_mul_f32_e32 v20, 0x3dd53b94, v8
	v_mul_f32_e32 v8, v97, v20
	v_mul_f32_e32 v9, v108, v20
	s_waitcnt vmcnt(0) lgkmcnt(0)
	v_mul_f32_e32 v8, v58, v8
	v_mul_f32_e32 v9, v59, v9
	v_mul_f32_e32 v10, v109, v20
	v_mul_f32_e32 v11, v110, v20
	v_mul_f32_e32 v10, v60, v10
	v_mul_f32_e32 v11, v61, v11
	v_cvt_pk_bf16_f32 v8, v8, v9
	v_cvt_pk_bf16_f32 v9, v10, v11
	ds_write_b64 v21, v[8:9]
	v_mul_f32_e32 v12, v111, v20
	v_mul_f32_e32 v13, v116, v20
	v_mul_f32_e32 v28, v117, v20
	v_mul_f32_e32 v29, v118, v20
	v_lshlrev_b32_e32 v184, 5, v102
	v_pk_mul_f32 v[14:15], v[14:15], v[20:21] op_sel_hi:[1,0]
	v_pk_mul_f32 v[40:41], v[40:41], v[20:21] op_sel_hi:[1,0]
	v_pk_mul_f32 v[6:7], v[6:7], v[20:21] op_sel_hi:[1,0]
	v_pk_mul_f32 v[4:5], v[4:5], v[20:21] op_sel_hi:[1,0]
	v_pk_mul_f32 v[0:1], v[0:1], v[20:21] op_sel_hi:[1,0]
	v_pk_mul_f32 v[2:3], v[2:3], v[20:21] op_sel_hi:[1,0]
	v_pk_mul_f32 v[38:39], v[38:39], v[20:21] op_sel_hi:[1,0]
	v_pk_mul_f32 v[24:25], v[24:25], v[20:21] op_sel_hi:[1,0]
	v_pk_mul_f32 v[22:23], v[22:23], v[20:21] op_sel_hi:[1,0]
	v_pk_mul_f32 v[26:27], v[26:27], v[20:21] op_sel_hi:[1,0]
	v_pk_mul_f32 v[16:17], v[16:17], v[20:21] op_sel_hi:[1,0]
	v_pk_mul_f32 v[18:19], v[18:19], v[20:21] op_sel_hi:[1,0]
	s_waitcnt vmcnt(0) lgkmcnt(0)
	v_mul_f32_e32 v8, v194, v12
	v_mul_f32_e32 v12, v112, v20
	v_mul_f32_e32 v9, v12, v195
	v_mul_f32_e32 v12, v113, v20
	v_mul_f32_e32 v10, v12, v196
	v_mul_f32_e32 v12, v114, v20
	v_mul_f32_e32 v11, v12, v197
	v_cvt_pk_bf16_f32 v8, v8, v9
	v_cvt_pk_bf16_f32 v9, v10, v11
	ds_write_b64 v21, v[8:9] offset:16
	v_mul_f32_e32 v12, v115, v20
	s_waitcnt vmcnt(0) lgkmcnt(0)
	v_mul_f32_e32 v8, v12, v198
	v_mul_f32_e32 v9, v13, v199
	v_mul_f32_e32 v10, v28, v200
	v_mul_f32_e32 v11, v29, v201
	v_cvt_pk_bf16_f32 v8, v8, v9
	v_cvt_pk_bf16_f32 v9, v10, v11
	ds_write_b64 v21, v[8:9] offset:32
	v_mul_f32_e32 v12, v119, v20
	v_mul_f32_e32 v13, v120, v20
	v_mul_f32_e32 v28, v121, v20
	v_mul_f32_e32 v29, v122, v20
	s_waitcnt vmcnt(0) lgkmcnt(0)
; DEV void epi_uq(f32x16 (&acc)[1][6], const Params& P, int layer, int batch, int m0, int head, int wid, int r32, int hi, char* lds) {
;     ...
; #pragma unroll
;   for (int ni = 0; ni < 4; ++ni)
; #pragma unroll
;     for (int r4 = 0; r4 < 4; ++r4) {
;       const int c = ni * 32 + r4 * 8 + hi * 4;
;       const float4 gg = *reinterpret_cast<const float4*>(g + c);
;       const f32x16& a = acc[0][ni];
;       st4lds(dst, c, a[r4 * 4] * inv * gg.x, a[r4 * 4 + 1] * inv * gg.y, a[r4 * 4 + 2] * inv * gg.z, a[r4 * 4 + 3] * inv * gg.w);
;     }
;   const int pos = batch ? t : (t & 4095);
;   const float2* rp = WS{P.ws}.rope() + (long)pos * 32;
; #pragma unroll
;   for (int r4 = 0; r4 < 4; ++r4) {
;     const int i = r4 * 8 + hi * 4;
;     const float4 g1 = *reinterpret_cast<const float4*>(g + 128 + i), g2 = *reinterpret_cast<const float4*>(g + 160 + i);
;     const float4 cs01 = *reinterpret_cast<const float4*>(rp + i), cs23 = *reinterpret_cast<const float4*>(rp + i + 2);
;     const float x1[4] = {acc[0][4][r4 * 4] * inv * g1.x, acc[0][4][r4 * 4 + 1] * inv * g1.y, acc[0][4][r4 * 4 + 2] * inv * g1.z, acc[0][4][r4 * 4 + 3] * inv * g1.w};
;     const float x2[4] = {acc[0][5][r4 * 4] * inv * g2.x, acc[0][5][r4 * 4 + 1] * inv * g2.y, acc[0][5][r4 * 4 + 2] * inv * g2.z, acc[0][5][r4 * 4 + 3] * inv * g2.w};
;     const float cc[4] = {cs01.x, cs01.z, cs23.x, cs23.z}, sn[4] = {cs01.y, cs01.w, cs23.y, cs23.w};
	v_mul_f32_e32 v8, v12, v202
	v_mul_f32_e32 v9, v13, v203
	v_mul_f32_e32 v10, v28, v204
	v_mul_f32_e32 v11, v29, v205
	v_cvt_pk_bf16_f32 v8, v8, v9
	v_cvt_pk_bf16_f32 v9, v10, v11
	ds_write_b64 v21, v[8:9] offset:48
	v_mul_f32_e32 v12, v123, v20
	v_mul_f32_e32 v13, v124, v20
	v_mul_f32_e32 v28, v125, v20
	v_mul_f32_e32 v29, v126, v20
	s_waitcnt vmcnt(0) lgkmcnt(0)
	v_mul_f32_e32 v8, v12, v206
	v_mul_f32_e32 v9, v13, v207
	v_mul_f32_e32 v10, v28, v208
	v_mul_f32_e32 v11, v29, v209
	v_cvt_pk_bf16_f32 v8, v8, v9
	v_cvt_pk_bf16_f32 v9, v10, v11
	ds_write_b64 v21, v[8:9] offset:64
	v_mul_f32_e32 v12, v127, v20
	v_mul_f32_e32 v13, v128, v20
	v_mul_f32_e32 v28, v129, v20
	v_mul_f32_e32 v29, v130, v20
	s_waitcnt vmcnt(0) lgkmcnt(0)
	v_mul_f32_e32 v8, v12, v210
	v_mul_f32_e32 v9, v13, v211
	v_mul_f32_e32 v10, v28, v212
	v_mul_f32_e32 v11, v29, v213
	v_cvt_pk_bf16_f32 v8, v8, v9
	v_cvt_pk_bf16_f32 v9, v10, v11
	ds_write_b64 v21, v[8:9] offset:80
	v_mul_f32_e32 v12, v80, v20
	v_mul_f32_e32 v13, v81, v20
	v_mul_f32_e32 v28, v82, v20
	v_mul_f32_e32 v29, v83, v20
	s_waitcnt vmcnt(0) lgkmcnt(0)
	v_mul_f32_e32 v8, v12, v214
	v_mul_f32_e32 v9, v13, v215
	v_mul_f32_e32 v10, v28, v216
	v_mul_f32_e32 v11, v29, v217
	v_cvt_pk_bf16_f32 v8, v8, v9
	v_cvt_pk_bf16_f32 v9, v10, v11
	ds_write_b64 v21, v[8:9] offset:96
	v_mul_f32_e32 v12, v72, v20
	v_mul_f32_e32 v13, v73, v20
	v_mul_f32_e32 v28, v74, v20
	v_mul_f32_e32 v29, v75, v20
	s_waitcnt vmcnt(0) lgkmcnt(0)
	v_mul_f32_e32 v8, v12, v218
	v_mul_f32_e32 v9, v13, v219
	v_mul_f32_e32 v10, v28, v220
	v_mul_f32_e32 v11, v29, v221
	v_cvt_pk_bf16_f32 v8, v8, v9
	v_cvt_pk_bf16_f32 v9, v10, v11
	ds_write_b64 v21, v[8:9] offset:112
	v_mul_f32_e32 v12, v68, v20
	v_mul_f32_e32 v13, v69, v20
	v_mul_f32_e32 v28, v70, v20
	v_mul_f32_e32 v29, v71, v20
	s_waitcnt vmcnt(0) lgkmcnt(0)
	v_mul_f32_e32 v8, v12, v222
	v_mul_f32_e32 v9, v13, v223
	v_mul_f32_e32 v10, v28, v224
	v_mul_f32_e32 v11, v29, v225
	v_cvt_pk_bf16_f32 v8, v8, v9
	v_cvt_pk_bf16_f32 v9, v10, v11
	ds_write_b64 v21, v[8:9] offset:128
	v_mul_f32_e32 v12, v64, v20
	v_mul_f32_e32 v13, v65, v20
	v_mul_f32_e32 v28, v66, v20
	v_mul_f32_e32 v29, v67, v20
	s_waitcnt vmcnt(0) lgkmcnt(0)
	v_mul_f32_e32 v8, v12, v232
	v_mul_f32_e32 v9, v13, v233
	v_mul_f32_e32 v10, v28, v234
	v_mul_f32_e32 v11, v29, v235
	v_cvt_pk_bf16_f32 v8, v8, v9
	v_cvt_pk_bf16_f32 v9, v10, v11
	ds_write_b64 v21, v[8:9] offset:144
	v_mul_f32_e32 v12, v54, v20
	v_mul_f32_e32 v13, v55, v20
	v_mul_f32_e32 v28, v56, v20
	v_mul_f32_e32 v29, v57, v20
	s_waitcnt vmcnt(0) lgkmcnt(0)
	v_mul_f32_e32 v8, v12, v236
	v_mul_f32_e32 v9, v13, v237
	v_mul_f32_e32 v10, v28, v238
	v_mul_f32_e32 v11, v29, v239
	v_cvt_pk_bf16_f32 v8, v8, v9
	v_cvt_pk_bf16_f32 v9, v10, v11
	ds_write_b64 v21, v[8:9] offset:160
	v_mul_f32_e32 v12, v50, v20
	v_mul_f32_e32 v13, v51, v20
	v_mul_f32_e32 v28, v52, v20
	v_mul_f32_e32 v29, v53, v20
	s_waitcnt vmcnt(0) lgkmcnt(0)
	v_mul_f32_e32 v8, v12, v240
	v_mul_f32_e32 v9, v13, v241
	v_mul_f32_e32 v10, v28, v242
	v_mul_f32_e32 v11, v29, v243
	v_cvt_pk_bf16_f32 v8, v8, v9
	v_cvt_pk_bf16_f32 v9, v10, v11
	ds_write_b64 v21, v[8:9] offset:176
	v_mul_f32_e32 v12, v48, v20
	v_mul_f32_e32 v13, v33, v20
	v_mul_f32_e32 v28, v49, v20
	v_mul_f32_e32 v29, v35, v20
	s_waitcnt vmcnt(0) lgkmcnt(0)
	v_mul_f32_e32 v8, v12, v244
	v_mul_f32_e32 v9, v13, v245
	v_mul_f32_e32 v10, v28, v246
	v_mul_f32_e32 v11, v29, v247
	v_cvt_pk_bf16_f32 v8, v8, v9
	v_cvt_pk_bf16_f32 v9, v10, v11
	ds_write_b64 v21, v[8:9] offset:192
	v_mul_f32_e32 v12, v131, v20
	v_mul_f32_e32 v13, v132, v20
	v_mul_f32_e32 v28, v133, v20
	v_mul_f32_e32 v29, v134, v20
	s_waitcnt vmcnt(0) lgkmcnt(0)
	v_mul_f32_e32 v8, v12, v248
	v_mul_f32_e32 v9, v13, v249
	v_mul_f32_e32 v10, v28, v250
	v_mul_f32_e32 v11, v29, v251
	v_cvt_pk_bf16_f32 v8, v8, v9
	v_cvt_pk_bf16_f32 v9, v10, v11
	ds_write_b64 v21, v[8:9] offset:208
	v_mul_f32_e32 v12, v135, v20
	v_mul_f32_e32 v13, v136, v20
	v_mul_f32_e32 v28, v137, v20
	v_mul_f32_e32 v29, v138, v20
	s_waitcnt vmcnt(0) lgkmcnt(0)
	v_mul_f32_e32 v8, v12, v170
	v_mul_f32_e32 v9, v13, v171
	v_mul_f32_e32 v10, v28, v172
	v_mul_f32_e32 v11, v29, v173
	v_cvt_pk_bf16_f32 v8, v8, v9
	v_cvt_pk_bf16_f32 v9, v10, v11
	ds_write_b64 v21, v[8:9] offset:224
	v_mul_f32_e32 v12, v139, v20
	v_mul_f32_e32 v13, v140, v20
	v_mul_f32_e32 v28, v141, v20
	v_mul_f32_e32 v29, v47, v20
	s_waitcnt vmcnt(0) lgkmcnt(0)
	v_mul_f32_e32 v8, v12, v174
	v_bitop3_b32 v12, v99, s3, v101 bitop3:0xc8
	v_cndmask_b32_e64 v12, v96, v12, s[26:27]
	v_mul_f32_e32 v9, v13, v175
	v_ashrrev_i32_e32 v13, 31, v12
	v_mul_f32_e32 v10, v28, v176
	v_mul_f32_e32 v11, v29, v177
	v_cvt_pk_bf16_f32 v8, v8, v9
	v_cvt_pk_bf16_f32 v9, v10, v11
	ds_write_b64 v21, v[8:9] offset:240
	v_lshlrev_b64 v[12:13], 8, v[12:13]
	global_load_dwordx4 v[8:11], v[36:37], off offset:1792
	global_load_dwordx4 v[48:51], v[36:37], off offset:1920
	v_lshl_add_u64 v[12:13], s[12:13], 0, v[12:13]
	v_lshl_add_u64 v[28:29], v[12:13], 0, v[184:185]
	global_load_dwordx4 v[52:55], v[28:29], off
	global_load_dwordx4 v[56:59], v[28:29], off offset:16
	v_pk_mul_f32 v[12:13], v[42:43], v[20:21] op_sel_hi:[1,0]
	v_pk_mul_f32 v[42:43], v[44:45], v[20:21] op_sel_hi:[1,0]
	s_waitcnt vmcnt(0) lgkmcnt(0)
; DEV void epi_uq(f32x16 (&acc)[1][6], const Params& P, int layer, int batch, int m0, int head, int wid, int r32, int hi, char* lds) {
;     ...
;   for (int r4 = 0; r4 < 4; ++r4) {
;     const int i = r4 * 8 + hi * 4;
;     const float4 g1 = *reinterpret_cast<const float4*>(g + 128 + i), g2 = *reinterpret_cast<const float4*>(g + 160 + i);
;     const float4 cs01 = *reinterpret_cast<const float4*>(rp + i), cs23 = *reinterpret_cast<const float4*>(rp + i + 2);
;     const float x1[4] = {acc[0][4][r4 * 4] * inv * g1.x, acc[0][4][r4 * 4 + 1] * inv * g1.y, acc[0][4][r4 * 4 + 2] * inv * g1.z, acc[0][4][r4 * 4 + 3] * inv * g1.w};
;     const float x2[4] = {acc[0][5][r4 * 4] * inv * g2.x, acc[0][5][r4 * 4 + 1] * inv * g2.y, acc[0][5][r4 * 4 + 2] * inv * g2.z, acc[0][5][r4 * 4 + 3] * inv * g2.w};
;     const float cc[4] = {cs01.x, cs01.z, cs23.x, cs23.z}, sn[4] = {cs01.y, cs01.w, cs23.y, cs23.w};
;     st4lds(dst, 128 + i, x1[0] * cc[0] - x2[0] * sn[0], x1[1] * cc[1] - x2[1] * sn[1], x1[2] * cc[2] - x2[2] * sn[2], x1[3] * cc[3] - x2[3] * sn[3]);
;     st4lds(dst, 160 + i, x1[0] * sn[0] + x2[0] * cc[0], x1[1] * sn[1] + x2[1] * cc[1], x1[2] * sn[2] + x2[2] * cc[2], x1[3] * sn[3] + x2[3] * cc[3]);
;   }
	v_mov_b32_e32 v44, v8
	v_mov_b32_e32 v45, v48
	v_mov_b32_e32 v48, v9
	v_mov_b32_e32 v8, v10
	v_mov_b32_e32 v9, v50
	v_mov_b32_e32 v50, v11
	v_pk_mul_f32 v[10:11], v[12:13], v[44:45]
	v_pk_mul_f32 v[12:13], v[42:43], v[48:49]
	v_pk_mul_f32 v[8:9], v[14:15], v[8:9]
	v_pk_mul_f32 v[14:15], v[40:41], v[50:51]
	v_pk_mul_f32 v[40:41], v[10:11], v[52:53]
	v_pk_mul_f32 v[42:43], v[12:13], v[54:55]
	v_pk_mul_f32 v[44:45], v[8:9], v[56:57]
	v_pk_mul_f32 v[48:49], v[14:15], v[58:59]
	v_pk_mul_f32 v[10:11], v[10:11], v[52:53] op_sel:[1,0] op_sel_hi:[0,1]
	v_pk_mul_f32 v[12:13], v[12:13], v[54:55] op_sel:[1,0] op_sel_hi:[0,1]
	v_pk_mul_f32 v[8:9], v[8:9], v[56:57] op_sel:[1,0] op_sel_hi:[0,1]
	v_pk_mul_f32 v[14:15], v[14:15], v[58:59] op_sel:[1,0] op_sel_hi:[0,1]
	v_sub_f32_e32 v33, v40, v41
	v_sub_f32_e32 v35, v42, v43
	v_sub_f32_e32 v40, v44, v45
	v_sub_f32_e32 v41, v48, v49
	v_add_f32_e32 v10, v10, v11
	v_add_f32_e32 v11, v12, v13
	v_add_f32_e32 v12, v8, v9
	v_cvt_pk_bf16_f32 v8, v33, v35
	v_cvt_pk_bf16_f32 v9, v40, v41
	v_add_f32_e32 v13, v14, v15
	ds_write_b64 v21, v[8:9] offset:256
	v_cvt_pk_bf16_f32 v8, v10, v11
	v_cvt_pk_bf16_f32 v9, v12, v13
	ds_write_b64 v21, v[8:9] offset:320
	global_load_dwordx4 v[8:11], v[36:37], off offset:1824
	global_load_dwordx4 v[12:15], v[36:37], off offset:1952
	global_load_dwordx4 v[40:43], v[28:29], off offset:64
	global_load_dwordx4 v[48:51], v[28:29], off offset:80
	v_and_b32_e32 v33, 63, v100
	v_mul_lo_u16_e32 v35, 43, v33
	v_or_b32_e32 v47, 0xc0, v33
	v_or_b32_e32 v52, 0x1c0, v33
	v_or_b32_e32 v53, 0x280, v33
	v_or_b32_e32 v54, 0x240, v33
	v_or_b32_e32 v55, 0x2c0, v33
	v_lshrrev_b16_e32 v35, 10, v35
	v_mul_lo_u16_e32 v56, 0xab, v47
	v_mul_u32_u24_e32 v60, 0xaab, v52
	v_mul_u32_u24_e32 v62, 0xaab, v54
	v_mul_u32_u24_e32 v63, 0xaab, v53
	v_mul_u32_u24_e32 v64, 0xaab, v55
	v_lshrrev_b16_e32 v56, 12, v56
	v_mul_u32_u24_e32 v65, 0x190, v35
	v_lshrrev_b32_e32 v71, 16, v63
	s_waitcnt vmcnt(0) lgkmcnt(0)
	v_mov_b32_e32 v44, v8
	v_mov_b32_e32 v45, v12
	v_mov_b32_e32 v12, v9
	v_mov_b32_e32 v8, v10
	v_mov_b32_e32 v9, v14
	v_mov_b32_e32 v14, v11
	v_pk_mul_f32 v[6:7], v[6:7], v[44:45]
	v_pk_mul_f32 v[4:5], v[4:5], v[12:13]
	v_pk_mul_f32 v[0:1], v[0:1], v[8:9]
	v_pk_mul_f32 v[2:3], v[2:3], v[14:15]
	v_pk_mul_f32 v[8:9], v[6:7], v[40:41]
	v_pk_mul_f32 v[10:11], v[4:5], v[42:43]
	v_pk_mul_f32 v[12:13], v[0:1], v[48:49]
	v_pk_mul_f32 v[14:15], v[2:3], v[50:51]
	v_pk_mul_f32 v[4:5], v[4:5], v[42:43] op_sel:[1,0] op_sel_hi:[0,1]
	v_pk_mul_f32 v[0:1], v[0:1], v[48:49] op_sel:[1,0] op_sel_hi:[0,1]
	v_pk_mul_f32 v[6:7], v[6:7], v[40:41] op_sel:[1,0] op_sel_hi:[0,1]
	v_pk_mul_f32 v[2:3], v[2:3], v[50:51] op_sel:[1,0] op_sel_hi:[0,1]
	v_sub_f32_e32 v8, v8, v9
	v_sub_f32_e32 v9, v10, v11
	v_sub_f32_e32 v10, v12, v13
	v_sub_f32_e32 v11, v14, v15
	v_add_f32_e32 v4, v4, v5
	v_add_f32_e32 v5, v0, v1
	v_cvt_pk_bf16_f32 v0, v8, v9
	v_cvt_pk_bf16_f32 v1, v10, v11
	v_add_f32_e32 v6, v6, v7
	v_add_f32_e32 v2, v2, v3
	ds_write_b64 v21, v[0:1] offset:272
	v_cvt_pk_bf16_f32 v0, v6, v4
	v_cvt_pk_bf16_f32 v1, v5, v2
	ds_write_b64 v21, v[0:1] offset:336
	global_load_dwordx4 v[12:15], v[36:37], off offset:1856
	global_load_dwordx4 v[8:11], v[36:37], off offset:1984
	global_load_dwordx4 v[0:3], v[28:29], off offset:128
	global_load_dwordx4 v[4:7], v[28:29], off offset:144
	v_or_b32_e32 v44, 64, v33
	v_or_b32_e32 v45, 0x80, v33
	v_mul_lo_u16_e32 v42, 43, v44
	v_mul_lo_u16_e32 v43, 0xab, v45
	v_lshrrev_b16_e32 v66, 10, v42
	v_lshrrev_b16_e32 v67, 12, v43
	v_or_b32_e32 v48, 0x100, v33
	v_or_b32_e32 v49, 0x180, v33
	v_or_b32_e32 v50, 0x140, v33
	v_or_b32_e32 v51, 0x200, v33
	v_mul_u32_u24_e32 v57, 0xaab, v48
	v_mul_u32_u24_e32 v58, 0xaab, v50
	v_mul_u32_u24_e32 v59, 0xaab, v49
	v_mul_u32_u24_e32 v61, 0xaab, v51
	v_mad_i32_i24 v33, v35, s58, v33
	v_lshrrev_b32_e32 v57, 16, v57
	v_lshrrev_b32_e32 v68, 16, v58
	v_lshrrev_b32_e32 v69, 16, v59
	v_perm_b32 v58, v59, v58, s44
	v_lshrrev_b32_e32 v59, 16, v60
	v_lshrrev_b32_e32 v70, 16, v61
	v_perm_b32 v60, v61, v60, s44
	v_lshrrev_b32_e32 v61, 16, v62
	v_perm_b32 v62, v63, v62, s44
	v_lshrrev_b32_e32 v63, 16, v64
	v_lshlrev_b32_e32 v64, 4, v33
	v_mul_u32_u24_e32 v35, 0x300, v35
	v_lshlrev_b32_e32 v184, 1, v35
	v_mov_b32_e32 v35, v30
	v_mov_b64_e32 v[40:41], s[14:15]
	v_mad_i64_i32 v[40:41], s[2:3], v99, s39, v[40:41]
	v_lshl_add_u64 v[40:41], v[40:41], 0, s[22:23]
	v_mad_i32_i24 v55, v63, s58, v55
	v_lshlrev_b32_e32 v80, 4, v55
	s_waitcnt vmcnt(0) lgkmcnt(0)
; #define LDSP(T) __attribute__((address_space(3))) T*
; template <int NCH, int STRIDE> DEV void slab_flush(char* slab, u16* grow0, int gstride, int lane) {
;   asm volatile("s_waitcnt lgkmcnt(0)" ::: "memory");
; #pragma unroll
;   for (int i = 0; i < NCH / 2; ++i) {
;     const int q = i * 64 + lane, row = q / NCH, cc = q - row * NCH;
;     const u32x4 v = *(LDSP(const u32x4))(slab + row * STRIDE + cc * 16);
;     *reinterpret_cast<u32x4*>(grow0 + (long)row * gstride + cc * 8) = v;
;   }
;   asm volatile("s_waitcnt lgkmcnt(0)" ::: "memory");
; }
; DEV void epi_uq(f32x16 (&acc)[1][6], const Params& P, int layer, int batch, int m0, int head, int wid, int r32, int hi, char* lds) {
;     ...
;   for (int r4 = 0; r4 < 4; ++r4) {
;     const int i = r4 * 8 + hi * 4;
;     const float4 g1 = *reinterpret_cast<const float4*>(g + 128 + i), g2 = *reinterpret_cast<const float4*>(g + 160 + i);
;     const float4 cs01 = *reinterpret_cast<const float4*>(rp + i), cs23 = *reinterpret_cast<const float4*>(rp + i + 2);
;     const float x1[4] = {acc[0][4][r4 * 4] * inv * g1.x, acc[0][4][r4 * 4 + 1] * inv * g1.y, acc[0][4][r4 * 4 + 2] * inv * g1.z, acc[0][4][r4 * 4 + 3] * inv * g1.w};
;     const float x2[4] = {acc[0][5][r4 * 4] * inv * g2.x, acc[0][5][r4 * 4 + 1] * inv * g2.y, acc[0][5][r4 * 4 + 2] * inv * g2.z, acc[0][5][r4 * 4 + 3] * inv * g2.w};
;     const float cc[4] = {cs01.x, cs01.z, cs23.x, cs23.z}, sn[4] = {cs01.y, cs01.w, cs23.y, cs23.w};
;     st4lds(dst, 128 + i, x1[0] * cc[0] - x2[0] * sn[0], x1[1] * cc[1] - x2[1] * sn[1], x1[2] * cc[2] - x2[2] * sn[2], x1[3] * cc[3] - x2[3] * sn[3]);
;     st4lds(dst, 160 + i, x1[0] * sn[0] + x2[0] * cc[0], x1[1] * sn[1] + x2[1] * cc[1], x1[2] * sn[2] + x2[2] * cc[2], x1[3] * sn[3] + x2[3] * cc[3]);
;   }
;   slab_flush<24, 400>(slab, WS{P.ws}.QB() + (long)(m0 + wid * 32) * 768 + head * 192, 768, hi * 32 + r32);
	v_mov_b32_e32 v42, v12
	v_mov_b32_e32 v43, v8
	v_mov_b32_e32 v8, v13
	v_mov_b32_e32 v12, v14
	v_mov_b32_e32 v13, v10
	v_mov_b32_e32 v10, v15
	v_pk_mul_f32 v[14:15], v[38:39], v[42:43]
	v_pk_mul_f32 v[8:9], v[24:25], v[8:9]
	v_pk_mul_f32 v[12:13], v[22:23], v[12:13]
	v_pk_mul_f32 v[10:11], v[26:27], v[10:11]
	v_pk_mul_f32 v[22:23], v[14:15], v[0:1]
	v_pk_mul_f32 v[24:25], v[8:9], v[2:3]
	v_pk_mul_f32 v[26:27], v[12:13], v[4:5]
	v_pk_mul_f32 v[38:39], v[10:11], v[6:7]
	v_pk_mul_f32 v[0:1], v[14:15], v[0:1] op_sel:[1,0] op_sel_hi:[0,1]
	v_pk_mul_f32 v[2:3], v[8:9], v[2:3] op_sel:[1,0] op_sel_hi:[0,1]
	v_pk_mul_f32 v[4:5], v[12:13], v[4:5] op_sel:[1,0] op_sel_hi:[0,1]
	v_pk_mul_f32 v[6:7], v[10:11], v[6:7] op_sel:[1,0] op_sel_hi:[0,1]
	v_sub_f32_e32 v8, v22, v23
	v_sub_f32_e32 v9, v24, v25
	v_sub_f32_e32 v10, v26, v27
	v_sub_f32_e32 v11, v38, v39
	v_add_f32_e32 v12, v0, v1
	v_cvt_pk_bf16_f32 v0, v8, v9
	v_cvt_pk_bf16_f32 v1, v10, v11
	v_add_f32_e32 v2, v2, v3
	v_add_f32_e32 v3, v4, v5
	v_add_f32_e32 v4, v6, v7
	ds_write_b64 v21, v[0:1] offset:288
	v_cvt_pk_bf16_f32 v0, v12, v2
	v_cvt_pk_bf16_f32 v1, v3, v4
	ds_write_b64 v21, v[0:1] offset:352
	global_load_dwordx4 v[0:3], v[36:37], off offset:1888
	global_load_dwordx4 v[4:7], v[36:37], off offset:2016
	global_load_dwordx4 v[8:11], v[28:29], off offset:192
	global_load_dwordx4 v[12:15], v[28:29], off offset:208
	v_lshlrev_b32_e32 v22, 3, v33
	v_mad_i32_i24 v24, v66, s58, v44
	v_mad_i32_i24 v33, v56, s58, v47
	v_mad_i32_i24 v29, v57, s58, v48
	v_mul_u32_u24_e32 v25, 0x190, v66
	v_mad_i32_i24 v26, v67, s58, v45
	v_mul_u32_u24_e32 v27, 0x190, v67
	v_mul_u32_u24_e32 v45, 0x300, v67
	v_mul_u32_u24_e32 v39, 0x190, v57
	v_pk_mul_lo_u16 v42, v58, s37 op_sel_hi:[1,0]
	v_mad_i32_i24 v43, v69, s58, v49
	v_mad_i32_i24 v44, v59, s58, v52
	v_mad_i32_i24 v52, v71, s58, v53
	v_add3_u32 v53, v46, v65, v64
	v_lshlrev_b32_e32 v64, 4, v24
	v_lshlrev_b32_e32 v67, 4, v33
	v_lshlrev_b32_e32 v28, 3, v33
	v_lshlrev_b32_e32 v33, 4, v29
	v_mul_u32_u24_e32 v37, 0x190, v56
	v_mul_u32_u24_e32 v47, 0x300, v56
	v_mul_u32_u24_e32 v56, 0x300, v57
	v_mad_i32_i24 v38, v68, s58, v50
	v_mul_u32_u24_e32 v57, 0x300, v68
	v_pk_mul_lo_u16 v48, v60, s37 op_sel_hi:[1,0]
	v_mad_i32_i24 v49, v70, s58, v51
	v_mul_u32_u24_e32 v60, 0x300, v70
	v_mad_i32_i24 v50, v61, s58, v54
	v_mul_u32_u24_e32 v54, 0x300, v61
	v_mul_u32_u24_e32 v61, 0x300, v71
	v_and_b32_e32 v68, 0xfff0, v42
	v_lshrrev_b32_e32 v70, 16, v42
	v_lshlrev_b32_e32 v71, 4, v43
	v_lshlrev_b32_e32 v42, 3, v43
	v_add3_u32 v43, v46, v25, v64
	v_add3_u32 v64, v46, v39, v33
	v_mov_b32_e32 v33, v31
	v_pk_mul_f32 v[30:31], v[34:35], v[20:21] op_sel_hi:[1,0]
	v_pk_mul_f32 v[32:33], v[32:33], v[20:21] op_sel_hi:[1,0]
	v_ashrrev_i32_e32 v23, 31, v22
	v_mul_u32_u24_e32 v66, 0x300, v66
	v_lshlrev_b32_e32 v24, 3, v24
	v_ashrrev_i32_e32 v25, 31, v24
	v_lshlrev_b32_e32 v65, 4, v26
	v_and_b32_e32 v72, 0xfff0, v48
	v_lshrrev_b32_e32 v74, 16, v48
	v_lshlrev_b32_e32 v75, 4, v49
	v_lshlrev_b32_e32 v48, 3, v49
	v_add3_u32 v49, v46, v27, v65
	v_lshlrev_b32_e32 v26, 3, v26
	v_ashrrev_i32_e32 v27, 31, v26
	v_pk_mul_lo_u16 v51, v62, s37 op_sel_hi:[1,0]
	v_lshlrev_b32_e32 v36, 3, v29
	v_and_b32_e32 v76, 0xfff0, v51
	v_lshrrev_b32_e32 v78, 16, v51
	v_add3_u32 v51, v46, v37, v67
	v_ashrrev_i32_e32 v29, 31, v28
	v_ashrrev_i32_e32 v37, 31, v36
	v_mul_u32_u24_e32 v58, 0x300, v69
	v_lshlrev_b32_e32 v69, 4, v38
	v_add3_u32 v65, v46, v68, v69
	v_lshlrev_b32_e32 v38, 3, v38
	v_ashrrev_i32_e32 v39, 31, v38
	v_lshlrev_b32_e32 v73, 4, v44
	v_mul_u32_u24_e32 v59, 0x300, v59
	v_lshlrev_b32_e32 v44, 3, v44
	v_lshlrev_b32_e32 v77, 4, v50
	v_lshlrev_b32_e32 v50, 3, v50
	v_lshlrev_b32_e32 v79, 4, v52
	v_lshlrev_b32_e32 v52, 3, v52
	v_mul_u32_u24_e32 v62, 0x190, v63
	v_mul_u32_u24_e32 v63, 0x300, v63
	s_waitcnt vmcnt(0) lgkmcnt(0)
	v_mov_b32_e32 v34, v0
	v_mov_b32_e32 v35, v4
	v_mov_b32_e32 v4, v1
	v_mov_b32_e32 v0, v2
	v_mov_b32_e32 v1, v6
	v_mov_b32_e32 v6, v3
	v_pk_mul_f32 v[2:3], v[16:17], v[34:35]
	v_pk_mul_f32 v[4:5], v[18:19], v[4:5]
	v_pk_mul_f32 v[0:1], v[30:31], v[0:1]
	v_pk_mul_f32 v[6:7], v[32:33], v[6:7]
	v_pk_mul_f32 v[16:17], v[2:3], v[8:9]
	v_pk_mul_f32 v[18:19], v[4:5], v[10:11]
	v_pk_mul_f32 v[30:31], v[0:1], v[12:13]
	v_pk_mul_f32 v[32:33], v[6:7], v[14:15]
	v_pk_mul_f32 v[2:3], v[2:3], v[8:9] op_sel:[1,0] op_sel_hi:[0,1]
	v_pk_mul_f32 v[4:5], v[4:5], v[10:11] op_sel:[1,0] op_sel_hi:[0,1]
	v_pk_mul_f32 v[0:1], v[0:1], v[12:13] op_sel:[1,0] op_sel_hi:[0,1]
	v_pk_mul_f32 v[6:7], v[6:7], v[14:15] op_sel:[1,0] op_sel_hi:[0,1]
	v_sub_f32_e32 v8, v16, v17
	v_sub_f32_e32 v9, v18, v19
	v_sub_f32_e32 v10, v30, v31
	v_sub_f32_e32 v11, v32, v33
	v_add_f32_e32 v2, v2, v3
	v_add_f32_e32 v3, v4, v5
	v_add_f32_e32 v4, v0, v1
	v_cvt_pk_bf16_f32 v0, v8, v9
	v_cvt_pk_bf16_f32 v1, v10, v11
	v_add_f32_e32 v5, v6, v7
	ds_write_b64 v21, v[0:1] offset:304
	v_cvt_pk_bf16_f32 v0, v2, v3
	v_cvt_pk_bf16_f32 v1, v4, v5
	ds_write_b64 v21, v[0:1] offset:368
	s_waitcnt lgkmcnt(0)
	ds_read_b128 v[0:3], v53
	v_lshl_add_u64 v[4:5], v[40:41], 0, v[184:185]
	v_lshl_add_u64 v[4:5], v[22:23], 1, v[4:5]
	v_lshlrev_b32_e32 v184, 1, v66
	v_add3_u32 v6, v46, v70, v71
	s_waitcnt lgkmcnt(0)
	global_store_dwordx4 v[4:5], v[0:3], off
	ds_read_b128 v[0:3], v43
	v_lshl_add_u64 v[4:5], v[40:41], 0, v[184:185]
	v_lshl_add_u64 v[4:5], v[24:25], 1, v[4:5]
	v_lshlrev_b32_e32 v184, 1, v45
	v_ashrrev_i32_e32 v43, 31, v42
	s_waitcnt lgkmcnt(0)
	global_store_dwordx4 v[4:5], v[0:3], off
	ds_read_b128 v[0:3], v49
	v_lshl_add_u64 v[4:5], v[40:41], 0, v[184:185]
	v_lshl_add_u64 v[4:5], v[26:27], 1, v[4:5]
	v_lshlrev_b32_e32 v184, 1, v47
	v_add3_u32 v7, v46, v72, v73
	s_waitcnt lgkmcnt(0)
; DEV int opaque_tid() { int t = threadIdx.x; asm volatile("" : "+v"(t)); return t; }
; #define LDSP(T) __attribute__((address_space(3))) T*
; #define GLOAD(kt, buf) do { _Pragma("unroll") for (int i = 0; i < 4; ++i) glds16(Ap + (long)i * 64 * lda + (kt) * 64, As + (buf) * 32768 + soff + i * 8192); \
;     _Pragma("unroll") for (int i = 0; i < NB; ++i) glds16(Bp + (long)i * 64 * ldb + (kt) * 64, Bs + (buf) * 32768 + soff + i * 8192); } while (0)
; template <int NCH, int STRIDE> DEV void slab_flush(char* slab, u16* grow0, int gstride, int lane) {
;   asm volatile("s_waitcnt lgkmcnt(0)" ::: "memory");
; #pragma unroll
;   for (int i = 0; i < NCH / 2; ++i) {
;     const int q = i * 64 + lane, row = q / NCH, cc = q - row * NCH;
;     const u32x4 v = *(LDSP(const u32x4))(slab + row * STRIDE + cc * 16);
;     *reinterpret_cast<u32x4*>(grow0 + (long)row * gstride + cc * 8) = v;
;   }
;   asm volatile("s_waitcnt lgkmcnt(0)" ::: "memory");
; }
; template <int WM, int WN, int BN, int EPI>
; DEV void gemm_tile(const u16* __restrict__ A, int lda, const u16* __restrict__ Bt, int ldb, int K, int m0, char* lds,
;                    const Params& P, int layer, int batch, int nt) {
;     ...
;   const int tid = opaque_tid(), wid = tid >> 6, lane = tid & 63, r32 = lane & 31, hi = lane >> 5;
;   const int wm = wid / WN, wn = wid % WN;
;   char* As = lds; char* Bs = lds + 65536;
;   f32x16 acc[MI][NI];
; #pragma unroll
;   for (int mi = 0; mi < MI; ++mi)
; #pragma unroll
;     for (int ni = 0; ni < NI; ++ni) acc[mi][ni] = f32x16{};
;   const int srow = tid >> 3, sch = (tid & 7) ^ ((srow >> 1) & 7);
;   const u16* Ap = A + (long)(m0 + srow) * lda + sch * 8;
;   const u16* Bp = Bt + (long)srow * ldb + sch * 8;
;   const int soff = tid * 16;
;     ...
;   GLOAD(0, 0); asm volatile("s_waitcnt vmcnt(0)" ::: "memory"); __syncthreads();
	global_store_dwordx4 v[4:5], v[0:3], off
	ds_read_b128 v[0:3], v51
	v_lshl_add_u64 v[4:5], v[40:41], 0, v[184:185]
	v_lshl_add_u64 v[4:5], v[28:29], 1, v[4:5]
	v_lshlrev_b32_e32 v184, 1, v56
	v_ashrrev_i32_e32 v45, 31, v44
	s_waitcnt lgkmcnt(0)
	global_store_dwordx4 v[4:5], v[0:3], off
	ds_read_b128 v[0:3], v64
	v_lshl_add_u64 v[4:5], v[40:41], 0, v[184:185]
	v_lshl_add_u64 v[4:5], v[36:37], 1, v[4:5]
	v_lshlrev_b32_e32 v184, 1, v57
	v_add3_u32 v8, v46, v74, v75
	s_waitcnt lgkmcnt(0)
	global_store_dwordx4 v[4:5], v[0:3], off
	ds_read_b128 v[0:3], v65
	v_lshl_add_u64 v[4:5], v[40:41], 0, v[184:185]
	v_lshl_add_u64 v[4:5], v[38:39], 1, v[4:5]
	v_lshlrev_b32_e32 v184, 1, v58
	v_ashrrev_i32_e32 v49, 31, v48
	s_waitcnt lgkmcnt(0)
	global_store_dwordx4 v[4:5], v[0:3], off
	ds_read_b128 v[0:3], v6
	v_lshl_add_u64 v[4:5], v[40:41], 0, v[184:185]
	v_lshl_add_u64 v[4:5], v[42:43], 1, v[4:5]
	v_lshlrev_b32_e32 v184, 1, v59
	v_add3_u32 v6, v46, v76, v77
	s_waitcnt lgkmcnt(0)
	global_store_dwordx4 v[4:5], v[0:3], off
	ds_read_b128 v[0:3], v7
	v_lshl_add_u64 v[4:5], v[40:41], 0, v[184:185]
	v_lshl_add_u64 v[4:5], v[44:45], 1, v[4:5]
	v_lshlrev_b32_e32 v184, 1, v60
	v_ashrrev_i32_e32 v51, 31, v50
	s_waitcnt lgkmcnt(0)
	global_store_dwordx4 v[4:5], v[0:3], off
	ds_read_b128 v[0:3], v8
	v_lshl_add_u64 v[4:5], v[40:41], 0, v[184:185]
	v_lshl_add_u64 v[4:5], v[48:49], 1, v[4:5]
	v_lshlrev_b32_e32 v184, 1, v54
	v_add3_u32 v7, v46, v78, v79
	s_waitcnt lgkmcnt(0)
	global_store_dwordx4 v[4:5], v[0:3], off
	ds_read_b128 v[0:3], v6
	v_lshl_add_u64 v[4:5], v[40:41], 0, v[184:185]
	v_lshl_add_u64 v[4:5], v[50:51], 1, v[4:5]
	v_lshlrev_b32_e32 v184, 1, v61
	v_ashrrev_i32_e32 v53, 31, v52
	s_waitcnt lgkmcnt(0)
	global_store_dwordx4 v[4:5], v[0:3], off
	ds_read_b128 v[0:3], v7
	v_lshl_add_u64 v[4:5], v[40:41], 0, v[184:185]
	v_lshl_add_u64 v[4:5], v[52:53], 1, v[4:5]
	v_add3_u32 v6, v46, v62, v80
	v_lshlrev_b32_e32 v184, 1, v63
	s_waitcnt lgkmcnt(0)
	global_store_dwordx4 v[4:5], v[0:3], off
	ds_read_b128 v[0:3], v6
	v_lshlrev_b32_e32 v6, 3, v55
	v_lshl_add_u64 v[4:5], v[40:41], 0, v[184:185]
	v_ashrrev_i32_e32 v7, 31, v6
	v_lshl_add_u64 v[4:5], v[6:7], 1, v[4:5]
	s_waitcnt lgkmcnt(0)
	global_store_dwordx4 v[4:5], v[0:3], off
	s_waitcnt lgkmcnt(0)
	s_waitcnt lgkmcnt(0)
	s_barrier
	s_cbranch_execnz .LBB0_355
.LBB0_359:
	s_lshl_b32 s2, s54, 16
	s_or_b32 s2, s2, s53
	s_add_u32 s60, s48, s2
	v_mov_b32_e32 v152, v226
	s_addc_u32 s61, s52, 0
	s_lshl_b32 s2, s55, 8
	s_mov_b64 s[62:63], 0xc000
	v_ashrrev_i32_e32 v0, 3, v152
	v_lshrrev_b32_e32 v1, 4, v152
	v_xor_b32_e32 v1, v1, v152
	v_add_u32_e32 v2, s2, v0
	v_ashrrev_i32_e32 v3, 31, v2
	v_lshlrev_b32_e32 v1, 4, v1
	v_lshlrev_b32_e32 v156, 4, v152
	v_lshlrev_b64 v[2:3], 8, v[2:3]
	v_and_b32_e32 v184, 0x70, v1
	v_ashrrev_i32_e32 v1, 31, v0
	v_add_u32_e32 v148, 0, v156
	v_lshl_add_u64 v[2:3], s[16:17], 0, v[2:3]
	v_lshlrev_b64 v[0:1], 8, v[0:1]
	v_readfirstlane_b32 s3, v148
	v_add_u32_e32 v5, 0x2000, v148
	v_lshl_add_u64 v[128:129], v[2:3], 0, v[184:185]
	v_lshl_add_u64 v[0:1], s[60:61], 0, v[0:1]
	s_mov_b32 m0, s3
	s_mov_b64 s[60:61], 0x4000
	v_readfirstlane_b32 s3, v5
	v_add_u32_e32 v5, 0x4000, v148
	global_load_lds_dwordx4 v[128:129], off
	v_lshl_add_u64 v[2:3], v[128:129], 0, s[60:61]
	s_mov_b32 m0, s3
	v_readfirstlane_b32 s3, v5
	v_add_u32_e32 v5, 0x6000, v148
	global_load_lds_dwordx4 v[2:3], off
	v_lshl_add_u64 v[2:3], v[128:129], 0, s[40:41]
	s_mov_b32 m0, s3
	v_readfirstlane_b32 s3, v5
	global_load_lds_dwordx4 v[2:3], off
	v_lshl_add_u64 v[2:3], v[128:129], 0, s[62:63]
	s_mov_b32 m0, s3
	s_add_i32 s3, 0, 0x10000
	global_load_lds_dwordx4 v[2:3], off
	v_add_u32_e32 v2, s3, v156
	v_add_u32_e32 v3, 0x2000, v2
	v_readfirstlane_b32 s22, v2
	v_lshl_add_u64 v[130:131], v[0:1], 0, v[184:185]
	s_mov_b32 m0, s22
	v_readfirstlane_b32 s22, v3
	v_add_u32_e32 v3, 0x4000, v2
	global_load_lds_dwordx4 v[130:131], off
	v_lshl_add_u64 v[0:1], v[130:131], 0, s[60:61]
	s_mov_b32 m0, s22
	v_readfirstlane_b32 s22, v3
	v_add_u32_e32 v2, 0x6000, v2
	global_load_lds_dwordx4 v[0:1], off
	v_lshl_add_u64 v[0:1], v[130:131], 0, s[40:41]
	s_mov_b32 m0, s22
	v_readfirstlane_b32 s22, v2
	v_and_b32_e32 v154, 31, v152
	global_load_lds_dwordx4 v[0:1], off
	v_lshl_add_u64 v[0:1], v[130:131], 0, s[62:63]
	s_mov_b32 m0, s22
	v_add_u32_e32 v5, 0x8000, v148
	global_load_lds_dwordx4 v[0:1], off
	v_lshlrev_b32_e32 v1, 7, v154
	v_add_u32_e32 v153, s3, v1
	s_add_i32 s3, 0, 0x18000
	v_ashrrev_i32_e32 v149, 6, v152
	v_add_u32_e32 v157, s3, v156
	v_readfirstlane_b32 s3, v5
	v_lshlrev_b32_e32 v0, 12, v149
	v_lshl_add_u64 v[2:3], v[128:129], 0, s[30:31]
	s_mov_b32 m0, s3
	v_readfirstlane_b32 s3, v157
	s_waitcnt vmcnt(0)
	s_waitcnt vmcnt(0) lgkmcnt(0)
	s_barrier
; #define SBAR() __builtin_amdgcn_sched_barrier(0)
; DEV void glds16(const u16* g, char* l) { __builtin_amdgcn_global_load_lds((const unsigned*)g, (unsigned*)l, 16, 0, 0); }
; template <int WM, int WN, int BN, int EPI>
; DEV void gemm_tile(const u16* __restrict__ A, int lda, const u16* __restrict__ Bt, int ldb, int K, int m0, char* lds,
;                    const Params& P, int layer, int batch, int nt) {
;     ...
;   for (int kt = 0; kt < nk; ++kt) {
;     const bool more = kt + 1 < nk;
;     const int nb = (kt + 1) & 1;
;     const char* as = As + (kt & 1) * 32768; const char* bs = Bs + (kt & 1) * 32768;
; #pragma unroll
;     for (int ks = 0; ks < 4; ++ks) {
;       if (more) { glds16(Ap + (long)ks * 64 * lda + (kt + 1) * 64, As + nb * 32768 + soff + ks * 8192);
;                   if (ks < NB) glds16(Bp + (long)ks * 64 * ldb + (kt + 1) * 64, Bs + nb * 32768 + soff + ks * 8192); }
;       SBAR();
;       bf16x8 xf[MI], wf[NI];
; #pragma unroll
;       for (int mi = 0; mi < MI; ++mi) xf[mi] = *reinterpret_cast<const bf16x8*>(as + swz128(wm * (MI * 32) + mi * 32 + r32, ks * 2 + hi));
; #pragma unroll
;       for (int ni = 0; ni < NI; ++ni) wf[ni] = *reinterpret_cast<const bf16x8*>(bs + swz128(wn * (NI * 32) + ni * 32 + r32, ks * 2 + hi));
; #pragma unroll
;       for (int mi = 0; mi < MI; ++mi)
; #pragma unroll
;         for (int ni = 0; ni < NI; ++ni) acc[mi][ni] = __builtin_amdgcn_mfma_f32_32x32x16_bf16(wf[ni], xf[mi], acc[mi][ni], 0, 0, 0);
;     }
	v_add3_u32 v151, 0, v0, v1
	v_lshl_add_u64 v[0:1], v[130:131], 0, s[30:31]
	global_load_lds_dwordx4 v[2:3], off
	s_mov_b32 m0, s3
	v_lshrrev_b32_e32 v4, 5, v152
	global_load_lds_dwordx4 v[0:1], off
	v_bfe_u32 v155, v152, 5, 1
	v_bfe_u32 v150, v152, 1, 3
	v_bitop3_b32 v0, v4, v150, 1 bitop3:0x6c
	v_lshlrev_b32_e32 v4, 4, v0
	v_add_u32_e32 v158, v153, v4
	ds_read_b128 v[0:3], v158
	v_add_u32_e32 v159, v151, v4
	ds_read_b128 v[64:67], v159
	v_add_u32_e32 v133, 0xa000, v148
	s_mov_b64 s[60:61], 0x4080
	v_add_u32_e32 v132, 0x2000, v157
	v_readfirstlane_b32 s3, v133
	v_lshl_add_u64 v[78:79], v[128:129], 0, s[60:61]
	s_mov_b32 m0, s3
	s_waitcnt lgkmcnt(0)
	v_mfma_f32_32x32x16_bf16 v[48:63], v[0:3], v[64:67], 0
	ds_read_b128 v[0:3], v158 offset:4096
	ds_read_b128 v[4:7], v158 offset:8192
	v_readfirstlane_b32 s3, v132
	v_lshl_add_u64 v[76:77], v[130:131], 0, s[60:61]
	s_waitcnt lgkmcnt(0)
	v_mfma_f32_32x32x16_bf16 v[32:47], v[0:3], v[64:67], 0
	ds_read_b128 v[0:3], v158 offset:12288
	ds_read_b128 v[68:71], v158 offset:16384
	s_waitcnt lgkmcnt(0)
	v_mfma_f32_32x32x16_bf16 v[112:127], v[68:71], v[64:67], 0
	ds_read_b128 v[68:71], v158 offset:20480
	ds_read_b128 v[72:75], v158 offset:24576
	s_waitcnt lgkmcnt(0)
	v_mfma_f32_32x32x16_bf16 v[96:111], v[68:71], v[64:67], 0
	ds_read_b128 v[68:71], v158 offset:28672
	global_load_lds_dwordx4 v[78:79], off
	s_mov_b32 m0, s3
	s_nop 0
	global_load_lds_dwordx4 v[76:77], off
	v_mfma_f32_32x32x16_bf16 v[16:31], v[4:7], v[64:67], 0
	v_mfma_f32_32x32x16_bf16 v[0:15], v[0:3], v[64:67], 0
	v_mfma_f32_32x32x16_bf16 v[80:95], v[72:75], v[64:67], 0
	s_waitcnt lgkmcnt(0)
	v_mfma_f32_32x32x16_bf16 v[64:79], v[68:71], v[64:67], 0
	v_bitop3_b32 v132, v155, v150, 2 bitop3:0x36
	v_lshlrev_b32_e32 v136, 4, v132
	v_add_u32_e32 v160, v153, v136
	ds_read_b128 v[132:135], v160
	v_add_u32_e32 v161, v151, v136
	ds_read_b128 v[136:139], v161
	v_add_u32_e32 v163, 0xc000, v148
	v_add_u32_e32 v162, 0x4000, v157
	v_readfirstlane_b32 s3, v163
	v_lshl_add_u64 v[146:147], v[128:129], 0, s[42:43]
	s_mov_b32 m0, s3
	v_readfirstlane_b32 s3, v162
	s_waitcnt lgkmcnt(0)
	v_mfma_f32_32x32x16_bf16 v[48:63], v[132:135], v[136:139], v[48:63]
	ds_read_b128 v[132:135], v160 offset:4096
	ds_read_b128 v[140:143], v160 offset:8192
	v_lshl_add_u64 v[144:145], v[130:131], 0, s[42:43]
	s_waitcnt lgkmcnt(0)
	v_mfma_f32_32x32x16_bf16 v[32:47], v[132:135], v[136:139], v[32:47]
	v_mfma_f32_32x32x16_bf16 v[16:31], v[140:143], v[136:139], v[16:31]
	ds_read_b128 v[132:135], v160 offset:12288
	ds_read_b128 v[140:143], v160 offset:16384
	s_waitcnt lgkmcnt(0)
	v_mfma_f32_32x32x16_bf16 v[0:15], v[132:135], v[136:139], v[0:15]
	v_mfma_f32_32x32x16_bf16 v[112:127], v[140:143], v[136:139], v[112:127]
	ds_read_b128 v[132:135], v160 offset:20480
	ds_read_b128 v[140:143], v160 offset:24576
	s_waitcnt lgkmcnt(0)
	v_mfma_f32_32x32x16_bf16 v[96:111], v[132:135], v[136:139], v[96:111]
	ds_read_b128 v[132:135], v160 offset:28672
	global_load_lds_dwordx4 v[146:147], off
	s_mov_b32 m0, s3
	s_nop 0
	global_load_lds_dwordx4 v[144:145], off
	v_mfma_f32_32x32x16_bf16 v[80:95], v[140:143], v[136:139], v[80:95]
	s_waitcnt lgkmcnt(0)
	v_mfma_f32_32x32x16_bf16 v[64:79], v[132:135], v[136:139], v[64:79]
	v_bitop3_b32 v132, v155, v150, 4 bitop3:0x36
	v_lshlrev_b32_e32 v136, 4, v132
	v_add_u32_e32 v144, v153, v136
	ds_read_b128 v[132:135], v144
	v_add_u32_e32 v145, v151, v136
	ds_read_b128 v[136:139], v145
	v_add_u32_e32 v147, 0xe000, v148
	s_mov_b64 s[60:61], 0xc080
	v_add_u32_e32 v146, 0x6000, v157
	v_readfirstlane_b32 s3, v147
	v_lshl_add_u64 v[128:129], v[128:129], 0, s[60:61]
	s_mov_b32 m0, s3
	s_waitcnt lgkmcnt(0)
	v_mfma_f32_32x32x16_bf16 v[48:63], v[132:135], v[136:139], v[48:63]
	ds_read_b128 v[132:135], v144 offset:4096
	ds_read_b128 v[140:143], v144 offset:8192
	v_readfirstlane_b32 s3, v146
	v_lshl_add_u64 v[130:131], v[130:131], 0, s[60:61]
	s_waitcnt lgkmcnt(0)
	v_mfma_f32_32x32x16_bf16 v[32:47], v[132:135], v[136:139], v[32:47]
	v_mfma_f32_32x32x16_bf16 v[16:31], v[140:143], v[136:139], v[16:31]
	ds_read_b128 v[132:135], v144 offset:12288
	ds_read_b128 v[140:143], v144 offset:16384
	s_waitcnt lgkmcnt(0)
	v_mfma_f32_32x32x16_bf16 v[0:15], v[132:135], v[136:139], v[0:15]
	v_mfma_f32_32x32x16_bf16 v[112:127], v[140:143], v[136:139], v[112:127]
	ds_read_b128 v[132:135], v144 offset:20480
	ds_read_b128 v[140:143], v144 offset:24576
	s_waitcnt lgkmcnt(0)
	v_mfma_f32_32x32x16_bf16 v[96:111], v[132:135], v[136:139], v[96:111]
	ds_read_b128 v[132:135], v144 offset:28672
	global_load_lds_dwordx4 v[128:129], off
	s_mov_b32 m0, s3
	s_nop 0
	global_load_lds_dwordx4 v[130:131], off
	v_mfma_f32_32x32x16_bf16 v[80:95], v[140:143], v[136:139], v[80:95]
	s_waitcnt lgkmcnt(0)
	v_mfma_f32_32x32x16_bf16 v[64:79], v[132:135], v[136:139], v[64:79]
	v_bitop3_b32 v128, v155, v150, 6 bitop3:0x36
	v_lshlrev_b32_e32 v132, 4, v128
	v_add_u32_e32 v148, v153, v132
	ds_read_b128 v[128:131], v148
	v_add_u32_e32 v140, v151, v132
	ds_read_b128 v[132:135], v140
	s_waitcnt lgkmcnt(0)
	v_mfma_f32_32x32x16_bf16 v[48:63], v[128:131], v[132:135], v[48:63]
	ds_read_b128 v[128:131], v148 offset:4096
	s_waitcnt lgkmcnt(0)
	v_mfma_f32_32x32x16_bf16 v[32:47], v[128:131], v[132:135], v[32:47]
	ds_read_b128 v[128:131], v148 offset:8192
	s_waitcnt lgkmcnt(0)
	v_mfma_f32_32x32x16_bf16 v[16:31], v[128:131], v[132:135], v[16:31]
	ds_read_b128 v[128:131], v148 offset:12288
	s_waitcnt lgkmcnt(0)
	v_mfma_f32_32x32x16_bf16 v[0:15], v[128:131], v[132:135], v[0:15]
	ds_read_b128 v[128:131], v148 offset:16384
	s_waitcnt lgkmcnt(0)
	v_mfma_f32_32x32x16_bf16 v[112:127], v[128:131], v[132:135], v[112:127]
	ds_read_b128 v[128:131], v148 offset:20480
	s_waitcnt lgkmcnt(0)
	v_mfma_f32_32x32x16_bf16 v[96:111], v[128:131], v[132:135], v[96:111]
	ds_read_b128 v[128:131], v148 offset:24576
	s_waitcnt lgkmcnt(0)
	v_mfma_f32_32x32x16_bf16 v[80:95], v[128:131], v[132:135], v[80:95]
	ds_read_b128 v[128:131], v148 offset:28672
	s_waitcnt vmcnt(0)
	s_waitcnt vmcnt(0) lgkmcnt(0)
	s_barrier
; #define SBAR() __builtin_amdgcn_sched_barrier(0)
;   DEV float* ssq_ckv() const { return (float*)(b + O_SSQCKV); }
; DEV void glds16(const u16* g, char* l) { __builtin_amdgcn_global_load_lds((const unsigned*)g, (unsigned*)l, 16, 0, 0); }
; DEV void epi_ukv(f32x16 (&acc)[1][8], const Params& P, int layer, int batch, int m0, int head, int wid, int r32, int hi, char* lds) {
;   const int t = m0 + wid * 32 + r32;
;   const float rc = __builtin_amdgcn_rsqf((WS{P.ws}.ssq_ckv()[t] + WS{P.ws}.ssq_ckv()[TB + t]) * (1.f / 128.f) + EPS);
; template <int WM, int WN, int BN, int EPI>
; DEV void gemm_tile(const u16* __restrict__ A, int lda, const u16* __restrict__ Bt, int ldb, int K, int m0, char* lds,
;                    const Params& P, int layer, int batch, int nt) {
;     ...
;   for (int kt = 0; kt < nk; ++kt) {
;     const bool more = kt + 1 < nk;
;     const int nb = (kt + 1) & 1;
;     const char* as = As + (kt & 1) * 32768; const char* bs = Bs + (kt & 1) * 32768;
; #pragma unroll
;     for (int ks = 0; ks < 4; ++ks) {
;       if (more) { glds16(Ap + (long)ks * 64 * lda + (kt + 1) * 64, As + nb * 32768 + soff + ks * 8192);
;                   if (ks < NB) glds16(Bp + (long)ks * 64 * ldb + (kt + 1) * 64, Bs + nb * 32768 + soff + ks * 8192); }
;       SBAR();
;       bf16x8 xf[MI], wf[NI];
; #pragma unroll
;       for (int mi = 0; mi < MI; ++mi) xf[mi] = *reinterpret_cast<const bf16x8*>(as + swz128(wm * (MI * 32) + mi * 32 + r32, ks * 2 + hi));
; #pragma unroll
;       for (int ni = 0; ni < NI; ++ni) wf[ni] = *reinterpret_cast<const bf16x8*>(bs + swz128(wn * (NI * 32) + ni * 32 + r32, ks * 2 + hi));
; #pragma unroll
;       for (int mi = 0; mi < MI; ++mi)
; #pragma unroll
;         for (int ni = 0; ni < NI; ++ni) acc[mi][ni] = __builtin_amdgcn_mfma_f32_32x32x16_bf16(wf[ni], xf[mi], acc[mi][ni], 0, 0, 0);
;     }
;     asm volatile("s_waitcnt vmcnt(0)" ::: "memory");
;     __syncthreads();
;   }
	v_mfma_f32_32x32x16_bf16 v[64:79], v[128:131], v[132:135], v[64:79]
	ds_read_b128 v[128:131], v158 offset:32768
	ds_read_b128 v[132:135], v159 offset:32768
	s_waitcnt lgkmcnt(0)
	v_mfma_f32_32x32x16_bf16 v[48:63], v[128:131], v[132:135], v[48:63]
	ds_read_b128 v[128:131], v158 offset:36864
	s_waitcnt lgkmcnt(0)
	v_mfma_f32_32x32x16_bf16 v[32:47], v[128:131], v[132:135], v[32:47]
	ds_read_b128 v[128:131], v158 offset:40960
	s_waitcnt lgkmcnt(0)
	v_mfma_f32_32x32x16_bf16 v[16:31], v[128:131], v[132:135], v[16:31]
	ds_read_b128 v[128:131], v158 offset:45056
	s_waitcnt lgkmcnt(0)
	v_mfma_f32_32x32x16_bf16 v[0:15], v[128:131], v[132:135], v[0:15]
	ds_read_b128 v[128:131], v158 offset:49152
	s_waitcnt lgkmcnt(0)
	v_mfma_f32_32x32x16_bf16 v[112:127], v[128:131], v[132:135], v[112:127]
	ds_read_b128 v[128:131], v158 offset:53248
	s_waitcnt lgkmcnt(0)
	v_mfma_f32_32x32x16_bf16 v[96:111], v[128:131], v[132:135], v[96:111]
	ds_read_b128 v[128:131], v158 offset:57344
	s_waitcnt lgkmcnt(0)
	v_mfma_f32_32x32x16_bf16 v[80:95], v[128:131], v[132:135], v[80:95]
	ds_read_b128 v[128:131], v158 offset:61440
	s_waitcnt lgkmcnt(0)
	v_mfma_f32_32x32x16_bf16 v[64:79], v[128:131], v[132:135], v[64:79]
	ds_read_b128 v[128:131], v160 offset:32768
	ds_read_b128 v[132:135], v161 offset:32768
	s_waitcnt lgkmcnt(0)
	v_mfma_f32_32x32x16_bf16 v[48:63], v[128:131], v[132:135], v[48:63]
	ds_read_b128 v[128:131], v160 offset:36864
	s_waitcnt lgkmcnt(0)
	v_mfma_f32_32x32x16_bf16 v[32:47], v[128:131], v[132:135], v[32:47]
	ds_read_b128 v[128:131], v160 offset:40960
	s_waitcnt lgkmcnt(0)
	v_mfma_f32_32x32x16_bf16 v[16:31], v[128:131], v[132:135], v[16:31]
	ds_read_b128 v[128:131], v160 offset:45056
	s_waitcnt lgkmcnt(0)
	v_mfma_f32_32x32x16_bf16 v[0:15], v[128:131], v[132:135], v[0:15]
	ds_read_b128 v[128:131], v160 offset:49152
	s_waitcnt lgkmcnt(0)
	v_mfma_f32_32x32x16_bf16 v[112:127], v[128:131], v[132:135], v[112:127]
	ds_read_b128 v[128:131], v160 offset:53248
	s_waitcnt lgkmcnt(0)
	v_mfma_f32_32x32x16_bf16 v[96:111], v[128:131], v[132:135], v[96:111]
	ds_read_b128 v[128:131], v160 offset:57344
	s_waitcnt lgkmcnt(0)
	v_mfma_f32_32x32x16_bf16 v[80:95], v[128:131], v[132:135], v[80:95]
	ds_read_b128 v[128:131], v160 offset:61440
	s_waitcnt lgkmcnt(0)
	v_mfma_f32_32x32x16_bf16 v[64:79], v[128:131], v[132:135], v[64:79]
	ds_read_b128 v[128:131], v144 offset:32768
	ds_read_b128 v[132:135], v145 offset:32768
	s_waitcnt lgkmcnt(0)
	v_mfma_f32_32x32x16_bf16 v[48:63], v[128:131], v[132:135], v[48:63]
	ds_read_b128 v[128:131], v144 offset:36864
	s_waitcnt lgkmcnt(0)
	v_mfma_f32_32x32x16_bf16 v[32:47], v[128:131], v[132:135], v[32:47]
	ds_read_b128 v[128:131], v144 offset:40960
	s_waitcnt lgkmcnt(0)
	v_mfma_f32_32x32x16_bf16 v[16:31], v[128:131], v[132:135], v[16:31]
	ds_read_b128 v[128:131], v144 offset:45056
	s_waitcnt lgkmcnt(0)
	v_mfma_f32_32x32x16_bf16 v[0:15], v[128:131], v[132:135], v[0:15]
	ds_read_b128 v[128:131], v144 offset:49152
	s_waitcnt lgkmcnt(0)
	v_mfma_f32_32x32x16_bf16 v[112:127], v[128:131], v[132:135], v[112:127]
	ds_read_b128 v[128:131], v144 offset:53248
	s_waitcnt lgkmcnt(0)
	v_mfma_f32_32x32x16_bf16 v[96:111], v[128:131], v[132:135], v[96:111]
	ds_read_b128 v[128:131], v144 offset:57344
	s_waitcnt lgkmcnt(0)
	v_mfma_f32_32x32x16_bf16 v[80:95], v[128:131], v[132:135], v[80:95]
	ds_read_b128 v[128:131], v144 offset:61440
	s_waitcnt lgkmcnt(0)
	v_mfma_f32_32x32x16_bf16 v[64:79], v[128:131], v[132:135], v[64:79]
	ds_read_b128 v[136:139], v148 offset:49152
	ds_read_b128 v[128:131], v140 offset:32768
	ds_read_b128 v[132:135], v148 offset:45056
	ds_read_b128 v[140:143], v148 offset:32768
	ds_read_b128 v[158:161], v148 offset:53248
	v_lshlrev_b32_e32 v157, 3, v155
	s_waitcnt lgkmcnt(3)
	v_mfma_f32_32x32x16_bf16 v[112:127], v[136:139], v[128:131], v[112:127]
	ds_read_b128 v[144:147], v148 offset:36864
	ds_read_b128 v[136:139], v148 offset:40960
	ds_read_b128 v[162:165], v148 offset:57344
	ds_read_b128 v[166:169], v148 offset:61440
	v_lshl_add_u32 v148, v149, 5, s2
	v_or_b32_e32 v150, v148, v154
	v_ashrrev_i32_e32 v151, 31, v150
	s_waitcnt vmcnt(0)
	s_waitcnt lgkmcnt(0)
	s_barrier
	v_mfma_f32_32x32x16_bf16 v[96:111], v[158:161], v[128:131], v[96:111]
	v_lshl_add_u64 v[158:159], v[150:151], 2, s[18:19]
	v_add_co_u32_e32 v160, vcc, s93, v158
	s_nop 1
	v_addc_co_u32_e32 v161, vcc, 0, v159, vcc
	global_load_dword v153, v[158:159], off
	s_nop 0
	global_load_dword v158, v[160:161], off
	v_mfma_f32_32x32x16_bf16 v[80:95], v[162:165], v[128:131], v[80:95]
	v_mul_lo_u32 v149, v149, s99
	v_mul_u32_u24_e32 v159, 0x110, v154
	v_and_b32_e32 v184, 0xf0, v156
	s_lshl_b32 s22, s54, 8
	s_movk_i32 s2, 0xfff
	s_waitcnt vmcnt(0) lgkmcnt(0)
;   DEV u16* VB() const { return (u16*)(b + O_VB); }
;   DEV float* ssq_ckv() const { return (float*)(b + O_SSQCKV); }
; #define LDSP(T) __attribute__((address_space(3))) T*
; template <int NCH, int STRIDE> DEV void slab_flush(char* slab, u16* grow0, int gstride, int lane) {
;   asm volatile("s_waitcnt lgkmcnt(0)" ::: "memory");
; #pragma unroll
;   for (int i = 0; i < NCH / 2; ++i) {
;     const int q = i * 64 + lane, row = q / NCH, cc = q - row * NCH;
;     const u32x4 v = *(LDSP(const u32x4))(slab + row * STRIDE + cc * 16);
;     *reinterpret_cast<u32x4*>(grow0 + (long)row * gstride + cc * 8) = v;
;   }
;   asm volatile("s_waitcnt lgkmcnt(0)" ::: "memory");
; }
; DEV void epi_ukv(f32x16 (&acc)[1][8], const Params& P, int layer, int batch, int m0, int head, int wid, int r32, int hi, char* lds) {
;     ...
;   const float rc = __builtin_amdgcn_rsqf((WS{P.ws}.ssq_ckv()[t] + WS{P.ws}.ssq_ckv()[TB + t]) * (1.f / 128.f) + EPS);
;   char* slab = lds + wid * 12800; char* vdst = slab + r32 * 272;
; #pragma unroll
;   for (int ni = 4; ni < 8; ++ni)
; #pragma unroll
;     for (int r4 = 0; r4 < 4; ++r4) {
;       const f32x16& a = acc[0][ni];
;       st4lds(vdst, (ni - 4) * 32 + r4 * 8 + hi * 4, a[r4 * 4] * rc, a[r4 * 4 + 1] * rc, a[r4 * 4 + 2] * rc, a[r4 * 4 + 3] * rc);
;     }
;   slab_flush<16, 272>(slab, WS{P.ws}.VB() + (long)(m0 + wid * 32) * 512 + head * 128, 512, hi * 32 + r32);
	v_add_f32_e32 v153, v153, v158
	v_fmamk_f32 v153, v153, 0x3c000000, v227
	v_rsq_f32_e32 v158, v153
	v_add_u32_e32 v153, 0, v149
	v_add3_u32 v149, v153, v159, v157
	v_mfma_f32_32x32x16_bf16 v[64:79], v[166:169], v[128:131], v[64:79]
	v_mul_f32_e32 v112, v112, v158
	v_mul_f32_e32 v113, v113, v158
	v_mul_f32_e32 v114, v114, v158
	v_mul_f32_e32 v115, v115, v158
	v_mul_f32_e32 v159, v80, v158
	v_mul_f32_e32 v160, v81, v158
	v_cvt_pk_bf16_f32 v80, v112, v113
	v_cvt_pk_bf16_f32 v81, v114, v115
	v_mul_f32_e32 v116, v116, v158
	v_mul_f32_e32 v117, v117, v158
	v_mul_f32_e32 v118, v118, v158
	v_mul_f32_e32 v119, v119, v158
	ds_write_b64 v149, v[80:81]
	v_cvt_pk_bf16_f32 v80, v116, v117
	v_cvt_pk_bf16_f32 v81, v118, v119
	v_mul_f32_e32 v120, v120, v158
	v_mul_f32_e32 v121, v121, v158
	v_mul_f32_e32 v122, v122, v158
	v_mul_f32_e32 v123, v123, v158
	ds_write_b64 v149, v[80:81] offset:16
	v_cvt_pk_bf16_f32 v80, v120, v121
	v_cvt_pk_bf16_f32 v81, v122, v123
	v_mul_f32_e32 v124, v124, v158
	v_mul_f32_e32 v125, v125, v158
	v_mul_f32_e32 v126, v126, v158
	v_mul_f32_e32 v127, v127, v158
	ds_write_b64 v149, v[80:81] offset:32
	v_cvt_pk_bf16_f32 v80, v124, v125
	v_cvt_pk_bf16_f32 v81, v126, v127
	v_mul_f32_e32 v96, v96, v158
	v_mul_f32_e32 v97, v97, v158
	v_mul_f32_e32 v98, v98, v158
	v_mul_f32_e32 v99, v99, v158
	ds_write_b64 v149, v[80:81] offset:48
	v_cvt_pk_bf16_f32 v80, v96, v97
	v_cvt_pk_bf16_f32 v81, v98, v99
	v_mul_f32_e32 v100, v100, v158
	v_mul_f32_e32 v101, v101, v158
	v_mul_f32_e32 v102, v102, v158
	v_mul_f32_e32 v103, v103, v158
	ds_write_b64 v149, v[80:81] offset:64
	v_cvt_pk_bf16_f32 v80, v100, v101
	v_cvt_pk_bf16_f32 v81, v102, v103
	v_mul_f32_e32 v104, v104, v158
	v_mul_f32_e32 v105, v105, v158
	v_mul_f32_e32 v106, v106, v158
	v_mul_f32_e32 v107, v107, v158
	ds_write_b64 v149, v[80:81] offset:80
	v_cvt_pk_bf16_f32 v80, v104, v105
	v_cvt_pk_bf16_f32 v81, v106, v107
	v_mul_f32_e32 v108, v108, v158
	v_mul_f32_e32 v109, v109, v158
	v_mul_f32_e32 v110, v110, v158
	v_mul_f32_e32 v111, v111, v158
	ds_write_b64 v149, v[80:81] offset:96
	v_cvt_pk_bf16_f32 v80, v108, v109
	v_cvt_pk_bf16_f32 v81, v110, v111
	v_mul_f32_e32 v82, v82, v158
	v_mul_f32_e32 v83, v83, v158
	ds_write_b64 v149, v[80:81] offset:112
	v_cvt_pk_bf16_f32 v80, v159, v160
	v_cvt_pk_bf16_f32 v81, v82, v83
	v_mul_f32_e32 v84, v84, v158
	v_mul_f32_e32 v85, v85, v158
	v_mul_f32_e32 v86, v86, v158
	v_mul_f32_e32 v87, v87, v158
	ds_write_b64 v149, v[80:81] offset:128
	v_cvt_pk_bf16_f32 v80, v84, v85
	v_cvt_pk_bf16_f32 v81, v86, v87
	ds_write_b64 v149, v[80:81] offset:144
	v_mul_f32_e32 v80, v88, v158
	v_mul_f32_e32 v81, v89, v158
	v_mul_f32_e32 v82, v90, v158
	v_mul_f32_e32 v83, v91, v158
	v_cvt_pk_bf16_f32 v80, v80, v81
	v_cvt_pk_bf16_f32 v81, v82, v83
	ds_write_b64 v149, v[80:81] offset:160
	v_mul_f32_e32 v80, v92, v158
	v_mul_f32_e32 v81, v93, v158
	v_mul_f32_e32 v64, v64, v158
	v_mul_f32_e32 v65, v65, v158
	v_mul_f32_e32 v82, v94, v158
	v_mul_f32_e32 v83, v95, v158
	v_cvt_pk_bf16_f32 v80, v80, v81
	v_cvt_pk_bf16_f32 v81, v82, v83
	ds_write_b64 v149, v[80:81] offset:176
	v_mul_f32_e32 v66, v66, v158
	v_mul_f32_e32 v67, v67, v158
	v_cvt_pk_bf16_f32 v64, v64, v65
	v_cvt_pk_bf16_f32 v65, v66, v67
	ds_write_b64 v149, v[64:65] offset:192
	v_mul_f32_e32 v64, v68, v158
	v_mul_f32_e32 v65, v69, v158
	v_mul_f32_e32 v66, v70, v158
	v_mul_f32_e32 v67, v71, v158
	v_cvt_pk_bf16_f32 v64, v64, v65
	v_cvt_pk_bf16_f32 v65, v66, v67
	ds_write_b64 v149, v[64:65] offset:208
	v_mul_f32_e32 v64, v72, v158
	v_mul_f32_e32 v65, v73, v158
	v_mul_f32_e32 v66, v74, v158
	v_mul_f32_e32 v67, v75, v158
	v_cvt_pk_bf16_f32 v64, v64, v65
	v_cvt_pk_bf16_f32 v65, v66, v67
	ds_write_b64 v149, v[64:65] offset:224
	v_mul_f32_e32 v64, v76, v158
	v_mul_f32_e32 v65, v77, v158
	v_mul_f32_e32 v66, v78, v158
	v_mul_f32_e32 v67, v79, v158
	v_cvt_pk_bf16_f32 v64, v64, v65
	v_cvt_pk_bf16_f32 v65, v66, v67
	ds_write_b64 v149, v[64:65] offset:240
	v_ashrrev_i32_e32 v149, 31, v148
	v_lshlrev_b64 v[64:65], 10, v[148:149]
	v_bfe_u32 v70, v152, 4, 2
	v_lshl_add_u64 v[68:69], s[24:25], 0, v[64:65]
	v_mul_u32_u24_e32 v64, 0x110, v70
	s_waitcnt lgkmcnt(0)
	v_add3_u32 v72, v153, v184, v64
	ds_read_b128 v[64:67], v72
	v_lshl_add_u64 v[68:69], v[68:69], 0, s[22:23]
	v_lshl_add_u64 v[68:69], v[68:69], 0, v[184:185]
	v_lshlrev_b32_e32 v184, 10, v70
	v_lshl_add_u64 v[70:71], v[68:69], 0, v[184:185]
	s_waitcnt lgkmcnt(0)
	global_store_dwordx4 v[70:71], v[64:67], off
	ds_read_b128 v[64:67], v72 offset:1088
	v_or_b32_e32 v70, 0x1000, v184
	v_mov_b32_e32 v71, v185
	v_lshl_add_u64 v[70:71], v[68:69], 0, v[70:71]
	v_mfma_f32_32x32x16_bf16 v[32:47], v[144:147], v[128:131], v[32:47]
	s_waitcnt lgkmcnt(0)
	global_store_dwordx4 v[70:71], v[64:67], off
	ds_read_b128 v[64:67], v72 offset:2176
	v_or_b32_e32 v70, 0x2000, v184
	v_mov_b32_e32 v71, v185
	v_lshl_add_u64 v[70:71], v[68:69], 0, v[70:71]
	s_mul_i32 s22, s54, 0x180
	s_waitcnt lgkmcnt(0)
	global_store_dwordx4 v[70:71], v[64:67], off
	ds_read_b128 v[64:67], v72 offset:3264
	v_or_b32_e32 v70, 0x3000, v184
	v_mov_b32_e32 v71, v185
	v_lshl_add_u64 v[70:71], v[68:69], 0, v[70:71]
	v_mfma_f32_32x32x16_bf16 v[48:63], v[140:143], v[128:131], v[48:63]
	s_waitcnt lgkmcnt(0)
	global_store_dwordx4 v[70:71], v[64:67], off
	ds_read_b128 v[64:67], v72 offset:4352
	v_or_b32_e32 v70, 0x4000, v184
	v_mov_b32_e32 v71, v185
	v_lshl_add_u64 v[70:71], v[68:69], 0, v[70:71]
	v_mul_f32_e32 v75, v32, v158
	s_waitcnt lgkmcnt(0)
	global_store_dwordx4 v[70:71], v[64:67], off
	ds_read_b128 v[64:67], v72 offset:5440
	v_or_b32_e32 v70, 0x5000, v184
	v_mov_b32_e32 v71, v185
	v_lshl_add_u64 v[70:71], v[68:69], 0, v[70:71]
	v_mul_f32_e32 v76, v33, v158
	s_waitcnt lgkmcnt(0)
;   DEV u16* VB() const { return (u16*)(b + O_VB); }
; DEV void epi_ukv(f32x16 (&acc)[1][8], const Params& P, int layer, int batch, int m0, int head, int wid, int r32, int hi, char* lds) {
;     ...
;   slab_flush<16, 272>(slab, WS{P.ws}.VB() + (long)(m0 + wid * 32) * 512 + head * 128, 512, hi * 32 + r32);
;   float s = 0.f;
; #pragma unroll
;   for (int ni = 0; ni < 4; ++ni)
; #pragma unroll
;     for (int r = 0; r < 16; ++r) { acc[0][ni][r] *= rc; s += acc[0][ni][r] * acc[0][ni][r]; }
;   float4 kr[2][4];
; #pragma unroll
;   for (int b = 0; b < 2; ++b)
; #pragma unroll
;     for (int r4 = 0; r4 < 4; ++r4) {
;       kr[b][r4] = *reinterpret_cast<const float4*>(WS{P.ws}.KR() + (long)t * 64 + b * 32 + r4 * 8 + hi * 4);
;       s += kr[b][r4].x * kr[b][r4].x + kr[b][r4].y * kr[b][r4].y + kr[b][r4].z * kr[b][r4].z + kr[b][r4].w * kr[b][r4].w;
;     }
;   s = swapsum(s);
;   const float inv = __builtin_amdgcn_rsqf(s * (1.f / 192.f) + EPS);
;   const float* g = WS{P.ws}.consts() + layer * 1024 + 512;
	global_store_dwordx4 v[70:71], v[64:67], off
	ds_read_b128 v[64:67], v72 offset:6528
	v_or_b32_e32 v70, 0x6000, v184
	v_mov_b32_e32 v71, v185
	v_lshl_add_u64 v[70:71], v[68:69], 0, v[70:71]
	v_or_b32_e32 v184, 0x7000, v184
	s_waitcnt lgkmcnt(0)
	global_store_dwordx4 v[70:71], v[64:67], off
	ds_read_b128 v[64:67], v72 offset:7616
	v_lshl_add_u64 v[68:69], v[68:69], 0, v[184:185]
	v_lshlrev_b64 v[32:33], 8, v[150:151]
	v_lshl_add_u64 v[32:33], s[68:69], 0, v[32:33]
	v_lshlrev_b32_e32 v184, 4, v155
	s_waitcnt lgkmcnt(0)
	global_store_dwordx4 v[68:69], v[64:67], off
	s_waitcnt lgkmcnt(0)
	v_mul_f32_e32 v73, v56, v158
	v_mul_f32_e32 v74, v57, v158
	v_lshl_add_u64 v[56:57], v[32:33], 0, v[184:185]
	v_mul_f32_e32 v64, v48, v158
	v_mul_f32_e32 v65, v49, v158
	v_mul_f32_e32 v67, v50, v158
	v_mul_f32_e32 v68, v51, v158
	global_load_dwordx4 v[48:51], v[56:57], off
	v_mul_f32_e32 v83, v40, v158
	v_mul_f32_e32 v84, v41, v158
	v_mul_f32_e32 v85, v42, v158
	v_mul_f32_e32 v86, v43, v158
	global_load_dwordx4 v[40:43], v[56:57], off offset:32
	v_mul_f32_e32 v79, v36, v158
	v_mul_f32_e32 v80, v37, v158
	v_mul_f32_e32 v81, v38, v158
	v_mul_f32_e32 v82, v39, v158
	global_load_dwordx4 v[36:39], v[56:57], off offset:64
	v_mfma_f32_32x32x16_bf16 v[16:31], v[136:139], v[128:131], v[16:31]
	v_mul_f32_e32 v77, v34, v158
	v_mul_f32_e32 v78, v35, v158
	global_load_dwordx4 v[32:35], v[56:57], off offset:96
	v_mul_f32_e32 v69, v52, v158
	v_mul_f32_e32 v70, v53, v158
	v_mul_f32_e32 v71, v54, v158
	v_mul_f32_e32 v72, v55, v158
	v_mul_f32_e32 v87, v44, v158
	v_mul_f32_e32 v88, v45, v158
	v_mul_f32_e32 v89, v46, v158
	v_mul_f32_e32 v90, v47, v158
	global_load_dwordx4 v[52:55], v[56:57], off offset:128
	global_load_dwordx4 v[44:47], v[56:57], off offset:160
	v_mul_f32_e32 v91, v16, v158
	v_mul_f32_e32 v92, v17, v158
	v_mul_f32_e32 v93, v18, v158
	v_mul_f32_e32 v94, v19, v158
	v_mul_f32_e32 v95, v20, v158
	v_mul_f32_e32 v96, v21, v158
	v_mul_f32_e32 v97, v22, v158
	v_mul_f32_e32 v98, v23, v158
	global_load_dwordx4 v[20:23], v[56:57], off offset:192
	global_load_dwordx4 v[16:19], v[56:57], off offset:224
	v_mul_f32_e32 v66, v65, v65
	v_fmac_f32_e32 v66, v64, v64
	v_fmac_f32_e32 v66, v67, v67
	v_fmac_f32_e32 v66, v68, v68
	v_fmac_f32_e32 v66, v69, v69
	v_mfma_f32_32x32x16_bf16 v[0:15], v[132:135], v[128:131], v[0:15]
	v_fmac_f32_e32 v66, v70, v70
	v_fmac_f32_e32 v66, v71, v71
	v_fmac_f32_e32 v66, v72, v72
	v_fmac_f32_e32 v66, v73, v73
	v_fmac_f32_e32 v66, v74, v74
	v_mul_f32_e32 v58, v58, v158
	v_fmac_f32_e32 v66, v58, v58
	v_mul_f32_e32 v59, v59, v158
	v_fmac_f32_e32 v66, v59, v59
	v_mul_f32_e32 v60, v60, v158
	v_fmac_f32_e32 v66, v60, v60
	v_mul_f32_e32 v61, v61, v158
	v_mul_f32_e32 v101, v26, v158
	v_mul_f32_e32 v56, v27, v158
	v_lshl_add_u64 v[26:27], s[10:11], 0, v[184:185]
	v_fmac_f32_e32 v66, v61, v61
	v_mul_f32_e32 v62, v62, v158
	v_mul_f32_e32 v57, v0, v158
	v_mul_f32_e32 v102, v1, v158
	v_mul_f32_e32 v103, v2, v158
	v_mul_f32_e32 v104, v3, v158
	global_load_dwordx4 v[0:3], v[26:27], off offset:2048
	global_load_dwordx4 v[194:197], v[26:27], off offset:2080
	global_load_dwordx4 v[198:201], v[26:27], off offset:2112
	global_load_dwordx4 v[202:205], v[26:27], off offset:2144
	global_load_dwordx4 v[206:209], v[26:27], off offset:2176
	global_load_dwordx4 v[210:213], v[26:27], off offset:2208
	global_load_dwordx4 v[214:217], v[26:27], off offset:2240
	global_load_dwordx4 v[218:221], v[26:27], off offset:2272
	global_load_dwordx4 v[222:225], v[26:27], off offset:2304
	global_load_dwordx4 v[232:235], v[26:27], off offset:2336
	global_load_dwordx4 v[236:239], v[26:27], off offset:2368
	global_load_dwordx4 v[240:243], v[26:27], off offset:2400
	global_load_dwordx4 v[244:247], v[26:27], off offset:2432
	global_load_dwordx4 v[248:251], v[26:27], off offset:2464
	global_load_dwordx4 v[170:173], v[26:27], off offset:2496
	global_load_dwordx4 v[174:177], v[26:27], off offset:2528
	v_fmac_f32_e32 v66, v62, v62
	v_mul_f32_e32 v63, v63, v158
	v_fmac_f32_e32 v66, v63, v63
	v_fmac_f32_e32 v66, v75, v75
	v_fmac_f32_e32 v66, v76, v76
	v_fmac_f32_e32 v66, v77, v77
	v_fmac_f32_e32 v66, v78, v78
	v_fmac_f32_e32 v66, v79, v79
	v_fmac_f32_e32 v66, v80, v80
	v_fmac_f32_e32 v66, v81, v81
	v_fmac_f32_e32 v66, v82, v82
	v_fmac_f32_e32 v66, v83, v83
	v_fmac_f32_e32 v66, v84, v84
	v_fmac_f32_e32 v66, v85, v85
	v_fmac_f32_e32 v66, v86, v86
	v_fmac_f32_e32 v66, v87, v87
	v_fmac_f32_e32 v66, v88, v88
	v_fmac_f32_e32 v66, v89, v89
	v_fmac_f32_e32 v66, v90, v90
	v_fmac_f32_e32 v66, v91, v91
	v_fmac_f32_e32 v66, v92, v92
	v_fmac_f32_e32 v66, v93, v93
	v_fmac_f32_e32 v66, v94, v94
	v_fmac_f32_e32 v66, v95, v95
	v_fmac_f32_e32 v66, v96, v96
	v_fmac_f32_e32 v66, v97, v97
	v_fmac_f32_e32 v66, v98, v98
	v_mul_f32_e32 v99, v24, v158
	v_fmac_f32_e32 v66, v99, v99
	v_mul_f32_e32 v100, v25, v158
	v_fmac_f32_e32 v66, v100, v100
	v_fmac_f32_e32 v66, v101, v101
	v_fmac_f32_e32 v66, v56, v56
	v_mul_f32_e32 v28, v28, v158
	v_fmac_f32_e32 v66, v28, v28
	v_mul_f32_e32 v29, v29, v158
	v_fmac_f32_e32 v66, v29, v29
	v_mul_f32_e32 v30, v30, v158
	v_fmac_f32_e32 v66, v30, v30
	v_mul_f32_e32 v31, v31, v158
	v_fmac_f32_e32 v66, v31, v31
	v_fmac_f32_e32 v66, v57, v57
	v_fmac_f32_e32 v66, v102, v102
	v_fmac_f32_e32 v66, v103, v103
	v_fmac_f32_e32 v66, v104, v104
	v_mul_f32_e32 v105, v4, v158
	v_fmac_f32_e32 v66, v105, v105
	v_mul_f32_e32 v106, v5, v158
	v_fmac_f32_e32 v66, v106, v106
	v_mul_f32_e32 v107, v6, v158
	v_fmac_f32_e32 v66, v107, v107
	v_mul_f32_e32 v108, v7, v158
	v_fmac_f32_e32 v66, v108, v108
	v_mul_f32_e32 v8, v8, v158
	v_fmac_f32_e32 v66, v8, v8
	v_mul_f32_e32 v9, v9, v158
	v_fmac_f32_e32 v66, v9, v9
	v_mul_f32_e32 v10, v10, v158
	v_fmac_f32_e32 v66, v10, v10
	v_mul_f32_e32 v11, v11, v158
	v_fmac_f32_e32 v66, v11, v11
	v_mul_f32_e32 v12, v12, v158
	v_fmac_f32_e32 v66, v12, v12
	v_mul_f32_e32 v13, v13, v158
	s_waitcnt vmcnt(0) lgkmcnt(0)
; DEV void epi_ukv(f32x16 (&acc)[1][8], const Params& P, int layer, int batch, int m0, int head, int wid, int r32, int hi, char* lds) {
;     ...
;       s += kr[b][r4].x * kr[b][r4].x + kr[b][r4].y * kr[b][r4].y + kr[b][r4].z * kr[b][r4].z + kr[b][r4].w * kr[b][r4].w;
;     }
;   s = swapsum(s);
;   const float inv = __builtin_amdgcn_rsqf(s * (1.f / 192.f) + EPS);
;   const float* g = WS{P.ws}.consts() + layer * 1024 + 512;
;   char* dst = slab + r32 * 400;
; #pragma unroll
;   for (int ni = 0; ni < 4; ++ni)
; #pragma unroll
;     for (int r4 = 0; r4 < 4; ++r4) {
;       const int c = ni * 32 + r4 * 8 + hi * 4;
;       const float4 gg = *reinterpret_cast<const float4*>(g + c);
;       const f32x16& a = acc[0][ni];
;       st4lds(dst, c, a[r4 * 4] * inv * gg.x, a[r4 * 4 + 1] * inv * gg.y, a[r4 * 4 + 2] * inv * gg.z, a[r4 * 4 + 3] * inv * gg.w);
;     }
	v_mul_f32_e32 v4, v49, v49
	v_fmac_f32_e32 v66, v13, v13
	v_mul_f32_e32 v14, v14, v158
	v_fmac_f32_e32 v4, v48, v48
	v_mul_f32_e32 v5, v41, v41
	v_fmac_f32_e32 v66, v14, v14
	v_mul_f32_e32 v15, v15, v158
	v_fmac_f32_e32 v4, v50, v50
	v_fmac_f32_e32 v5, v40, v40
	v_fmac_f32_e32 v66, v15, v15
	v_fmac_f32_e32 v4, v51, v51
	v_fmac_f32_e32 v5, v42, v42
	v_add_f32_e32 v4, v66, v4
	v_fmac_f32_e32 v5, v43, v43
	v_add_f32_e32 v4, v4, v5
	v_mul_f32_e32 v5, v37, v37
	v_fmac_f32_e32 v5, v36, v36
	v_fmac_f32_e32 v5, v38, v38
	v_fmac_f32_e32 v5, v39, v39
	v_add_f32_e32 v4, v4, v5
	v_mul_f32_e32 v5, v33, v33
	v_fmac_f32_e32 v5, v32, v32
	v_fmac_f32_e32 v5, v34, v34
	v_fmac_f32_e32 v5, v35, v35
	v_mov_b32_e32 v6, v53
	v_mov_b32_e32 v7, v45
	v_add_f32_e32 v24, v4, v5
	v_mov_b32_e32 v4, v52
	v_mov_b32_e32 v5, v44
	v_pk_mul_f32 v[6:7], v[6:7], v[6:7]
	v_lshlrev_b32_e32 v184, 5, v155
	v_pk_fma_f32 v[4:5], v[4:5], v[4:5], v[6:7]
	v_mov_b32_e32 v6, v54
	v_mov_b32_e32 v7, v46
	v_pk_fma_f32 v[4:5], v[6:7], v[6:7], v[4:5]
	v_mov_b32_e32 v6, v55
	v_mov_b32_e32 v7, v47
	v_pk_fma_f32 v[4:5], v[6:7], v[6:7], v[4:5]
	v_mov_b32_e32 v6, v21
	v_add_f32_e32 v4, v24, v4
	v_mov_b32_e32 v7, v17
	v_add_f32_e32 v24, v4, v5
	v_mov_b32_e32 v4, v20
	v_mov_b32_e32 v5, v16
	v_pk_mul_f32 v[6:7], v[6:7], v[6:7]
	s_nop 0
	v_pk_fma_f32 v[4:5], v[4:5], v[4:5], v[6:7]
	v_mov_b32_e32 v6, v22
	v_mov_b32_e32 v7, v18
	v_pk_fma_f32 v[4:5], v[6:7], v[6:7], v[4:5]
	v_mov_b32_e32 v6, v23
	v_mov_b32_e32 v7, v19
	v_pk_fma_f32 v[4:5], v[6:7], v[6:7], v[4:5]
	s_nop 0
	v_add_f32_e32 v4, v24, v4
	v_add_f32_e32 v4, v4, v5
	v_mov_b32_e32 v5, v4
	s_nop 1
	v_permlane32_swap_b32_e32 v4, v5
	v_add_f32_e32 v4, v4, v5
	v_fmamk_f32 v4, v4, 0x3baaaaab, v227
	v_rsq_f32_e32 v24, v4
	v_mul_u32_u24_e32 v4, 0x190, v154
	v_add3_u32 v25, v153, v4, v157
	v_mul_f32_e32 v5, v64, v24
	v_mul_f32_e32 v0, v0, v5
	v_mul_f32_e32 v5, v65, v24
	v_mul_f32_e32 v1, v1, v5
	v_mul_f32_e32 v5, v67, v24
	v_mul_f32_e32 v2, v2, v5
	v_mul_f32_e32 v5, v68, v24
	v_mul_f32_e32 v3, v3, v5
	v_cvt_pk_bf16_f32 v0, v0, v1
	v_cvt_pk_bf16_f32 v1, v2, v3
	ds_write_b64 v25, v[0:1]
	v_mul_f32_e32 v4, v69, v24
	v_mul_f32_e32 v5, v74, v24
	v_mul_f32_e32 v6, v62, v24
	v_mul_f32_e32 v7, v63, v24
	s_waitcnt vmcnt(0) lgkmcnt(0)
	v_mul_f32_e32 v0, v4, v194
	v_mul_f32_e32 v4, v70, v24
	v_mul_f32_e32 v1, v4, v195
	v_mul_f32_e32 v4, v71, v24
	v_mul_f32_e32 v2, v4, v196
	v_mul_f32_e32 v4, v72, v24
	v_mul_f32_e32 v3, v4, v197
	v_cvt_pk_bf16_f32 v0, v0, v1
	v_cvt_pk_bf16_f32 v1, v2, v3
	ds_write_b64 v25, v[0:1] offset:16
	v_mul_f32_e32 v4, v73, v24
	s_waitcnt vmcnt(0) lgkmcnt(0)
	v_mul_f32_e32 v0, v4, v198
	v_mul_f32_e32 v4, v58, v24
	v_mul_f32_e32 v1, v5, v199
	v_mul_f32_e32 v2, v4, v200
	v_mul_f32_e32 v4, v59, v24
	v_mul_f32_e32 v3, v4, v201
	v_cvt_pk_bf16_f32 v0, v0, v1
	v_cvt_pk_bf16_f32 v1, v2, v3
	ds_write_b64 v25, v[0:1] offset:32
	v_mul_f32_e32 v4, v60, v24
	v_mul_f32_e32 v5, v61, v24
	s_waitcnt vmcnt(0) lgkmcnt(0)
	v_mul_f32_e32 v0, v4, v202
	v_mul_f32_e32 v1, v5, v203
	v_mul_f32_e32 v2, v6, v204
	v_mul_f32_e32 v3, v7, v205
	v_cvt_pk_bf16_f32 v0, v0, v1
	v_cvt_pk_bf16_f32 v1, v2, v3
	ds_write_b64 v25, v[0:1] offset:48
	v_mul_f32_e32 v4, v75, v24
	v_mul_f32_e32 v5, v76, v24
	v_mul_f32_e32 v6, v77, v24
	v_mul_f32_e32 v7, v78, v24
	s_waitcnt vmcnt(0) lgkmcnt(0)
	v_mul_f32_e32 v0, v4, v206
	v_mul_f32_e32 v1, v5, v207
	v_mul_f32_e32 v2, v6, v208
	v_mul_f32_e32 v3, v7, v209
	v_cvt_pk_bf16_f32 v0, v0, v1
	v_cvt_pk_bf16_f32 v1, v2, v3
	ds_write_b64 v25, v[0:1] offset:64
	v_mul_f32_e32 v4, v79, v24
	v_mul_f32_e32 v5, v80, v24
	v_mul_f32_e32 v6, v81, v24
	v_mul_f32_e32 v7, v82, v24
	s_waitcnt vmcnt(0) lgkmcnt(0)
	v_mul_f32_e32 v0, v4, v210
	v_mul_f32_e32 v1, v5, v211
	v_mul_f32_e32 v2, v6, v212
	v_mul_f32_e32 v3, v7, v213
	v_cvt_pk_bf16_f32 v0, v0, v1
	v_cvt_pk_bf16_f32 v1, v2, v3
	ds_write_b64 v25, v[0:1] offset:80
	v_mul_f32_e32 v4, v83, v24
	v_mul_f32_e32 v5, v84, v24
	v_mul_f32_e32 v6, v85, v24
	v_mul_f32_e32 v7, v86, v24
	s_waitcnt vmcnt(0) lgkmcnt(0)
	v_mul_f32_e32 v0, v4, v214
	v_mul_f32_e32 v1, v5, v215
	v_mul_f32_e32 v2, v6, v216
	v_mul_f32_e32 v3, v7, v217
	v_cvt_pk_bf16_f32 v0, v0, v1
	v_cvt_pk_bf16_f32 v1, v2, v3
	ds_write_b64 v25, v[0:1] offset:96
	v_mul_f32_e32 v4, v87, v24
	v_mul_f32_e32 v5, v88, v24
	v_mul_f32_e32 v6, v89, v24
	v_mul_f32_e32 v7, v90, v24
	s_waitcnt vmcnt(0) lgkmcnt(0)
	v_mul_f32_e32 v0, v4, v218
	v_mul_f32_e32 v1, v5, v219
	v_mul_f32_e32 v2, v6, v220
	v_mul_f32_e32 v3, v7, v221
	v_cvt_pk_bf16_f32 v0, v0, v1
	v_cvt_pk_bf16_f32 v1, v2, v3
	ds_write_b64 v25, v[0:1] offset:112
	v_mul_f32_e32 v4, v91, v24
	v_mul_f32_e32 v5, v92, v24
	v_mul_f32_e32 v6, v93, v24
	v_mul_f32_e32 v7, v94, v24
	s_waitcnt vmcnt(0) lgkmcnt(0)
	v_mul_f32_e32 v0, v4, v222
	v_mul_f32_e32 v1, v5, v223
	v_mul_f32_e32 v2, v6, v224
	v_mul_f32_e32 v3, v7, v225
	v_cvt_pk_bf16_f32 v0, v0, v1
	v_cvt_pk_bf16_f32 v1, v2, v3
	ds_write_b64 v25, v[0:1] offset:128
	v_mul_f32_e32 v4, v95, v24
	v_mul_f32_e32 v5, v96, v24
	v_mul_f32_e32 v6, v97, v24
	v_mul_f32_e32 v7, v98, v24
	s_waitcnt vmcnt(0) lgkmcnt(0)
	v_mul_f32_e32 v0, v4, v232
	v_mul_f32_e32 v1, v5, v233
	v_mul_f32_e32 v2, v6, v234
	v_mul_f32_e32 v3, v7, v235
	v_cvt_pk_bf16_f32 v0, v0, v1
	v_cvt_pk_bf16_f32 v1, v2, v3
	ds_write_b64 v25, v[0:1] offset:144
	v_mul_f32_e32 v4, v99, v24
	v_mul_f32_e32 v5, v100, v24
	v_mul_f32_e32 v6, v101, v24
	v_mul_f32_e32 v7, v56, v24
	s_waitcnt vmcnt(0) lgkmcnt(0)
; DEV void epi_ukv(f32x16 (&acc)[1][8], const Params& P, int layer, int batch, int m0, int head, int wid, int r32, int hi, char* lds) {
;     ...
; #pragma unroll
;   for (int ni = 0; ni < 4; ++ni)
; #pragma unroll
;     for (int r4 = 0; r4 < 4; ++r4) {
;       const int c = ni * 32 + r4 * 8 + hi * 4;
;       const float4 gg = *reinterpret_cast<const float4*>(g + c);
;       const f32x16& a = acc[0][ni];
;       st4lds(dst, c, a[r4 * 4] * inv * gg.x, a[r4 * 4 + 1] * inv * gg.y, a[r4 * 4 + 2] * inv * gg.z, a[r4 * 4 + 3] * inv * gg.w);
;     }
;   const int pos = batch ? t : (t & 4095);
;   const float2* rp = WS{P.ws}.rope() + (long)pos * 32;
; #pragma unroll
;   for (int r4 = 0; r4 < 4; ++r4) {
;     const int i = r4 * 8 + hi * 4;
;     const float4 g1 = *reinterpret_cast<const float4*>(g + 128 + i), g2 = *reinterpret_cast<const float4*>(g + 160 + i);
;     const float4 cs01 = *reinterpret_cast<const float4*>(rp + i), cs23 = *reinterpret_cast<const float4*>(rp + i + 2);
;     const float x1[4] = {kr[0][r4].x * inv * g1.x, kr[0][r4].y * inv * g1.y, kr[0][r4].z * inv * g1.z, kr[0][r4].w * inv * g1.w};
;     const float x2[4] = {kr[1][r4].x * inv * g2.x, kr[1][r4].y * inv * g2.y, kr[1][r4].z * inv * g2.z, kr[1][r4].w * inv * g2.w};
;     const float cc[4] = {cs01.x, cs01.z, cs23.x, cs23.z}, sn[4] = {cs01.y, cs01.w, cs23.y, cs23.w};
;     st4lds(dst, 128 + i, x1[0] * cc[0] - x2[0] * sn[0], x1[1] * cc[1] - x2[1] * sn[1], x1[2] * cc[2] - x2[2] * sn[2], x1[3] * cc[3] - x2[3] * sn[3]);
;     st4lds(dst, 160 + i, x1[0] * sn[0] + x2[0] * cc[0], x1[1] * sn[1] + x2[1] * cc[1], x1[2] * sn[2] + x2[2] * cc[2], x1[3] * sn[3] + x2[3] * cc[3]);
	v_mul_f32_e32 v0, v4, v236
	v_mul_f32_e32 v1, v5, v237
	v_mul_f32_e32 v2, v6, v238
	v_mul_f32_e32 v3, v7, v239
	v_cvt_pk_bf16_f32 v0, v0, v1
	v_cvt_pk_bf16_f32 v1, v2, v3
	ds_write_b64 v25, v[0:1] offset:160
	v_mul_f32_e32 v4, v28, v24
	v_mul_f32_e32 v5, v29, v24
	v_mul_f32_e32 v6, v30, v24
	v_mul_f32_e32 v7, v31, v24
	v_mov_b32_e32 v30, v48
	v_mov_b32_e32 v31, v52
	v_mov_b32_e32 v52, v49
	v_mov_b32_e32 v48, v50
	v_mov_b32_e32 v49, v54
	v_mov_b32_e32 v54, v51
	v_pk_mul_f32 v[30:31], v[30:31], v[24:25] op_sel_hi:[1,0]
	v_pk_mul_f32 v[50:51], v[52:53], v[24:25] op_sel_hi:[1,0]
	v_pk_mul_f32 v[48:49], v[48:49], v[24:25] op_sel_hi:[1,0]
	v_pk_mul_f32 v[52:53], v[54:55], v[24:25] op_sel_hi:[1,0]
	s_waitcnt vmcnt(0) lgkmcnt(0)
	v_mul_f32_e32 v0, v4, v240
	v_mul_f32_e32 v1, v5, v241
	v_mul_f32_e32 v2, v6, v242
	v_mul_f32_e32 v3, v7, v243
	v_cvt_pk_bf16_f32 v0, v0, v1
	v_cvt_pk_bf16_f32 v1, v2, v3
	ds_write_b64 v25, v[0:1] offset:176
	v_mul_f32_e32 v4, v57, v24
	v_mul_f32_e32 v5, v102, v24
	v_mul_f32_e32 v6, v103, v24
	v_mul_f32_e32 v7, v104, v24
	s_waitcnt vmcnt(0) lgkmcnt(0)
	v_mul_f32_e32 v0, v4, v244
	v_mul_f32_e32 v1, v5, v245
	v_mul_f32_e32 v2, v6, v246
	v_mul_f32_e32 v3, v7, v247
	v_cvt_pk_bf16_f32 v0, v0, v1
	v_cvt_pk_bf16_f32 v1, v2, v3
	ds_write_b64 v25, v[0:1] offset:192
	v_mul_f32_e32 v4, v105, v24
	v_mul_f32_e32 v5, v106, v24
	v_mul_f32_e32 v6, v107, v24
	v_mul_f32_e32 v7, v108, v24
	s_waitcnt vmcnt(0) lgkmcnt(0)
	v_mul_f32_e32 v0, v4, v248
	v_mul_f32_e32 v1, v5, v249
	v_mul_f32_e32 v2, v6, v250
	v_mul_f32_e32 v3, v7, v251
	v_cvt_pk_bf16_f32 v0, v0, v1
	v_cvt_pk_bf16_f32 v1, v2, v3
	ds_write_b64 v25, v[0:1] offset:208
	v_mul_f32_e32 v4, v8, v24
	v_mul_f32_e32 v5, v9, v24
	v_mul_f32_e32 v6, v10, v24
	v_mul_f32_e32 v7, v11, v24
	v_bitop3_b32 v8, v148, s2, v154 bitop3:0xc8
	v_cndmask_b32_e64 v8, v150, v8, s[26:27]
	v_ashrrev_i32_e32 v9, 31, v8
	v_lshlrev_b64 v[8:9], 8, v[8:9]
	v_lshl_add_u64 v[8:9], s[12:13], 0, v[8:9]
	v_lshl_add_u64 v[28:29], v[8:9], 0, v[184:185]
	s_waitcnt vmcnt(0) lgkmcnt(0)
	v_mul_f32_e32 v0, v4, v170
	v_mul_f32_e32 v1, v5, v171
	v_mul_f32_e32 v2, v6, v172
	v_mul_f32_e32 v3, v7, v173
	v_cvt_pk_bf16_f32 v0, v0, v1
	v_cvt_pk_bf16_f32 v1, v2, v3
	ds_write_b64 v25, v[0:1] offset:224
	v_mul_f32_e32 v4, v12, v24
	v_mul_f32_e32 v5, v13, v24
	v_mul_f32_e32 v6, v14, v24
	v_mul_f32_e32 v7, v15, v24
	s_waitcnt vmcnt(0) lgkmcnt(0)
	v_mul_f32_e32 v0, v4, v174
	v_mul_f32_e32 v1, v5, v175
	v_mul_f32_e32 v2, v6, v176
	v_mul_f32_e32 v3, v7, v177
	v_cvt_pk_bf16_f32 v0, v0, v1
	v_cvt_pk_bf16_f32 v1, v2, v3
	ds_write_b64 v25, v[0:1] offset:240
	global_load_dwordx4 v[0:3], v[26:27], off offset:2560
	global_load_dwordx4 v[4:7], v[26:27], off offset:2688
	global_load_dwordx4 v[8:11], v[28:29], off
	global_load_dwordx4 v[12:15], v[28:29], off offset:16
	s_waitcnt vmcnt(0) lgkmcnt(0)
	v_mov_b32_e32 v54, v0
	v_mov_b32_e32 v55, v4
	v_mov_b32_e32 v4, v1
	v_mov_b32_e32 v0, v2
	v_mov_b32_e32 v1, v6
	v_mov_b32_e32 v6, v3
	v_pk_mul_f32 v[2:3], v[30:31], v[54:55]
	v_pk_mul_f32 v[4:5], v[50:51], v[4:5]
	v_pk_mul_f32 v[0:1], v[48:49], v[0:1]
	v_pk_mul_f32 v[6:7], v[52:53], v[6:7]
	v_pk_mul_f32 v[30:31], v[2:3], v[8:9]
	v_pk_mul_f32 v[48:49], v[4:5], v[10:11]
	v_pk_mul_f32 v[50:51], v[0:1], v[12:13]
	v_pk_mul_f32 v[52:53], v[6:7], v[14:15]
	v_pk_mul_f32 v[2:3], v[2:3], v[8:9] op_sel:[1,0] op_sel_hi:[0,1]
	v_pk_mul_f32 v[4:5], v[4:5], v[10:11] op_sel:[1,0] op_sel_hi:[0,1]
	v_pk_mul_f32 v[0:1], v[0:1], v[12:13] op_sel:[1,0] op_sel_hi:[0,1]
	v_pk_mul_f32 v[6:7], v[6:7], v[14:15] op_sel:[1,0] op_sel_hi:[0,1]
	v_sub_f32_e32 v8, v30, v31
	v_sub_f32_e32 v9, v48, v49
	v_sub_f32_e32 v10, v50, v51
	v_sub_f32_e32 v11, v52, v53
	v_add_f32_e32 v2, v2, v3
	v_add_f32_e32 v3, v4, v5
	v_add_f32_e32 v4, v0, v1
	v_cvt_pk_bf16_f32 v0, v8, v9
	v_cvt_pk_bf16_f32 v1, v10, v11
	v_add_f32_e32 v5, v6, v7
	ds_write_b64 v25, v[0:1] offset:256
	v_cvt_pk_bf16_f32 v0, v2, v3
	v_cvt_pk_bf16_f32 v1, v4, v5
	ds_write_b64 v25, v[0:1] offset:320
	global_load_dwordx4 v[0:3], v[26:27], off offset:2592
	global_load_dwordx4 v[4:7], v[26:27], off offset:2720
	global_load_dwordx4 v[8:11], v[28:29], off offset:64
	global_load_dwordx4 v[12:15], v[28:29], off offset:80
	v_mov_b32_e32 v30, v40
	v_mov_b32_e32 v31, v44
	v_mov_b32_e32 v44, v41
	v_mov_b32_e32 v40, v42
	v_mov_b32_e32 v41, v46
	v_mov_b32_e32 v46, v43
	v_pk_mul_f32 v[30:31], v[30:31], v[24:25] op_sel_hi:[1,0]
	v_pk_mul_f32 v[42:43], v[44:45], v[24:25] op_sel_hi:[1,0]
	v_pk_mul_f32 v[40:41], v[40:41], v[24:25] op_sel_hi:[1,0]
	v_pk_mul_f32 v[44:45], v[46:47], v[24:25] op_sel_hi:[1,0]
	s_waitcnt vmcnt(0) lgkmcnt(0)
; #define LDSP(T) __attribute__((address_space(3))) T*
; template <int NCH, int STRIDE> DEV void slab_flush(char* slab, u16* grow0, int gstride, int lane) {
;   asm volatile("s_waitcnt lgkmcnt(0)" ::: "memory");
; #pragma unroll
;   for (int i = 0; i < NCH / 2; ++i) {
;     const int q = i * 64 + lane, row = q / NCH, cc = q - row * NCH;
;     const u32x4 v = *(LDSP(const u32x4))(slab + row * STRIDE + cc * 16);
;     *reinterpret_cast<u32x4*>(grow0 + (long)row * gstride + cc * 8) = v;
; DEV void epi_ukv(f32x16 (&acc)[1][8], const Params& P, int layer, int batch, int m0, int head, int wid, int r32, int hi, char* lds) {
;     ...
; #pragma unroll
;   for (int r4 = 0; r4 < 4; ++r4) {
;     const int i = r4 * 8 + hi * 4;
;     const float4 g1 = *reinterpret_cast<const float4*>(g + 128 + i), g2 = *reinterpret_cast<const float4*>(g + 160 + i);
;     const float4 cs01 = *reinterpret_cast<const float4*>(rp + i), cs23 = *reinterpret_cast<const float4*>(rp + i + 2);
;     const float x1[4] = {kr[0][r4].x * inv * g1.x, kr[0][r4].y * inv * g1.y, kr[0][r4].z * inv * g1.z, kr[0][r4].w * inv * g1.w};
;     const float x2[4] = {kr[1][r4].x * inv * g2.x, kr[1][r4].y * inv * g2.y, kr[1][r4].z * inv * g2.z, kr[1][r4].w * inv * g2.w};
;     const float cc[4] = {cs01.x, cs01.z, cs23.x, cs23.z}, sn[4] = {cs01.y, cs01.w, cs23.y, cs23.w};
;     st4lds(dst, 128 + i, x1[0] * cc[0] - x2[0] * sn[0], x1[1] * cc[1] - x2[1] * sn[1], x1[2] * cc[2] - x2[2] * sn[2], x1[3] * cc[3] - x2[3] * sn[3]);
;     st4lds(dst, 160 + i, x1[0] * sn[0] + x2[0] * cc[0], x1[1] * sn[1] + x2[1] * cc[1], x1[2] * sn[2] + x2[2] * cc[2], x1[3] * sn[3] + x2[3] * cc[3]);
;   }
;   slab_flush<24, 400>(slab, WS{P.ws}.KB() + (long)(m0 + wid * 32) * 768 + head * 192, 768, hi * 32 + r32);
	v_mov_b32_e32 v46, v0
	v_mov_b32_e32 v47, v4
	v_mov_b32_e32 v4, v1
	v_mov_b32_e32 v0, v2
	v_mov_b32_e32 v1, v6
	v_mov_b32_e32 v6, v3
	v_pk_mul_f32 v[2:3], v[30:31], v[46:47]
	v_pk_mul_f32 v[4:5], v[42:43], v[4:5]
	v_pk_mul_f32 v[0:1], v[40:41], v[0:1]
	v_pk_mul_f32 v[6:7], v[44:45], v[6:7]
	v_pk_mul_f32 v[30:31], v[2:3], v[8:9]
	v_pk_mul_f32 v[40:41], v[4:5], v[10:11]
	v_pk_mul_f32 v[42:43], v[0:1], v[12:13]
	v_pk_mul_f32 v[44:45], v[6:7], v[14:15]
	v_pk_mul_f32 v[2:3], v[2:3], v[8:9] op_sel:[1,0] op_sel_hi:[0,1]
	v_pk_mul_f32 v[4:5], v[4:5], v[10:11] op_sel:[1,0] op_sel_hi:[0,1]
	v_pk_mul_f32 v[0:1], v[0:1], v[12:13] op_sel:[1,0] op_sel_hi:[0,1]
	v_pk_mul_f32 v[6:7], v[6:7], v[14:15] op_sel:[1,0] op_sel_hi:[0,1]
	v_sub_f32_e32 v8, v30, v31
	v_sub_f32_e32 v9, v40, v41
	v_sub_f32_e32 v10, v42, v43
	v_sub_f32_e32 v11, v44, v45
	v_add_f32_e32 v2, v2, v3
	v_add_f32_e32 v3, v4, v5
	v_add_f32_e32 v4, v0, v1
	v_cvt_pk_bf16_f32 v0, v8, v9
	v_cvt_pk_bf16_f32 v1, v10, v11
	v_add_f32_e32 v5, v6, v7
	ds_write_b64 v25, v[0:1] offset:272
	v_cvt_pk_bf16_f32 v0, v2, v3
	v_cvt_pk_bf16_f32 v1, v4, v5
	ds_write_b64 v25, v[0:1] offset:336
	global_load_dwordx4 v[8:11], v[26:27], off offset:2624
	global_load_dwordx4 v[4:7], v[26:27], off offset:2752
	global_load_dwordx4 v[0:3], v[28:29], off offset:128
	global_load_dwordx4 v[12:15], v[28:29], off offset:144
	v_and_b32_e32 v40, 63, v152
	v_mul_lo_u16_e32 v41, 43, v40
	v_or_b32_e32 v42, 64, v40
	v_or_b32_e32 v43, 0x80, v40
	v_lshrrev_b16_e32 v41, 10, v41
	v_mul_lo_u16_e32 v53, 43, v42
	v_mul_lo_u16_e32 v54, 0xab, v43
	v_or_b32_e32 v44, 0xc0, v40
	v_or_b32_e32 v45, 0x100, v40
	v_or_b32_e32 v46, 0x180, v40
	v_or_b32_e32 v47, 0x140, v40
	v_or_b32_e32 v48, 0x200, v40
	v_or_b32_e32 v49, 0x1c0, v40
	v_or_b32_e32 v50, 0x280, v40
	v_or_b32_e32 v51, 0x240, v40
	v_or_b32_e32 v52, 0x2c0, v40
	v_mad_i32_i24 v40, v41, s58, v40
	v_mul_u32_u24_e32 v64, 0x190, v41
	v_mul_u32_u24_e32 v65, 0x300, v41
	v_lshrrev_b16_e32 v41, 10, v53
	v_lshrrev_b16_e32 v53, 12, v54
	v_mad_i32_i24 v69, v41, s58, v42
	v_mad_i32_i24 v72, v53, s58, v43
	v_mov_b32_e32 v42, v36
	v_mov_b32_e32 v43, v20
	v_mov_b32_e32 v20, v37
	v_mov_b32_e32 v36, v38
	v_mov_b32_e32 v37, v22
	v_mov_b32_e32 v22, v39
	v_pk_mul_f32 v[38:39], v[42:43], v[24:25] op_sel_hi:[1,0]
	v_pk_mul_f32 v[20:21], v[20:21], v[24:25] op_sel_hi:[1,0]
	v_pk_mul_f32 v[36:37], v[36:37], v[24:25] op_sel_hi:[1,0]
	v_pk_mul_f32 v[22:23], v[22:23], v[24:25] op_sel_hi:[1,0]
	v_mul_lo_u16_e32 v55, 0xab, v44
	v_mul_u32_u24_e32 v56, 0xaab, v45
	v_mul_u32_u24_e32 v57, 0xaab, v47
	v_mul_u32_u24_e32 v58, 0xaab, v46
	v_mul_u32_u24_e32 v59, 0xaab, v49
	v_mul_u32_u24_e32 v60, 0xaab, v48
	v_mul_u32_u24_e32 v61, 0xaab, v51
	v_mul_u32_u24_e32 v62, 0xaab, v50
	v_mov_b64_e32 v[30:31], s[70:71]
	v_mul_u32_u24_e32 v63, 0xaab, v52
	v_lshrrev_b16_e32 v54, 12, v55
	v_lshrrev_b32_e32 v55, 16, v56
	v_lshrrev_b32_e32 v56, 16, v57
	v_lshrrev_b32_e32 v66, 16, v58
	v_perm_b32 v57, v58, v57, s44
	v_lshrrev_b32_e32 v58, 16, v59
	v_lshrrev_b32_e32 v67, 16, v60
	v_perm_b32 v59, v60, v59, s44
	v_lshrrev_b32_e32 v60, 16, v61
	v_lshrrev_b32_e32 v68, 16, v62
	v_mad_i64_i32 v[30:31], s[2:3], v148, s39, v[30:31]
	v_perm_b32 v61, v62, v61, s44
	v_lshrrev_b32_e32 v62, 16, v63
	v_lshlrev_b32_e32 v63, 4, v40
	v_mad_i32_i24 v48, v67, s58, v48
	v_mad_i32_i24 v51, v60, s58, v51
	v_mad_i32_i24 v50, v68, s58, v50
	v_mad_i32_i24 v52, v62, s58, v52
	v_lshlrev_b32_e32 v75, 4, v48
	v_lshlrev_b32_e32 v77, 4, v51
	v_lshlrev_b32_e32 v78, 4, v50
	v_lshlrev_b32_e32 v40, 3, v40
	v_lshlrev_b32_e32 v184, 1, v65
	v_mul_u32_u24_e32 v70, 0x190, v41
	v_mul_u32_u24_e32 v71, 0x300, v41
	v_ashrrev_i32_e32 v41, 31, v40
	v_lshlrev_b32_e32 v79, 4, v52
	s_waitcnt vmcnt(0) lgkmcnt(0)
	v_mov_b32_e32 v42, v8
	v_mov_b32_e32 v43, v4
	v_mov_b32_e32 v4, v9
	v_mov_b32_e32 v8, v10
	v_mov_b32_e32 v9, v6
	v_mov_b32_e32 v6, v11
	v_pk_mul_f32 v[10:11], v[38:39], v[42:43]
	v_pk_mul_f32 v[4:5], v[20:21], v[4:5]
	v_pk_mul_f32 v[8:9], v[36:37], v[8:9]
	v_pk_mul_f32 v[6:7], v[22:23], v[6:7]
	v_pk_mul_f32 v[20:21], v[10:11], v[0:1]
	v_pk_mul_f32 v[22:23], v[4:5], v[2:3]
	v_pk_mul_f32 v[36:37], v[8:9], v[12:13]
	v_pk_mul_f32 v[38:39], v[6:7], v[14:15]
	v_pk_mul_f32 v[0:1], v[10:11], v[0:1] op_sel:[1,0] op_sel_hi:[0,1]
	v_pk_mul_f32 v[2:3], v[4:5], v[2:3] op_sel:[1,0] op_sel_hi:[0,1]
	v_pk_mul_f32 v[4:5], v[8:9], v[12:13] op_sel:[1,0] op_sel_hi:[0,1]
	v_pk_mul_f32 v[6:7], v[6:7], v[14:15] op_sel:[1,0] op_sel_hi:[0,1]
	v_sub_f32_e32 v8, v20, v21
	v_sub_f32_e32 v9, v22, v23
	v_sub_f32_e32 v10, v36, v37
	v_sub_f32_e32 v11, v38, v39
	v_add_f32_e32 v12, v0, v1
	v_cvt_pk_bf16_f32 v0, v8, v9
	v_cvt_pk_bf16_f32 v1, v10, v11
	v_add_f32_e32 v2, v2, v3
	v_add_f32_e32 v3, v4, v5
	v_add_f32_e32 v4, v6, v7
	ds_write_b64 v25, v[0:1] offset:288
	v_cvt_pk_bf16_f32 v0, v12, v2
	v_cvt_pk_bf16_f32 v1, v3, v4
	ds_write_b64 v25, v[0:1] offset:352
	global_load_dwordx4 v[0:3], v[26:27], off offset:2656
	global_load_dwordx4 v[4:7], v[26:27], off offset:2784
	global_load_dwordx4 v[8:11], v[28:29], off offset:192
	global_load_dwordx4 v[12:15], v[28:29], off offset:208
	v_mad_i32_i24 v23, v54, s58, v44
	v_mad_i32_i24 v36, v55, s58, v45
	v_mad_i32_i24 v38, v56, s58, v47
	v_mad_i32_i24 v42, v66, s58, v46
	v_mad_i32_i24 v44, v58, s58, v49
	v_pk_mul_lo_u16 v46, v59, s37 op_sel_hi:[1,0]
	v_mul_u32_u24_e32 v39, 0x190, v55
	v_mul_u32_u24_e32 v45, 0x300, v55
	v_pk_mul_lo_u16 v29, v57, s37 op_sel_hi:[1,0]
	v_mul_u32_u24_e32 v47, 0x300, v56
	v_mul_u32_u24_e32 v55, 0x300, v67
	v_pk_mul_lo_u16 v56, v61, s37 op_sel_hi:[1,0]
	v_mul_u32_u24_e32 v57, 0x300, v60
	v_mul_u32_u24_e32 v59, 0x190, v62
	v_mul_u32_u24_e32 v60, 0x300, v62
; #define LDSP(T) __attribute__((address_space(3))) T*
; template <int NCH, int STRIDE> DEV void slab_flush(char* slab, u16* grow0, int gstride, int lane) {
;   asm volatile("s_waitcnt lgkmcnt(0)" ::: "memory");
; #pragma unroll
;   for (int i = 0; i < NCH / 2; ++i) {
;     const int q = i * 64 + lane, row = q / NCH, cc = q - row * NCH;
;     const u32x4 v = *(LDSP(const u32x4))(slab + row * STRIDE + cc * 16);
;     *reinterpret_cast<u32x4*>(grow0 + (long)row * gstride + cc * 8) = v;
;   }
;   asm volatile("s_waitcnt lgkmcnt(0)" ::: "memory");
; }
; DEV void epi_ukv(f32x16 (&acc)[1][8], const Params& P, int layer, int batch, int m0, int head, int wid, int r32, int hi, char* lds) {
;     ...
; #pragma unroll
;   for (int r4 = 0; r4 < 4; ++r4) {
;     const int i = r4 * 8 + hi * 4;
;     const float4 g1 = *reinterpret_cast<const float4*>(g + 128 + i), g2 = *reinterpret_cast<const float4*>(g + 160 + i);
;     const float4 cs01 = *reinterpret_cast<const float4*>(rp + i), cs23 = *reinterpret_cast<const float4*>(rp + i + 2);
;     const float x1[4] = {kr[0][r4].x * inv * g1.x, kr[0][r4].y * inv * g1.y, kr[0][r4].z * inv * g1.z, kr[0][r4].w * inv * g1.w};
;     const float x2[4] = {kr[1][r4].x * inv * g2.x, kr[1][r4].y * inv * g2.y, kr[1][r4].z * inv * g2.z, kr[1][r4].w * inv * g2.w};
;     const float cc[4] = {cs01.x, cs01.z, cs23.x, cs23.z}, sn[4] = {cs01.y, cs01.w, cs23.y, cs23.w};
;     st4lds(dst, 128 + i, x1[0] * cc[0] - x2[0] * sn[0], x1[1] * cc[1] - x2[1] * sn[1], x1[2] * cc[2] - x2[2] * sn[2], x1[3] * cc[3] - x2[3] * sn[3]);
;     st4lds(dst, 160 + i, x1[0] * sn[0] + x2[0] * cc[0], x1[1] * sn[1] + x2[1] * cc[1], x1[2] * sn[2] + x2[2] * cc[2], x1[3] * sn[3] + x2[3] * cc[3]);
;   }
;   slab_flush<24, 400>(slab, WS{P.ws}.KB() + (long)(m0 + wid * 32) * 768 + head * 192, 768, hi * 32 + r32);
	v_lshl_add_u64 v[20:21], v[30:31], 0, s[22:23]
	v_add3_u32 v61, v153, v64, v63
	v_lshlrev_b32_e32 v31, 4, v69
	v_lshlrev_b32_e32 v22, 3, v69
	v_lshlrev_b32_e32 v62, 4, v72
	v_lshlrev_b32_e32 v26, 3, v72
	v_lshlrev_b32_e32 v64, 4, v36
	v_lshlrev_b32_e32 v30, 3, v36
	v_lshlrev_b32_e32 v67, 4, v38
	v_lshlrev_b32_e32 v36, 3, v38
	v_lshlrev_b32_e32 v69, 4, v42
	v_lshlrev_b32_e32 v38, 3, v42
	v_and_b32_e32 v72, 0xfff0, v46
	v_lshlrev_b32_e32 v73, 4, v44
	v_lshlrev_b32_e32 v42, 3, v44
	v_lshrrev_b32_e32 v74, 16, v46
	v_lshlrev_b32_e32 v44, 3, v48
	v_lshlrev_b32_e32 v46, 3, v51
	v_lshlrev_b32_e32 v48, 3, v50
	v_mov_b32_e32 v50, v32
	v_mov_b32_e32 v51, v16
	v_mov_b32_e32 v16, v33
	v_mov_b32_e32 v32, v34
	v_mov_b32_e32 v33, v18
	v_mov_b32_e32 v18, v35
	v_pk_mul_f32 v[34:35], v[50:51], v[24:25] op_sel_hi:[1,0]
	v_pk_mul_f32 v[16:17], v[16:17], v[24:25] op_sel_hi:[1,0]
	v_pk_mul_f32 v[32:33], v[32:33], v[24:25] op_sel_hi:[1,0]
	v_pk_mul_f32 v[18:19], v[18:19], v[24:25] op_sel_hi:[1,0]
	v_add3_u32 v70, v153, v70, v31
	v_lshlrev_b32_e32 v63, 4, v23
	v_lshlrev_b32_e32 v28, 3, v23
	v_ashrrev_i32_e32 v23, 31, v22
	v_mul_u32_u24_e32 v27, 0x190, v53
	v_add3_u32 v62, v153, v27, v62
	v_mul_u32_u24_e32 v43, 0x300, v53
	v_ashrrev_i32_e32 v27, 31, v26
	v_mul_u32_u24_e32 v37, 0x190, v54
	v_add3_u32 v63, v153, v37, v63
	v_mul_u32_u24_e32 v53, 0x300, v54
	v_mul_u32_u24_e32 v54, 0x300, v66
	v_mul_u32_u24_e32 v49, 0x300, v58
	v_mul_u32_u24_e32 v58, 0x300, v68
	v_and_b32_e32 v66, 0xfff0, v29
	v_lshrrev_b32_e32 v68, 16, v29
	v_ashrrev_i32_e32 v29, 31, v28
	v_add3_u32 v64, v153, v39, v64
	v_ashrrev_i32_e32 v31, 31, v30
	v_add3_u32 v66, v153, v66, v67
	v_ashrrev_i32_e32 v37, 31, v36
	v_ashrrev_i32_e32 v39, 31, v38
	v_and_b32_e32 v76, 0xfff0, v56
	v_lshrrev_b32_e32 v56, 16, v56
	s_waitcnt vmcnt(0) lgkmcnt(0)
	v_mov_b32_e32 v50, v0
	v_mov_b32_e32 v51, v4
	v_mov_b32_e32 v4, v1
	v_mov_b32_e32 v0, v2
	v_mov_b32_e32 v1, v6
	v_mov_b32_e32 v6, v3
	v_pk_mul_f32 v[2:3], v[34:35], v[50:51]
	v_pk_mul_f32 v[4:5], v[16:17], v[4:5]
	v_pk_mul_f32 v[0:1], v[32:33], v[0:1]
	v_pk_mul_f32 v[6:7], v[18:19], v[6:7]
	v_pk_mul_f32 v[16:17], v[2:3], v[8:9]
	v_pk_mul_f32 v[18:19], v[4:5], v[10:11]
	v_pk_mul_f32 v[32:33], v[0:1], v[12:13]
	v_pk_mul_f32 v[34:35], v[6:7], v[14:15]
	v_pk_mul_f32 v[2:3], v[2:3], v[8:9] op_sel:[1,0] op_sel_hi:[0,1]
	v_pk_mul_f32 v[4:5], v[4:5], v[10:11] op_sel:[1,0] op_sel_hi:[0,1]
	v_pk_mul_f32 v[0:1], v[0:1], v[12:13] op_sel:[1,0] op_sel_hi:[0,1]
	v_pk_mul_f32 v[6:7], v[6:7], v[14:15] op_sel:[1,0] op_sel_hi:[0,1]
	v_sub_f32_e32 v8, v16, v17
	v_sub_f32_e32 v9, v18, v19
	v_sub_f32_e32 v10, v32, v33
	v_sub_f32_e32 v11, v34, v35
	v_add_f32_e32 v2, v2, v3
	v_add_f32_e32 v3, v4, v5
	v_add_f32_e32 v4, v0, v1
	v_cvt_pk_bf16_f32 v0, v8, v9
	v_cvt_pk_bf16_f32 v1, v10, v11
	v_add_f32_e32 v5, v6, v7
	ds_write_b64 v25, v[0:1] offset:304
	v_cvt_pk_bf16_f32 v0, v2, v3
	v_cvt_pk_bf16_f32 v1, v4, v5
	ds_write_b64 v25, v[0:1] offset:368
	s_waitcnt lgkmcnt(0)
	ds_read_b128 v[0:3], v61
	v_lshl_add_u64 v[4:5], v[20:21], 0, v[184:185]
	v_lshl_add_u64 v[4:5], v[40:41], 1, v[4:5]
	v_lshlrev_b32_e32 v184, 1, v71
	v_add3_u32 v6, v153, v68, v69
	s_waitcnt lgkmcnt(0)
	global_store_dwordx4 v[4:5], v[0:3], off
	ds_read_b128 v[0:3], v70
	v_lshl_add_u64 v[4:5], v[20:21], 0, v[184:185]
	v_lshl_add_u64 v[4:5], v[22:23], 1, v[4:5]
	v_lshlrev_b32_e32 v184, 1, v43
	v_add3_u32 v7, v153, v72, v73
	s_waitcnt lgkmcnt(0)
	global_store_dwordx4 v[4:5], v[0:3], off
	ds_read_b128 v[0:3], v62
	v_lshl_add_u64 v[4:5], v[20:21], 0, v[184:185]
	v_lshl_add_u64 v[4:5], v[26:27], 1, v[4:5]
	v_lshlrev_b32_e32 v184, 1, v53
	v_ashrrev_i32_e32 v43, 31, v42
	s_waitcnt lgkmcnt(0)
	global_store_dwordx4 v[4:5], v[0:3], off
	ds_read_b128 v[0:3], v63
	v_lshl_add_u64 v[4:5], v[20:21], 0, v[184:185]
	v_lshl_add_u64 v[4:5], v[28:29], 1, v[4:5]
	v_lshlrev_b32_e32 v184, 1, v45
	v_add3_u32 v8, v153, v74, v75
	s_waitcnt lgkmcnt(0)
	global_store_dwordx4 v[4:5], v[0:3], off
	ds_read_b128 v[0:3], v64
	v_lshl_add_u64 v[4:5], v[20:21], 0, v[184:185]
	v_lshl_add_u64 v[4:5], v[30:31], 1, v[4:5]
	v_lshlrev_b32_e32 v184, 1, v47
	v_ashrrev_i32_e32 v45, 31, v44
	s_waitcnt lgkmcnt(0)
	global_store_dwordx4 v[4:5], v[0:3], off
	ds_read_b128 v[0:3], v66
	v_lshl_add_u64 v[4:5], v[20:21], 0, v[184:185]
	v_lshl_add_u64 v[4:5], v[36:37], 1, v[4:5]
	v_lshlrev_b32_e32 v184, 1, v54
	v_ashrrev_i32_e32 v47, 31, v46
	s_waitcnt lgkmcnt(0)
	global_store_dwordx4 v[4:5], v[0:3], off
	ds_read_b128 v[0:3], v6
	v_lshl_add_u64 v[4:5], v[20:21], 0, v[184:185]
	v_lshl_add_u64 v[4:5], v[38:39], 1, v[4:5]
	v_lshlrev_b32_e32 v184, 1, v49
	v_add3_u32 v6, v153, v76, v77
	s_waitcnt lgkmcnt(0)
	global_store_dwordx4 v[4:5], v[0:3], off
	ds_read_b128 v[0:3], v7
	v_lshl_add_u64 v[4:5], v[20:21], 0, v[184:185]
	v_lshl_add_u64 v[4:5], v[42:43], 1, v[4:5]
	v_lshlrev_b32_e32 v184, 1, v55
	v_add3_u32 v7, v153, v56, v78
	s_waitcnt lgkmcnt(0)
	global_store_dwordx4 v[4:5], v[0:3], off
	ds_read_b128 v[0:3], v8
	v_lshl_add_u64 v[4:5], v[20:21], 0, v[184:185]
	v_lshl_add_u64 v[4:5], v[44:45], 1, v[4:5]
	v_lshlrev_b32_e32 v184, 1, v57
	v_ashrrev_i32_e32 v49, 31, v48
	s_waitcnt lgkmcnt(0)
	global_store_dwordx4 v[4:5], v[0:3], off
	ds_read_b128 v[0:3], v6
	v_lshl_add_u64 v[4:5], v[20:21], 0, v[184:185]
	v_lshl_add_u64 v[4:5], v[46:47], 1, v[4:5]
	v_lshlrev_b32_e32 v184, 1, v58
	v_add3_u32 v6, v153, v59, v79
	s_waitcnt lgkmcnt(0)
	global_store_dwordx4 v[4:5], v[0:3], off
	ds_read_b128 v[0:3], v7
	v_lshl_add_u64 v[4:5], v[20:21], 0, v[184:185]
	v_lshl_add_u64 v[4:5], v[48:49], 1, v[4:5]
	v_lshlrev_b32_e32 v184, 1, v60
	s_waitcnt lgkmcnt(0)
	global_store_dwordx4 v[4:5], v[0:3], off
	ds_read_b128 v[0:3], v6
	v_lshlrev_b32_e32 v6, 3, v52
	v_lshl_add_u64 v[4:5], v[20:21], 0, v[184:185]
	v_ashrrev_i32_e32 v7, 31, v6
	v_lshl_add_u64 v[4:5], v[6:7], 1, v[4:5]
	s_waitcnt lgkmcnt(0)
	global_store_dwordx4 v[4:5], v[0:3], off
	s_waitcnt lgkmcnt(0)
	s_waitcnt lgkmcnt(0)
	s_barrier
	s_branch .LBB0_355

; DEV void attn_a_item(const Params& P, int layer, int batch, int item, char* lds) {
;   const int tid = opaque_tid(), wid = tid >> 6, lane = tid & 63, r32 = lane & 31, hi = lane >> 5;
;   const int seqlen = batch ? 16384 : 4096;
;   const int head = 3 - (item >> 7), k_ = item & 127;
;   const int kk_ = batch ? k_ : (k_ >> 2), mid_ = batch ? 64 : 16;
;   const int qb = mid_ + ((kk_ & 1) ? -((kk_ + 1) >> 1) : (kk_ >> 1));
;   const int seq = batch ? 0 : (k_ & 3);
;   const long tok0 = (long)seq * 4096;
;   const int c = wid >> 2, wq = wid & 3;
;   const int qpos = qb * 128 + wq * 32 + r32;
;   char* V_lds = lds; char* K_lds = lds + 32768;
;   float* wsl = reinterpret_cast<float*>(lds + LDS_WS) + wid * 64;
;   const float lam = WS{P.ws}.consts()[layer * 1024 + 0], nMC = -WS{P.ws}.consts()[layer * 1024 + 1], lam_init = WS{P.ws}.consts()[layer * 1024 + 3];
;   const float nslope = -exp2f(-2.f * (float)(head + 1)) * LOG2E;
;   bf16x8 qr[4];
;   {
;     const u16* Qw = WS{P.ws}.QA() + (tok0 + qpos) * 512 + head * 128 + c * 64 + hi * 8;
; #pragma unroll
;     for (int ks = 0; ks < 4; ++ks) qr[ks] = *reinterpret_cast<const bf16x8*>(Qw + ks * 16);
;   }
;   const u16* Kh = WS{P.ws}.KA() + tok0 * 512 + head * 128;
;   const u16* Vh = WS{P.ws}.VA() + tok0 * 512 + head * 128;
;   int akoff[2], avoff[2], ldst[2];
; #pragma unroll
;   for (int i = 0; i < 2; ++i) {
;     const int p = (wid + 8 * i) * 1024 + lane * 16;
;     ldst[i] = p;
;     const int row = p >> 8, cB = (p & 255) ^ ((row & 7) << 4);
;     akoff[i] = row * 512 + (cB >> 1);
;     const int st = p >> 9, within = p & 511, kk = (st >> 2) * 8 + (within >> 6);
;     const int k = kk, col = (st & 3) * 32 + ((within & 63) >> 1);
;     avoff[i] = k * 512 + col;
;   }
;   const int vb0 = (int)(uintptr_t)V_lds + v_rd_base(lane);
;     ...
;   f32x16 o[4] = {f32x16{}, f32x16{}, f32x16{}, f32x16{}};
;   float lsum = 0.f;
;   const int NT = seqlen >> 6;
; DEV void phase_attn(const Params& P, int layer, int batch, char* lds) {
;     ...
;   for (;;) {
;     if (threadIdx.x == 0) *qw = (int)__hip_atomic_fetch_add(ctr, 1u, __ATOMIC_RELAXED, __HIP_MEMORY_SCOPE_AGENT);
;     __syncthreads();
;     const int it = __builtin_amdgcn_readfirstlane(*qw);
;     __syncthreads();
;     if (it >= 768) break;
;     if (it < 256) attn_b_item(P, layer, batch, it, lds);
;     else          attn_a_item(P, layer, batch, it - 256, lds);
.LBB0_371:
	s_or_b64 exec, exec, s[2:3]
	s_mov_b32 s100, 0
	s_add_i32 s2, 0, 0x207f0
	s_cmp_lg_u32 s2, -1
	s_cselect_b32 s2, s2, 0
	s_cselect_b32 s3, s21, 0
	v_mov_b32_e32 v0, s2
	v_mov_b32_e32 v1, s3
	s_waitcnt lgkmcnt(0)
	s_barrier
	flat_load_dword v0, v[0:1] sc0 sc1
	s_waitcnt vmcnt(0)
	s_mov_b64 s[2:3], -1
	s_waitcnt lgkmcnt(0)
	s_barrier
	v_readfirstlane_b32 s63, v0
	s_cmpk_gt_i32 s63, 0x2ff
	s_cbranch_scc1 .LBB0_368
	s_cmpk_gt_i32 s63, 0xff
	s_cbranch_scc0 .LBB0_390
	s_add_i32 s22, s63, 0xffffff00
	s_and_b32 s18, s63, 0x7f
	s_bfe_u32 s19, s63, 0x50002
	s_and_b64 s[2:3], s[26:27], exec
	s_cselect_b32 s2, s19, s18
	s_add_i32 s18, s2, 1
	s_lshr_b32 s18, s18, 1
	s_and_b32 s3, s2, 1
	s_sub_i32 s18, 0, s18
	s_lshr_b32 s2, s2, 1
	s_cmp_eq_u32 s3, 0
	s_cselect_b32 s2, s2, s18
	v_readlane_b32 s3, v254, 32
	v_mov_b32_e32 v159, v226
	s_add_i32 s24, s2, s3
	s_lshl_b32 s2, s22, 12
	s_and_b32 s18, s2, 0x3000
	v_ashrrev_i32_e32 v4, 6, v159
	s_and_b64 s[2:3], s[26:27], exec
	v_lshlrev_b32_e32 v161, 5, v4
	v_and_b32_e32 v162, 31, v159
	s_cselect_b32 s19, 0, 0
	s_cselect_b32 s18, s18, 0
	s_lshl_b32 s64, s24, 7
	v_and_b32_e32 v163, 0x60, v161
	v_or3_b32 v0, v162, s64, v163
	s_lshr_b32 s2, s22, 6
	s_and_b32 s2, s2, 6
	v_ashrrev_i32_e32 v1, 31, v0
	s_or_b32 s2, s2, -8
	v_lshl_add_u64 v[0:1], s[18:19], 0, v[0:1]
	v_ashrrev_i32_e32 v164, 8, v159
	v_mov_b64_e32 v[2:3], s[8:9]
	v_ldexp_f32 v13, 1.0, s2
	v_lshlrev_b64 v[0:1], 10, v[0:1]
	s_andn2_b32 s2, 0x180, s22
	global_load_dwordx2 v[128:129], v[2:3], off
	global_load_dword v158, v[2:3], off offset:12
	v_lshl_add_u64 v[0:1], s[10:11], 0, v[0:1]
	s_lshl_b32 s22, s2, 1
	v_lshlrev_b32_e32 v2, 6, v164
	v_and_b32_e32 v165, 63, v159
	v_lshl_add_u64 v[0:1], v[0:1], 0, s[22:23]
	v_ashrrev_i32_e32 v3, 31, v2
	v_lshl_add_u64 v[0:1], v[2:3], 1, v[0:1]
	v_lshlrev_b32_e32 v6, 10, v4
	v_lshlrev_b32_e32 v3, 4, v165
	v_bfe_u32 v8, v159, 2, 3
	v_or_b32_e32 v166, v6, v3
	v_ashrrev_i32_e32 v4, 8, v6
	v_lshlrev_b32_e32 v11, 3, v165
	v_and_or_b32 v9, v4, s45, v8
	v_lshrrev_b32_e32 v5, 4, v166
	v_bfe_u32 v160, v159, 5, 1
	s_lshl_b32 s2, s18, 10
	v_and_b32_e32 v2, 24, v11
	v_and_b32_e32 v5, 0x60, v5
	v_lshlrev_b32_e32 v9, 9, v9
	v_lshlrev_b32_e32 v184, 4, v160
	s_add_u32 s24, s34, s2
	v_or3_b32 v14, v9, v5, v2
	v_add_u32_e32 v9, 0x2000, v6
	v_lshl_add_u64 v[0:1], v[0:1], 0, v[184:185]
	s_addc_u32 s25, s35, 0
	v_or_b32_e32 v15, v9, v3
	v_mul_f32_e32 v130, 0xbfb8aa3b, v13
	global_load_dwordx4 v[96:99], v[0:1], off
	global_load_dwordx4 v[100:103], v[0:1], off offset:32
	global_load_dwordx4 v[104:107], v[0:1], off offset:64
	global_load_dwordx4 v[108:111], v[0:1], off offset:96
	s_add_u32 s65, s36, s2
	v_ashrrev_i32_e32 v0, 8, v166
	v_ashrrev_i32_e32 v6, 8, v15
	v_div_scale_f32 v13, s[2:3], v130, v130, s46
	v_and_b32_e32 v7, 0xf0, v3
	v_lshlrev_b32_e32 v1, 4, v0
	v_lshlrev_b32_e32 v10, 4, v6
	v_rcp_f32_e32 v19, v13
	v_bitop3_b32 v1, v1, v7, s95 bitop3:0x6c
	v_bitop3_b32 v7, v10, v7, s95 bitop3:0x6c
	v_ashrrev_i32_e32 v10, 8, v9
	v_and_or_b32 v17, v10, s45, v8
	v_lshrrev_b32_e32 v15, 4, v15
	v_and_b32_e32 v15, 0x60, v15
	v_lshlrev_b32_e32 v17, 9, v17
	v_or3_b32 v18, v17, v15, v2
	v_fma_f32 v15, -v13, v19, 1.0
	v_fmac_f32_e32 v19, v15, v19
	v_div_scale_f32 v15, vcc, s46, v130, s46
	v_mul_f32_e32 v17, v15, v19
	v_fma_f32 v20, -v13, v17, v15
	v_fmac_f32_e32 v17, v20, v19
	v_fma_f32 v13, -v13, v17, v15
	v_div_fmas_f32 v13, v13, v19, v17
	v_div_fixup_f32 v13, v13, v130, s46
	v_min_f32_e32 v13, 0x49742400, v13
	v_cvt_i32_f32_e32 v13, v13
	s_addc_u32 s68, s38, 0
	s_add_u32 s3, s24, s22
	s_addc_u32 s71, s25, 0
	s_add_u32 s74, s65, s22
	v_readfirstlane_b32 s24, v13
	s_addc_u32 s75, s68, 0
	s_sub_i32 s2, s64, s24
	s_ashr_i32 s2, s2, 6
	s_or_b32 s65, s64, 0x7f
	s_max_i32 s2, s2, 0
	s_add_i32 s24, s65, s24
	s_ashr_i32 s78, s24, 6
	s_lshl_b32 s24, s2, 6
	s_mov_b32 s25, s23
	s_lshl_b64 s[68:69], s[24:25], 10
	v_lshlrev_b32_e32 v0, 9, v0
	v_lshrrev_b32_e32 v1, 1, v1
	s_add_u32 s70, s3, s68
	v_add_u32_e32 v20, 0, v166
	v_or_b32_e32 v12, v1, v0
	s_addc_u32 s71, s71, s69
	v_add_u32_e32 v15, 0x8000, v20
	s_add_u32 s68, s74, s68
	v_ashrrev_i32_e32 v13, 31, v12
	v_readfirstlane_b32 s3, v15
	v_lshlrev_b32_e32 v6, 9, v6
	v_lshrrev_b32_e32 v7, 1, v7
	s_addc_u32 s69, s75, s69
	v_lshl_add_u64 v[12:13], v[12:13], 1, s[70:71]
	s_mov_b32 m0, s3
	v_ashrrev_i32_e32 v15, 31, v14
	v_or_b32_e32 v16, v7, v6
	global_load_lds_dwordx4 v[12:13], off
	v_lshl_add_u64 v[12:13], v[14:15], 1, s[68:69]
	v_readfirstlane_b32 s3, v20
	v_add_u32_e32 v14, 0xa000, v20
	s_mov_b32 m0, s3
	v_ashrrev_i32_e32 v17, 31, v16
	v_readfirstlane_b32 s3, v14
	v_add_u32_e32 v14, 0x2000, v20
	global_load_lds_dwordx4 v[12:13], off
	v_lshl_add_u64 v[12:13], v[16:17], 1, s[70:71]
	s_mov_b32 m0, s3
	v_ashrrev_i32_e32 v19, 31, v18
	v_readfirstlane_b32 s3, v14
	global_load_lds_dwordx4 v[12:13], off
	v_lshl_add_u64 v[12:13], v[18:19], 1, s[68:69]
	s_mov_b32 m0, s3
	s_min_i32 s70, s49, s78
	global_load_lds_dwordx4 v[12:13], off
	s_waitcnt vmcnt(0)
	s_mov_b32 s25, 0
	s_cmp_gt_i32 s2, s70
	s_waitcnt vmcnt(0) lgkmcnt(0)
	s_barrier
	s_cbranch_scc1 .LBB0_382
; DEV int v_rd_base(int lane) { return ((lane & 3) << 3) | (((lane >> 2) & 3) << 6) | (((lane >> 4) & 1) << 5) | (((lane >> 5) & 1) << 8); }
; DEV void attn_a_item(const Params& P, int layer, int batch, int item, char* lds) {
;     ...
;   const int vb0 = (int)(uintptr_t)V_lds + v_rd_base(lane);
;     ...
;   f32x16 o[4] = {f32x16{}, f32x16{}, f32x16{}, f32x16{}};
;   float lsum = 0.f;
;   const int NT = seqlen >> 6;
;   const int Dk = (int)fminf(160.f / -nslope, 1.0e6f);
;   const int jlo = max(0, (qb * 128 - Dk) >> 6), jhi = min(NT - 1, (qb * 128 + 127 + Dk) >> 6);
;   ALOAD(0, jlo * 64); asm volatile("s_waitcnt vmcnt(0)" ::: "memory"); __syncthreads();
;   for (int j = jlo; j <= jhi; ++j) {
;     const int bcur = (j - jlo) & 1;
;     const char* Ks = K_lds + bcur * 16384;
;     f32x16 p0, p1;
;     {
;       const float dbase = (float)(j * 64 - qpos + 4 * hi);
;       const int q0 = qb * 128;
;       if (j * 64 + 63 < q0 || j * 64 > q0 + 127) {
;         const float step = (j * 64 < q0) ? -nslope : nslope;
;         const float base = fmaf(dbase, step, nMC), step8 = 8.f * step;
;         p0[0] = base; p0[1] = base + step; p0[2] = fmaf(2.f, step, base); p0[3] = fmaf(3.f, step, base);
; #pragma unroll
;         for (int r = 4; r < 16; ++r) p0[r] = p0[r - 4] + step8;
; #pragma unroll
;         for (int r = 0; r < 4; ++r) p1[r] = p0[r + 12] + step8;
; #pragma unroll
;         for (int r = 4; r < 16; ++r) p1[r] = p1[r - 4] + step8;
;       } else {
;         float d0[16], d1[16];
;         d0[0] = dbase; d0[1] = dbase + 1.f; d0[2] = dbase + 2.f; d0[3] = d0[1] + 2.f;
; #pragma unroll
;         for (int r = 4; r < 16; ++r) d0[r] = d0[r - 4] + 8.f;
; #pragma unroll
;         for (int r = 0; r < 4; ++r) d1[r] = d0[r + 12] + 8.f;
; #pragma unroll
;         for (int r = 4; r < 16; ++r) d1[r] = d1[r - 4] + 8.f;
; #pragma unroll
;         for (int r = 0; r < 16; ++r) { p0[r] = fmaf(fabsf(d0[r]), nslope, nMC); p1[r] = fmaf(fabsf(d1[r]), nslope, nMC); }
;       }
;     }
;     const int vb = vb0 + bcur * 16384;
;     bf16x8 pa0, pa1, pa2, pa3;
;     s16x4 fa[8], fb[8];
;     bf16x8 kf[8];
; #pragma unroll
;     for (int ks = 0; ks < 4; ++ks) {
;       const int cb = c * 128 + (ks * 16 + hi * 8) * 2;
;       kf[2 * ks] = *reinterpret_cast<const bf16x8*>(Ks + KSWZ(r32, cb));
;       kf[2 * ks + 1] = *reinterpret_cast<const bf16x8*>(Ks + KSWZ(32 + r32, cb));
;     }
	s_cmp_lg_u32 0, -1
	v_and_b32_e32 v13, 0xc0, v3
	s_cselect_b32 s3, 0, 0
	v_lshlrev_b32_e32 v12, 1, v165
	v_add_u32_e32 v13, s3, v13
	s_mov_b32 s3, s23
	v_and_b32_e32 v12, 32, v12
	v_and_b32_e32 v11, 0x118, v11
	s_lshl_b64 s[68:69], s[2:3], 16
	s_lshl_b64 s[74:75], s[18:19], 10
	v_add_u32_e32 v3, v9, v3
	v_add3_u32 v173, v13, v12, v11
	s_add_u32 s3, s68, s74
	v_lshlrev_b32_e32 v10, 9, v10
	v_lshlrev_b32_e32 v11, 9, v8
	s_movk_i32 s74, 0xf000
	v_lshrrev_b32_e32 v3, 4, v3
	v_and_or_b32 v8, v10, s74, v11
	v_and_b32_e32 v3, 0x60, v3
	v_or3_b32 v8, v8, v3, v2
	v_lshlrev_b32_e32 v3, 9, v4
	s_addc_u32 s71, s69, s75
	v_and_or_b32 v3, v3, s74, v11
	s_add_u32 s68, s55, s3
	v_or3_b32 v2, v3, v5, v2
	v_ashrrev_i32_e32 v9, 31, v8
	s_addc_u32 s69, s60, s71
	v_ashrrev_i32_e32 v3, 31, v2
	v_lshl_add_u64 v[150:151], v[8:9], 1, s[68:69]
	v_lshl_add_u64 v[152:153], v[2:3], 1, s[68:69]
	s_add_u32 s68, s61, s3
	v_add_u32_e32 v0, v1, v0
	v_lshlrev_b32_e32 v14, 2, v160
	s_addc_u32 s69, s62, s71
	v_ashrrev_i32_e32 v1, 31, v0
	v_lshlrev_b32_e32 v15, 7, v164
	v_lshlrev_b32_e32 v17, 4, v159
	v_add_u32_e32 v2, v7, v6
	v_lshl_add_u64 v[156:157], v[0:1], 1, s[68:69]
	v_sub_u32_e32 v0, v14, v162
	v_or_b32_e32 v16, v184, v15
	v_and_b32_e32 v17, 0x70, v17
	v_xor_b32_e32 v132, 0x80000000, v129
	v_ashrrev_i32_e32 v3, 31, v2
	v_sub_u32_e32 v0, v0, v163
	v_mov_b32_e32 v167, 0
	v_lshl_add_u32 v168, v162, 8, 0
	v_bitop3_b32 v169, v184, v17, v15 bitop3:0x36
	v_bitop3_b32 v170, v16, v17, 32 bitop3:0x36
	v_bitop3_b32 v171, v16, v17, 64 bitop3:0x36
	v_bitop3_b32 v172, v16, v17, s56 bitop3:0x36
	v_mov_b32_e32 v134, v130
	v_mov_b32_e32 v135, v130
	v_mov_b32_e32 v133, v132
	v_mov_b32_e32 v136, v132
	v_mov_b32_e32 v137, v132
	v_mov_b32_e32 v138, v132
	v_mov_b32_e32 v139, v132
	v_mov_b32_e32 v140, v132
	v_mov_b32_e32 v141, v132
	v_mov_b32_e32 v142, v132
	v_mov_b32_e32 v143, v132
	v_mov_b32_e32 v144, v132
	v_mov_b32_e32 v145, v132
	v_mov_b32_e32 v146, v132
	v_mov_b32_e32 v147, v132
	v_mov_b32_e32 v148, v132
	v_mov_b32_e32 v149, v132
	v_lshl_add_u64 v[154:155], v[2:3], 1, s[68:69]
	v_subrev_u32_e32 v174, s64, v0
	v_mov_b32_e32 v48, 0
	v_mov_b32_e32 v49, v167
	v_mov_b32_e32 v50, v167
	v_mov_b32_e32 v51, v167
	v_mov_b32_e32 v52, v167
	v_mov_b32_e32 v53, v167
	v_mov_b32_e32 v54, v167
	v_mov_b32_e32 v55, v167
	v_mov_b32_e32 v56, v167
	v_mov_b32_e32 v57, v167
	v_mov_b32_e32 v58, v167
	v_mov_b32_e32 v59, v167
	v_mov_b32_e32 v60, v167
	v_mov_b32_e32 v61, v167
	v_mov_b32_e32 v62, v167
	v_mov_b32_e32 v63, v167
	v_mov_b32_e32 v32, 0
	v_mov_b32_e32 v33, v167
	v_mov_b32_e32 v34, v167
	v_mov_b32_e32 v35, v167
	v_mov_b32_e32 v36, v167
	v_mov_b32_e32 v37, v167
	v_mov_b32_e32 v38, v167
	v_mov_b32_e32 v39, v167
	v_mov_b32_e32 v40, v167
	v_mov_b32_e32 v41, v167
	v_mov_b32_e32 v42, v167
	v_mov_b32_e32 v43, v167
	v_mov_b32_e32 v44, v167
	v_mov_b32_e32 v45, v167
	v_mov_b32_e32 v46, v167
	v_mov_b32_e32 v47, v167
	v_mov_b32_e32 v16, 0
	v_mov_b32_e32 v17, v167
	v_mov_b32_e32 v18, v167
	v_mov_b32_e32 v19, v167
	v_mov_b32_e32 v20, v167
	v_mov_b32_e32 v21, v167
	v_mov_b32_e32 v22, v167
	v_mov_b32_e32 v23, v167
	v_mov_b32_e32 v24, v167
	v_mov_b32_e32 v25, v167
	v_mov_b32_e32 v26, v167
	v_mov_b32_e32 v27, v167
	v_mov_b32_e32 v28, v167
	v_mov_b32_e32 v29, v167
	v_mov_b32_e32 v30, v167
	v_mov_b32_e32 v31, v167
	v_mov_b32_e32 v0, 0
	v_mov_b32_e32 v1, v167
	v_mov_b32_e32 v2, v167
	v_mov_b32_e32 v3, v167
	v_mov_b32_e32 v4, v167
	v_mov_b32_e32 v5, v167
	v_mov_b32_e32 v6, v167
	v_mov_b32_e32 v7, v167
	v_mov_b32_e32 v8, v167
	v_mov_b32_e32 v9, v167
	v_mov_b32_e32 v10, v167
	v_mov_b32_e32 v11, v167
	v_mov_b32_e32 v12, v167
	v_mov_b32_e32 v13, v167
	v_mov_b32_e32 v14, v167
	v_mov_b32_e32 v15, v167
	v_add_u32_e32 v186, v168, v169
	v_add_u32_e32 v187, v168, v170
	v_add_u32_e32 v188, v168, v171
	v_add_u32_e32 v189, v168, v172
	v_add_u32_e32 v186, 0x8000, v186
	v_add_u32_e32 v187, 0x8000, v187
	v_add_u32_e32 v188, 0x8000, v188
	v_add_u32_e32 v189, 0x8000, v189
	v_and_b32_e32 v218, 3, v162
	v_lshlrev_b32_e32 v218, 2, v218
	v_bfe_u32 v219, v162, 2, 2
	v_or_b32_e32 v218, v218, v219
	v_lshl_or_b32 v219, v164, 3, v160
	v_or_b32_e32 v220, 0, v219
	v_xor_b32_e32 v220, v220, v218
	v_lshl_add_u32 v169, v220, 4, v168
	v_add_u32_e32 v169, 0x8000, v169
; DEV void attn_a_item(const Params& P, int layer, int batch, int item, char* lds) {
;     ...
;   for (int j = jlo; j <= jhi; ++j) {
;     const int bcur = (j - jlo) & 1;
;     const char* Ks = K_lds + bcur * 16384;
;     f32x16 p0, p1;
;     {
;       const float dbase = (float)(j * 64 - qpos + 4 * hi);
;       const int q0 = qb * 128;
;       if (j * 64 + 63 < q0 || j * 64 > q0 + 127) {
;         const float step = (j * 64 < q0) ? -nslope : nslope;
;         const float base = fmaf(dbase, step, nMC), step8 = 8.f * step;
;         p0[0] = base; p0[1] = base + step; p0[2] = fmaf(2.f, step, base); p0[3] = fmaf(3.f, step, base);
; #pragma unroll
;         for (int r = 4; r < 16; ++r) p0[r] = p0[r - 4] + step8;
; #pragma unroll
;         for (int r = 0; r < 4; ++r) p1[r] = p0[r + 12] + step8;
; #pragma unroll
;         for (int r = 4; r < 16; ++r) p1[r] = p1[r - 4] + step8;
;       } else {
;         float d0[16], d1[16];
;         d0[0] = dbase; d0[1] = dbase + 1.f; d0[2] = dbase + 2.f; d0[3] = d0[1] + 2.f;
; #pragma unroll
;         for (int r = 4; r < 16; ++r) d0[r] = d0[r - 4] + 8.f;
; #pragma unroll
;         for (int r = 0; r < 4; ++r) d1[r] = d0[r + 12] + 8.f;
; #pragma unroll
;         for (int r = 4; r < 16; ++r) d1[r] = d1[r - 4] + 8.f;
; #pragma unroll
;         for (int r = 0; r < 16; ++r) { p0[r] = fmaf(fabsf(d0[r]), nslope, nMC); p1[r] = fmaf(fabsf(d1[r]), nslope, nMC); }
;       }
;     }
;     const int vb = vb0 + bcur * 16384;
;     bf16x8 pa0, pa1, pa2, pa3;
;     s16x4 fa[8], fb[8];
;     bf16x8 kf[8];
; #pragma unroll
;     for (int ks = 0; ks < 4; ++ks) {
;       const int cb = c * 128 + (ks * 16 + hi * 8) * 2;
;       kf[2 * ks] = *reinterpret_cast<const bf16x8*>(Ks + KSWZ(r32, cb));
;       kf[2 * ks + 1] = *reinterpret_cast<const bf16x8*>(Ks + KSWZ(32 + r32, cb));
;     }
	v_or_b32_e32 v220, 2, v219
	v_xor_b32_e32 v220, v220, v218
	v_lshl_add_u32 v170, v220, 4, v168
	v_add_u32_e32 v170, 0x8000, v170
	v_or_b32_e32 v220, 4, v219
	v_xor_b32_e32 v220, v220, v218
	v_lshl_add_u32 v171, v220, 4, v168
	v_add_u32_e32 v171, 0x8000, v171
	v_or_b32_e32 v220, 6, v219
	v_xor_b32_e32 v220, v220, v218
	v_lshl_add_u32 v172, v220, 4, v168
	v_add_u32_e32 v172, 0x8000, v172
	v_readfirstlane_b32 s100, v166
	v_readfirstlane_b32 s25, v130
	v_cvt_f32_i32_e32 v166, v174
	s_nop 0
	v_mov_b32_e32 v112, v166
	v_add_f32_e32 v113, 0x3f800000, v166
	v_add_f32_e32 v114, 0x40000000, v166
	v_add_f32_e32 v115, 0x40400000, v166
	v_add_f32_e32 v116, 0x41000000, v166
	v_add_f32_e32 v117, 0x41100000, v166
	v_add_f32_e32 v118, 0x41200000, v166
	v_add_f32_e32 v119, 0x41300000, v166
	v_add_f32_e32 v120, 0x41800000, v166
	v_add_f32_e32 v121, 0x41880000, v166
	v_add_f32_e32 v122, 0x41900000, v166
	v_add_f32_e32 v123, 0x41980000, v166
	v_add_f32_e32 v124, 0x41c00000, v166
	v_add_f32_e32 v125, 0x41c80000, v166
	v_add_f32_e32 v126, 0x41d00000, v166
	v_add_f32_e32 v127, 0x41d80000, v166
	v_add_f32_e32 v133, 0x42000000, v166
	v_add_f32_e32 v134, 0x42040000, v166
	v_add_f32_e32 v135, 0x42080000, v166
	v_add_f32_e32 v136, 0x420c0000, v166
	v_add_f32_e32 v137, 0x42200000, v166
	v_add_f32_e32 v138, 0x42240000, v166
	v_add_f32_e32 v139, 0x42280000, v166
	v_add_f32_e32 v140, 0x422c0000, v166
	v_add_f32_e32 v141, 0x42400000, v166
	v_add_f32_e32 v142, 0x42440000, v166
	v_add_f32_e32 v143, 0x42480000, v166
	v_add_f32_e32 v144, 0x424c0000, v166
	v_add_f32_e32 v145, 0x42600000, v166
	v_add_f32_e32 v146, 0x42640000, v166
	v_add_f32_e32 v147, 0x42680000, v166
	v_add_f32_e32 v148, 0x426c0000, v166
	v_readfirstlane_b32 s71, v156
	v_readfirstlane_b32 s101, v157
	s_nop 3
	s_sub_u32 s71, s71, 0x1000
	s_subb_u32 s101, s101, 0
	v_subrev_u32_e32 v174, s71, v156
	v_subrev_u32_e32 v175, s71, v154
	s_add_u32 s68, s71, s22
	s_addc_u32 s69, s101, 0
	v_lshrrev_b32_e32 v221, 6, v159
	v_bfe_u32 v222, v165, 4, 2
	v_lshlrev_b32_e32 v222, 2, v222
	v_and_b32_e32 v223, 3, v221
	v_or_b32_e32 v222, v222, v223
	v_and_b32_e32 v223, 15, v165
	v_xor_b32_e32 v223, v223, v222
	v_lshrrev_b32_e32 v224, 4, v165
	v_lshlrev_b32_e32 v224, 10, v224
	v_lshl_add_u32 v224, v223, 4, v224
	v_and_b32_e32 v225, 1, v221
	v_lshlrev_b32_e32 v225, 6, v225
	v_sub_u32_e32 v224, v224, v225
	v_add_u32_e32 v174, 0x1000, v224
	v_add_u32_e32 v175, 0x8000, v174
	v_readfirstlane_b32 s71, v152
	v_readfirstlane_b32 s101, v153
	s_nop 3
	s_sub_u32 s71, s71, 0x1000
	s_subb_u32 s101, s101, 0
	v_subrev_u32_e32 v149, s71, v152
	v_subrev_u32_e32 v131, s71, v150
	s_add_u32 s74, s71, s22
	s_addc_u32 s75, s101, 0
	s_xor_b32 s65, s25, 0x80000000
	s_lshr_b32 s78, s64, 6
	v_mov_b32_e32 v154, 0
	v_mov_b32_e32 v155, 0
	v_mov_b32_e32 v156, 0
	v_mov_b32_e32 v157, 0
	v_mov_b32_e32 v202, 0
	v_mov_b32_e32 v203, 0
	v_mov_b32_e32 v204, 0
	v_mov_b32_e32 v205, 0
	v_mov_b32_e32 v206, 0
	v_mov_b32_e32 v207, 0
	v_mov_b32_e32 v208, 0
	v_mov_b32_e32 v209, 0
	v_mov_b32_e32 v210, 0
	v_mov_b32_e32 v211, 0
	v_mov_b32_e32 v212, 0
	v_mov_b32_e32 v213, 0
	v_mov_b32_e32 v214, 0
	v_mov_b32_e32 v215, 0
	v_mov_b32_e32 v216, 0
	v_mov_b32_e32 v217, 0
	s_cmp_lt_i32 s2, s78
	s_cselect_b32 s3, s65, s25
	s_sub_u32 s71, s2, s78
	s_cmp_lt_u32 s71, 2
	s_cselect_b64 vcc, -1, 0
	v_cvt_f32_i32_e32 v129, s24
	s_nop 0
	v_fma_f32 v168, v129, s3, v132
	ds_read_b128 v[218:221], v186 offset:0
	ds_read_b128 v[222:225], v187 offset:0
	ds_read_b128 v[232:235], v188 offset:0
	ds_read_b128 v[236:239], v189 offset:0
	ds_read_b128 v[240:243], v186 offset:8192
	ds_read_b128 v[244:247], v187 offset:8192
	ds_read_b128 v[248:251], v188 offset:8192
	ds_read_b128 v[194:197], v189 offset:8192
	s_cbranch_vccnz .Ldfa_diag_f_a
	v_fma_f32 v64, v112, s3, v168
	v_fma_f32 v65, v113, s3, v168
	v_fma_f32 v66, v114, s3, v168
	v_fma_f32 v67, v115, s3, v168
	v_fma_f32 v68, v116, s3, v168
	v_fma_f32 v69, v117, s3, v168
	v_fma_f32 v70, v118, s3, v168
	v_fma_f32 v71, v119, s3, v168
	v_fma_f32 v72, v120, s3, v168
	v_fma_f32 v73, v121, s3, v168
	v_fma_f32 v74, v122, s3, v168
	v_fma_f32 v75, v123, s3, v168
	v_fma_f32 v76, v124, s3, v168
	v_fma_f32 v77, v125, s3, v168
	v_fma_f32 v78, v126, s3, v168
	v_fma_f32 v79, v127, s3, v168

;   DEV u16* VB() const { return (u16*)(b + O_VB); }
; DEV int opaque_tid() { int t = threadIdx.x; asm volatile("" : "+v"(t)); return t; }
; DEV int v_rd_base(int lane) { return ((lane & 3) << 3) | (((lane >> 2) & 3) << 6) | (((lane >> 4) & 1) << 5) | (((lane >> 5) & 1) << 8); }
; DEV void attn_b_item(const Params& P, int layer, int batch, int item, char* lds) {
;   const int tid = opaque_tid(), wid = tid >> 6, lane = tid & 63, r32 = lane & 31, hi = lane >> 5;
;   const int seqlen = batch ? 16384 : 4096;
;   const int xcd = item & 7, jj = item >> 3;
;   const int sh = batch ? (xcd >> 1) : (2 * xcd + (jj >> 4));
;   const int qb = batch ? ((xcd & 1) * 32 + jj) : (jj & 15);
;   const int head = sh & 3, seq = sh >> 2;
;   const long tok0 = (long)seq * 4096;
;   const int qpos = qb * 256 + wid * 32 + r32;
;   char* V_lds = lds; char* K_lds = lds + 32768;
;   float* wsl = reinterpret_cast<float*>(lds + LDS_WS) + wid * 64;
;   const float nMC = -WS{P.ws}.consts()[layer * 1024 + 2];
;   bf16x8 qr[12];
;   {
;     const u16* Qw = WS{P.ws}.QB() + (tok0 + qpos) * 768 + head * 192 + hi * 8;
; #pragma unroll
;     for (int ks = 0; ks < 12; ++ks) qr[ks] = *reinterpret_cast<const bf16x8*>(Qw + ks * 16);
;   }
;   const u16* Kh = WS{P.ws}.KB() + tok0 * 768 + head * 192;
;   const u16* Vh = WS{P.ws}.VB() + tok0 * 512 + head * 128;
;   int bkoff[3], bvoff[2], ldst[3];
; #pragma unroll
;   for (int i = 0; i < 3; ++i) {
;     const int p = (wid + 8 * i) * 1024 + lane * 16;
;     ldst[i] = p;
;     const int row = p / 384, pch = (p - row * 384) >> 4, ch = pch ^ ((row >> 1) & 7);
;     bkoff[i] = row * 768 + ch * 8;
;     if (i < 2) {
;       const int st = p >> 9, within = p & 511, kk = (st >> 2) * 8 + (within >> 6);
;       const int k = kk, col = (st & 3) * 32 + ((within & 63) >> 1);
;       bvoff[i] = k * 512 + col;
;     }
;   }
;   const int vb0 = (int)(uintptr_t)V_lds + v_rd_base(lane);
;   const int kq = r32 * 384, ksw = (r32 >> 1) & 7;
;     ...
;   f32x16 o[4] = {f32x16{}, f32x16{}, f32x16{}, f32x16{}};
;   float lsum = 0.f;
;   const int NT = seqlen >> 6;
;   BLOAD(0, 0); asm volatile("s_waitcnt vmcnt(0)" ::: "memory"); __syncthreads();
.LBB0_390:
	s_and_b64 vcc, exec, s[2:3]
	s_cbranch_vccz .LBB0_367
	s_and_b32 s2, s63, 7
	s_lshl_b32 s2, s2, 1
	s_ashr_i32 s3, s63, 7
	s_ashr_i32 s18, s63, 3
	s_bfe_u32 s19, s63, 0x20001
	s_add_i32 s22, s2, s3
	s_and_b64 s[2:3], s[26:27], exec
	s_cselect_b32 s19, s22, s19
	s_lshl_b32 s2, s63, 5
	s_and_b32 s2, s2, 32
	s_add_i32 s22, s2, s18
	s_and_b32 s18, s18, 15
	v_mov_b32_e32 v158, v226
	s_and_b64 s[2:3], s[26:27], exec
	s_cselect_b32 s18, s18, s22
	v_ashrrev_i32_e32 v4, 6, v158
	s_lshl_b32 s63, s18, 8
	v_lshlrev_b32_e32 v144, 5, v4
	v_and_b32_e32 v157, 31, v158
	s_ashr_i32 s24, s19, 2
	v_add_u32_e32 v0, s63, v144
	s_ashr_i32 s25, s24, 31
	v_or_b32_e32 v0, v0, v157
	s_lshl_b64 s[2:3], s[24:25], 12
	v_ashrrev_i32_e32 v1, 31, v0
	v_lshl_add_u64 v[0:1], s[2:3], 0, v[0:1]
	v_mov_b64_e32 v[2:3], s[16:17]
	s_and_b32 s65, s19, 3
	v_mad_u64_u32 v[2:3], s[18:19], v0, s39, v[2:3]
	v_bfe_u32 v156, v158, 5, 1
	v_mad_i32_i24 v3, v1, s39, v3
	s_mul_i32 s22, s65, 0x180
	v_lshl_add_u64 v[0:1], v[2:3], 0, s[22:23]
	v_lshlrev_b32_e32 v184, 4, v156
	v_and_b32_e32 v145, 63, v158
	v_lshl_add_u64 v[0:1], v[0:1], 0, v[184:185]
	global_load_dwordx4 v[96:99], v[0:1], off
	global_load_dwordx4 v[100:103], v[0:1], off offset:32
	global_load_dwordx4 v[104:107], v[0:1], off offset:64
	global_load_dwordx4 v[108:111], v[0:1], off offset:96
	global_load_dwordx4 v[112:115], v[0:1], off offset:128
	global_load_dwordx4 v[116:119], v[0:1], off offset:160
	global_load_dwordx4 v[120:123], v[0:1], off offset:192
	global_load_dwordx4 v[124:127], v[0:1], off offset:224
	global_load_dwordx4 v[128:131], v[0:1], off offset:256
	global_load_dwordx4 v[132:135], v[0:1], off offset:288
	global_load_dwordx4 v[136:139], v[0:1], off offset:320
	global_load_dwordx4 v[140:143], v[0:1], off offset:352
	v_lshlrev_b32_e32 v0, 10, v4
	v_lshlrev_b32_e32 v2, 4, v145
	v_or_b32_e32 v6, v0, v2
	v_mul_hi_i32 v7, v6, s57
	v_lshrrev_b32_e32 v8, 31, v7
	v_ashrrev_i32_e32 v7, 6, v7
	v_add_u32_e32 v7, v7, v8
	v_mad_i32_i24 v8, v7, s47, v6
	v_ashrrev_i32_e32 v8, 4, v8
	v_lshrrev_b32_e32 v9, 1, v7
	v_bfe_u32 v1, v158, 2, 3
	v_bitop3_b32 v8, v8, v9, 7 bitop3:0x78
	v_mul_i32_i24_e32 v7, 0x300, v7
	v_lshlrev_b32_e32 v4, 2, v4
	v_lshlrev_b32_e32 v3, 3, v145
	v_lshl_add_u32 v146, v8, 3, v7
	v_and_or_b32 v4, v4, s45, v1
	v_lshrrev_b32_e32 v7, 4, v6
	v_add_u32_e32 v0, 0x2000, v0
	v_and_b32_e32 v5, 24, v3
	v_and_b32_e32 v7, 0x60, v7
	v_lshlrev_b32_e32 v4, 9, v4
	v_or_b32_e32 v159, v0, v2
	v_lshrrev_b32_e32 v0, 8, v0
	v_or3_b32 v148, v4, v7, v5
	v_mul_hi_i32 v4, v159, s57
	v_and_or_b32 v0, v0, s45, v1
	v_lshrrev_b32_e32 v1, 4, v159
	v_lshrrev_b32_e32 v7, 31, v4
	v_ashrrev_i32_e32 v4, 6, v4
	v_and_b32_e32 v1, 0x60, v1
	v_lshlrev_b32_e32 v0, 9, v0
	v_add_u32_e32 v160, 0x4000, v6
	s_mul_i32 s19, s24, 0x600000
	v_add_u32_e32 v4, v4, v7
	v_or3_b32 v152, v0, v1, v5
	v_mul_hi_i32 v0, v160, s57
	s_mul_hi_i32 s18, s24, 0x600000
	s_add_u32 s19, s48, s19
	v_mad_i32_i24 v7, v4, s47, v159
	v_lshrrev_b32_e32 v1, 31, v0
	v_ashrrev_i32_e32 v0, 6, v0
	s_addc_u32 s64, s52, s18
	v_ashrrev_i32_e32 v7, 4, v7
	v_lshrrev_b32_e32 v8, 1, v4
	v_add_u32_e32 v0, v0, v1
	s_add_u32 s18, s19, s22
	v_bitop3_b32 v7, v7, v8, 7 bitop3:0x78
	v_mul_i32_i24_e32 v4, 0x300, v4
	v_mad_i32_i24 v1, v0, s47, v160
	v_add_u32_e32 v161, 0, v6
	s_addc_u32 s19, s64, 0
	s_lshl_b64 s[24:25], s[24:25], 22
	s_lshl_b32 s64, s65, 7
	v_lshl_add_u32 v150, v7, 3, v4
	v_ashrrev_i32_e32 v1, 4, v1
	v_lshrrev_b32_e32 v4, 1, v0
	v_add_u32_e32 v162, 0x8000, v161
	v_bitop3_b32 v1, v1, v4, 7 bitop3:0x78
	v_mul_i32_i24_e32 v0, 0x300, v0
	s_add_u32 s22, s53, s24
	v_ashrrev_i32_e32 v147, 31, v146
	v_readfirstlane_b32 s24, v162
	v_add_u32_e32 v163, 0xa000, v161
	v_lshl_add_u32 v154, v1, 3, v0
	v_lshl_add_u64 v[0:1], v[146:147], 1, s[18:19]
	s_mov_b32 m0, s24
	v_ashrrev_i32_e32 v151, 31, v150
	v_readfirstlane_b32 s24, v163
	v_add_u32_e32 v164, 0xc000, v161
	global_load_lds_dwordx4 v[0:1], off
	v_lshl_add_u64 v[0:1], v[150:151], 1, s[18:19]
	s_mov_b32 m0, s24
	v_readfirstlane_b32 s24, v164
	s_addc_u32 s25, s54, s25
	global_load_lds_dwordx4 v[0:1], off
	s_mov_b32 m0, s24
	s_lshl_b32 s24, s65, 8
	v_ashrrev_i32_e32 v155, 31, v154
	s_add_u32 s24, s22, s24
	v_lshl_add_u64 v[0:1], v[154:155], 1, s[18:19]
	s_addc_u32 s25, s25, 0
	v_ashrrev_i32_e32 v149, 31, v148
	v_readfirstlane_b32 s22, v161
	v_add_u32_e32 v165, 0x2000, v161
	global_load_lds_dwordx4 v[0:1], off
	v_lshl_add_u64 v[0:1], v[148:149], 1, s[24:25]
	s_mov_b32 m0, s22
	v_ashrrev_i32_e32 v153, 31, v152
	v_readfirstlane_b32 s22, v165
	global_load_lds_dwordx4 v[0:1], off
	v_lshl_add_u64 v[0:1], v[152:153], 1, s[24:25]
	s_mov_b32 m0, s22
	s_cmp_lg_u32 0, -1
	global_load_lds_dwordx4 v[0:1], off
	v_lshlrev_b32_e32 v4, 1, v158
	v_and_b32_e32 v2, 0xc0, v2
	s_cselect_b32 s22, 0, 0
	v_and_b32_e32 v3, 0x100, v3
	v_lshrrev_b32_e32 v7, 1, v158
	v_and_b32_e32 v0, 32, v4
	v_add3_u32 v2, v2, s22, v5
	v_bfe_u32 v1, v158, 1, 3
	v_add3_u32 v166, v2, v0, v3
	v_bitop3_b32 v0, v156, v7, 7 bitop3:0x78
	v_lshlrev_b32_e32 v169, 4, v0
	v_bitop3_b32 v0, v156, v1, 2 bitop3:0x36
	v_lshlrev_b32_e32 v170, 4, v0
	v_bitop3_b32 v0, v156, v1, 4 bitop3:0x36
	v_lshlrev_b32_e32 v171, 4, v0
	v_bitop3_b32 v0, v156, v1, 6 bitop3:0x36
	v_lshlrev_b32_e32 v172, 4, v0
	v_bitop3_b32 v0, v156, v1, 8 bitop3:0x36
	v_lshlrev_b32_e32 v173, 4, v0
	v_bitop3_b32 v0, v156, v1, 10 bitop3:0x36
	v_lshlrev_b32_e32 v174, 4, v0
	v_bitop3_b32 v0, v156, v1, 12 bitop3:0x36
	v_lshlrev_b32_e32 v175, 4, v0
	v_bitop3_b32 v0, v156, v1, 14 bitop3:0x36
	v_lshlrev_b32_e32 v176, 4, v0
	v_bitop3_b32 v0, v156, v1, 16 bitop3:0x36
	v_lshlrev_b32_e32 v177, 4, v0
	v_bitop3_b32 v0, v156, v1, 18 bitop3:0x36
	s_waitcnt vmcnt(0)
; DEV int v_rd_base(int lane) { return ((lane & 3) << 3) | (((lane >> 2) & 3) << 6) | (((lane >> 4) & 1) << 5) | (((lane >> 5) & 1) << 8); }
; #define BLOAD(b, k0) do { _Pragma("unroll") for (int i = 0; i < 3; ++i) glds16(Kh + (long)(k0) * 768 + bkoff[i], K_lds + (b) * 24576 + ldst[i]); \
;     _Pragma("unroll") for (int i = 0; i < 2; ++i) glds16(Vh + (long)(k0) * 512 + bvoff[i], V_lds + (b) * 16384 + ldst[i]); } while (0)
; DEV void attn_b_item(const Params& P, int layer, int batch, int item, char* lds) {
;     ...
;   const int vb0 = (int)(uintptr_t)V_lds + v_rd_base(lane);
;   const int kq = r32 * 384, ksw = (r32 >> 1) & 7;
;     ...
;   f32x16 o[4] = {f32x16{}, f32x16{}, f32x16{}, f32x16{}};
;   float lsum = 0.f;
;   const int NT = seqlen >> 6;
;   BLOAD(0, 0); asm volatile("s_waitcnt vmcnt(0)" ::: "memory"); __syncthreads();
; #pragma unroll 2
;   for (int j = 0; j < NT; ++j) {
;     const char* Ks = K_lds + (j & 1) * 24576;
;     const int vb = vb0 + (j & 1) * 16384;
;     f32x16 p0, p1;
; #pragma unroll
;     for (int r = 0; r < 16; ++r) { p0[r] = 0.f; p1[r] = 0.f; }
	s_movk_i32 s22, 0x180
	v_lshlrev_b32_e32 v178, 4, v0
	v_bitop3_b32 v0, v156, v1, 20 bitop3:0x36
	v_mad_u32_u24 v167, v157, s22, 0
	v_lshlrev_b32_e32 v179, 4, v0
	v_bitop3_b32 v0, v156, v1, 22 bitop3:0x36
	v_mov_b32_e32 v182, 0
	s_mov_b32 s65, 0
	v_add_u32_e32 v168, 0x8000, v167
	v_lshlrev_b32_e32 v180, 4, v0
	v_add_u32_e32 v181, 0x4000, v166
	s_movk_i32 s68, 0x80
	v_mov_b32_e32 v48, 0
	v_mov_b32_e32 v49, v182
	v_mov_b32_e32 v50, v182
	v_mov_b32_e32 v51, v182
	v_mov_b32_e32 v52, v182
	v_mov_b32_e32 v53, v182
	v_mov_b32_e32 v54, v182
	v_mov_b32_e32 v55, v182
	v_mov_b32_e32 v56, v182
	v_mov_b32_e32 v57, v182
	v_mov_b32_e32 v58, v182
	v_mov_b32_e32 v59, v182
	v_mov_b32_e32 v60, v182
	v_mov_b32_e32 v61, v182
	v_mov_b32_e32 v62, v182
	v_mov_b32_e32 v63, v182
	v_mov_b32_e32 v32, 0
	v_mov_b32_e32 v33, v182
	v_mov_b32_e32 v34, v182
	v_mov_b32_e32 v35, v182
	v_mov_b32_e32 v36, v182
	v_mov_b32_e32 v37, v182
	v_mov_b32_e32 v38, v182
	v_mov_b32_e32 v39, v182
	v_mov_b32_e32 v40, v182
	v_mov_b32_e32 v41, v182
	v_mov_b32_e32 v42, v182
	v_mov_b32_e32 v43, v182
	v_mov_b32_e32 v44, v182
	v_mov_b32_e32 v45, v182
	v_mov_b32_e32 v46, v182
	v_mov_b32_e32 v47, v182
	v_mov_b32_e32 v16, 0
	v_mov_b32_e32 v17, v182
	v_mov_b32_e32 v18, v182
	v_mov_b32_e32 v19, v182
	v_mov_b32_e32 v20, v182
	v_mov_b32_e32 v21, v182
	v_mov_b32_e32 v22, v182
	v_mov_b32_e32 v23, v182
	v_mov_b32_e32 v24, v182
	v_mov_b32_e32 v25, v182
	v_mov_b32_e32 v26, v182
	v_mov_b32_e32 v27, v182
	v_mov_b32_e32 v28, v182
	v_mov_b32_e32 v29, v182
	v_mov_b32_e32 v30, v182
	v_mov_b32_e32 v31, v182
	v_mov_b32_e32 v0, 0
	v_mov_b32_e32 v1, v182
	v_mov_b32_e32 v2, v182
	v_mov_b32_e32 v3, v182
	v_mov_b32_e32 v4, v182
	v_mov_b32_e32 v5, v182
	v_mov_b32_e32 v6, v182
	v_mov_b32_e32 v7, v182
	v_mov_b32_e32 v8, v182
	v_mov_b32_e32 v9, v182
	v_mov_b32_e32 v10, v182
	v_mov_b32_e32 v11, v182
	v_mov_b32_e32 v12, v182
	v_mov_b32_e32 v13, v182
	v_mov_b32_e32 v14, v182
	v_mov_b32_e32 v15, v182
	s_waitcnt vmcnt(0) lgkmcnt(0)
	s_barrier
	v_add_u32_e32 v169, v167, v169
	v_add_u32_e32 v170, v167, v170
	v_add_u32_e32 v171, v167, v171
	v_add_u32_e32 v172, v167, v172
	v_add_u32_e32 v169, 0x8000, v169
	v_add_u32_e32 v170, 0x8000, v170
	v_add_u32_e32 v171, 0x8000, v171
	v_add_u32_e32 v172, 0x8000, v172
	v_lshlrev_b32_e32 v146, 1, v146
	v_lshlrev_b32_e32 v148, 1, v148
	v_lshlrev_b32_e32 v150, 1, v150
	v_lshlrev_b32_e32 v152, 1, v152
	v_lshlrev_b32_e32 v154, 1, v154
	v_readfirstlane_b32 s100, v162
	v_readfirstlane_b32 s101, v161
	s_add_u32 s68, s18, 0x18000
	s_addc_u32 s69, s19, 0
	s_add_u32 s70, s24, 0x10000
	s_addc_u32 s71, s25, 0
	s_mov_b32 s65, 0
	v_mov_b32_e32 v80, 0
	v_mov_b32_e32 v81, 0
	v_mov_b32_e32 v82, 0
	v_mov_b32_e32 v83, 0
	v_mov_b32_e32 v84, 0
	v_mov_b32_e32 v85, 0
	v_mov_b32_e32 v86, 0
	v_mov_b32_e32 v87, 0
	v_mov_b32_e32 v88, 0
	v_mov_b32_e32 v89, 0
	v_mov_b32_e32 v90, 0
	v_mov_b32_e32 v91, 0
	v_mov_b32_e32 v92, 0
	v_mov_b32_e32 v93, 0
	v_mov_b32_e32 v94, 0
	v_mov_b32_e32 v95, 0
	v_mov_b32_e32 v198, 0
	v_mov_b32_e32 v199, 0
	v_mov_b32_e32 v200, 0
	v_mov_b32_e32 v201, 0
	v_mov_b32_e32 v202, 0
	v_mov_b32_e32 v203, 0
	v_mov_b32_e32 v204, 0
	v_mov_b32_e32 v205, 0
	v_mov_b32_e32 v206, 0
	v_mov_b32_e32 v207, 0
	v_mov_b32_e32 v208, 0
	v_mov_b32_e32 v209, 0
	v_mov_b32_e32 v210, 0
	v_mov_b32_e32 v211, 0
	v_mov_b32_e32 v212, 0
	v_mov_b32_e32 v213, 0
	v_mov_b32_e32 v214, 0
	v_mov_b32_e32 v215, 0
	v_mov_b32_e32 v216, 0
	v_mov_b32_e32 v217, 0
	s_nop 1

; #define PG_STAGE(bufoff, gbase, voff) do { _Pragma("unroll") for (int _i = 0; _i < 2; ++_i) \
;     __builtin_amdgcn_global_load_lds((const unsigned*)((const char*)(gbase) + (voff)[_i]), (PG_LAS unsigned*)(lds + (bufoff) + ldsw + _i * 8192), 16, 0, 0); } while (0)
; #define PG_LDA(dst, b, h) do { _Pragma("unroll") for (int m = 0; m < 4; ++m) _Pragma("unroll") for (int k = 0; k < 2; ++k) dst[m][k] = *(const PG_LAS bf16x8*)(lds + PG_SA(b, h) + aoff + m * 2048 + k * 1024); } while (0)
; #define PG_LDB(dst, b, h) do { _Pragma("unroll") for (int n = 0; n < 2; ++n) _Pragma("unroll") for (int k = 0; k < 2; ++k) dst[n][k] = *(const PG_LAS bf16x8*)(lds + PG_SB(b, h) + boff + n * 2048 + k * 1024); } while (0)
; #define PG_WAIT_V(n) asm volatile("s_waitcnt vmcnt(" #n ")" ::: "memory")
; #define PG_WAIT_L(n) asm volatile("s_waitcnt lgkmcnt(" #n ")" ::: "memory")
; #define PG_BAR __builtin_amdgcn_s_barrier()
; template <class Epi>
; DEV void pg_gemm_phase(PG_LAS unsigned char* lds, const u16* gA, const u16* gBt, int M, int N, int K, const PgOrder& S, const Epi& E) {
;     ...
;     for (int t = 0; t < nt; t += 2) {
;       const bool last = (t == nt - 2);
;       const char* a1 = cA + (size_t)(t + 1) * kstep;
;       const char* a2 = last ? nA : cA + (size_t)(t + 2) * kstep; const char* b2 = last ? nB : cB + (size_t)(t + 2) * kstep;
;       const char* a3 = a2 + kstep; const char* b3 = b2 + kstep;
;       PG_LDB(B0, 0, 0); PG_SCHED; PG_LDA(At, 0, 0); PG_STAGE(PG_SA(1, 1), a1 + hstepA, voffA);
;       PG_WAIT_L(8); PG_BAR; PG_WAIT_L(0); PG_MMA(0, 0, At, B0); PG_BAR; PG_SCHED;
;       PG_LDB(B1, 0, 1); PG_STAGE(PG_SB(0, 0), b2, voffB);
;       PG_BAR; PG_WAIT_L(0); PG_MMA(0, 1, At, B1); PG_BAR;
;       PG_LDA(At, 0, 1); PG_STAGE(PG_SA(0, 0), a2, voffA);
;       PG_BAR; PG_WAIT_L(0); PG_MMA(1, 0, At, B0); PG_BAR; PG_SCHED;
;       PG_STAGE(PG_SB(0, 1), b2 + hstepB, voffB);
;       PG_WAIT_V(6); PG_BAR; PG_MMA(1, 1, At, B1); PG_BAR;
;       PG_LDB(B0, 1, 0); PG_SCHED; PG_LDA(At, 1, 0); PG_STAGE(PG_SA(0, 1), a2 + hstepA, voffA);
;       PG_WAIT_L(8); PG_BAR; PG_WAIT_L(0); PG_MMA(0, 0, At, B0); PG_BAR; PG_SCHED;
;       PG_LDB(B1, 1, 1); PG_STAGE(PG_SB(1, 0), b3, voffB);
;       PG_BAR; PG_WAIT_L(0); PG_MMA(0, 1, At, B1); PG_BAR;
;       PG_LDA(At, 1, 1); PG_STAGE(PG_SA(1, 0), a3, voffA);
;       PG_BAR; PG_WAIT_L(0); PG_MMA(1, 0, At, B0); PG_BAR; PG_SCHED;
.LBB0_423:
	s_add_u32 s74, s8, 0xfffc0080
	s_addc_u32 s75, s9, -1
	s_add_i32 s89, 0, 0x10000
	v_add_u32_e32 v140, s89, v233
	ds_read_b128 v[128:131], v140
	ds_read_b128 v[132:135], v140 offset:1024
	ds_read_b128 v[136:139], v140 offset:2048
	ds_read_b128 v[140:143], v140 offset:3072
	s_cmp_eq_u32 s88, 12
	s_cselect_b32 s79, s3, s75
	s_cselect_b32 s78, s19, s74
	s_cselect_b32 s75, s17, s87
	s_cselect_b32 s74, s71, s86
	v_lshl_add_u64 v[176:177], s[8:9], 0, v[202:203]
	s_add_i32 m0, s55, 0xc000
	ds_read_b128 v[144:147], v235
	ds_read_b128 v[148:151], v235 offset:1024
	ds_read_b128 v[152:155], v235 offset:2048
	ds_read_b128 v[156:159], v235 offset:3072
	ds_read_b128 v[160:163], v235 offset:4096
	ds_read_b128 v[164:167], v235 offset:5120
	ds_read_b128 v[168:171], v235 offset:6144
	ds_read_b128 v[172:175], v235 offset:7168
	global_load_lds_dwordx4 v[176:177], off
	v_lshl_add_u64 v[176:177], s[8:9], 0, v[200:201]
	s_add_i32 m0, s55, 0xe000
	s_nop 0
	global_load_lds_dwordx4 v[176:177], off
	s_waitcnt lgkmcnt(8)
	s_barrier
	s_waitcnt lgkmcnt(0)
	s_setprio 1
	s_waitcnt lgkmcnt(0)
	v_mfma_f32_16x16x32_bf16 v[124:127], v[128:131], v[144:147], v[124:127]
	v_mfma_f32_16x16x32_bf16 v[120:123], v[136:139], v[144:147], v[120:123]
	v_mfma_f32_16x16x32_bf16 v[108:111], v[128:131], v[152:155], v[108:111]
	v_mfma_f32_16x16x32_bf16 v[104:107], v[136:139], v[152:155], v[104:107]
	v_mfma_f32_16x16x32_bf16 v[92:95], v[128:131], v[160:163], v[92:95]
	v_mfma_f32_16x16x32_bf16 v[88:91], v[136:139], v[160:163], v[88:91]
	v_mfma_f32_16x16x32_bf16 v[76:79], v[128:131], v[168:171], v[76:79]
	v_mfma_f32_16x16x32_bf16 v[72:75], v[136:139], v[168:171], v[72:75]
	v_mfma_f32_16x16x32_bf16 v[124:127], v[132:135], v[148:151], v[124:127]
	v_mfma_f32_16x16x32_bf16 v[120:123], v[140:143], v[148:151], v[120:123]
	v_mfma_f32_16x16x32_bf16 v[108:111], v[132:135], v[156:159], v[108:111]
	v_mfma_f32_16x16x32_bf16 v[104:107], v[140:143], v[156:159], v[104:107]
	v_mfma_f32_16x16x32_bf16 v[92:95], v[132:135], v[164:167], v[92:95]
	v_mfma_f32_16x16x32_bf16 v[88:91], v[140:143], v[164:167], v[88:91]
	v_mfma_f32_16x16x32_bf16 v[76:79], v[132:135], v[172:175], v[76:79]
	v_mfma_f32_16x16x32_bf16 v[72:75], v[140:143], v[172:175], v[72:75]
	s_setprio 0
	s_barrier
	s_add_i32 s92, 0, 0x14000
	s_add_i32 s89, s89, s54
	v_add_u32_e32 v204, s92, v233
	v_lshl_add_u64 v[208:209], s[74:75], 0, v[184:185]
	s_mov_b32 m0, s89
	ds_read_b128 v[176:179], v204
	ds_read_b128 v[180:183], v204 offset:1024
	ds_read_b128 v[186:189], v204 offset:2048
	ds_read_b128 v[204:207], v204 offset:3072
	global_load_lds_dwordx4 v[208:209], off
	v_lshl_add_u64 v[210:211], s[74:75], 0, v[198:199]
	s_add_i32 m0, s89, 0x2000
	s_nop 0
	global_load_lds_dwordx4 v[210:211], off
	s_barrier
	s_waitcnt lgkmcnt(0)
	s_setprio 1
	s_waitcnt lgkmcnt(0)
	v_mfma_f32_16x16x32_bf16 v[116:119], v[176:179], v[144:147], v[116:119]
	v_mfma_f32_16x16x32_bf16 v[112:115], v[186:189], v[144:147], v[112:115]
	v_mfma_f32_16x16x32_bf16 v[100:103], v[176:179], v[152:155], v[100:103]
	v_mfma_f32_16x16x32_bf16 v[96:99], v[186:189], v[152:155], v[96:99]
	v_mfma_f32_16x16x32_bf16 v[84:87], v[176:179], v[160:163], v[84:87]
	v_mfma_f32_16x16x32_bf16 v[80:83], v[186:189], v[160:163], v[80:83]
	v_mfma_f32_16x16x32_bf16 v[68:71], v[176:179], v[168:171], v[68:71]
	v_mfma_f32_16x16x32_bf16 v[64:67], v[186:189], v[168:171], v[64:67]
	v_mfma_f32_16x16x32_bf16 v[116:119], v[180:183], v[148:151], v[116:119]
	v_mfma_f32_16x16x32_bf16 v[112:115], v[204:207], v[148:151], v[112:115]
	v_mfma_f32_16x16x32_bf16 v[100:103], v[180:183], v[156:159], v[100:103]
	v_mfma_f32_16x16x32_bf16 v[96:99], v[204:207], v[156:159], v[96:99]
	v_mfma_f32_16x16x32_bf16 v[84:87], v[180:183], v[164:167], v[84:87]
	v_mfma_f32_16x16x32_bf16 v[80:83], v[204:207], v[164:167], v[80:83]
	v_mfma_f32_16x16x32_bf16 v[68:71], v[180:183], v[172:175], v[68:71]
	v_mfma_f32_16x16x32_bf16 v[64:67], v[204:207], v[172:175], v[64:67]
	s_setprio 0
	s_mov_b32 m0, s55
	v_lshl_add_u64 v[212:213], s[78:79], 0, v[194:195]
	s_barrier
	ds_read_b128 v[144:147], v235 offset:16384
	ds_read_b128 v[148:151], v235 offset:17408
	ds_read_b128 v[152:155], v235 offset:18432
	ds_read_b128 v[156:159], v235 offset:19456
	ds_read_b128 v[160:163], v235 offset:20480
	ds_read_b128 v[164:167], v235 offset:21504
	ds_read_b128 v[168:171], v235 offset:22528
	ds_read_b128 v[172:175], v235 offset:23552
	global_load_lds_dwordx4 v[212:213], off
	v_lshl_add_u64 v[214:215], s[78:79], 0, v[196:197]
	s_mov_b32 m0, s60
	s_nop 0
	global_load_lds_dwordx4 v[214:215], off
	s_barrier
	s_waitcnt lgkmcnt(0)
	s_setprio 1
	s_waitcnt lgkmcnt(0)
	v_mfma_f32_16x16x32_bf16 v[60:63], v[128:131], v[144:147], v[60:63]
	v_mfma_f32_16x16x32_bf16 v[56:59], v[136:139], v[144:147], v[56:59]
	v_mfma_f32_16x16x32_bf16 v[44:47], v[128:131], v[152:155], v[44:47]
	v_mfma_f32_16x16x32_bf16 v[40:43], v[136:139], v[152:155], v[40:43]
	v_mfma_f32_16x16x32_bf16 v[28:31], v[128:131], v[160:163], v[28:31]
	v_mfma_f32_16x16x32_bf16 v[24:27], v[136:139], v[160:163], v[24:27]
	v_mfma_f32_16x16x32_bf16 v[12:15], v[128:131], v[168:171], v[12:15]
	v_mfma_f32_16x16x32_bf16 v[8:11], v[136:139], v[168:171], v[8:11]
	v_mfma_f32_16x16x32_bf16 v[60:63], v[132:135], v[148:151], v[60:63]
	v_mfma_f32_16x16x32_bf16 v[56:59], v[140:143], v[148:151], v[56:59]
	v_mfma_f32_16x16x32_bf16 v[44:47], v[132:135], v[156:159], v[44:47]
	v_mfma_f32_16x16x32_bf16 v[40:43], v[140:143], v[156:159], v[40:43]
	v_mfma_f32_16x16x32_bf16 v[28:31], v[132:135], v[164:167], v[28:31]
	v_mfma_f32_16x16x32_bf16 v[24:27], v[140:143], v[164:167], v[24:27]
	v_mfma_f32_16x16x32_bf16 v[12:15], v[132:135], v[172:175], v[12:15]
	v_mfma_f32_16x16x32_bf16 v[8:11], v[140:143], v[172:175], v[8:11]
	s_setprio 0
	s_barrier
; #define PG_STAGE(bufoff, gbase, voff) do { _Pragma("unroll") for (int _i = 0; _i < 2; ++_i) \
;     __builtin_amdgcn_global_load_lds((const unsigned*)((const char*)(gbase) + (voff)[_i]), (PG_LAS unsigned*)(lds + (bufoff) + ldsw + _i * 8192), 16, 0, 0); } while (0)
; #define PG_LDA(dst, b, h) do { _Pragma("unroll") for (int m = 0; m < 4; ++m) _Pragma("unroll") for (int k = 0; k < 2; ++k) dst[m][k] = *(const PG_LAS bf16x8*)(lds + PG_SA(b, h) + aoff + m * 2048 + k * 1024); } while (0)
; #define PG_LDB(dst, b, h) do { _Pragma("unroll") for (int n = 0; n < 2; ++n) _Pragma("unroll") for (int k = 0; k < 2; ++k) dst[n][k] = *(const PG_LAS bf16x8*)(lds + PG_SB(b, h) + boff + n * 2048 + k * 1024); } while (0)
; #define PG_MMA(ai, bj, At, Bt) do { __builtin_amdgcn_s_setprio(1); _Pragma("unroll") for (int m = 0; m < 4; ++m) _Pragma("unroll") for (int n = 0; n < 2; ++n) _Pragma("unroll") for (int k = 0; k < 2; ++k) \
;     acc[ai][bj][m][n] = __builtin_amdgcn_mfma_f32_16x16x32_bf16(Bt[n][k], At[m][k], acc[ai][bj][m][n], 0, 0, 0); __builtin_amdgcn_s_setprio(0); } while (0)
; #define PG_WAIT_V(n) asm volatile("s_waitcnt vmcnt(" #n ")" ::: "memory")
; template <class Epi>
; DEV void pg_gemm_phase(PG_LAS unsigned char* lds, const u16* gA, const u16* gBt, int M, int N, int K, const PgOrder& S, const Epi& E) {
;     ...
;       PG_LDB(B0, 0, 0); PG_SCHED; PG_LDA(At, 0, 0); PG_STAGE(PG_SA(1, 1), a1 + hstepA, voffA);
;       PG_WAIT_L(8); PG_BAR; PG_WAIT_L(0); PG_MMA(0, 0, At, B0); PG_BAR; PG_SCHED;
;       PG_LDB(B1, 0, 1); PG_STAGE(PG_SB(0, 0), b2, voffB);
;       PG_BAR; PG_WAIT_L(0); PG_MMA(0, 1, At, B1); PG_BAR;
;       PG_LDA(At, 0, 1); PG_STAGE(PG_SA(0, 0), a2, voffA);
;       PG_BAR; PG_WAIT_L(0); PG_MMA(1, 0, At, B0); PG_BAR; PG_SCHED;
;       PG_STAGE(PG_SB(0, 1), b2 + hstepB, voffB);
;       PG_WAIT_V(6); PG_BAR; PG_MMA(1, 1, At, B1); PG_BAR;
;       PG_LDB(B0, 1, 0); PG_SCHED; PG_LDA(At, 1, 0); PG_STAGE(PG_SA(0, 1), a2 + hstepA, voffA);
;       PG_WAIT_L(8); PG_BAR; PG_WAIT_L(0); PG_MMA(0, 0, At, B0); PG_BAR; PG_SCHED;
;       PG_LDB(B1, 1, 1); PG_STAGE(PG_SB(1, 0), b3, voffB);
;       PG_BAR; PG_WAIT_L(0); PG_MMA(0, 1, At, B1); PG_BAR;
;       PG_LDA(At, 1, 1); PG_STAGE(PG_SA(1, 0), a3, voffA);
;       PG_BAR; PG_WAIT_L(0); PG_MMA(1, 0, At, B0); PG_BAR; PG_SCHED;
;       PG_STAGE(PG_SB(1, 1), b3 + hstepB, voffB);
;       PG_WAIT_V(6); PG_BAR; PG_MMA(1, 1, At, B1); PG_BAR;
	s_add_u32 s90, s74, 0x10000
	s_addc_u32 s91, s75, 0
	s_add_i32 s89, s92, s54
	v_lshl_add_u64 v[128:129], s[90:91], 0, v[184:185]
	s_mov_b32 m0, s89
	s_nop 0
	global_load_lds_dwordx4 v[128:129], off
	v_lshl_add_u64 v[128:129], s[90:91], 0, v[198:199]
	s_add_i32 m0, s89, 0x2000
	s_nop 0
	global_load_lds_dwordx4 v[128:129], off
	s_waitcnt vmcnt(6)
	s_barrier
	s_setprio 1
	v_mfma_f32_16x16x32_bf16 v[52:55], v[176:179], v[144:147], v[52:55]
	v_mfma_f32_16x16x32_bf16 v[48:51], v[186:189], v[144:147], v[48:51]
	v_mfma_f32_16x16x32_bf16 v[36:39], v[176:179], v[152:155], v[36:39]
	v_mfma_f32_16x16x32_bf16 v[32:35], v[186:189], v[152:155], v[32:35]
	v_mfma_f32_16x16x32_bf16 v[20:23], v[176:179], v[160:163], v[20:23]
	v_mfma_f32_16x16x32_bf16 v[16:19], v[186:189], v[160:163], v[16:19]
	v_mfma_f32_16x16x32_bf16 v[4:7], v[176:179], v[168:171], v[4:7]
	v_mfma_f32_16x16x32_bf16 v[0:3], v[186:189], v[168:171], v[0:3]
	v_mfma_f32_16x16x32_bf16 v[52:55], v[180:183], v[148:151], v[52:55]
	v_mfma_f32_16x16x32_bf16 v[48:51], v[204:207], v[148:151], v[48:51]
	v_mfma_f32_16x16x32_bf16 v[36:39], v[180:183], v[156:159], v[36:39]
	v_mfma_f32_16x16x32_bf16 v[32:35], v[204:207], v[156:159], v[32:35]
	v_mfma_f32_16x16x32_bf16 v[20:23], v[180:183], v[164:167], v[20:23]
	v_mfma_f32_16x16x32_bf16 v[16:19], v[204:207], v[164:167], v[16:19]
	v_mfma_f32_16x16x32_bf16 v[4:7], v[180:183], v[172:175], v[4:7]
	v_mfma_f32_16x16x32_bf16 v[0:3], v[204:207], v[172:175], v[0:3]
	s_setprio 0
	s_add_i32 s89, 0, 0x18000
	v_add_u32_e32 v140, s89, v233
	s_barrier
	ds_read_b128 v[128:131], v140
	ds_read_b128 v[132:135], v140 offset:1024
	ds_read_b128 v[136:139], v140 offset:2048
	ds_read_b128 v[140:143], v140 offset:3072
	s_add_u32 s78, s78, 0x40000
	s_addc_u32 s79, s79, 0
	s_mov_b32 m0, s61
	v_lshl_add_u64 v[176:177], s[78:79], 0, v[194:195]
	ds_read_b128 v[144:147], v235 offset:32768
	ds_read_b128 v[148:151], v235 offset:33792
	ds_read_b128 v[152:155], v235 offset:34816
	ds_read_b128 v[156:159], v235 offset:35840
	ds_read_b128 v[160:163], v235 offset:36864
	ds_read_b128 v[164:167], v235 offset:37888
	ds_read_b128 v[168:171], v235 offset:38912
	ds_read_b128 v[172:175], v235 offset:39936
	global_load_lds_dwordx4 v[176:177], off
	v_lshl_add_u64 v[176:177], s[78:79], 0, v[196:197]
	s_mov_b32 m0, s62
	s_nop 0
	global_load_lds_dwordx4 v[176:177], off
	s_waitcnt lgkmcnt(8)
	s_barrier
	s_waitcnt lgkmcnt(0)
	s_setprio 1
	s_waitcnt lgkmcnt(0)
	v_mfma_f32_16x16x32_bf16 v[124:127], v[128:131], v[144:147], v[124:127]
	v_mfma_f32_16x16x32_bf16 v[120:123], v[136:139], v[144:147], v[120:123]
	v_mfma_f32_16x16x32_bf16 v[108:111], v[128:131], v[152:155], v[108:111]
	v_mfma_f32_16x16x32_bf16 v[104:107], v[136:139], v[152:155], v[104:107]
	v_mfma_f32_16x16x32_bf16 v[92:95], v[128:131], v[160:163], v[92:95]
	v_mfma_f32_16x16x32_bf16 v[88:91], v[136:139], v[160:163], v[88:91]
	v_mfma_f32_16x16x32_bf16 v[76:79], v[128:131], v[168:171], v[76:79]
	v_mfma_f32_16x16x32_bf16 v[72:75], v[136:139], v[168:171], v[72:75]
	v_mfma_f32_16x16x32_bf16 v[124:127], v[132:135], v[148:151], v[124:127]
	v_mfma_f32_16x16x32_bf16 v[120:123], v[140:143], v[148:151], v[120:123]
	v_mfma_f32_16x16x32_bf16 v[108:111], v[132:135], v[156:159], v[108:111]
	v_mfma_f32_16x16x32_bf16 v[104:107], v[140:143], v[156:159], v[104:107]
	v_mfma_f32_16x16x32_bf16 v[92:95], v[132:135], v[164:167], v[92:95]
	v_mfma_f32_16x16x32_bf16 v[88:91], v[140:143], v[164:167], v[88:91]
	v_mfma_f32_16x16x32_bf16 v[76:79], v[132:135], v[172:175], v[76:79]
	v_mfma_f32_16x16x32_bf16 v[72:75], v[140:143], v[172:175], v[72:75]
	s_setprio 0
	s_barrier
	s_add_i32 s78, 0, 0x1c000
	s_add_i32 s79, s89, s54
	v_add_u32_e32 v204, s78, v233
	v_lshl_add_u64 v[208:209], v[208:209], 0, s[30:31]
	s_mov_b32 m0, s79
	ds_read_b128 v[176:179], v204
	ds_read_b128 v[180:183], v204 offset:1024
	ds_read_b128 v[186:189], v204 offset:2048
	ds_read_b128 v[204:207], v204 offset:3072
	global_load_lds_dwordx4 v[208:209], off
	v_lshl_add_u64 v[208:209], v[210:211], 0, s[30:31]
	s_add_i32 m0, s79, 0x2000
	s_nop 0
	global_load_lds_dwordx4 v[208:209], off
	s_barrier
	s_waitcnt lgkmcnt(0)
	s_setprio 1
	s_waitcnt lgkmcnt(0)
	v_mfma_f32_16x16x32_bf16 v[116:119], v[176:179], v[144:147], v[116:119]
	v_mfma_f32_16x16x32_bf16 v[112:115], v[186:189], v[144:147], v[112:115]
	v_mfma_f32_16x16x32_bf16 v[100:103], v[176:179], v[152:155], v[100:103]
	v_mfma_f32_16x16x32_bf16 v[96:99], v[186:189], v[152:155], v[96:99]
	v_mfma_f32_16x16x32_bf16 v[84:87], v[176:179], v[160:163], v[84:87]
	v_mfma_f32_16x16x32_bf16 v[80:83], v[186:189], v[160:163], v[80:83]
	v_mfma_f32_16x16x32_bf16 v[68:71], v[176:179], v[168:171], v[68:71]
	v_mfma_f32_16x16x32_bf16 v[64:67], v[186:189], v[168:171], v[64:67]
	v_mfma_f32_16x16x32_bf16 v[116:119], v[180:183], v[148:151], v[116:119]
	v_mfma_f32_16x16x32_bf16 v[112:115], v[204:207], v[148:151], v[112:115]
	v_mfma_f32_16x16x32_bf16 v[100:103], v[180:183], v[156:159], v[100:103]
	v_mfma_f32_16x16x32_bf16 v[96:99], v[204:207], v[156:159], v[96:99]
	v_mfma_f32_16x16x32_bf16 v[84:87], v[180:183], v[164:167], v[84:87]
	v_mfma_f32_16x16x32_bf16 v[80:83], v[204:207], v[164:167], v[80:83]
	v_mfma_f32_16x16x32_bf16 v[68:71], v[180:183], v[172:175], v[68:71]
	v_mfma_f32_16x16x32_bf16 v[64:67], v[204:207], v[172:175], v[64:67]
	s_setprio 0
	s_mov_b32 m0, s63
	v_lshl_add_u64 v[208:209], v[212:213], 0, s[30:31]
	s_barrier
	ds_read_b128 v[144:147], v235 offset:49152
	ds_read_b128 v[148:151], v235 offset:50176
	ds_read_b128 v[152:155], v235 offset:51200
	ds_read_b128 v[156:159], v235 offset:52224
	ds_read_b128 v[160:163], v235 offset:53248
	ds_read_b128 v[164:167], v235 offset:54272
	ds_read_b128 v[168:171], v235 offset:55296
	ds_read_b128 v[172:175], v235 offset:56320
	global_load_lds_dwordx4 v[208:209], off
	v_lshl_add_u64 v[208:209], v[214:215], 0, s[30:31]
	s_mov_b32 m0, s64
	s_nop 0
	global_load_lds_dwordx4 v[208:209], off
	s_barrier
; #define PG_WAIT_V(n) asm volatile("s_waitcnt vmcnt(" #n ")" ::: "memory")
;   DEV void operator()(f32x4 (&acc)[2][2][4][2], const PgUnit& u, int ui, int wr, int wc, int fr, int fq) const {
;     const Params& P = *Pp; const int nt = u.pn;
;     const int n0 = nt * 256 + wc * 64 + 8 * fq;
; #pragma unroll
;     for (int ai = 0; ai < 2; ++ai) {
;       float4 xv[4][2][2];
; #pragma unroll
;       for (int m = 0; m < 4; ++m) {
;         const int t = u.pm * 256 + ai * 128 + wr * 64 + m * 16 + fr;
;         const float* xr = layer == 0 ? (batch ? P.xin1 : P.xin0) + (long)t * DM + n0 : P.out + ((long)batch * TB + t) * DM + n0;
; #pragma unroll
;         for (int bj = 0; bj < 2; ++bj) { xv[m][bj][0] = *reinterpret_cast<const float4*>(xr + bj * 32); xv[m][bj][1] = *reinterpret_cast<const float4*>(xr + bj * 32 + 4); }
;       }
; #pragma unroll
;       for (int m = 0; m < 4; ++m) {
;         const int t = u.pm * 256 + ai * 128 + wr * 64 + m * 16 + fr;
;         const long tg = (long)batch * TB + t;
;         float s = 0.f;
; #pragma unroll
;         for (int bj = 0; bj < 2; ++bj) {
;           const int n = n0 + bj * 32;
;           const float4 x0 = xv[m][bj][0], x1 = xv[m][bj][1];
;           const f32x4 a0 = acc[ai][bj][m][0], a1 = acc[ai][bj][m][1];
;           float o[8] = {x0.x + a0[0], x0.y + a0[1], x0.z + a0[2], x0.w + a0[3], x1.x + a1[0], x1.y + a1[1], x1.z + a1[2], x1.w + a1[3]};
;           *reinterpret_cast<float4*>(P.out + tg * DM + n) = make_float4(o[0], o[1], o[2], o[3]);
;           *reinterpret_cast<float4*>(P.out + tg * DM + n + 4) = make_float4(o[4], o[5], o[6], o[7]);
; template <class Epi>
; DEV void pg_gemm_phase(PG_LAS unsigned char* lds, const u16* gA, const u16* gBt, int M, int N, int K, const PgOrder& S, const Epi& E) {
;     ...
;       PG_WAIT_V(6); PG_BAR; PG_MMA(1, 1, At, B1); PG_BAR;
;       PG_LDB(B0, 1, 0); PG_SCHED; PG_LDA(At, 1, 0); PG_STAGE(PG_SA(0, 1), a2 + hstepA, voffA);
;       PG_WAIT_L(8); PG_BAR; PG_WAIT_L(0); PG_MMA(0, 0, At, B0); PG_BAR; PG_SCHED;
;       PG_LDB(B1, 1, 1); PG_STAGE(PG_SB(1, 0), b3, voffB);
;       PG_BAR; PG_WAIT_L(0); PG_MMA(0, 1, At, B1); PG_BAR;
;       PG_LDA(At, 1, 1); PG_STAGE(PG_SA(1, 0), a3, voffA);
;       PG_BAR; PG_WAIT_L(0); PG_MMA(1, 0, At, B0); PG_BAR; PG_SCHED;
;       PG_STAGE(PG_SB(1, 1), b3 + hstepB, voffB);
;       PG_WAIT_V(6); PG_BAR; PG_MMA(1, 1, At, B1); PG_BAR;
;     }
	s_waitcnt lgkmcnt(0)
	s_setprio 1
	s_waitcnt lgkmcnt(0)
	v_mfma_f32_16x16x32_bf16 v[60:63], v[128:131], v[144:147], v[60:63]
	v_mfma_f32_16x16x32_bf16 v[56:59], v[136:139], v[144:147], v[56:59]
	v_mfma_f32_16x16x32_bf16 v[44:47], v[128:131], v[152:155], v[44:47]
	v_mfma_f32_16x16x32_bf16 v[40:43], v[136:139], v[152:155], v[40:43]
	v_mfma_f32_16x16x32_bf16 v[28:31], v[128:131], v[160:163], v[28:31]
	v_mfma_f32_16x16x32_bf16 v[24:27], v[136:139], v[160:163], v[24:27]
	v_mfma_f32_16x16x32_bf16 v[12:15], v[128:131], v[168:171], v[12:15]
	v_mfma_f32_16x16x32_bf16 v[8:11], v[136:139], v[168:171], v[8:11]
	v_mfma_f32_16x16x32_bf16 v[60:63], v[132:135], v[148:151], v[60:63]
	v_mfma_f32_16x16x32_bf16 v[56:59], v[140:143], v[148:151], v[56:59]
	v_mfma_f32_16x16x32_bf16 v[44:47], v[132:135], v[156:159], v[44:47]
	v_mfma_f32_16x16x32_bf16 v[40:43], v[140:143], v[156:159], v[40:43]
	v_mfma_f32_16x16x32_bf16 v[28:31], v[132:135], v[164:167], v[28:31]
	v_mfma_f32_16x16x32_bf16 v[24:27], v[140:143], v[164:167], v[24:27]
	v_mfma_f32_16x16x32_bf16 v[12:15], v[132:135], v[172:175], v[12:15]
	v_mfma_f32_16x16x32_bf16 v[8:11], v[140:143], v[172:175], v[8:11]
	s_setprio 0
	s_barrier
	s_add_u32 s74, s74, 0x10080
	s_addc_u32 s75, s75, 0
	s_add_i32 s78, s78, s54
	v_lshl_add_u64 v[128:129], s[74:75], 0, v[184:185]
	s_mov_b32 m0, s78
	s_nop 0
	global_load_lds_dwordx4 v[128:129], off
	v_lshl_add_u64 v[128:129], s[74:75], 0, v[198:199]
	s_add_i32 m0, s78, 0x2000
	s_nop 0
	global_load_lds_dwordx4 v[128:129], off
	s_waitcnt vmcnt(6)
	s_barrier
	s_setprio 1
	v_mfma_f32_16x16x32_bf16 v[52:55], v[176:179], v[144:147], v[52:55]
	v_mfma_f32_16x16x32_bf16 v[48:51], v[186:189], v[144:147], v[48:51]
	v_mfma_f32_16x16x32_bf16 v[36:39], v[176:179], v[152:155], v[36:39]
	v_mfma_f32_16x16x32_bf16 v[32:35], v[186:189], v[152:155], v[32:35]
	v_mfma_f32_16x16x32_bf16 v[20:23], v[176:179], v[160:163], v[20:23]
	v_mfma_f32_16x16x32_bf16 v[16:19], v[186:189], v[160:163], v[16:19]
	v_mfma_f32_16x16x32_bf16 v[4:7], v[176:179], v[168:171], v[4:7]
	v_mfma_f32_16x16x32_bf16 v[0:3], v[186:189], v[168:171], v[0:3]
	v_mfma_f32_16x16x32_bf16 v[52:55], v[180:183], v[148:151], v[52:55]
	v_mfma_f32_16x16x32_bf16 v[48:51], v[204:207], v[148:151], v[48:51]
	v_mfma_f32_16x16x32_bf16 v[36:39], v[180:183], v[156:159], v[36:39]
	v_mfma_f32_16x16x32_bf16 v[32:35], v[204:207], v[156:159], v[32:35]
	v_mfma_f32_16x16x32_bf16 v[20:23], v[180:183], v[164:167], v[20:23]
	v_mfma_f32_16x16x32_bf16 v[16:19], v[204:207], v[164:167], v[16:19]
	v_mfma_f32_16x16x32_bf16 v[4:7], v[180:183], v[172:175], v[4:7]
	v_mfma_f32_16x16x32_bf16 v[0:3], v[204:207], v[172:175], v[0:3]
	s_setprio 0
	s_add_i32 s88, s88, 2
	s_add_u32 s86, s86, 0x100
	s_addc_u32 s87, s87, 0
	s_add_u32 s8, s8, 0x100
	s_addc_u32 s9, s9, 0
	s_cmp_gt_u32 s88, 13
	s_barrier
	s_cbranch_scc0 .LBB0_423
	v_lshl_add_u32 v208, s2, 8, v232
	v_lshl_or_b32 v204, s70, 8, v234
	v_ashrrev_i32_e32 v209, 31, v208
	v_or_b32_e32 v220, 16, v208
	v_ashrrev_i32_e32 v205, 31, v204
	v_lshlrev_b64 v[222:223], 12, v[208:209]
	v_ashrrev_i32_e32 v221, 31, v220
	v_lshl_add_u64 v[128:129], s[14:15], 0, v[222:223]
	v_lshlrev_b64 v[206:207], 2, v[204:205]
	v_lshlrev_b64 v[218:219], 12, v[220:221]
	v_or_b32_e32 v216, 32, v208
	v_lshl_add_u64 v[224:225], v[128:129], 0, v[206:207]
	v_lshl_add_u64 v[128:129], s[14:15], 0, v[218:219]
	v_ashrrev_i32_e32 v217, 31, v216
	v_lshl_add_u64 v[128:129], v[128:129], 0, v[206:207]
	v_lshlrev_b64 v[214:215], 12, v[216:217]
	v_or_b32_e32 v212, 48, v208
	s_waitcnt vmcnt(0)
	global_load_dwordx4 v[180:183], v[224:225], off offset:128
	global_load_dwordx4 v[176:179], v[224:225], off offset:144
	global_load_dwordx4 v[172:175], v[128:129], off
	global_load_dwordx4 v[168:171], v[128:129], off offset:16
	global_load_dwordx4 v[164:167], v[128:129], off offset:128
	global_load_dwordx4 v[160:163], v[128:129], off offset:144
	v_lshl_add_u64 v[128:129], s[14:15], 0, v[214:215]
	v_ashrrev_i32_e32 v213, 31, v212
	v_lshl_add_u64 v[128:129], v[128:129], 0, v[206:207]
	v_lshlrev_b64 v[210:211], 12, v[212:213]
	global_load_dwordx4 v[156:159], v[128:129], off
	global_load_dwordx4 v[152:155], v[128:129], off offset:16
	global_load_dwordx4 v[148:151], v[128:129], off offset:128
	global_load_dwordx4 v[144:147], v[128:129], off offset:144
	v_lshl_add_u64 v[128:129], s[14:15], 0, v[210:211]
	v_lshl_add_u64 v[128:129], v[128:129], 0, v[206:207]
	v_lshlrev_b64 v[186:187], 10, v[208:209]
	global_load_dwordx4 v[140:143], v[128:129], off
	global_load_dwordx4 v[136:139], v[128:129], off offset:16
	global_load_dwordx4 v[132:135], v[128:129], off offset:128
	s_nop 0
	global_load_dwordx4 v[128:131], v[128:129], off offset:144
	v_lshl_add_u64 v[238:239], v[186:187], 0, s[72:73]
	global_load_dwordx4 v[186:189], v[224:225], off
	v_mov_b32_e32 v236, 0
	s_andn2_b64 vcc, exec, s[84:85]
	s_waitcnt vmcnt(0) lgkmcnt(0)
	v_pk_add_f32 v[124:125], v[124:125], v[186:187]
	v_pk_add_f32 v[126:127], v[126:127], v[188:189]
	global_load_dwordx4 v[186:189], v[224:225], off offset:16
	v_lshl_add_u64 v[224:225], v[238:239], 1, s[10:11]
	s_waitcnt vmcnt(0) lgkmcnt(0)
	v_pk_add_f32 v[120:121], v[120:121], v[186:187]
	v_lshl_add_u64 v[186:187], s[12:13], 0, v[222:223]
	v_lshl_add_u64 v[222:223], v[186:187], 0, v[206:207]
	v_cndmask_b32_e64 v186, 0, 1, s[84:85]
	v_pk_add_f32 v[122:123], v[122:123], v[188:189]
	v_cmp_ne_u32_e64 s[8:9], 1, v186
	global_store_dwordx4 v[222:223], v[124:127], off
	global_store_dwordx4 v[222:223], v[120:123], off offset:16
	s_cbranch_vccnz .LBB0_426
	v_cvt_pk_bf16_f32 v186, v124, v125
	v_pk_mul_f32 v[124:125], v[124:125], v[124:125]
	v_cvt_pk_bf16_f32 v187, v126, v127
	v_pk_mul_f32 v[126:127], v[126:127], v[126:127]
	v_add_f32_e32 v124, v124, v125
	v_add_f32_e32 v124, v126, v124
	v_cvt_pk_bf16_f32 v188, v120, v121
	v_pk_mul_f32 v[120:121], v[120:121], v[120:121]
	v_add_f32_e32 v124, v127, v124
	v_add_f32_e32 v120, v120, v124
	v_cvt_pk_bf16_f32 v189, v122, v123
	v_pk_mul_f32 v[122:123], v[122:123], v[122:123]
	v_add_f32_e32 v120, v121, v120
	v_lshl_add_u64 v[236:237], v[204:205], 1, v[224:225]
	v_add_f32_e32 v120, v122, v120
	global_store_dwordx4 v[236:237], v[186:189], off
	v_add_f32_e32 v236, v123, v120
; DEV float red4(float s) { s += SWZ_XOR(s, 16); return swapsum(s); }
;   DEV void operator()(f32x4 (&acc)[2][2][4][2], const PgUnit& u, int ui, int wr, int wc, int fr, int fq) const {
;     ...
;         for (int bj = 0; bj < 2; ++bj) {
;           const int n = n0 + bj * 32;
;           const float4 x0 = xv[m][bj][0], x1 = xv[m][bj][1];
;           const f32x4 a0 = acc[ai][bj][m][0], a1 = acc[ai][bj][m][1];
;           float o[8] = {x0.x + a0[0], x0.y + a0[1], x0.z + a0[2], x0.w + a0[3], x1.x + a1[0], x1.y + a1[1], x1.z + a1[2], x1.w + a1[3]};
;           *reinterpret_cast<float4*>(P.out + tg * DM + n) = make_float4(o[0], o[1], o[2], o[3]);
;           *reinterpret_cast<float4*>(P.out + tg * DM + n + 4) = make_float4(o[4], o[5], o[6], o[7]);
;           if (layer == 0) {
;             store8bf(WS{P.ws}.XB() + tg * DM + n, o);
; #pragma unroll
;             for (int e = 0; e < 8; ++e) s += o[e] * o[e];
;           }
;         }
;         if (layer == 0) { s = red4(s); if (fq == 0) WS{P.ws}.ssq_x()[((long)batch * 16 + nt * 4 + wc) * TB + t] = s; }
.LBB0_426:
	s_lshl_b32 s2, s70, 2
	s_ashr_i32 s3, s2, 31
	s_or_b64 s[70:71], s[2:3], s[22:23]
	v_pk_add_f32 v[116:117], v[116:117], v[180:181]
	v_pk_add_f32 v[118:119], v[118:119], v[182:183]
	v_pk_add_f32 v[112:113], v[112:113], v[176:177]
	v_pk_add_f32 v[114:115], v[114:115], v[178:179]
	s_and_b64 vcc, exec, s[8:9]
	global_store_dwordx4 v[222:223], v[116:119], off offset:128
	global_store_dwordx4 v[222:223], v[112:115], off offset:144
	s_cbranch_vccnz .LBB0_430
	v_cvt_pk_bf16_f32 v120, v116, v117
	v_pk_mul_f32 v[116:117], v[116:117], v[116:117]
	v_lshl_add_u64 v[124:125], v[204:205], 1, v[224:225]
	v_add_f32_e32 v116, v116, v236
	v_cvt_pk_bf16_f32 v121, v118, v119
	v_cvt_pk_bf16_f32 v122, v112, v113
	v_cvt_pk_bf16_f32 v123, v114, v115
	global_store_dwordx4 v[124:125], v[120:123], off offset:64
	v_pk_mul_f32 v[112:113], v[112:113], v[112:113]
	s_nop 0
	v_add_f32_e32 v120, v117, v116
	v_pk_mul_f32 v[116:117], v[118:119], v[118:119]
	s_nop 0
	v_add_f32_e32 v116, v116, v120
	v_add_f32_e32 v116, v117, v116
	v_add_f32_e32 v112, v112, v116
	v_add_f32_e32 v116, v113, v112
	v_pk_mul_f32 v[112:113], v[114:115], v[114:115]
	s_nop 0
	v_add_f32_e32 v112, v112, v116
	v_add_f32_e32 v112, v113, v112
	ds_swizzle_b32 v113, v112 offset:swizzle(SWAP,16)
	s_waitcnt lgkmcnt(0)
	v_add_f32_e32 v112, v112, v113
	v_mov_b32_e32 v113, v112
	s_nop 1
	v_permlane32_swap_b32_e32 v112, v113
	s_and_saveexec_b64 s[2:3], s[4:5]
	s_cbranch_execz .LBB0_429
	s_lshl_b64 s[74:75], s[70:71], 16
	s_add_u32 s74, s82, s74
	s_addc_u32 s75, s83, s75
	v_add_f32_e32 v114, v112, v113
	v_lshl_add_u64 v[112:113], v[208:209], 2, s[74:75]
	global_store_dword v[112:113], v114, off

; DEV float red4(float s) { s += SWZ_XOR(s, 16); return swapsum(s); }
;   DEV void operator()(f32x4 (&acc)[2][2][4][2], const PgUnit& u, int ui, int wr, int wc, int fr, int fq) const {
;     ...
;       for (int m = 0; m < 4; ++m) {
;         const int t = u.pm * 256 + ai * 128 + wr * 64 + m * 16 + fr;
;         const float* xr = layer == 0 ? (batch ? P.xin1 : P.xin0) + (long)t * DM + n0 : P.out + ((long)batch * TB + t) * DM + n0;
; #pragma unroll
;         for (int bj = 0; bj < 2; ++bj) { xv[m][bj][0] = *reinterpret_cast<const float4*>(xr + bj * 32); xv[m][bj][1] = *reinterpret_cast<const float4*>(xr + bj * 32 + 4); }
;       }
; #pragma unroll
;       for (int m = 0; m < 4; ++m) {
;         const int t = u.pm * 256 + ai * 128 + wr * 64 + m * 16 + fr;
;         const long tg = (long)batch * TB + t;
;         float s = 0.f;
; #pragma unroll
;         for (int bj = 0; bj < 2; ++bj) {
;           const int n = n0 + bj * 32;
;           const float4 x0 = xv[m][bj][0], x1 = xv[m][bj][1];
;           const f32x4 a0 = acc[ai][bj][m][0], a1 = acc[ai][bj][m][1];
;           float o[8] = {x0.x + a0[0], x0.y + a0[1], x0.z + a0[2], x0.w + a0[3], x1.x + a1[0], x1.y + a1[1], x1.z + a1[2], x1.w + a1[3]};
;           *reinterpret_cast<float4*>(P.out + tg * DM + n) = make_float4(o[0], o[1], o[2], o[3]);
;           *reinterpret_cast<float4*>(P.out + tg * DM + n + 4) = make_float4(o[4], o[5], o[6], o[7]);
;           if (layer == 0) {
;             store8bf(WS{P.ws}.XB() + tg * DM + n, o);
; #pragma unroll
;             for (int e = 0; e < 8; ++e) s += o[e] * o[e];
;           }
;         }
;         if (layer == 0) { s = red4(s); if (fq == 0) WS{P.ws}.ssq_x()[((long)batch * 16 + nt * 4 + wc) * TB + t] = s; }
.LBB0_430:
	s_nop 0
	v_lshlrev_b64 v[112:113], 10, v[220:221]
	v_lshl_add_u64 v[114:115], v[112:113], 0, s[72:73]
	v_lshl_add_u64 v[112:113], s[12:13], 0, v[218:219]
	v_pk_add_f32 v[108:109], v[108:109], v[172:173]
	v_pk_add_f32 v[110:111], v[110:111], v[174:175]
	v_pk_add_f32 v[104:105], v[104:105], v[168:169]
	v_pk_add_f32 v[106:107], v[106:107], v[170:171]
	v_lshl_add_u64 v[112:113], v[204:205], 2, v[112:113]
	v_mov_b32_e32 v116, 0
	s_and_b64 vcc, exec, s[8:9]
	v_lshl_add_u64 v[114:115], v[114:115], 1, s[10:11]
	global_store_dwordx4 v[112:113], v[108:111], off
	global_store_dwordx4 v[112:113], v[104:107], off offset:16
	s_cbranch_vccnz .LBB0_432
	v_cvt_pk_bf16_f32 v116, v108, v109
	v_pk_mul_f32 v[108:109], v[108:109], v[108:109]
	v_cvt_pk_bf16_f32 v117, v110, v111
	v_pk_mul_f32 v[110:111], v[110:111], v[110:111]
	v_add_f32_e32 v108, v108, v109
	v_add_f32_e32 v108, v110, v108
	v_cvt_pk_bf16_f32 v118, v104, v105
	v_pk_mul_f32 v[104:105], v[104:105], v[104:105]
	v_add_f32_e32 v108, v111, v108
	v_add_f32_e32 v104, v104, v108
	v_cvt_pk_bf16_f32 v119, v106, v107
	v_pk_mul_f32 v[106:107], v[106:107], v[106:107]
	v_add_f32_e32 v104, v105, v104
	v_lshl_add_u64 v[120:121], v[204:205], 1, v[114:115]
	v_add_f32_e32 v104, v106, v104
	global_store_dwordx4 v[120:121], v[116:119], off
	s_nop 1
	v_add_f32_e32 v116, v107, v104
.LBB0_432:
	v_pk_add_f32 v[100:101], v[100:101], v[164:165]
	v_pk_add_f32 v[102:103], v[102:103], v[166:167]
	v_pk_add_f32 v[96:97], v[96:97], v[160:161]
	v_pk_add_f32 v[98:99], v[98:99], v[162:163]
	s_and_b64 vcc, exec, s[8:9]
	global_store_dwordx4 v[112:113], v[100:103], off offset:128
	global_store_dwordx4 v[112:113], v[96:99], off offset:144
	s_cbranch_vccnz .LBB0_436
	v_cvt_pk_bf16_f32 v104, v100, v101
	v_pk_mul_f32 v[100:101], v[100:101], v[100:101]
	v_lshl_add_u64 v[108:109], v[204:205], 1, v[114:115]
	v_add_f32_e32 v100, v100, v116
	v_cvt_pk_bf16_f32 v105, v102, v103
	v_cvt_pk_bf16_f32 v106, v96, v97
	v_cvt_pk_bf16_f32 v107, v98, v99
	global_store_dwordx4 v[108:109], v[104:107], off offset:64
	v_pk_mul_f32 v[96:97], v[96:97], v[96:97]
	s_nop 0
	v_add_f32_e32 v104, v101, v100
	v_pk_mul_f32 v[100:101], v[102:103], v[102:103]
	s_nop 0
	v_add_f32_e32 v100, v100, v104
	v_add_f32_e32 v100, v101, v100
	v_add_f32_e32 v96, v96, v100
	v_add_f32_e32 v100, v97, v96
	v_pk_mul_f32 v[96:97], v[98:99], v[98:99]
	s_nop 0
	v_add_f32_e32 v96, v96, v100
	v_add_f32_e32 v96, v97, v96
	ds_swizzle_b32 v97, v96 offset:swizzle(SWAP,16)
	s_waitcnt lgkmcnt(0)
	v_add_f32_e32 v96, v96, v97
	v_mov_b32_e32 v97, v96
	s_nop 1
	v_permlane32_swap_b32_e32 v96, v97
	s_and_saveexec_b64 s[2:3], s[4:5]
	s_cbranch_execz .LBB0_435
	s_lshl_b64 s[74:75], s[70:71], 16
	s_add_u32 s74, s82, s74
	s_addc_u32 s75, s83, s75
	v_add_f32_e32 v98, v96, v97
	v_lshl_add_u64 v[96:97], v[208:209], 2, s[74:75]
	global_store_dword v[96:97], v98, off offset:64

; DEV float red4(float s) { s += SWZ_XOR(s, 16); return swapsum(s); }
;   DEV void operator()(f32x4 (&acc)[2][2][4][2], const PgUnit& u, int ui, int wr, int wc, int fr, int fq) const {
;     ...
;       for (int m = 0; m < 4; ++m) {
;         const int t = u.pm * 256 + ai * 128 + wr * 64 + m * 16 + fr;
;         const long tg = (long)batch * TB + t;
;         float s = 0.f;
; #pragma unroll
;         for (int bj = 0; bj < 2; ++bj) {
;           const int n = n0 + bj * 32;
;           const float4 x0 = xv[m][bj][0], x1 = xv[m][bj][1];
;           const f32x4 a0 = acc[ai][bj][m][0], a1 = acc[ai][bj][m][1];
;           float o[8] = {x0.x + a0[0], x0.y + a0[1], x0.z + a0[2], x0.w + a0[3], x1.x + a1[0], x1.y + a1[1], x1.z + a1[2], x1.w + a1[3]};
;           *reinterpret_cast<float4*>(P.out + tg * DM + n) = make_float4(o[0], o[1], o[2], o[3]);
;           *reinterpret_cast<float4*>(P.out + tg * DM + n + 4) = make_float4(o[4], o[5], o[6], o[7]);
;           if (layer == 0) {
;             store8bf(WS{P.ws}.XB() + tg * DM + n, o);
; #pragma unroll
;             for (int e = 0; e < 8; ++e) s += o[e] * o[e];
;           }
;         }
;         if (layer == 0) { s = red4(s); if (fq == 0) WS{P.ws}.ssq_x()[((long)batch * 16 + nt * 4 + wc) * TB + t] = s; }
.LBB0_436:
	s_nop 0
	v_lshlrev_b64 v[96:97], 10, v[216:217]
	v_lshl_add_u64 v[98:99], v[96:97], 0, s[72:73]
	v_lshl_add_u64 v[96:97], s[12:13], 0, v[214:215]
	v_pk_add_f32 v[92:93], v[92:93], v[156:157]
	v_pk_add_f32 v[94:95], v[94:95], v[158:159]
	v_pk_add_f32 v[88:89], v[88:89], v[152:153]
	v_pk_add_f32 v[90:91], v[90:91], v[154:155]
	v_lshl_add_u64 v[96:97], v[204:205], 2, v[96:97]
	v_mov_b32_e32 v100, 0
	s_and_b64 vcc, exec, s[8:9]
	v_lshl_add_u64 v[98:99], v[98:99], 1, s[10:11]
	global_store_dwordx4 v[96:97], v[92:95], off
	global_store_dwordx4 v[96:97], v[88:91], off offset:16
	s_cbranch_vccnz .LBB0_438
	v_cvt_pk_bf16_f32 v100, v92, v93
	v_pk_mul_f32 v[92:93], v[92:93], v[92:93]
	v_cvt_pk_bf16_f32 v101, v94, v95
	v_pk_mul_f32 v[94:95], v[94:95], v[94:95]
	v_add_f32_e32 v92, v92, v93
	v_add_f32_e32 v92, v94, v92
	v_cvt_pk_bf16_f32 v102, v88, v89
	v_pk_mul_f32 v[88:89], v[88:89], v[88:89]
	v_add_f32_e32 v92, v95, v92
	v_add_f32_e32 v88, v88, v92
	v_cvt_pk_bf16_f32 v103, v90, v91
	v_pk_mul_f32 v[90:91], v[90:91], v[90:91]
	v_add_f32_e32 v88, v89, v88
	v_lshl_add_u64 v[104:105], v[204:205], 1, v[98:99]
	v_add_f32_e32 v88, v90, v88
	global_store_dwordx4 v[104:105], v[100:103], off
	s_nop 1
	v_add_f32_e32 v100, v91, v88
.LBB0_438:
	v_pk_add_f32 v[84:85], v[84:85], v[148:149]
	v_pk_add_f32 v[86:87], v[86:87], v[150:151]
	v_pk_add_f32 v[80:81], v[80:81], v[144:145]
	v_pk_add_f32 v[82:83], v[82:83], v[146:147]
	s_and_b64 vcc, exec, s[8:9]
	global_store_dwordx4 v[96:97], v[84:87], off offset:128
	global_store_dwordx4 v[96:97], v[80:83], off offset:144
	s_cbranch_vccnz .LBB0_442
	v_cvt_pk_bf16_f32 v88, v84, v85
	v_pk_mul_f32 v[84:85], v[84:85], v[84:85]
	v_lshl_add_u64 v[92:93], v[204:205], 1, v[98:99]
	v_add_f32_e32 v84, v84, v100
	v_cvt_pk_bf16_f32 v89, v86, v87
	v_cvt_pk_bf16_f32 v90, v80, v81
	v_cvt_pk_bf16_f32 v91, v82, v83
	global_store_dwordx4 v[92:93], v[88:91], off offset:64
	v_pk_mul_f32 v[80:81], v[80:81], v[80:81]
	s_nop 0
	v_add_f32_e32 v88, v85, v84
	v_pk_mul_f32 v[84:85], v[86:87], v[86:87]
	s_nop 0
	v_add_f32_e32 v84, v84, v88
	v_add_f32_e32 v84, v85, v84
	v_add_f32_e32 v80, v80, v84
	v_add_f32_e32 v84, v81, v80
	v_pk_mul_f32 v[80:81], v[82:83], v[82:83]
	s_nop 0
	v_add_f32_e32 v80, v80, v84
	v_add_f32_e32 v80, v81, v80
	ds_swizzle_b32 v81, v80 offset:swizzle(SWAP,16)
	s_waitcnt lgkmcnt(0)
	v_add_f32_e32 v80, v80, v81
	v_mov_b32_e32 v81, v80
	s_nop 1
	v_permlane32_swap_b32_e32 v80, v81
	s_and_saveexec_b64 s[2:3], s[4:5]
	s_cbranch_execz .LBB0_441
	s_lshl_b64 s[74:75], s[70:71], 16
	s_add_u32 s74, s82, s74
	s_addc_u32 s75, s83, s75
	v_add_f32_e32 v82, v80, v81
	v_lshl_add_u64 v[80:81], v[208:209], 2, s[74:75]
	global_store_dword v[80:81], v82, off offset:128

; DEV float red4(float s) { s += SWZ_XOR(s, 16); return swapsum(s); }
;   DEV void operator()(f32x4 (&acc)[2][2][4][2], const PgUnit& u, int ui, int wr, int wc, int fr, int fq) const {
;     ...
;       for (int m = 0; m < 4; ++m) {
;         const int t = u.pm * 256 + ai * 128 + wr * 64 + m * 16 + fr;
;         const long tg = (long)batch * TB + t;
;         float s = 0.f;
; #pragma unroll
;         for (int bj = 0; bj < 2; ++bj) {
;           const int n = n0 + bj * 32;
;           const float4 x0 = xv[m][bj][0], x1 = xv[m][bj][1];
;           const f32x4 a0 = acc[ai][bj][m][0], a1 = acc[ai][bj][m][1];
;           float o[8] = {x0.x + a0[0], x0.y + a0[1], x0.z + a0[2], x0.w + a0[3], x1.x + a1[0], x1.y + a1[1], x1.z + a1[2], x1.w + a1[3]};
;           *reinterpret_cast<float4*>(P.out + tg * DM + n) = make_float4(o[0], o[1], o[2], o[3]);
;           *reinterpret_cast<float4*>(P.out + tg * DM + n + 4) = make_float4(o[4], o[5], o[6], o[7]);
;           if (layer == 0) {
;             store8bf(WS{P.ws}.XB() + tg * DM + n, o);
; #pragma unroll
;             for (int e = 0; e < 8; ++e) s += o[e] * o[e];
;           }
;         }
;         if (layer == 0) { s = red4(s); if (fq == 0) WS{P.ws}.ssq_x()[((long)batch * 16 + nt * 4 + wc) * TB + t] = s; }
.LBB0_442:
	s_nop 0
	v_lshlrev_b64 v[80:81], 10, v[212:213]
	v_lshl_add_u64 v[82:83], v[80:81], 0, s[72:73]
	v_lshl_add_u64 v[80:81], s[12:13], 0, v[210:211]
	v_pk_add_f32 v[76:77], v[76:77], v[140:141]
	v_pk_add_f32 v[78:79], v[78:79], v[142:143]
	v_pk_add_f32 v[72:73], v[72:73], v[136:137]
	v_pk_add_f32 v[74:75], v[74:75], v[138:139]
	v_lshl_add_u64 v[80:81], v[204:205], 2, v[80:81]
	v_mov_b32_e32 v84, 0
	s_and_b64 vcc, exec, s[8:9]
	v_lshl_add_u64 v[82:83], v[82:83], 1, s[10:11]
	global_store_dwordx4 v[80:81], v[76:79], off
	global_store_dwordx4 v[80:81], v[72:75], off offset:16
	s_cbranch_vccnz .LBB0_444
	v_cvt_pk_bf16_f32 v84, v76, v77
	v_pk_mul_f32 v[76:77], v[76:77], v[76:77]
	v_cvt_pk_bf16_f32 v85, v78, v79
	v_pk_mul_f32 v[78:79], v[78:79], v[78:79]
	v_add_f32_e32 v76, v76, v77
	v_add_f32_e32 v76, v78, v76
	v_cvt_pk_bf16_f32 v86, v72, v73
	v_pk_mul_f32 v[72:73], v[72:73], v[72:73]
	v_add_f32_e32 v76, v79, v76
	v_add_f32_e32 v72, v72, v76
	v_cvt_pk_bf16_f32 v87, v74, v75
	v_pk_mul_f32 v[74:75], v[74:75], v[74:75]
	v_add_f32_e32 v72, v73, v72
	v_lshl_add_u64 v[88:89], v[204:205], 1, v[82:83]
	v_add_f32_e32 v72, v74, v72
	global_store_dwordx4 v[88:89], v[84:87], off
	s_nop 1
	v_add_f32_e32 v84, v75, v72
.LBB0_444:
	v_pk_add_f32 v[68:69], v[68:69], v[132:133]
	v_pk_add_f32 v[70:71], v[70:71], v[134:135]
	v_pk_add_f32 v[64:65], v[64:65], v[128:129]
	v_pk_add_f32 v[66:67], v[66:67], v[130:131]
	s_and_b64 vcc, exec, s[8:9]
	v_mov_b64_e32 v[72:73], s[12:13]
	global_store_dwordx4 v[80:81], v[68:71], off offset:128
	global_store_dwordx4 v[80:81], v[64:67], off offset:144
	s_cbranch_vccnz .LBB0_448
	v_cvt_pk_bf16_f32 v72, v68, v69
	v_pk_mul_f32 v[68:69], v[68:69], v[68:69]
	v_lshl_add_u64 v[76:77], v[204:205], 1, v[82:83]
	v_add_f32_e32 v68, v68, v84
	v_cvt_pk_bf16_f32 v73, v70, v71
	v_cvt_pk_bf16_f32 v74, v64, v65
	v_cvt_pk_bf16_f32 v75, v66, v67
	global_store_dwordx4 v[76:77], v[72:75], off offset:64
	v_pk_mul_f32 v[64:65], v[64:65], v[64:65]
	s_nop 0
	v_add_f32_e32 v72, v69, v68
	v_pk_mul_f32 v[68:69], v[70:71], v[70:71]
	s_nop 0
	v_add_f32_e32 v68, v68, v72
	v_add_f32_e32 v68, v69, v68
	v_add_f32_e32 v64, v64, v68
	v_add_f32_e32 v68, v65, v64
	v_pk_mul_f32 v[64:65], v[66:67], v[66:67]
	v_mov_b64_e32 v[72:73], s[76:77]
	v_add_f32_e32 v64, v64, v68
	v_add_f32_e32 v64, v65, v64
	ds_swizzle_b32 v65, v64 offset:swizzle(SWAP,16)
	s_waitcnt lgkmcnt(0)
	v_add_f32_e32 v64, v64, v65
	v_mov_b32_e32 v65, v64
	s_nop 1
	v_permlane32_swap_b32_e32 v64, v65
	s_and_saveexec_b64 s[2:3], s[4:5]
	s_cbranch_execz .LBB0_447
	s_lshl_b64 s[74:75], s[70:71], 16
	s_add_u32 s74, s82, s74
	s_addc_u32 s75, s83, s75
	v_add_f32_e32 v66, v64, v65
	v_lshl_add_u64 v[64:65], v[208:209], 2, s[74:75]
	v_mov_b64_e32 v[72:73], s[76:77]
	global_store_dword v[64:65], v66, off offset:192

; DEV float red4(float s) { s += SWZ_XOR(s, 16); return swapsum(s); }
;   DEV void operator()(f32x4 (&acc)[2][2][4][2], const PgUnit& u, int ui, int wr, int wc, int fr, int fq) const {
;     ...
;     for (int ai = 0; ai < 2; ++ai) {
;       float4 xv[4][2][2];
; #pragma unroll
;       for (int m = 0; m < 4; ++m) {
;         const int t = u.pm * 256 + ai * 128 + wr * 64 + m * 16 + fr;
;         const float* xr = layer == 0 ? (batch ? P.xin1 : P.xin0) + (long)t * DM + n0 : P.out + ((long)batch * TB + t) * DM + n0;
; #pragma unroll
;         for (int bj = 0; bj < 2; ++bj) { xv[m][bj][0] = *reinterpret_cast<const float4*>(xr + bj * 32); xv[m][bj][1] = *reinterpret_cast<const float4*>(xr + bj * 32 + 4); }
;       }
; #pragma unroll
;       for (int m = 0; m < 4; ++m) {
;         const int t = u.pm * 256 + ai * 128 + wr * 64 + m * 16 + fr;
;         const long tg = (long)batch * TB + t;
;         float s = 0.f;
; #pragma unroll
;         for (int bj = 0; bj < 2; ++bj) {
;           const int n = n0 + bj * 32;
;           const float4 x0 = xv[m][bj][0], x1 = xv[m][bj][1];
;           const f32x4 a0 = acc[ai][bj][m][0], a1 = acc[ai][bj][m][1];
;           float o[8] = {x0.x + a0[0], x0.y + a0[1], x0.z + a0[2], x0.w + a0[3], x1.x + a1[0], x1.y + a1[1], x1.z + a1[2], x1.w + a1[3]};
;           *reinterpret_cast<float4*>(P.out + tg * DM + n) = make_float4(o[0], o[1], o[2], o[3]);
;           *reinterpret_cast<float4*>(P.out + tg * DM + n + 4) = make_float4(o[4], o[5], o[6], o[7]);
;           if (layer == 0) {
;             store8bf(WS{P.ws}.XB() + tg * DM + n, o);
; #pragma unroll
;             for (int e = 0; e < 8; ++e) s += o[e] * o[e];
;           }
;         }
;         if (layer == 0) { s = red4(s); if (fq == 0) WS{P.ws}.ssq_x()[((long)batch * 16 + nt * 4 + wc) * TB + t] = s; }
.LBB0_448:
	v_add_u32_e32 v132, 0x80, v208
	v_ashrrev_i32_e32 v133, 31, v132
	v_add_u32_e32 v128, 0x90, v208
	v_lshlrev_b64 v[138:139], 12, v[132:133]
	v_ashrrev_i32_e32 v129, 31, v128
	v_lshl_add_u64 v[64:65], s[14:15], 0, v[138:139]
	v_lshlrev_b64 v[130:131], 12, v[128:129]
	v_add_u32_e32 v124, 0xa0, v208
	v_lshl_add_u64 v[140:141], v[64:65], 0, v[206:207]
	v_lshl_add_u64 v[64:65], s[14:15], 0, v[130:131]
	v_ashrrev_i32_e32 v125, 31, v124
	v_lshl_add_u64 v[64:65], v[64:65], 0, v[206:207]
	v_lshlrev_b64 v[126:127], 12, v[124:125]
	v_add_u32_e32 v120, 0xb0, v208
	global_load_dwordx4 v[116:119], v[140:141], off offset:128
	global_load_dwordx4 v[112:115], v[140:141], off offset:144
	global_load_dwordx4 v[108:111], v[64:65], off
	global_load_dwordx4 v[104:107], v[64:65], off offset:16
	global_load_dwordx4 v[100:103], v[64:65], off offset:128
	global_load_dwordx4 v[96:99], v[64:65], off offset:144
	v_lshl_add_u64 v[64:65], s[14:15], 0, v[126:127]
	v_ashrrev_i32_e32 v121, 31, v120
	v_lshl_add_u64 v[64:65], v[64:65], 0, v[206:207]
	v_lshlrev_b64 v[122:123], 12, v[120:121]
	global_load_dwordx4 v[92:95], v[64:65], off
	global_load_dwordx4 v[88:91], v[64:65], off offset:16
	global_load_dwordx4 v[84:87], v[64:65], off offset:128
	global_load_dwordx4 v[80:83], v[64:65], off offset:144
	v_lshl_add_u64 v[64:65], v[72:73], 0, v[122:123]
	v_lshl_add_u64 v[64:65], v[64:65], 0, v[206:207]
	v_lshlrev_b64 v[134:135], 10, v[132:133]
	global_load_dwordx4 v[76:79], v[64:65], off
	global_load_dwordx4 v[72:75], v[64:65], off offset:16
	global_load_dwordx4 v[68:71], v[64:65], off offset:128
	s_nop 0
	global_load_dwordx4 v[64:67], v[64:65], off offset:144
	v_lshl_add_u64 v[142:143], v[134:135], 0, s[72:73]
	global_load_dwordx4 v[134:137], v[140:141], off
	s_and_b64 vcc, exec, s[8:9]
	s_waitcnt vmcnt(0) lgkmcnt(0)
	v_pk_add_f32 v[60:61], v[60:61], v[134:135]
	v_pk_add_f32 v[62:63], v[62:63], v[136:137]
	global_load_dwordx4 v[134:137], v[140:141], off offset:16
	s_waitcnt vmcnt(0) lgkmcnt(0)
	v_pk_add_f32 v[56:57], v[56:57], v[134:135]
	v_lshl_add_u64 v[134:135], s[12:13], 0, v[138:139]
	v_pk_add_f32 v[58:59], v[58:59], v[136:137]
	v_lshl_add_u64 v[134:135], v[134:135], 0, v[206:207]
	v_mov_b32_e32 v138, 0
	v_lshl_add_u64 v[136:137], v[142:143], 1, s[10:11]
	global_store_dwordx4 v[134:135], v[60:63], off
	global_store_dwordx4 v[134:135], v[56:59], off offset:16
	s_cbranch_vccnz .LBB0_450
	v_cvt_pk_bf16_f32 v138, v60, v61
	v_pk_mul_f32 v[60:61], v[60:61], v[60:61]
	v_cvt_pk_bf16_f32 v139, v62, v63
	v_pk_mul_f32 v[62:63], v[62:63], v[62:63]
	v_add_f32_e32 v60, v60, v61
	v_add_f32_e32 v60, v62, v60
	v_cvt_pk_bf16_f32 v140, v56, v57
	v_pk_mul_f32 v[56:57], v[56:57], v[56:57]
	v_add_f32_e32 v60, v63, v60
	v_add_f32_e32 v56, v56, v60
	v_cvt_pk_bf16_f32 v141, v58, v59
	v_pk_mul_f32 v[58:59], v[58:59], v[58:59]
	v_add_f32_e32 v56, v57, v56
	v_lshl_add_u64 v[142:143], v[204:205], 1, v[136:137]
	v_add_f32_e32 v56, v58, v56
	global_store_dwordx4 v[142:143], v[138:141], off
	s_nop 1
	v_add_f32_e32 v138, v59, v56
.LBB0_450:
	v_pk_add_f32 v[52:53], v[52:53], v[116:117]
	v_pk_add_f32 v[54:55], v[54:55], v[118:119]
	v_pk_add_f32 v[48:49], v[48:49], v[112:113]
	v_pk_add_f32 v[50:51], v[50:51], v[114:115]
	s_and_b64 vcc, exec, s[8:9]
	global_store_dwordx4 v[134:135], v[52:55], off offset:128
	global_store_dwordx4 v[134:135], v[48:51], off offset:144
	s_cbranch_vccnz .LBB0_454
	v_cvt_pk_bf16_f32 v56, v52, v53
	v_pk_mul_f32 v[52:53], v[52:53], v[52:53]
	v_lshl_add_u64 v[60:61], v[204:205], 1, v[136:137]
	v_add_f32_e32 v52, v52, v138
	v_cvt_pk_bf16_f32 v57, v54, v55
	v_cvt_pk_bf16_f32 v58, v48, v49
	v_cvt_pk_bf16_f32 v59, v50, v51
	global_store_dwordx4 v[60:61], v[56:59], off offset:64
	v_pk_mul_f32 v[48:49], v[48:49], v[48:49]
	s_nop 0
	v_add_f32_e32 v56, v53, v52
	v_pk_mul_f32 v[52:53], v[54:55], v[54:55]
	s_nop 0
	v_add_f32_e32 v52, v52, v56
	v_add_f32_e32 v52, v53, v52
	v_add_f32_e32 v48, v48, v52
	v_add_f32_e32 v52, v49, v48
	v_pk_mul_f32 v[48:49], v[50:51], v[50:51]
	s_nop 0
	v_add_f32_e32 v48, v48, v52
	v_add_f32_e32 v48, v49, v48
	ds_swizzle_b32 v49, v48 offset:swizzle(SWAP,16)
	s_waitcnt lgkmcnt(0)
	v_add_f32_e32 v48, v48, v49
	v_mov_b32_e32 v49, v48
	s_nop 1
	v_permlane32_swap_b32_e32 v48, v49
	s_and_saveexec_b64 s[2:3], s[4:5]
	s_cbranch_execz .LBB0_453
	s_lshl_b64 s[74:75], s[70:71], 16
	s_add_u32 s74, s82, s74
	s_addc_u32 s75, s83, s75
	v_add_f32_e32 v50, v48, v49
	v_lshl_add_u64 v[48:49], v[132:133], 2, s[74:75]
	global_store_dword v[48:49], v50, off

; DEV float red4(float s) { s += SWZ_XOR(s, 16); return swapsum(s); }
;   DEV void operator()(f32x4 (&acc)[2][2][4][2], const PgUnit& u, int ui, int wr, int wc, int fr, int fq) const {
;     ...
;       for (int m = 0; m < 4; ++m) {
;         const int t = u.pm * 256 + ai * 128 + wr * 64 + m * 16 + fr;
;         const long tg = (long)batch * TB + t;
;         float s = 0.f;
; #pragma unroll
;         for (int bj = 0; bj < 2; ++bj) {
;           const int n = n0 + bj * 32;
;           const float4 x0 = xv[m][bj][0], x1 = xv[m][bj][1];
;           const f32x4 a0 = acc[ai][bj][m][0], a1 = acc[ai][bj][m][1];
;           float o[8] = {x0.x + a0[0], x0.y + a0[1], x0.z + a0[2], x0.w + a0[3], x1.x + a1[0], x1.y + a1[1], x1.z + a1[2], x1.w + a1[3]};
;           *reinterpret_cast<float4*>(P.out + tg * DM + n) = make_float4(o[0], o[1], o[2], o[3]);
;           *reinterpret_cast<float4*>(P.out + tg * DM + n + 4) = make_float4(o[4], o[5], o[6], o[7]);
;           if (layer == 0) {
;             store8bf(WS{P.ws}.XB() + tg * DM + n, o);
; #pragma unroll
;             for (int e = 0; e < 8; ++e) s += o[e] * o[e];
;           }
;         }
;         if (layer == 0) { s = red4(s); if (fq == 0) WS{P.ws}.ssq_x()[((long)batch * 16 + nt * 4 + wc) * TB + t] = s; }
.LBB0_454:
	s_nop 0
	v_lshlrev_b64 v[48:49], 10, v[128:129]
	v_lshl_add_u64 v[50:51], v[48:49], 0, s[72:73]
	v_lshl_add_u64 v[48:49], s[12:13], 0, v[130:131]
	v_pk_add_f32 v[44:45], v[44:45], v[108:109]
	v_pk_add_f32 v[46:47], v[46:47], v[110:111]
	v_pk_add_f32 v[40:41], v[40:41], v[104:105]
	v_pk_add_f32 v[42:43], v[42:43], v[106:107]
	v_lshl_add_u64 v[48:49], v[204:205], 2, v[48:49]
	v_mov_b32_e32 v52, 0
	s_and_b64 vcc, exec, s[8:9]
	v_lshl_add_u64 v[50:51], v[50:51], 1, s[10:11]
	global_store_dwordx4 v[48:49], v[44:47], off
	global_store_dwordx4 v[48:49], v[40:43], off offset:16
	s_cbranch_vccnz .LBB0_456
	v_cvt_pk_bf16_f32 v52, v44, v45
	v_pk_mul_f32 v[44:45], v[44:45], v[44:45]
	v_cvt_pk_bf16_f32 v53, v46, v47
	v_pk_mul_f32 v[46:47], v[46:47], v[46:47]
	v_add_f32_e32 v44, v44, v45
	v_add_f32_e32 v44, v46, v44
	v_cvt_pk_bf16_f32 v54, v40, v41
	v_pk_mul_f32 v[40:41], v[40:41], v[40:41]
	v_add_f32_e32 v44, v47, v44
	v_add_f32_e32 v40, v40, v44
	v_cvt_pk_bf16_f32 v55, v42, v43
	v_pk_mul_f32 v[42:43], v[42:43], v[42:43]
	v_add_f32_e32 v40, v41, v40
	v_lshl_add_u64 v[56:57], v[204:205], 1, v[50:51]
	v_add_f32_e32 v40, v42, v40
	global_store_dwordx4 v[56:57], v[52:55], off
	s_nop 1
	v_add_f32_e32 v52, v43, v40
.LBB0_456:
	v_pk_add_f32 v[36:37], v[36:37], v[100:101]
	v_pk_add_f32 v[38:39], v[38:39], v[102:103]
	v_pk_add_f32 v[32:33], v[32:33], v[96:97]
	v_pk_add_f32 v[34:35], v[34:35], v[98:99]
	s_and_b64 vcc, exec, s[8:9]
	global_store_dwordx4 v[48:49], v[36:39], off offset:128
	global_store_dwordx4 v[48:49], v[32:35], off offset:144
	s_cbranch_vccnz .LBB0_460
	v_cvt_pk_bf16_f32 v40, v36, v37
	v_pk_mul_f32 v[36:37], v[36:37], v[36:37]
	v_lshl_add_u64 v[44:45], v[204:205], 1, v[50:51]
	v_add_f32_e32 v36, v36, v52
	v_cvt_pk_bf16_f32 v41, v38, v39
	v_cvt_pk_bf16_f32 v42, v32, v33
	v_cvt_pk_bf16_f32 v43, v34, v35
	global_store_dwordx4 v[44:45], v[40:43], off offset:64
	v_pk_mul_f32 v[32:33], v[32:33], v[32:33]
	s_nop 0
	v_add_f32_e32 v40, v37, v36
	v_pk_mul_f32 v[36:37], v[38:39], v[38:39]
	s_nop 0
	v_add_f32_e32 v36, v36, v40
	v_add_f32_e32 v36, v37, v36
	v_add_f32_e32 v32, v32, v36
	v_add_f32_e32 v36, v33, v32
	v_pk_mul_f32 v[32:33], v[34:35], v[34:35]
	s_nop 0
	v_add_f32_e32 v32, v32, v36
	v_add_f32_e32 v32, v33, v32
	ds_swizzle_b32 v33, v32 offset:swizzle(SWAP,16)
	s_waitcnt lgkmcnt(0)
	v_add_f32_e32 v32, v32, v33
	v_mov_b32_e32 v33, v32
	s_nop 1
	v_permlane32_swap_b32_e32 v32, v33
	s_and_saveexec_b64 s[2:3], s[4:5]
	s_cbranch_execz .LBB0_459
	s_lshl_b64 s[74:75], s[70:71], 16
	s_add_u32 s74, s82, s74
	s_addc_u32 s75, s83, s75
	v_add_f32_e32 v34, v32, v33
	v_lshl_add_u64 v[32:33], v[128:129], 2, s[74:75]
	global_store_dword v[32:33], v34, off

; DEV float red4(float s) { s += SWZ_XOR(s, 16); return swapsum(s); }
;   DEV void operator()(f32x4 (&acc)[2][2][4][2], const PgUnit& u, int ui, int wr, int wc, int fr, int fq) const {
;     ...
;       for (int m = 0; m < 4; ++m) {
;         const int t = u.pm * 256 + ai * 128 + wr * 64 + m * 16 + fr;
;         const long tg = (long)batch * TB + t;
;         float s = 0.f;
; #pragma unroll
;         for (int bj = 0; bj < 2; ++bj) {
;           const int n = n0 + bj * 32;
;           const float4 x0 = xv[m][bj][0], x1 = xv[m][bj][1];
;           const f32x4 a0 = acc[ai][bj][m][0], a1 = acc[ai][bj][m][1];
;           float o[8] = {x0.x + a0[0], x0.y + a0[1], x0.z + a0[2], x0.w + a0[3], x1.x + a1[0], x1.y + a1[1], x1.z + a1[2], x1.w + a1[3]};
;           *reinterpret_cast<float4*>(P.out + tg * DM + n) = make_float4(o[0], o[1], o[2], o[3]);
;           *reinterpret_cast<float4*>(P.out + tg * DM + n + 4) = make_float4(o[4], o[5], o[6], o[7]);
;           if (layer == 0) {
;             store8bf(WS{P.ws}.XB() + tg * DM + n, o);
; #pragma unroll
;             for (int e = 0; e < 8; ++e) s += o[e] * o[e];
;           }
;         }
;         if (layer == 0) { s = red4(s); if (fq == 0) WS{P.ws}.ssq_x()[((long)batch * 16 + nt * 4 + wc) * TB + t] = s; }
.LBB0_460:
	s_nop 0
	v_lshlrev_b64 v[32:33], 10, v[124:125]
	v_lshl_add_u64 v[34:35], v[32:33], 0, s[72:73]
	v_lshl_add_u64 v[32:33], s[12:13], 0, v[126:127]
	v_pk_add_f32 v[28:29], v[28:29], v[92:93]
	v_pk_add_f32 v[30:31], v[30:31], v[94:95]
	v_pk_add_f32 v[24:25], v[24:25], v[88:89]
	v_pk_add_f32 v[26:27], v[26:27], v[90:91]
	v_lshl_add_u64 v[32:33], v[204:205], 2, v[32:33]
	v_mov_b32_e32 v36, 0
	s_and_b64 vcc, exec, s[8:9]
	v_lshl_add_u64 v[34:35], v[34:35], 1, s[10:11]
	global_store_dwordx4 v[32:33], v[28:31], off
	global_store_dwordx4 v[32:33], v[24:27], off offset:16
	s_cbranch_vccnz .LBB0_462
	v_cvt_pk_bf16_f32 v36, v28, v29
	v_pk_mul_f32 v[28:29], v[28:29], v[28:29]
	v_cvt_pk_bf16_f32 v37, v30, v31
	v_pk_mul_f32 v[30:31], v[30:31], v[30:31]
	v_add_f32_e32 v28, v28, v29
	v_add_f32_e32 v28, v30, v28
	v_cvt_pk_bf16_f32 v38, v24, v25
	v_pk_mul_f32 v[24:25], v[24:25], v[24:25]
	v_add_f32_e32 v28, v31, v28
	v_add_f32_e32 v24, v24, v28
	v_cvt_pk_bf16_f32 v39, v26, v27
	v_pk_mul_f32 v[26:27], v[26:27], v[26:27]
	v_add_f32_e32 v24, v25, v24
	v_lshl_add_u64 v[40:41], v[204:205], 1, v[34:35]
	v_add_f32_e32 v24, v26, v24
	global_store_dwordx4 v[40:41], v[36:39], off
	s_nop 1
	v_add_f32_e32 v36, v27, v24
.LBB0_462:
	v_pk_add_f32 v[20:21], v[20:21], v[84:85]
	v_pk_add_f32 v[22:23], v[22:23], v[86:87]
	v_pk_add_f32 v[16:17], v[16:17], v[80:81]
	v_pk_add_f32 v[18:19], v[18:19], v[82:83]
	s_and_b64 vcc, exec, s[8:9]
	global_store_dwordx4 v[32:33], v[20:23], off offset:128
	global_store_dwordx4 v[32:33], v[16:19], off offset:144
	s_cbranch_vccnz .LBB0_466
	v_cvt_pk_bf16_f32 v24, v20, v21
	v_pk_mul_f32 v[20:21], v[20:21], v[20:21]
	v_lshl_add_u64 v[28:29], v[204:205], 1, v[34:35]
	v_add_f32_e32 v20, v20, v36
	v_cvt_pk_bf16_f32 v25, v22, v23
	v_cvt_pk_bf16_f32 v26, v16, v17
	v_cvt_pk_bf16_f32 v27, v18, v19
	global_store_dwordx4 v[28:29], v[24:27], off offset:64
	v_pk_mul_f32 v[16:17], v[16:17], v[16:17]
	s_nop 0
	v_add_f32_e32 v24, v21, v20
	v_pk_mul_f32 v[20:21], v[22:23], v[22:23]
	s_nop 0
	v_add_f32_e32 v20, v20, v24
	v_add_f32_e32 v20, v21, v20
	v_add_f32_e32 v16, v16, v20
	v_add_f32_e32 v20, v17, v16
	v_pk_mul_f32 v[16:17], v[18:19], v[18:19]
	s_nop 0
	v_add_f32_e32 v16, v16, v20
	v_add_f32_e32 v16, v17, v16
	ds_swizzle_b32 v17, v16 offset:swizzle(SWAP,16)
	s_waitcnt lgkmcnt(0)
	v_add_f32_e32 v16, v16, v17
	v_mov_b32_e32 v17, v16
	s_nop 1
	v_permlane32_swap_b32_e32 v16, v17
	s_and_saveexec_b64 s[2:3], s[4:5]
	s_cbranch_execz .LBB0_465
	s_lshl_b64 s[74:75], s[70:71], 16
	s_add_u32 s74, s82, s74
	s_addc_u32 s75, s83, s75
	v_add_f32_e32 v18, v16, v17
	v_lshl_add_u64 v[16:17], v[124:125], 2, s[74:75]
	global_store_dword v[16:17], v18, off

; DEV float red4(float s) { s += SWZ_XOR(s, 16); return swapsum(s); }
;   DEV void operator()(f32x4 (&acc)[2][2][4][2], const PgUnit& u, int ui, int wr, int wc, int fr, int fq) const {
;     ...
;       for (int m = 0; m < 4; ++m) {
;         const int t = u.pm * 256 + ai * 128 + wr * 64 + m * 16 + fr;
;         const long tg = (long)batch * TB + t;
;         float s = 0.f;
; #pragma unroll
;         for (int bj = 0; bj < 2; ++bj) {
;           const int n = n0 + bj * 32;
;           const float4 x0 = xv[m][bj][0], x1 = xv[m][bj][1];
;           const f32x4 a0 = acc[ai][bj][m][0], a1 = acc[ai][bj][m][1];
;           float o[8] = {x0.x + a0[0], x0.y + a0[1], x0.z + a0[2], x0.w + a0[3], x1.x + a1[0], x1.y + a1[1], x1.z + a1[2], x1.w + a1[3]};
;           *reinterpret_cast<float4*>(P.out + tg * DM + n) = make_float4(o[0], o[1], o[2], o[3]);
;           *reinterpret_cast<float4*>(P.out + tg * DM + n + 4) = make_float4(o[4], o[5], o[6], o[7]);
;           if (layer == 0) {
;             store8bf(WS{P.ws}.XB() + tg * DM + n, o);
; #pragma unroll
;             for (int e = 0; e < 8; ++e) s += o[e] * o[e];
;           }
;         }
;         if (layer == 0) { s = red4(s); if (fq == 0) WS{P.ws}.ssq_x()[((long)batch * 16 + nt * 4 + wc) * TB + t] = s; }
; template <class Epi>
; DEV void pg_gemm_phase(PG_LAS unsigned char* lds, const u16* gA, const u16* gBt, int M, int N, int K, const PgOrder& S, const Epi& E) {
;     ...
;     E(acc, cur, ui, wr, wc, fr, fq);
.LBB0_466:
	s_nop 0
	v_lshlrev_b64 v[16:17], 10, v[120:121]
	v_lshl_add_u64 v[18:19], v[16:17], 0, s[72:73]
	v_lshl_add_u64 v[16:17], s[12:13], 0, v[122:123]
	v_pk_add_f32 v[12:13], v[12:13], v[76:77]
	v_pk_add_f32 v[14:15], v[14:15], v[78:79]
	v_pk_add_f32 v[8:9], v[8:9], v[72:73]
	v_pk_add_f32 v[10:11], v[10:11], v[74:75]
	v_lshl_add_u64 v[16:17], v[204:205], 2, v[16:17]
	v_mov_b32_e32 v20, 0
	s_and_b64 vcc, exec, s[8:9]
	v_lshl_add_u64 v[18:19], v[18:19], 1, s[10:11]
	global_store_dwordx4 v[16:17], v[12:15], off
	global_store_dwordx4 v[16:17], v[8:11], off offset:16
	s_cbranch_vccnz .LBB0_468
	v_cvt_pk_bf16_f32 v20, v12, v13
	v_pk_mul_f32 v[12:13], v[12:13], v[12:13]
	v_cvt_pk_bf16_f32 v21, v14, v15
	v_pk_mul_f32 v[14:15], v[14:15], v[14:15]
	v_add_f32_e32 v12, v12, v13
	v_add_f32_e32 v12, v14, v12
	v_cvt_pk_bf16_f32 v22, v8, v9
	v_pk_mul_f32 v[8:9], v[8:9], v[8:9]
	v_add_f32_e32 v12, v15, v12
	v_add_f32_e32 v8, v8, v12
	v_cvt_pk_bf16_f32 v23, v10, v11
	v_pk_mul_f32 v[10:11], v[10:11], v[10:11]
	v_add_f32_e32 v8, v9, v8
	v_lshl_add_u64 v[24:25], v[204:205], 1, v[18:19]
	v_add_f32_e32 v8, v10, v8
	global_store_dwordx4 v[24:25], v[20:23], off
	s_nop 1
	v_add_f32_e32 v20, v11, v8
.LBB0_468:
	v_pk_add_f32 v[4:5], v[4:5], v[68:69]
	v_pk_add_f32 v[6:7], v[6:7], v[70:71]
	v_pk_add_f32 v[0:1], v[0:1], v[64:65]
	v_pk_add_f32 v[2:3], v[2:3], v[66:67]
	s_and_b64 vcc, exec, s[8:9]
	global_store_dwordx4 v[16:17], v[4:7], off offset:128
	global_store_dwordx4 v[16:17], v[0:3], off offset:144
	s_cbranch_vccnz .LBB0_415
	v_cvt_pk_bf16_f32 v8, v4, v5
	v_pk_mul_f32 v[4:5], v[4:5], v[4:5]
	v_lshl_add_u64 v[12:13], v[204:205], 1, v[18:19]
	v_add_f32_e32 v4, v4, v20
	v_cvt_pk_bf16_f32 v9, v6, v7
	v_cvt_pk_bf16_f32 v10, v0, v1
	v_cvt_pk_bf16_f32 v11, v2, v3
	global_store_dwordx4 v[12:13], v[8:11], off offset:64
	v_pk_mul_f32 v[0:1], v[0:1], v[0:1]
	s_nop 0
	v_add_f32_e32 v8, v5, v4
	v_pk_mul_f32 v[4:5], v[6:7], v[6:7]
	s_nop 0
	v_add_f32_e32 v4, v4, v8
	v_add_f32_e32 v4, v5, v4
	v_add_f32_e32 v0, v0, v4
	v_add_f32_e32 v4, v1, v0
	v_pk_mul_f32 v[0:1], v[2:3], v[2:3]
	s_nop 0
	v_add_f32_e32 v0, v0, v4
	v_add_f32_e32 v0, v1, v0
	ds_swizzle_b32 v1, v0 offset:swizzle(SWAP,16)
	s_waitcnt lgkmcnt(0)
	v_add_f32_e32 v0, v0, v1
	v_mov_b32_e32 v1, v0
	s_nop 1
	v_permlane32_swap_b32_e32 v0, v1
	s_and_saveexec_b64 s[2:3], s[4:5]
	s_cbranch_execz .LBB0_414
	s_lshl_b64 s[8:9], s[70:71], 16
	s_add_u32 s8, s82, s8
	s_addc_u32 s9, s83, s9
	v_add_f32_e32 v2, v0, v1
	v_lshl_add_u64 v[0:1], v[120:121], 2, s[8:9]
	global_store_dword v[0:1], v2, off
	s_branch .LBB0_414
